# GEMM K-loops: removed the compiler's duplicate lgkmcnt(0) that directly followed an identical wait before each MFMA group (74 sites)
# speedup vs baseline: 1.0116x; 1.0116x over previous
; #define PG8_STAGE(bufoff, gbase, voff) do { _Pragma("unroll") for (int _i = 0; _i < 2; ++_i) \
;         __builtin_amdgcn_global_load_lds((const unsigned*)((const char*)(gbase) + (voff)[_i]), (LAS unsigned*)(lds + (bufoff) + ldsw + _i * 8192), 16, 0, 0); } while (0)
; #define PG8_STAGE_A(bufoff, gbase, h, vv) do { if constexpr (GATHER) { _Pragma("unroll") for (int _i = 0; _i < 2; ++_i) \
;         __builtin_amdgcn_global_load_lds((const unsigned*)((const char*)(gbase) + (vv)[h][_i]), (LAS unsigned*)(lds + (bufoff) + ldsw + _i * 8192), 16, 0, 0); } \
;         else { PG8_STAGE(bufoff, (gbase) + (h) * hstepA, voffA); } } while (0)
; #define PG8_LDA(dst, b, h) do { _Pragma("unroll") for (int m = 0; m < 4; ++m) _Pragma("unroll") for (int k = 0; k < 2; ++k) dst[m][k] = *(const LAS bf16x8*)(lds + PG8_SA(b, h) + aoff + m * 2048 + k * 1024); } while (0)
; #define PG8_LDB(dst, b, h) do { _Pragma("unroll") for (int n = 0; n < 2; ++n) _Pragma("unroll") for (int k = 0; k < 2; ++k) dst[n][k] = *(const LAS bf16x8*)(lds + PG8_SB(b, h) + boff + n * 2048 + k * 1024); } while (0)
; #define PG8_WAIT_L(n) asm volatile("s_waitcnt lgkmcnt(" #n ")" ::: "memory")
; template <class Epi, class Sched>
; __device__ __forceinline__ void gemm_phase(LAS unsigned char* lds, const int K, const int lda, const int ldb, const Sched& S, const Epi& E) {
;     ...
;         for (int t = 0; t < nt; t += 2) {
;             const bool last = (t == nt - 2);
;             const char* a1 = cA + (size_t)(t + 1) * kstep;
;             const char* a2 = last ? nA : cA + (size_t)(t + 2) * kstep; const char* b2 = last ? nB : cB + (size_t)(t + 2) * kstep;
;             const char* a3 = a2 + kstep; const char* b3 = b2 + kstep;
;             PG8_LDB(B0, 0, 0); PG8_SCHED; PG8_LDA(At, 0, 0); PG8_STAGE_A(PG8_SA(1, 1), a1, 1, vcur);
;             if constexpr (GATHER) { if (last) {
; #pragma unroll
;                 for (int h = 0; h < 2; ++h)
; #pragma unroll
;                     for (int i = 0; i < 2; ++i) vcur[h][i] = vnxt[h][i]; } }
;             PG8_WAIT_L(8); PG8_BAR; PG8_WAIT_L(0); PG8_MMA(0, 0, At, B0); PG8_BAR; PG8_SCHED;
;             PG8_LDB(B1, 0, 1); PG8_STAGE(PG8_SB(0, 0), b2, voffB);
;             PG8_BAR; PG8_WAIT_L(0); PG8_MMA(0, 1, At, B1); PG8_BAR;
;             PG8_LDA(At, 0, 1); PG8_STAGE_A(PG8_SA(0, 0), a2, 0, vcur);
;             PG8_BAR; PG8_WAIT_L(0); PG8_MMA(1, 0, At, B0); PG8_BAR; PG8_SCHED;
.LBB0_202:
	s_add_u32 s34, s16, 0x100
	s_addc_u32 s35, s17, 0
	s_add_i32 s2, 0, 0x10000
	v_add_u32_e32 v140, s2, v143
	ds_read_b128 v[146:149], v140
	ds_read_b128 v[150:153], v140 offset:1024
	ds_read_b128 v[154:157], v140 offset:2048
	ds_read_b128 v[158:161], v140 offset:3072
	s_cmp_eq_u32 s39, 4
	s_cselect_b64 vcc, -1, 0
	s_cselect_b32 s37, s5, s35
	s_cselect_b32 s36, s4, s34
	v_cndmask_b32_e32 v141, v139, v137, vcc
	v_cndmask_b32_e32 v140, v138, v136, vcc
	v_lshl_add_u64 v[194:195], s[16:17], 0, v[132:133]
	s_add_i32 m0, s45, 0xc000
	ds_read_b128 v[162:165], v145
	ds_read_b128 v[166:169], v145 offset:1024
	ds_read_b128 v[170:173], v145 offset:2048
	ds_read_b128 v[174:177], v145 offset:3072
	ds_read_b128 v[178:181], v145 offset:4096
	ds_read_b128 v[182:185], v145 offset:5120
	ds_read_b128 v[186:189], v145 offset:6144
	ds_read_b128 v[190:193], v145 offset:7168
	global_load_lds_dwordx4 v[194:195], off
	v_lshl_add_u64 v[194:195], s[16:17], 0, v[134:135]
	s_add_i32 m0, s45, 0xe000
	s_nop 0
	global_load_lds_dwordx4 v[194:195], off
	s_waitcnt lgkmcnt(8)
	s_barrier
	s_waitcnt lgkmcnt(0)
	s_setprio 1
	v_mfma_f32_16x16x32_bf16 v[126:129], v[146:149], v[162:165], v[126:129]
	v_mfma_f32_16x16x32_bf16 v[122:125], v[154:157], v[162:165], v[122:125]
	v_mfma_f32_16x16x32_bf16 v[118:121], v[146:149], v[170:173], v[118:121]
	v_mfma_f32_16x16x32_bf16 v[114:117], v[154:157], v[170:173], v[114:117]
	v_mfma_f32_16x16x32_bf16 v[106:109], v[146:149], v[178:181], v[106:109]
	v_mfma_f32_16x16x32_bf16 v[98:101], v[154:157], v[178:181], v[98:101]
	v_mfma_f32_16x16x32_bf16 v[90:93], v[146:149], v[186:189], v[90:93]
	v_mfma_f32_16x16x32_bf16 v[82:85], v[154:157], v[186:189], v[82:85]
	v_mfma_f32_16x16x32_bf16 v[126:129], v[150:153], v[166:169], v[126:129]
	v_mfma_f32_16x16x32_bf16 v[122:125], v[158:161], v[166:169], v[122:125]
	v_mfma_f32_16x16x32_bf16 v[118:121], v[150:153], v[174:177], v[118:121]
	v_mfma_f32_16x16x32_bf16 v[114:117], v[158:161], v[174:177], v[114:117]
	v_mfma_f32_16x16x32_bf16 v[106:109], v[150:153], v[182:185], v[106:109]
	v_mfma_f32_16x16x32_bf16 v[98:101], v[158:161], v[182:185], v[98:101]
	v_mfma_f32_16x16x32_bf16 v[90:93], v[150:153], v[190:193], v[90:93]
	v_mfma_f32_16x16x32_bf16 v[82:85], v[158:161], v[190:193], v[82:85]
	s_setprio 0
	s_barrier
	s_add_i32 s3, 0, 0x14000
	v_add_u32_e32 v194, s3, v143
	s_add_i32 s2, s2, s44
	ds_read_b128 v[216:219], v194
	ds_read_b128 v[220:223], v194 offset:1024
	ds_read_b128 v[224:227], v194 offset:2048
	ds_read_b128 v[228:231], v194 offset:3072
	v_lshl_add_u64 v[194:195], v[140:141], 0, v[0:1]
	s_mov_b32 m0, s2
	v_lshl_add_u64 v[214:215], v[140:141], 0, v[130:131]
	global_load_lds_dwordx4 v[194:195], off
	s_add_i32 m0, s2, 0x2000
	s_nop 0
	global_load_lds_dwordx4 v[214:215], off
	s_barrier
	s_waitcnt lgkmcnt(0)
	s_setprio 1
	v_mfma_f32_16x16x32_bf16 v[110:113], v[216:219], v[162:165], v[110:113]
	v_mfma_f32_16x16x32_bf16 v[102:105], v[224:227], v[162:165], v[102:105]
	v_mfma_f32_16x16x32_bf16 v[94:97], v[216:219], v[170:173], v[94:97]
	v_mfma_f32_16x16x32_bf16 v[86:89], v[224:227], v[170:173], v[86:89]
	v_mfma_f32_16x16x32_bf16 v[78:81], v[216:219], v[178:181], v[78:81]
	v_mfma_f32_16x16x32_bf16 v[74:77], v[224:227], v[178:181], v[74:77]
	v_mfma_f32_16x16x32_bf16 v[70:73], v[216:219], v[186:189], v[70:73]
	v_mfma_f32_16x16x32_bf16 v[66:69], v[224:227], v[186:189], v[66:69]
	v_mfma_f32_16x16x32_bf16 v[110:113], v[220:223], v[166:169], v[110:113]
	v_mfma_f32_16x16x32_bf16 v[102:105], v[228:231], v[166:169], v[102:105]
	v_mfma_f32_16x16x32_bf16 v[94:97], v[220:223], v[174:177], v[94:97]
	v_mfma_f32_16x16x32_bf16 v[86:89], v[228:231], v[174:177], v[86:89]
	v_mfma_f32_16x16x32_bf16 v[78:81], v[220:223], v[182:185], v[78:81]
	v_mfma_f32_16x16x32_bf16 v[74:77], v[228:231], v[182:185], v[74:77]
	v_mfma_f32_16x16x32_bf16 v[70:73], v[220:223], v[190:193], v[70:73]
	v_mfma_f32_16x16x32_bf16 v[66:69], v[228:231], v[190:193], v[66:69]
	s_setprio 0
	s_mov_b32 m0, s45
	v_lshl_add_u64 v[232:233], s[36:37], 0, v[0:1]
	s_barrier
	ds_read_b128 v[162:165], v145 offset:16384
	ds_read_b128 v[166:169], v145 offset:17408
	ds_read_b128 v[170:173], v145 offset:18432
	ds_read_b128 v[174:177], v145 offset:19456
	ds_read_b128 v[178:181], v145 offset:20480
	ds_read_b128 v[182:185], v145 offset:21504
	ds_read_b128 v[186:189], v145 offset:22528
	ds_read_b128 v[190:193], v145 offset:23552
	global_load_lds_dwordx4 v[232:233], off
	v_lshl_add_u64 v[234:235], s[36:37], 0, v[130:131]
	s_mov_b32 m0, s48
	s_nop 0
	global_load_lds_dwordx4 v[234:235], off
	s_barrier
	s_waitcnt lgkmcnt(0)
	s_setprio 1
	v_mfma_f32_16x16x32_bf16 v[62:65], v[146:149], v[162:165], v[62:65]
	v_mfma_f32_16x16x32_bf16 v[58:61], v[154:157], v[162:165], v[58:61]
	v_mfma_f32_16x16x32_bf16 v[54:57], v[146:149], v[170:173], v[54:57]
	v_mfma_f32_16x16x32_bf16 v[50:53], v[154:157], v[170:173], v[50:53]
	v_mfma_f32_16x16x32_bf16 v[38:41], v[146:149], v[178:181], v[38:41]
	v_mfma_f32_16x16x32_bf16 v[34:37], v[154:157], v[178:181], v[34:37]
	v_mfma_f32_16x16x32_bf16 v[22:25], v[146:149], v[186:189], v[22:25]
	v_mfma_f32_16x16x32_bf16 v[18:21], v[154:157], v[186:189], v[18:21]
	v_mfma_f32_16x16x32_bf16 v[62:65], v[150:153], v[166:169], v[62:65]
	v_mfma_f32_16x16x32_bf16 v[58:61], v[158:161], v[166:169], v[58:61]
	v_mfma_f32_16x16x32_bf16 v[54:57], v[150:153], v[174:177], v[54:57]
	v_mfma_f32_16x16x32_bf16 v[50:53], v[158:161], v[174:177], v[50:53]
	v_mfma_f32_16x16x32_bf16 v[38:41], v[150:153], v[182:185], v[38:41]
	v_mfma_f32_16x16x32_bf16 v[34:37], v[158:161], v[182:185], v[34:37]
	v_mfma_f32_16x16x32_bf16 v[22:25], v[150:153], v[190:193], v[22:25]
	v_mfma_f32_16x16x32_bf16 v[18:21], v[158:161], v[190:193], v[18:21]
	s_setprio 0
	s_barrier
; #define PG8_STAGE(bufoff, gbase, voff) do { _Pragma("unroll") for (int _i = 0; _i < 2; ++_i) \
;         __builtin_amdgcn_global_load_lds((const unsigned*)((const char*)(gbase) + (voff)[_i]), (LAS unsigned*)(lds + (bufoff) + ldsw + _i * 8192), 16, 0, 0); } while (0)
; #define PG8_STAGE_A(bufoff, gbase, h, vv) do { if constexpr (GATHER) { _Pragma("unroll") for (int _i = 0; _i < 2; ++_i) \
;         __builtin_amdgcn_global_load_lds((const unsigned*)((const char*)(gbase) + (vv)[h][_i]), (LAS unsigned*)(lds + (bufoff) + ldsw + _i * 8192), 16, 0, 0); } \
;         else { PG8_STAGE(bufoff, (gbase) + (h) * hstepA, voffA); } } while (0)
; #define PG8_LDA(dst, b, h) do { _Pragma("unroll") for (int m = 0; m < 4; ++m) _Pragma("unroll") for (int k = 0; k < 2; ++k) dst[m][k] = *(const LAS bf16x8*)(lds + PG8_SA(b, h) + aoff + m * 2048 + k * 1024); } while (0)
; #define PG8_LDB(dst, b, h) do { _Pragma("unroll") for (int n = 0; n < 2; ++n) _Pragma("unroll") for (int k = 0; k < 2; ++k) dst[n][k] = *(const LAS bf16x8*)(lds + PG8_SB(b, h) + boff + n * 2048 + k * 1024); } while (0)
; #define PG8_MMA(ai, bj, At, Bt) do { __builtin_amdgcn_s_setprio(1); _Pragma("unroll") for (int m = 0; m < 4; ++m) _Pragma("unroll") for (int n = 0; n < 2; ++n) _Pragma("unroll") for (int k = 0; k < 2; ++k) \
;         acc[ai][bj][m][n] = __builtin_amdgcn_mfma_f32_16x16x32_bf16(Bt[n][k], At[m][k], acc[ai][bj][m][n], 0, 0, 0); __builtin_amdgcn_s_setprio(0); } while (0)
; #define PG8_WAIT_V(n) asm volatile("s_waitcnt vmcnt(" #n ")" ::: "memory")
; #define PG8_WAIT_L(n) asm volatile("s_waitcnt lgkmcnt(" #n ")" ::: "memory")
; #define PG8_BAR __builtin_amdgcn_s_barrier()
; template <class Epi, class Sched>
; __device__ __forceinline__ void gemm_phase(LAS unsigned char* lds, const int K, const int lda, const int ldb, const Sched& S, const Epi& E) {
;     ...
;             PG8_STAGE(PG8_SB(0, 1), b2 + hstepB, voffB);
;             PG8_WAIT_V(6); PG8_BAR; PG8_MMA(1, 1, At, B1); PG8_BAR;
;             PG8_LDB(B0, 1, 0); PG8_SCHED; PG8_LDA(At, 1, 0); PG8_STAGE_A(PG8_SA(0, 1), a2, 1, vcur);
;             PG8_WAIT_L(8); PG8_BAR; PG8_WAIT_L(0); PG8_MMA(0, 0, At, B0); PG8_BAR; PG8_SCHED;
;             PG8_LDB(B1, 1, 1); PG8_STAGE(PG8_SB(1, 0), b3, voffB);
;             PG8_BAR; PG8_WAIT_L(0); PG8_MMA(0, 1, At, B1); PG8_BAR;
;             PG8_LDA(At, 1, 1); PG8_STAGE_A(PG8_SA(1, 0), a3, 0, vcur);
	v_lshl_add_u64 v[146:147], v[140:141], 0, s[40:41]
	s_add_i32 s2, s3, s44
	v_lshl_add_u64 v[148:149], v[146:147], 0, v[0:1]
	s_mov_b32 m0, s2
	v_lshl_add_u64 v[146:147], v[146:147], 0, v[130:131]
	global_load_lds_dwordx4 v[148:149], off
	s_add_i32 m0, s2, 0x2000
	s_nop 0
	global_load_lds_dwordx4 v[146:147], off
	s_waitcnt vmcnt(6)
	s_barrier
	s_setprio 1
	v_mfma_f32_16x16x32_bf16 v[46:49], v[216:219], v[162:165], v[46:49]
	v_mfma_f32_16x16x32_bf16 v[42:45], v[224:227], v[162:165], v[42:45]
	v_mfma_f32_16x16x32_bf16 v[30:33], v[216:219], v[170:173], v[30:33]
	v_mfma_f32_16x16x32_bf16 v[26:29], v[224:227], v[170:173], v[26:29]
	v_mfma_f32_16x16x32_bf16 v[14:17], v[216:219], v[178:181], v[14:17]
	v_mfma_f32_16x16x32_bf16 v[10:13], v[224:227], v[178:181], v[10:13]
	v_mfma_f32_16x16x32_bf16 v[6:9], v[216:219], v[186:189], v[6:9]
	v_mfma_f32_16x16x32_bf16 v[2:5], v[224:227], v[186:189], v[2:5]
	v_mfma_f32_16x16x32_bf16 v[46:49], v[220:223], v[166:169], v[46:49]
	v_mfma_f32_16x16x32_bf16 v[42:45], v[228:231], v[166:169], v[42:45]
	v_mfma_f32_16x16x32_bf16 v[30:33], v[220:223], v[174:177], v[30:33]
	v_mfma_f32_16x16x32_bf16 v[26:29], v[228:231], v[174:177], v[26:29]
	v_mfma_f32_16x16x32_bf16 v[14:17], v[220:223], v[182:185], v[14:17]
	v_mfma_f32_16x16x32_bf16 v[10:13], v[228:231], v[182:185], v[10:13]
	v_mfma_f32_16x16x32_bf16 v[6:9], v[220:223], v[190:193], v[6:9]
	v_mfma_f32_16x16x32_bf16 v[2:5], v[228:231], v[190:193], v[2:5]
	s_setprio 0
	s_add_i32 s2, 0, 0x18000
	v_add_u32_e32 v158, s2, v143
	s_barrier
	ds_read_b128 v[146:149], v158
	ds_read_b128 v[150:153], v158 offset:1024
	ds_read_b128 v[154:157], v158 offset:2048
	ds_read_b128 v[158:161], v158 offset:3072
	s_add_u32 s16, s36, 0xe0000
	s_addc_u32 s17, s37, 0
	s_mov_b32 m0, s49
	v_lshl_add_u64 v[216:217], s[16:17], 0, v[0:1]
	ds_read_b128 v[162:165], v145 offset:32768
	ds_read_b128 v[166:169], v145 offset:33792
	ds_read_b128 v[170:173], v145 offset:34816
	ds_read_b128 v[174:177], v145 offset:35840
	ds_read_b128 v[178:181], v145 offset:36864
	ds_read_b128 v[182:185], v145 offset:37888
	ds_read_b128 v[186:189], v145 offset:38912
	ds_read_b128 v[190:193], v145 offset:39936
	global_load_lds_dwordx4 v[216:217], off
	v_lshl_add_u64 v[216:217], s[16:17], 0, v[130:131]
	s_mov_b32 m0, s52
	s_nop 0
	global_load_lds_dwordx4 v[216:217], off
	s_waitcnt lgkmcnt(8)
	s_barrier
	s_waitcnt lgkmcnt(0)
	s_setprio 1
	v_mfma_f32_16x16x32_bf16 v[126:129], v[146:149], v[162:165], v[126:129]
	v_mfma_f32_16x16x32_bf16 v[122:125], v[154:157], v[162:165], v[122:125]
	v_mfma_f32_16x16x32_bf16 v[118:121], v[146:149], v[170:173], v[118:121]
	v_mfma_f32_16x16x32_bf16 v[114:117], v[154:157], v[170:173], v[114:117]
	v_mfma_f32_16x16x32_bf16 v[106:109], v[146:149], v[178:181], v[106:109]
	v_mfma_f32_16x16x32_bf16 v[98:101], v[154:157], v[178:181], v[98:101]
	v_mfma_f32_16x16x32_bf16 v[90:93], v[146:149], v[186:189], v[90:93]
	v_mfma_f32_16x16x32_bf16 v[82:85], v[154:157], v[186:189], v[82:85]
	v_mfma_f32_16x16x32_bf16 v[126:129], v[150:153], v[166:169], v[126:129]
	v_mfma_f32_16x16x32_bf16 v[122:125], v[158:161], v[166:169], v[122:125]
	v_mfma_f32_16x16x32_bf16 v[118:121], v[150:153], v[174:177], v[118:121]
	v_mfma_f32_16x16x32_bf16 v[114:117], v[158:161], v[174:177], v[114:117]
	v_mfma_f32_16x16x32_bf16 v[106:109], v[150:153], v[182:185], v[106:109]
	v_mfma_f32_16x16x32_bf16 v[98:101], v[158:161], v[182:185], v[98:101]
	v_mfma_f32_16x16x32_bf16 v[90:93], v[150:153], v[190:193], v[90:93]
	v_mfma_f32_16x16x32_bf16 v[82:85], v[158:161], v[190:193], v[82:85]
	s_setprio 0
	s_barrier
	s_add_i32 s3, 0, 0x1c000
	s_add_i32 s2, s2, s44
	v_add_u32_e32 v228, s3, v143
	v_lshl_add_u64 v[194:195], v[194:195], 0, s[64:65]
	s_mov_b32 m0, s2
	ds_read_b128 v[216:219], v228
	ds_read_b128 v[220:223], v228 offset:1024
	ds_read_b128 v[224:227], v228 offset:2048
	ds_read_b128 v[228:231], v228 offset:3072
	global_load_lds_dwordx4 v[194:195], off
	v_lshl_add_u64 v[194:195], v[214:215], 0, s[64:65]
	s_add_i32 m0, s2, 0x2000
	s_nop 0
	global_load_lds_dwordx4 v[194:195], off
	s_barrier
	s_waitcnt lgkmcnt(0)
	s_setprio 1
	v_mfma_f32_16x16x32_bf16 v[110:113], v[216:219], v[162:165], v[110:113]
	v_mfma_f32_16x16x32_bf16 v[102:105], v[224:227], v[162:165], v[102:105]
	v_mfma_f32_16x16x32_bf16 v[94:97], v[216:219], v[170:173], v[94:97]
	v_mfma_f32_16x16x32_bf16 v[86:89], v[224:227], v[170:173], v[86:89]
	v_mfma_f32_16x16x32_bf16 v[78:81], v[216:219], v[178:181], v[78:81]
	v_mfma_f32_16x16x32_bf16 v[74:77], v[224:227], v[178:181], v[74:77]
	v_mfma_f32_16x16x32_bf16 v[70:73], v[216:219], v[186:189], v[70:73]
	v_mfma_f32_16x16x32_bf16 v[66:69], v[224:227], v[186:189], v[66:69]
	v_mfma_f32_16x16x32_bf16 v[110:113], v[220:223], v[166:169], v[110:113]
	v_mfma_f32_16x16x32_bf16 v[102:105], v[228:231], v[166:169], v[102:105]
	v_mfma_f32_16x16x32_bf16 v[94:97], v[220:223], v[174:177], v[94:97]
	v_mfma_f32_16x16x32_bf16 v[86:89], v[228:231], v[174:177], v[86:89]
	v_mfma_f32_16x16x32_bf16 v[78:81], v[220:223], v[182:185], v[78:81]
	v_mfma_f32_16x16x32_bf16 v[74:77], v[228:231], v[182:185], v[74:77]
	v_mfma_f32_16x16x32_bf16 v[70:73], v[220:223], v[190:193], v[70:73]
	v_mfma_f32_16x16x32_bf16 v[66:69], v[228:231], v[190:193], v[66:69]
	s_setprio 0
	s_mov_b32 m0, s53
	v_lshl_add_u64 v[194:195], v[232:233], 0, s[64:65]
	s_barrier
	ds_read_b128 v[162:165], v145 offset:49152
	ds_read_b128 v[166:169], v145 offset:50176
	ds_read_b128 v[170:173], v145 offset:51200
	ds_read_b128 v[174:177], v145 offset:52224
	ds_read_b128 v[178:181], v145 offset:53248
	ds_read_b128 v[182:185], v145 offset:54272
	ds_read_b128 v[186:189], v145 offset:55296
	ds_read_b128 v[190:193], v145 offset:56320
	global_load_lds_dwordx4 v[194:195], off
	v_lshl_add_u64 v[194:195], v[234:235], 0, s[64:65]
	s_mov_b32 m0, s54
	s_nop 0
	global_load_lds_dwordx4 v[194:195], off
	s_barrier
; #define PG8_STAGE(bufoff, gbase, voff) do { _Pragma("unroll") for (int _i = 0; _i < 2; ++_i) \
;         __builtin_amdgcn_global_load_lds((const unsigned*)((const char*)(gbase) + (voff)[_i]), (LAS unsigned*)(lds + (bufoff) + ldsw + _i * 8192), 16, 0, 0); } while (0)
; #define PG8_MMA(ai, bj, At, Bt) do { __builtin_amdgcn_s_setprio(1); _Pragma("unroll") for (int m = 0; m < 4; ++m) _Pragma("unroll") for (int n = 0; n < 2; ++n) _Pragma("unroll") for (int k = 0; k < 2; ++k) \
;         acc[ai][bj][m][n] = __builtin_amdgcn_mfma_f32_16x16x32_bf16(Bt[n][k], At[m][k], acc[ai][bj][m][n], 0, 0, 0); __builtin_amdgcn_s_setprio(0); } while (0)
; #define PG8_WAIT_V(n) asm volatile("s_waitcnt vmcnt(" #n ")" ::: "memory")
; #define PG8_WAIT_L(n) asm volatile("s_waitcnt lgkmcnt(" #n ")" ::: "memory")
; #define PG8_BAR __builtin_amdgcn_s_barrier()
; #define PG8_SCHED __builtin_amdgcn_sched_barrier(0)
; template <class Epi, class Sched>
; __device__ __forceinline__ void gemm_phase(LAS unsigned char* lds, const int K, const int lda, const int ldb, const Sched& S, const Epi& E) {
;     ...
;             PG8_BAR; PG8_WAIT_L(0); PG8_MMA(1, 0, At, B0); PG8_BAR; PG8_SCHED;
;             PG8_STAGE(PG8_SB(1, 1), b3 + hstepB, voffB);
;             PG8_WAIT_V(6); PG8_BAR; PG8_MMA(1, 1, At, B1); PG8_BAR;
;         }
;     __device__ __forceinline__ void operator()(const Acc& acc, const Unit& u, int wr, int wc, int fr, int fq) const {
;         const int ks = u.pn % KSPL, pn = u.pn / KSPL;
;         const int row0 = u.pm * BM + wr * 64 + fr, col0 = pn * BM + wc * 32 + 4 * fq;
;         float* base = Yp + (size_t)ks * 2048 * D;
; #pragma unroll
;         for (int ai = 0; ai < 2; ++ai)
; #pragma unroll
;             for (int m = 0; m < 4; ++m) { float* rp = base + (size_t)(row0 + ai * HALF + m * 16) * D + col0;
; #pragma unroll
;                 for (int bj = 0; bj < 2; ++bj)
; #pragma unroll
;                     for (int n = 0; n < 2; ++n) *(f32x4*)(rp + bj * HALF + n * 16) = acc[ai][bj][m][n]; }
;     }
	s_waitcnt lgkmcnt(0)
	s_setprio 1
	v_mfma_f32_16x16x32_bf16 v[62:65], v[146:149], v[162:165], v[62:65]
	v_mfma_f32_16x16x32_bf16 v[58:61], v[154:157], v[162:165], v[58:61]
	v_mfma_f32_16x16x32_bf16 v[54:57], v[146:149], v[170:173], v[54:57]
	v_mfma_f32_16x16x32_bf16 v[50:53], v[154:157], v[170:173], v[50:53]
	v_mfma_f32_16x16x32_bf16 v[38:41], v[146:149], v[178:181], v[38:41]
	v_mfma_f32_16x16x32_bf16 v[34:37], v[154:157], v[178:181], v[34:37]
	v_mfma_f32_16x16x32_bf16 v[22:25], v[146:149], v[186:189], v[22:25]
	v_mfma_f32_16x16x32_bf16 v[18:21], v[154:157], v[186:189], v[18:21]
	v_mfma_f32_16x16x32_bf16 v[62:65], v[150:153], v[166:169], v[62:65]
	v_mfma_f32_16x16x32_bf16 v[58:61], v[158:161], v[166:169], v[58:61]
	v_mfma_f32_16x16x32_bf16 v[54:57], v[150:153], v[174:177], v[54:57]
	v_mfma_f32_16x16x32_bf16 v[50:53], v[158:161], v[174:177], v[50:53]
	v_mfma_f32_16x16x32_bf16 v[38:41], v[150:153], v[182:185], v[38:41]
	v_mfma_f32_16x16x32_bf16 v[34:37], v[158:161], v[182:185], v[34:37]
	v_mfma_f32_16x16x32_bf16 v[22:25], v[150:153], v[190:193], v[22:25]
	v_mfma_f32_16x16x32_bf16 v[18:21], v[158:161], v[190:193], v[18:21]
	s_setprio 0
	s_barrier
	v_lshl_add_u64 v[140:141], v[140:141], 0, s[42:43]
	s_add_i32 s2, s3, s44
	v_lshl_add_u64 v[146:147], v[140:141], 0, v[0:1]
	s_mov_b32 m0, s2
	v_lshl_add_u64 v[140:141], v[140:141], 0, v[130:131]
	global_load_lds_dwordx4 v[146:147], off
	s_add_i32 m0, s2, 0x2000
	s_nop 0
	global_load_lds_dwordx4 v[140:141], off
	s_waitcnt vmcnt(6)
	s_barrier
	s_setprio 1
	v_mfma_f32_16x16x32_bf16 v[46:49], v[216:219], v[162:165], v[46:49]
	v_mfma_f32_16x16x32_bf16 v[42:45], v[224:227], v[162:165], v[42:45]
	v_mfma_f32_16x16x32_bf16 v[30:33], v[216:219], v[170:173], v[30:33]
	v_mfma_f32_16x16x32_bf16 v[26:29], v[224:227], v[170:173], v[26:29]
	v_mfma_f32_16x16x32_bf16 v[14:17], v[216:219], v[178:181], v[14:17]
	v_mfma_f32_16x16x32_bf16 v[10:13], v[224:227], v[178:181], v[10:13]
	v_mfma_f32_16x16x32_bf16 v[6:9], v[216:219], v[186:189], v[6:9]
	v_mfma_f32_16x16x32_bf16 v[2:5], v[224:227], v[186:189], v[2:5]
	v_mfma_f32_16x16x32_bf16 v[46:49], v[220:223], v[166:169], v[46:49]
	v_mfma_f32_16x16x32_bf16 v[42:45], v[228:231], v[166:169], v[42:45]
	v_mfma_f32_16x16x32_bf16 v[30:33], v[220:223], v[174:177], v[30:33]
	v_mfma_f32_16x16x32_bf16 v[26:29], v[228:231], v[174:177], v[26:29]
	v_mfma_f32_16x16x32_bf16 v[14:17], v[220:223], v[182:185], v[14:17]
	v_mfma_f32_16x16x32_bf16 v[10:13], v[228:231], v[182:185], v[10:13]
	v_mfma_f32_16x16x32_bf16 v[6:9], v[220:223], v[190:193], v[6:9]
	v_mfma_f32_16x16x32_bf16 v[2:5], v[228:231], v[190:193], v[2:5]
	s_setprio 0
	s_add_i32 s39, s39, 2
	v_lshl_add_u64 v[138:139], v[138:139], 0, s[46:47]
	s_cmp_gt_u32 s39, 5
	s_mov_b64 s[16:17], s[34:35]
	s_barrier
	s_cbranch_scc0 .LBB0_202
	s_mul_hi_i32 s2, s55, 0x92492493
	s_add_i32 s2, s2, s55
	s_lshr_b32 s3, s2, 31
	s_ashr_i32 s2, s2, 2
	s_add_i32 s2, s2, s3
	s_mul_i32 s3, s2, 7
	s_sub_i32 s16, s55, s3
	s_ashr_i32 s17, s16, 31
	v_lshl_or_b32 v140, s2, 8, v144
	s_lshl_b64 s[16:17], s[16:17], 23
	v_readlane_b32 s2, v250, 55
	v_lshl_add_u32 v138, s30, 8, v142
	v_readlane_b32 s3, v250, 56
	s_add_u32 s16, s2, s16
	s_addc_u32 s17, s3, s17
	v_ashrrev_i32_e32 v141, 31, v140
	v_ashrrev_i32_e32 v139, 31, v138
	v_lshl_add_u64 v[140:141], v[140:141], 2, s[16:17]
	v_lshlrev_b64 v[146:147], 12, v[138:139]
	v_lshl_add_u64 v[146:147], v[140:141], 0, v[146:147]
	global_store_dwordx4 v[146:147], v[126:129], off
	global_store_dwordx4 v[146:147], v[122:125], off offset:64
	global_store_dwordx4 v[146:147], v[110:113], off offset:512
	global_store_dwordx4 v[146:147], v[102:105], off offset:576
	s_mov_b64 s[2:3], 0x80000
	s_mov_b32 s55, s38
	v_or_b32_e32 v102, 16, v138
	v_ashrrev_i32_e32 v103, 31, v102
	v_lshlrev_b64 v[102:103], 12, v[102:103]
	v_lshl_add_u64 v[102:103], v[140:141], 0, v[102:103]
	global_store_dwordx4 v[102:103], v[118:121], off
	global_store_dwordx4 v[102:103], v[114:117], off offset:64
	global_store_dwordx4 v[102:103], v[94:97], off offset:512
	global_store_dwordx4 v[102:103], v[86:89], off offset:576
	s_mov_b32 s30, s62
	s_mov_b64 s[16:17], s[4:5]
	v_or_b32_e32 v86, 32, v138
	v_ashrrev_i32_e32 v87, 31, v86
	v_lshlrev_b64 v[86:87], 12, v[86:87]
	v_lshl_add_u64 v[86:87], v[140:141], 0, v[86:87]
	global_store_dwordx4 v[86:87], v[106:109], off
	global_store_dwordx4 v[86:87], v[98:101], off offset:64
	global_store_dwordx4 v[86:87], v[78:81], off offset:512
	global_store_dwordx4 v[86:87], v[74:77], off offset:576
	s_nop 1
	v_or_b32_e32 v74, 48, v138
	v_ashrrev_i32_e32 v75, 31, v74
	v_lshlrev_b64 v[74:75], 12, v[74:75]
	v_lshl_add_u64 v[74:75], v[140:141], 0, v[74:75]
	global_store_dwordx4 v[74:75], v[90:93], off
	global_store_dwordx4 v[74:75], v[82:85], off offset:64
	global_store_dwordx4 v[74:75], v[70:73], off offset:512
	global_store_dwordx4 v[74:75], v[66:69], off offset:576
	s_nop 1
	v_lshl_add_u64 v[66:67], v[146:147], 0, s[2:3]
	s_mov_b32 s2, 0x80000
	v_add_co_u32_e32 v68, vcc, s2, v146
	s_mov_b64 s[2:3], 0x90000
	s_nop 0
	v_addc_co_u32_e32 v69, vcc, 0, v147, vcc
	global_store_dwordx4 v[68:69], v[62:65], off
	global_store_dwordx4 v[66:67], v[58:61], off offset:64
	global_store_dwordx4 v[66:67], v[46:49], off offset:512
	global_store_dwordx4 v[66:67], v[42:45], off offset:576
	s_nop 1
	v_lshl_add_u64 v[42:43], v[146:147], 0, s[2:3]
	s_mov_b32 s2, 0x90000
	v_add_co_u32_e32 v44, vcc, s2, v146
	s_mov_b64 s[2:3], 0xa0000
	s_nop 0
	v_addc_co_u32_e32 v45, vcc, 0, v147, vcc
	global_store_dwordx4 v[44:45], v[54:57], off
	global_store_dwordx4 v[42:43], v[50:53], off offset:64
	global_store_dwordx4 v[42:43], v[30:33], off offset:512
	global_store_dwordx4 v[42:43], v[26:29], off offset:576
	s_nop 1
	v_lshl_add_u64 v[26:27], v[146:147], 0, s[2:3]
	s_mov_b32 s2, 0xa0000
	v_add_co_u32_e32 v28, vcc, s2, v146
	s_mov_b64 s[2:3], 0xb0000
	s_nop 0
	v_addc_co_u32_e32 v29, vcc, 0, v147, vcc
	global_store_dwordx4 v[28:29], v[38:41], off
	global_store_dwordx4 v[26:27], v[34:37], off offset:64
	global_store_dwordx4 v[26:27], v[14:17], off offset:512
	global_store_dwordx4 v[26:27], v[10:13], off offset:576
	s_nop 1
	v_add_co_u32_e32 v12, vcc, 0xb0000, v146
	v_lshl_add_u64 v[10:11], v[146:147], 0, s[2:3]
	s_nop 0
	v_addc_co_u32_e32 v13, vcc, 0, v147, vcc
	global_store_dwordx4 v[12:13], v[22:25], off
	global_store_dwordx4 v[10:11], v[18:21], off offset:64
	global_store_dwordx4 v[10:11], v[6:9], off offset:512
	global_store_dwordx4 v[10:11], v[2:5], off offset:576
	s_and_b64 vcc, exec, s[14:15]
	s_nop 0
	v_mov_b64_e32 v[2:3], v[136:137]
	s_cbranch_vccz .LBB0_197
	s_waitcnt vmcnt(0)
	s_mov_b32 s47, s94
	s_cmpk_gt_u32 s19, 0xff
	s_cbranch_scc1 .LBB0_206
	s_barrier

; #define PG8_STAGE(bufoff, gbase, voff) do { _Pragma("unroll") for (int _i = 0; _i < 2; ++_i) \
;         __builtin_amdgcn_global_load_lds((const unsigned*)((const char*)(gbase) + (voff)[_i]), (LAS unsigned*)(lds + (bufoff) + ldsw + _i * 8192), 16, 0, 0); } while (0)
; #define PG8_STAGE_A(bufoff, gbase, h, vv) do { if constexpr (GATHER) { _Pragma("unroll") for (int _i = 0; _i < 2; ++_i) \
;         __builtin_amdgcn_global_load_lds((const unsigned*)((const char*)(gbase) + (vv)[h][_i]), (LAS unsigned*)(lds + (bufoff) + ldsw + _i * 8192), 16, 0, 0); } \
;         else { PG8_STAGE(bufoff, (gbase) + (h) * hstepA, voffA); } } while (0)
; #define PG8_WAIT_L(n) asm volatile("s_waitcnt lgkmcnt(" #n ")" ::: "memory")
; #define PG8_BAR __builtin_amdgcn_s_barrier()
; template <class Epi, class Sched>
; __device__ __forceinline__ void gemm_phase(LAS unsigned char* lds, const int K, const int lda, const int ldb, const Sched& S, const Epi& E) {
;     ...
;         const bool has_next = S.next(ui + 1, nxt);
;         const char* nA = has_next ? nxt.a : cA; const char* nB = has_next ? nxt.b : cB;
;         if constexpr (GATHER) {
;             nA = cA;
;             if (has_next) mk_off(ix1, vnxt);
;             else {
; #pragma unroll
;                 for (int h = 0; h < 2; ++h)
; #pragma unroll
;                     for (int i = 0; i < 2; ++i) vnxt[h][i] = vcur[h][i];
;             }
;         }
; #pragma unroll 1
;         for (int t = 0; t < nt; t += 2) {
;             const bool last = (t == nt - 2);
;             const char* a1 = cA + (size_t)(t + 1) * kstep;
;             const char* a2 = last ? nA : cA + (size_t)(t + 2) * kstep; const char* b2 = last ? nB : cB + (size_t)(t + 2) * kstep;
;             const char* a3 = a2 + kstep; const char* b3 = b2 + kstep;
;             PG8_LDB(B0, 0, 0); PG8_SCHED; PG8_LDA(At, 0, 0); PG8_STAGE_A(PG8_SA(1, 1), a1, 1, vcur);
;             if constexpr (GATHER) { if (last) {
; #pragma unroll
;                 for (int h = 0; h < 2; ++h)
; #pragma unroll
;                     for (int i = 0; i < 2; ++i) vcur[h][i] = vnxt[h][i]; } }
;             PG8_WAIT_L(8); PG8_BAR; PG8_WAIT_L(0); PG8_MMA(0, 0, At, B0); PG8_BAR; PG8_SCHED;
;             PG8_LDB(B1, 0, 1); PG8_STAGE(PG8_SB(0, 0), b2, voffB);
;             PG8_BAR; PG8_WAIT_L(0); PG8_MMA(0, 1, At, B1); PG8_BAR;
;             PG8_LDA(At, 0, 1); PG8_STAGE_A(PG8_SA(0, 0), a2, 0, vcur);
.LBB0_256:
	s_add_u32 s2, s10, s34
	s_addc_u32 s3, s11, s35
	s_add_u32 s9, s2, 0x100
	s_addc_u32 s20, s3, 0
	s_and_b64 s[36:37], s[16:17], exec
	s_cselect_b32 s39, s1, s20
	s_cselect_b32 s38, s0, s9
	s_add_u32 s9, s12, s34
	s_addc_u32 s20, s13, s35
	s_add_u32 s9, s9, 0x100
	s_addc_u32 s20, s20, 0
	s_add_i32 s21, 0, 0x10000
	s_and_b64 s[16:17], s[16:17], exec
	s_cselect_b32 s41, s5, s20
	s_cselect_b32 s40, s4, s9
	s_add_u32 s42, s2, 0x40080
	s_addc_u32 s43, s3, 0
	s_add_i32 s71, s21, s19
	s_add_i32 m0, s30, 0xc000
	s_add_i32 s2, s30, 0xe000
	s_add_i32 s70, 0, 0x14000
	s_add_i32 s69, s71, 0x2000
	s_add_u32 s36, s40, 0x10000
	v_add_u32_e32 v138, s21, v141
	s_addc_u32 s37, s41, 0
	s_add_i32 s66, s70, s19
	ds_read_b128 v[144:147], v138
	ds_read_b128 v[148:151], v138 offset:1024
	ds_read_b128 v[152:155], v138 offset:2048
	ds_read_b128 v[156:159], v138 offset:3072
	s_add_i32 s63, s66, 0x2000
	s_add_i32 s62, 0, 0x18000
	s_add_u32 s34, s38, 0x40000
	s_addc_u32 s35, s39, 0
	s_add_i32 s60, s62, s19
	s_add_i32 s55, 0, 0x1c000
	s_add_i32 s9, s60, 0x2000
	s_add_u32 s16, s40, 0x10080
	s_addc_u32 s17, s41, 0
	s_add_i32 s68, s55, s19
	s_add_i32 s67, s68, 0x2000
	v_lshl_add_u64 v[138:139], s[42:43], 0, v[136:137]
	ds_read_b128 v[160:163], v142
	ds_read_b128 v[164:167], v142 offset:1024
	ds_read_b128 v[168:171], v142 offset:2048
	ds_read_b128 v[172:175], v142 offset:3072
	ds_read_b128 v[176:179], v142 offset:4096
	ds_read_b128 v[180:183], v142 offset:5120
	ds_read_b128 v[184:187], v142 offset:6144
	ds_read_b128 v[188:191], v142 offset:7168
	global_load_lds_dwordx4 v[138:139], off
	v_lshl_add_u64 v[138:139], s[42:43], 0, v[132:133]
	s_mov_b32 m0, s2
	s_nop 0
	global_load_lds_dwordx4 v[138:139], off
	s_waitcnt lgkmcnt(8)
	s_barrier
	s_waitcnt lgkmcnt(0)
	s_setprio 1
	v_mfma_f32_16x16x32_bf16 v[126:129], v[144:147], v[160:163], v[126:129]
	v_mfma_f32_16x16x32_bf16 v[122:125], v[152:155], v[160:163], v[122:125]
	v_mfma_f32_16x16x32_bf16 v[118:121], v[144:147], v[168:171], v[118:121]
	v_mfma_f32_16x16x32_bf16 v[110:113], v[152:155], v[168:171], v[110:113]
	v_mfma_f32_16x16x32_bf16 v[102:105], v[144:147], v[176:179], v[102:105]
	v_mfma_f32_16x16x32_bf16 v[94:97], v[152:155], v[176:179], v[94:97]
	v_mfma_f32_16x16x32_bf16 v[86:89], v[144:147], v[184:187], v[86:89]
	v_mfma_f32_16x16x32_bf16 v[78:81], v[152:155], v[184:187], v[78:81]
	v_mfma_f32_16x16x32_bf16 v[126:129], v[148:151], v[164:167], v[126:129]
	v_mfma_f32_16x16x32_bf16 v[122:125], v[156:159], v[164:167], v[122:125]
	v_mfma_f32_16x16x32_bf16 v[118:121], v[148:151], v[172:175], v[118:121]
	v_mfma_f32_16x16x32_bf16 v[110:113], v[156:159], v[172:175], v[110:113]
	v_mfma_f32_16x16x32_bf16 v[102:105], v[148:151], v[180:183], v[102:105]
	v_mfma_f32_16x16x32_bf16 v[94:97], v[156:159], v[180:183], v[94:97]
	v_mfma_f32_16x16x32_bf16 v[86:89], v[148:151], v[188:191], v[86:89]
	v_mfma_f32_16x16x32_bf16 v[78:81], v[156:159], v[188:191], v[78:81]
	s_setprio 0
	s_barrier
	v_add_u32_e32 v138, s70, v141
	s_mov_b32 m0, s71
	ds_read_b128 v[192:195], v138
	ds_read_b128 v[216:219], v138 offset:1024
	ds_read_b128 v[220:223], v138 offset:2048
	ds_read_b128 v[224:227], v138 offset:3072
	v_lshl_add_u64 v[138:139], s[40:41], 0, v[134:135]
	global_load_lds_dwordx4 v[138:139], off
	v_lshl_add_u64 v[214:215], s[40:41], 0, v[130:131]
	s_mov_b32 m0, s69
	s_nop 0
	global_load_lds_dwordx4 v[214:215], off
	s_barrier
	s_waitcnt lgkmcnt(0)
	s_setprio 1
	v_mfma_f32_16x16x32_bf16 v[114:117], v[192:195], v[160:163], v[114:117]
	v_mfma_f32_16x16x32_bf16 v[106:109], v[220:223], v[160:163], v[106:109]
	v_mfma_f32_16x16x32_bf16 v[98:101], v[192:195], v[168:171], v[98:101]
	v_mfma_f32_16x16x32_bf16 v[90:93], v[220:223], v[168:171], v[90:93]
	v_mfma_f32_16x16x32_bf16 v[82:85], v[192:195], v[176:179], v[82:85]
	v_mfma_f32_16x16x32_bf16 v[74:77], v[220:223], v[176:179], v[74:77]
	v_mfma_f32_16x16x32_bf16 v[70:73], v[192:195], v[184:187], v[70:73]
	v_mfma_f32_16x16x32_bf16 v[66:69], v[220:223], v[184:187], v[66:69]
	v_mfma_f32_16x16x32_bf16 v[114:117], v[216:219], v[164:167], v[114:117]
	v_mfma_f32_16x16x32_bf16 v[106:109], v[224:227], v[164:167], v[106:109]
	v_mfma_f32_16x16x32_bf16 v[98:101], v[216:219], v[172:175], v[98:101]
	v_mfma_f32_16x16x32_bf16 v[90:93], v[224:227], v[172:175], v[90:93]
	v_mfma_f32_16x16x32_bf16 v[82:85], v[216:219], v[180:183], v[82:85]
	v_mfma_f32_16x16x32_bf16 v[74:77], v[224:227], v[180:183], v[74:77]
	v_mfma_f32_16x16x32_bf16 v[70:73], v[216:219], v[188:191], v[70:73]
	v_mfma_f32_16x16x32_bf16 v[66:69], v[224:227], v[188:191], v[66:69]
	s_setprio 0
	s_mov_b32 m0, s30
	v_lshl_add_u64 v[228:229], s[38:39], 0, v[136:137]
	s_barrier
	ds_read_b128 v[160:163], v142 offset:16384
	ds_read_b128 v[164:167], v142 offset:17408
	ds_read_b128 v[168:171], v142 offset:18432
	ds_read_b128 v[172:175], v142 offset:19456
	ds_read_b128 v[176:179], v142 offset:20480
	ds_read_b128 v[180:183], v142 offset:21504
	ds_read_b128 v[184:187], v142 offset:22528
	ds_read_b128 v[188:191], v142 offset:23552
	global_load_lds_dwordx4 v[228:229], off
	v_lshl_add_u64 v[230:231], s[38:39], 0, v[132:133]
	s_mov_b32 m0, s44
	s_nop 0
	global_load_lds_dwordx4 v[230:231], off
	s_barrier
; #define PG8_STAGE(bufoff, gbase, voff) do { _Pragma("unroll") for (int _i = 0; _i < 2; ++_i) \
;         __builtin_amdgcn_global_load_lds((const unsigned*)((const char*)(gbase) + (voff)[_i]), (LAS unsigned*)(lds + (bufoff) + ldsw + _i * 8192), 16, 0, 0); } while (0)
; #define PG8_STAGE_A(bufoff, gbase, h, vv) do { if constexpr (GATHER) { _Pragma("unroll") for (int _i = 0; _i < 2; ++_i) \
;         __builtin_amdgcn_global_load_lds((const unsigned*)((const char*)(gbase) + (vv)[h][_i]), (LAS unsigned*)(lds + (bufoff) + ldsw + _i * 8192), 16, 0, 0); } \
;         else { PG8_STAGE(bufoff, (gbase) + (h) * hstepA, voffA); } } while (0)
; #define PG8_LDA(dst, b, h) do { _Pragma("unroll") for (int m = 0; m < 4; ++m) _Pragma("unroll") for (int k = 0; k < 2; ++k) dst[m][k] = *(const LAS bf16x8*)(lds + PG8_SA(b, h) + aoff + m * 2048 + k * 1024); } while (0)
; #define PG8_LDB(dst, b, h) do { _Pragma("unroll") for (int n = 0; n < 2; ++n) _Pragma("unroll") for (int k = 0; k < 2; ++k) dst[n][k] = *(const LAS bf16x8*)(lds + PG8_SB(b, h) + boff + n * 2048 + k * 1024); } while (0)
; #define PG8_MMA(ai, bj, At, Bt) do { __builtin_amdgcn_s_setprio(1); _Pragma("unroll") for (int m = 0; m < 4; ++m) _Pragma("unroll") for (int n = 0; n < 2; ++n) _Pragma("unroll") for (int k = 0; k < 2; ++k) \
;         acc[ai][bj][m][n] = __builtin_amdgcn_mfma_f32_16x16x32_bf16(Bt[n][k], At[m][k], acc[ai][bj][m][n], 0, 0, 0); __builtin_amdgcn_s_setprio(0); } while (0)
; #define PG8_WAIT_V(n) asm volatile("s_waitcnt vmcnt(" #n ")" ::: "memory")
; #define PG8_BAR __builtin_amdgcn_s_barrier()
; template <class Epi, class Sched>
; __device__ __forceinline__ void gemm_phase(LAS unsigned char* lds, const int K, const int lda, const int ldb, const Sched& S, const Epi& E) {
;     ...
;             PG8_BAR; PG8_WAIT_L(0); PG8_MMA(1, 0, At, B0); PG8_BAR; PG8_SCHED;
;             PG8_STAGE(PG8_SB(0, 1), b2 + hstepB, voffB);
;             PG8_WAIT_V(6); PG8_BAR; PG8_MMA(1, 1, At, B1); PG8_BAR;
;             PG8_LDB(B0, 1, 0); PG8_SCHED; PG8_LDA(At, 1, 0); PG8_STAGE_A(PG8_SA(0, 1), a2, 1, vcur);
;             PG8_WAIT_L(8); PG8_BAR; PG8_WAIT_L(0); PG8_MMA(0, 0, At, B0); PG8_BAR; PG8_SCHED;
;             PG8_LDB(B1, 1, 1); PG8_STAGE(PG8_SB(1, 0), b3, voffB);
;             PG8_BAR; PG8_WAIT_L(0); PG8_MMA(0, 1, At, B1); PG8_BAR;
;             PG8_LDA(At, 1, 1); PG8_STAGE_A(PG8_SA(1, 0), a3, 0, vcur);
	s_waitcnt lgkmcnt(0)
	s_setprio 1
	v_mfma_f32_16x16x32_bf16 v[62:65], v[144:147], v[160:163], v[62:65]
	v_mfma_f32_16x16x32_bf16 v[58:61], v[152:155], v[160:163], v[58:61]
	v_mfma_f32_16x16x32_bf16 v[54:57], v[144:147], v[168:171], v[54:57]
	v_mfma_f32_16x16x32_bf16 v[46:49], v[152:155], v[168:171], v[46:49]
	v_mfma_f32_16x16x32_bf16 v[38:41], v[144:147], v[176:179], v[38:41]
	v_mfma_f32_16x16x32_bf16 v[30:33], v[152:155], v[176:179], v[30:33]
	v_mfma_f32_16x16x32_bf16 v[22:25], v[144:147], v[184:187], v[22:25]
	v_mfma_f32_16x16x32_bf16 v[14:17], v[152:155], v[184:187], v[14:17]
	v_mfma_f32_16x16x32_bf16 v[62:65], v[148:151], v[164:167], v[62:65]
	v_mfma_f32_16x16x32_bf16 v[58:61], v[156:159], v[164:167], v[58:61]
	v_mfma_f32_16x16x32_bf16 v[54:57], v[148:151], v[172:175], v[54:57]
	v_mfma_f32_16x16x32_bf16 v[46:49], v[156:159], v[172:175], v[46:49]
	v_mfma_f32_16x16x32_bf16 v[38:41], v[148:151], v[180:183], v[38:41]
	v_mfma_f32_16x16x32_bf16 v[30:33], v[156:159], v[180:183], v[30:33]
	v_mfma_f32_16x16x32_bf16 v[22:25], v[148:151], v[188:191], v[22:25]
	v_mfma_f32_16x16x32_bf16 v[14:17], v[156:159], v[188:191], v[14:17]
	s_setprio 0
	s_barrier
	s_mov_b32 m0, s66
	v_lshl_add_u64 v[144:145], s[36:37], 0, v[134:135]
	global_load_lds_dwordx4 v[144:145], off
	v_lshl_add_u64 v[144:145], s[36:37], 0, v[130:131]
	s_mov_b32 m0, s63
	s_nop 0
	global_load_lds_dwordx4 v[144:145], off
	s_waitcnt vmcnt(6)
	s_barrier
	s_setprio 1
	v_mfma_f32_16x16x32_bf16 v[50:53], v[192:195], v[160:163], v[50:53]
	v_mfma_f32_16x16x32_bf16 v[42:45], v[220:223], v[160:163], v[42:45]
	v_mfma_f32_16x16x32_bf16 v[34:37], v[192:195], v[168:171], v[34:37]
	v_mfma_f32_16x16x32_bf16 v[26:29], v[220:223], v[168:171], v[26:29]
	v_mfma_f32_16x16x32_bf16 v[18:21], v[192:195], v[176:179], v[18:21]
	v_mfma_f32_16x16x32_bf16 v[10:13], v[220:223], v[176:179], v[10:13]
	v_mfma_f32_16x16x32_bf16 v[6:9], v[192:195], v[184:187], v[6:9]
	v_mfma_f32_16x16x32_bf16 v[2:5], v[220:223], v[184:187], v[2:5]
	v_mfma_f32_16x16x32_bf16 v[50:53], v[216:219], v[164:167], v[50:53]
	v_mfma_f32_16x16x32_bf16 v[42:45], v[224:227], v[164:167], v[42:45]
	v_mfma_f32_16x16x32_bf16 v[34:37], v[216:219], v[172:175], v[34:37]
	v_mfma_f32_16x16x32_bf16 v[26:29], v[224:227], v[172:175], v[26:29]
	v_mfma_f32_16x16x32_bf16 v[18:21], v[216:219], v[180:183], v[18:21]
	v_mfma_f32_16x16x32_bf16 v[10:13], v[224:227], v[180:183], v[10:13]
	v_mfma_f32_16x16x32_bf16 v[6:9], v[216:219], v[188:191], v[6:9]
	v_mfma_f32_16x16x32_bf16 v[2:5], v[224:227], v[188:191], v[2:5]
	s_setprio 0
	v_add_u32_e32 v143, s62, v141
	s_barrier
	ds_read_b128 v[144:147], v143
	ds_read_b128 v[148:151], v143 offset:1024
	ds_read_b128 v[152:155], v143 offset:2048
	ds_read_b128 v[156:159], v143 offset:3072
	s_mov_b32 m0, s45
	v_lshl_add_u64 v[192:193], s[34:35], 0, v[136:137]
	ds_read_b128 v[160:163], v142 offset:32768
	ds_read_b128 v[164:167], v142 offset:33792
	ds_read_b128 v[168:171], v142 offset:34816
	ds_read_b128 v[172:175], v142 offset:35840
	ds_read_b128 v[176:179], v142 offset:36864
	ds_read_b128 v[180:183], v142 offset:37888
	ds_read_b128 v[184:187], v142 offset:38912
	ds_read_b128 v[188:191], v142 offset:39936
	global_load_lds_dwordx4 v[192:193], off
	v_lshl_add_u64 v[192:193], s[34:35], 0, v[132:133]
	s_mov_b32 m0, s46
	s_nop 0
	global_load_lds_dwordx4 v[192:193], off
	s_waitcnt lgkmcnt(8)
	s_barrier
	s_waitcnt lgkmcnt(0)
	s_setprio 1
	v_mfma_f32_16x16x32_bf16 v[126:129], v[144:147], v[160:163], v[126:129]
	v_mfma_f32_16x16x32_bf16 v[122:125], v[152:155], v[160:163], v[122:125]
	v_mfma_f32_16x16x32_bf16 v[118:121], v[144:147], v[168:171], v[118:121]
	v_mfma_f32_16x16x32_bf16 v[110:113], v[152:155], v[168:171], v[110:113]
	v_mfma_f32_16x16x32_bf16 v[102:105], v[144:147], v[176:179], v[102:105]
	v_mfma_f32_16x16x32_bf16 v[94:97], v[152:155], v[176:179], v[94:97]
	v_mfma_f32_16x16x32_bf16 v[86:89], v[144:147], v[184:187], v[86:89]
	v_mfma_f32_16x16x32_bf16 v[78:81], v[152:155], v[184:187], v[78:81]
	v_mfma_f32_16x16x32_bf16 v[126:129], v[148:151], v[164:167], v[126:129]
	v_mfma_f32_16x16x32_bf16 v[122:125], v[156:159], v[164:167], v[122:125]
	v_mfma_f32_16x16x32_bf16 v[118:121], v[148:151], v[172:175], v[118:121]
	v_mfma_f32_16x16x32_bf16 v[110:113], v[156:159], v[172:175], v[110:113]
	v_mfma_f32_16x16x32_bf16 v[102:105], v[148:151], v[180:183], v[102:105]
	v_mfma_f32_16x16x32_bf16 v[94:97], v[156:159], v[180:183], v[94:97]
	v_mfma_f32_16x16x32_bf16 v[86:89], v[148:151], v[188:191], v[86:89]
	v_mfma_f32_16x16x32_bf16 v[78:81], v[156:159], v[188:191], v[78:81]
	s_setprio 0
	s_barrier
	s_mov_b32 m0, s60
	v_add_u32_e32 v143, s55, v141
	v_lshl_add_u64 v[138:139], v[138:139], 0, s[64:65]
	ds_read_b128 v[192:195], v143
	ds_read_b128 v[216:219], v143 offset:1024
	ds_read_b128 v[220:223], v143 offset:2048
	ds_read_b128 v[224:227], v143 offset:3072
	global_load_lds_dwordx4 v[138:139], off
	v_lshl_add_u64 v[138:139], v[214:215], 0, s[64:65]
	s_mov_b32 m0, s9
	s_nop 0
	global_load_lds_dwordx4 v[138:139], off
	s_barrier
	s_waitcnt lgkmcnt(0)
	s_setprio 1
	v_mfma_f32_16x16x32_bf16 v[114:117], v[192:195], v[160:163], v[114:117]
	v_mfma_f32_16x16x32_bf16 v[106:109], v[220:223], v[160:163], v[106:109]
	v_mfma_f32_16x16x32_bf16 v[98:101], v[192:195], v[168:171], v[98:101]
	v_mfma_f32_16x16x32_bf16 v[90:93], v[220:223], v[168:171], v[90:93]
	v_mfma_f32_16x16x32_bf16 v[82:85], v[192:195], v[176:179], v[82:85]
	v_mfma_f32_16x16x32_bf16 v[74:77], v[220:223], v[176:179], v[74:77]
	v_mfma_f32_16x16x32_bf16 v[70:73], v[192:195], v[184:187], v[70:73]
	v_mfma_f32_16x16x32_bf16 v[66:69], v[220:223], v[184:187], v[66:69]
	v_mfma_f32_16x16x32_bf16 v[114:117], v[216:219], v[164:167], v[114:117]
	v_mfma_f32_16x16x32_bf16 v[106:109], v[224:227], v[164:167], v[106:109]
	v_mfma_f32_16x16x32_bf16 v[98:101], v[216:219], v[172:175], v[98:101]
	v_mfma_f32_16x16x32_bf16 v[90:93], v[224:227], v[172:175], v[90:93]
	v_mfma_f32_16x16x32_bf16 v[82:85], v[216:219], v[180:183], v[82:85]
	v_mfma_f32_16x16x32_bf16 v[74:77], v[224:227], v[180:183], v[74:77]
	v_mfma_f32_16x16x32_bf16 v[70:73], v[216:219], v[188:191], v[70:73]
	v_mfma_f32_16x16x32_bf16 v[66:69], v[224:227], v[188:191], v[66:69]
	s_setprio 0
	s_mov_b32 m0, s47
	v_lshl_add_u64 v[138:139], v[228:229], 0, s[64:65]
	s_barrier
; #define PG8_STAGE(bufoff, gbase, voff) do { _Pragma("unroll") for (int _i = 0; _i < 2; ++_i) \
;         __builtin_amdgcn_global_load_lds((const unsigned*)((const char*)(gbase) + (voff)[_i]), (LAS unsigned*)(lds + (bufoff) + ldsw + _i * 8192), 16, 0, 0); } while (0)
; #define PG8_STAGE_A(bufoff, gbase, h, vv) do { if constexpr (GATHER) { _Pragma("unroll") for (int _i = 0; _i < 2; ++_i) \
;         __builtin_amdgcn_global_load_lds((const unsigned*)((const char*)(gbase) + (vv)[h][_i]), (LAS unsigned*)(lds + (bufoff) + ldsw + _i * 8192), 16, 0, 0); } \
;         else { PG8_STAGE(bufoff, (gbase) + (h) * hstepA, voffA); } } while (0)
; #define PG8_LDA(dst, b, h) do { _Pragma("unroll") for (int m = 0; m < 4; ++m) _Pragma("unroll") for (int k = 0; k < 2; ++k) dst[m][k] = *(const LAS bf16x8*)(lds + PG8_SA(b, h) + aoff + m * 2048 + k * 1024); } while (0)
; #define PG8_MMA(ai, bj, At, Bt) do { __builtin_amdgcn_s_setprio(1); _Pragma("unroll") for (int m = 0; m < 4; ++m) _Pragma("unroll") for (int n = 0; n < 2; ++n) _Pragma("unroll") for (int k = 0; k < 2; ++k) \
;         acc[ai][bj][m][n] = __builtin_amdgcn_mfma_f32_16x16x32_bf16(Bt[n][k], At[m][k], acc[ai][bj][m][n], 0, 0, 0); __builtin_amdgcn_s_setprio(0); } while (0)
; #define PG8_WAIT_V(n) asm volatile("s_waitcnt vmcnt(" #n ")" ::: "memory")
; #define PG8_WAIT_L(n) asm volatile("s_waitcnt lgkmcnt(" #n ")" ::: "memory")
; #define PG8_BAR __builtin_amdgcn_s_barrier()
; #define PG8_SCHED __builtin_amdgcn_sched_barrier(0)
; template <class Epi, class Sched>
; __device__ __forceinline__ void gemm_phase(LAS unsigned char* lds, const int K, const int lda, const int ldb, const Sched& S, const Epi& E) {
;     ...
;             PG8_LDA(At, 1, 1); PG8_STAGE_A(PG8_SA(1, 0), a3, 0, vcur);
;             PG8_BAR; PG8_WAIT_L(0); PG8_MMA(1, 0, At, B0); PG8_BAR; PG8_SCHED;
;             PG8_STAGE(PG8_SB(1, 1), b3 + hstepB, voffB);
;             PG8_WAIT_V(6); PG8_BAR; PG8_MMA(1, 1, At, B1); PG8_BAR;
;         }
	ds_read_b128 v[160:163], v142 offset:49152
	ds_read_b128 v[164:167], v142 offset:50176
	ds_read_b128 v[168:171], v142 offset:51200
	ds_read_b128 v[172:175], v142 offset:52224
	ds_read_b128 v[176:179], v142 offset:53248
	ds_read_b128 v[180:183], v142 offset:54272
	ds_read_b128 v[184:187], v142 offset:55296
	ds_read_b128 v[188:191], v142 offset:56320
	global_load_lds_dwordx4 v[138:139], off
	v_lshl_add_u64 v[138:139], v[230:231], 0, s[64:65]
	s_mov_b32 m0, s48
	s_nop 0
	global_load_lds_dwordx4 v[138:139], off
	s_barrier
	s_waitcnt lgkmcnt(0)
	s_setprio 1
	v_mfma_f32_16x16x32_bf16 v[62:65], v[144:147], v[160:163], v[62:65]
	v_mfma_f32_16x16x32_bf16 v[58:61], v[152:155], v[160:163], v[58:61]
	v_mfma_f32_16x16x32_bf16 v[54:57], v[144:147], v[168:171], v[54:57]
	v_mfma_f32_16x16x32_bf16 v[46:49], v[152:155], v[168:171], v[46:49]
	v_mfma_f32_16x16x32_bf16 v[38:41], v[144:147], v[176:179], v[38:41]
	v_mfma_f32_16x16x32_bf16 v[30:33], v[152:155], v[176:179], v[30:33]
	v_mfma_f32_16x16x32_bf16 v[22:25], v[144:147], v[184:187], v[22:25]
	v_mfma_f32_16x16x32_bf16 v[14:17], v[152:155], v[184:187], v[14:17]
	v_mfma_f32_16x16x32_bf16 v[62:65], v[148:151], v[164:167], v[62:65]
	v_mfma_f32_16x16x32_bf16 v[58:61], v[156:159], v[164:167], v[58:61]
	v_mfma_f32_16x16x32_bf16 v[54:57], v[148:151], v[172:175], v[54:57]
	v_mfma_f32_16x16x32_bf16 v[46:49], v[156:159], v[172:175], v[46:49]
	v_mfma_f32_16x16x32_bf16 v[38:41], v[148:151], v[180:183], v[38:41]
	v_mfma_f32_16x16x32_bf16 v[30:33], v[156:159], v[180:183], v[30:33]
	v_mfma_f32_16x16x32_bf16 v[22:25], v[148:151], v[188:191], v[22:25]
	v_mfma_f32_16x16x32_bf16 v[14:17], v[156:159], v[188:191], v[14:17]
	s_setprio 0
	s_barrier
	s_mov_b32 m0, s68
	v_lshl_add_u64 v[138:139], s[16:17], 0, v[134:135]
	global_load_lds_dwordx4 v[138:139], off
	v_lshl_add_u64 v[138:139], s[16:17], 0, v[130:131]
	s_mov_b32 m0, s67
	s_nop 0
	global_load_lds_dwordx4 v[138:139], off
	s_waitcnt vmcnt(6)
	s_barrier
	s_setprio 1
	v_mfma_f32_16x16x32_bf16 v[50:53], v[192:195], v[160:163], v[50:53]
	v_mfma_f32_16x16x32_bf16 v[42:45], v[220:223], v[160:163], v[42:45]
	v_mfma_f32_16x16x32_bf16 v[34:37], v[192:195], v[168:171], v[34:37]
	v_mfma_f32_16x16x32_bf16 v[26:29], v[220:223], v[168:171], v[26:29]
	v_mfma_f32_16x16x32_bf16 v[18:21], v[192:195], v[176:179], v[18:21]
	v_mfma_f32_16x16x32_bf16 v[10:13], v[220:223], v[176:179], v[10:13]
	v_mfma_f32_16x16x32_bf16 v[6:9], v[192:195], v[184:187], v[6:9]
	v_mfma_f32_16x16x32_bf16 v[2:5], v[220:223], v[184:187], v[2:5]
	v_mfma_f32_16x16x32_bf16 v[50:53], v[216:219], v[164:167], v[50:53]
	v_mfma_f32_16x16x32_bf16 v[42:45], v[224:227], v[164:167], v[42:45]
	v_mfma_f32_16x16x32_bf16 v[34:37], v[216:219], v[172:175], v[34:37]
	v_mfma_f32_16x16x32_bf16 v[26:29], v[224:227], v[172:175], v[26:29]
	v_mfma_f32_16x16x32_bf16 v[18:21], v[216:219], v[180:183], v[18:21]
	v_mfma_f32_16x16x32_bf16 v[10:13], v[224:227], v[180:183], v[10:13]
	v_mfma_f32_16x16x32_bf16 v[6:9], v[216:219], v[188:191], v[6:9]
	v_mfma_f32_16x16x32_bf16 v[2:5], v[224:227], v[188:191], v[2:5]
	s_setprio 0
	s_andn2_b64 vcc, exec, s[14:15]
	s_mov_b64 s[16:17], -1
	s_mov_b64 s[14:15], 0
	s_mov_b64 s[34:35], 0x100
	s_barrier
	s_cbranch_vccz .LBB0_256
; __device__ __forceinline__ unsigned pk2(float lo, float hi) { unsigned r; asm("v_cvt_pk_bf16_f32 %0, %1, %2" : "=v"(r) : "v"(lo), "v"(hi)); return r; }
; #define PG8_WAIT_V(n) asm volatile("s_waitcnt vmcnt(" #n ")" ::: "memory")
; #define PG8_BAR __builtin_amdgcn_s_barrier()
; template <class Epi, class Sched>
; __device__ __forceinline__ void gemm_phase(LAS unsigned char* lds, const int K, const int lda, const int ldb, const Sched& S, const Epi& E) {
;     ...
;     PG8_WAIT_V(0);
;     if (wr == 0) PG8_BAR;
;     PG8_BAR;
;     __device__ __forceinline__ void operator()(const Acc& acc, const Unit& u, int wr, int wc, int fr, int fq) const {
;         const int pm = u.pm & 3, jg = u.pm >> 2, j = jg >> 2, g = jg & 3;
;         const int row0 = pm * BM + wr * 64 + fr, col0 = wc * 32 + 8 * fq;
;         bf16_t* base = W + ((size_t)j * 2048 + (size_t)u.pn * 1024) * 1024 + g * 256;
; #pragma unroll
;         for (int ai = 0; ai < 2; ++ai)
; #pragma unroll
;             for (int m = 0; m < 4; ++m) { bf16_t* rp = base + (size_t)(row0 + ai * HALF + m * 16) * 1024 + col0;
; #pragma unroll
;                 for (int bj = 0; bj < 2; ++bj) { const f32x4 v0 = acc[ai][bj][m][0], v1 = acc[ai][bj][m][1];
;                     u32x4 o; o.x = pk2(v0[0], v0[1]); o.y = pk2(v0[2], v0[3]); o.z = pk2(v1[0], v1[1]); o.w = pk2(v1[2], v1[3]);
;                     *(u32x4*)(rp + bj * HALF) = o; } }
;     }
	s_ashr_i32 s10, s54, 4
	s_lshl_b32 s2, s54, 8
	s_and_b32 s2, s2, 0x300
	s_ashr_i32 s11, s10, 31
	v_add_u32_e32 v144, s2, v140
	s_ashr_i32 s9, s8, 31
	s_lshl_b64 s[10:11], s[10:11], 22
	v_readlane_b32 s2, v250, 61
	s_add_u32 s2, s2, s10
	v_readlane_b32 s3, v250, 62
	s_addc_u32 s3, s3, s11
	s_lshl_b64 s[8:9], s[8:9], 21
	s_add_u32 s2, s2, s8
	s_addc_u32 s3, s3, s9
	s_lshl_b32 s8, s54, 7
	s_and_b32 s8, s8, 0x600
	s_add_u32 s8, s2, s8
	s_addc_u32 s9, s3, 0
	v_ashrrev_i32_e32 v145, 31, v144
	v_lshl_add_u64 v[146:147], s[8:9], 0, v[0:1]
	v_lshlrev_b64 v[138:139], 11, v[144:145]
	v_lshl_add_u64 v[138:139], v[146:147], 0, v[138:139]
	s_mov_b64 s[2:3], 0x40000
	v_cvt_pk_bf16_f32 v70, v70, v71
	v_cvt_pk_bf16_f32 v71, v72, v73
	v_cvt_pk_bf16_f32 v72, v66, v67
	v_lshl_add_u64 v[66:67], v[138:139], 0, s[2:3]
	s_mov_b32 s2, 0x40000
	v_cvt_pk_bf16_f32 v62, v62, v63
	v_cvt_pk_bf16_f32 v63, v64, v65
	v_cvt_pk_bf16_f32 v64, v58, v59
	v_add_co_u32_e32 v58, vcc, s2, v138
	v_cvt_pk_bf16_f32 v50, v50, v51
	v_cvt_pk_bf16_f32 v51, v52, v53
	s_mov_b64 s[2:3], 0x48000
	s_nop 0
	v_addc_co_u32_e32 v59, vcc, 0, v139, vcc
	s_mov_b32 s68, 0x48000
	v_cvt_pk_bf16_f32 v52, v42, v43
	v_cvt_pk_bf16_f32 v53, v44, v45
	global_store_dwordx4 v[66:67], v[50:53], off offset:256
	v_cvt_pk_bf16_f32 v44, v46, v47
	v_add_co_u32_e32 v46, vcc, s68, v138
	s_nop 0
	v_lshl_add_u64 v[50:51], v[138:139], 0, s[2:3]
	v_cvt_pk_bf16_f32 v34, v34, v35
	v_cvt_pk_bf16_f32 v35, v36, v37
	s_mov_b64 s[2:3], 0x50000
	v_cvt_pk_bf16_f32 v114, v114, v115
	v_cvt_pk_bf16_f32 v115, v116, v117
	v_cvt_pk_bf16_f32 v116, v106, v107
	v_or_b32_e32 v106, 16, v144
	v_addc_co_u32_e32 v47, vcc, 0, v139, vcc
	v_cvt_pk_bf16_f32 v36, v26, v27
	v_cvt_pk_bf16_f32 v37, v28, v29
	global_store_dwordx4 v[50:51], v[34:37], off offset:256
	v_ashrrev_i32_e32 v107, 31, v106
	v_cvt_pk_bf16_f32 v98, v98, v99
	v_cvt_pk_bf16_f32 v99, v100, v101
	v_cvt_pk_bf16_f32 v100, v90, v91
	v_or_b32_e32 v90, 32, v144
	v_lshl_add_u64 v[34:35], v[138:139], 0, s[2:3]
	s_mov_b32 s2, 0x50000
	v_cvt_pk_bf16_f32 v28, v30, v31
	v_add_co_u32_e32 v30, vcc, s2, v138
	v_cvt_pk_bf16_f32 v18, v18, v19
	v_cvt_pk_bf16_f32 v19, v20, v21
	s_mov_b64 s[2:3], 0x58000
	v_lshlrev_b64 v[106:107], 11, v[106:107]
	v_ashrrev_i32_e32 v91, 31, v90
	v_cvt_pk_bf16_f32 v82, v82, v83
	v_cvt_pk_bf16_f32 v83, v84, v85
	v_cvt_pk_bf16_f32 v84, v74, v75
	v_or_b32_e32 v74, 48, v144
	v_addc_co_u32_e32 v31, vcc, 0, v139, vcc
	v_cvt_pk_bf16_f32 v20, v10, v11
	v_cvt_pk_bf16_f32 v21, v12, v13
	global_store_dwordx4 v[34:35], v[18:21], off offset:256
	v_cvt_pk_bf16_f32 v117, v108, v109
	global_store_dwordx4 v[138:139], v[114:117], off offset:256
	v_lshlrev_b64 v[90:91], 11, v[90:91]
	v_lshl_add_u64 v[18:19], v[138:139], 0, s[2:3]
	s_mov_b32 s2, 0x58000
	v_lshl_add_u64 v[114:115], v[146:147], 0, v[106:107]
	v_ashrrev_i32_e32 v75, 31, v74
	v_cvt_pk_bf16_f32 v12, v14, v15
	v_add_co_u32_e32 v14, vcc, s2, v138
	v_cvt_pk_bf16_f32 v101, v92, v93
	global_store_dwordx4 v[114:115], v[98:101], off offset:256
	v_lshlrev_b64 v[74:75], 11, v[74:75]
	v_addc_co_u32_e32 v15, vcc, 0, v139, vcc
	v_lshl_add_u64 v[98:99], v[146:147], 0, v[90:91]
	v_cvt_pk_bf16_f32 v85, v76, v77
	global_store_dwordx4 v[98:99], v[82:85], off offset:256
	s_and_b64 vcc, exec, s[6:7]
	s_mov_b32 s8, s52
	v_lshl_add_u64 v[82:83], v[146:147], 0, v[74:75]
	s_mov_b32 s54, s53
	s_mov_b64 s[12:13], s[4:5]
	s_mov_b64 s[10:11], s[0:1]
	v_cvt_pk_bf16_f32 v126, v126, v127
	v_cvt_pk_bf16_f32 v127, v128, v129
	v_cvt_pk_bf16_f32 v128, v122, v123
	v_cvt_pk_bf16_f32 v129, v124, v125
	global_store_dwordx4 v[138:139], v[126:129], off
	v_cvt_pk_bf16_f32 v106, v118, v119
	v_cvt_pk_bf16_f32 v107, v120, v121
	v_cvt_pk_bf16_f32 v108, v110, v111
	v_cvt_pk_bf16_f32 v109, v112, v113
	global_store_dwordx4 v[114:115], v[106:109], off
	v_cvt_pk_bf16_f32 v90, v102, v103
	v_cvt_pk_bf16_f32 v91, v104, v105
	v_cvt_pk_bf16_f32 v92, v94, v95
	v_cvt_pk_bf16_f32 v93, v96, v97
	global_store_dwordx4 v[98:99], v[90:93], off
	v_cvt_pk_bf16_f32 v74, v86, v87
	v_cvt_pk_bf16_f32 v75, v88, v89
	v_cvt_pk_bf16_f32 v76, v78, v79
	v_cvt_pk_bf16_f32 v77, v80, v81
	global_store_dwordx4 v[82:83], v[74:77], off
	v_cvt_pk_bf16_f32 v73, v68, v69
	global_store_dwordx4 v[82:83], v[70:73], off offset:256
	v_cvt_pk_bf16_f32 v65, v60, v61
	global_store_dwordx4 v[58:59], v[62:65], off
	v_cvt_pk_bf16_f32 v42, v54, v55
	v_cvt_pk_bf16_f32 v43, v56, v57
	v_cvt_pk_bf16_f32 v45, v48, v49
	global_store_dwordx4 v[46:47], v[42:45], off
	v_cvt_pk_bf16_f32 v26, v38, v39
	v_cvt_pk_bf16_f32 v27, v40, v41
	v_cvt_pk_bf16_f32 v29, v32, v33
	global_store_dwordx4 v[30:31], v[26:29], off
	v_cvt_pk_bf16_f32 v10, v22, v23
	v_cvt_pk_bf16_f32 v11, v24, v25
	v_cvt_pk_bf16_f32 v13, v16, v17
	global_store_dwordx4 v[14:15], v[10:13], off
	v_cvt_pk_bf16_f32 v6, v6, v7
	v_cvt_pk_bf16_f32 v7, v8, v9
	v_cvt_pk_bf16_f32 v8, v2, v3
	v_cvt_pk_bf16_f32 v9, v4, v5
	global_store_dwordx4 v[18:19], v[6:9], off offset:256
	s_cbranch_vccz .LBB0_253
	s_waitcnt vmcnt(0)
	v_readlane_b32 s52, v253, 11
	v_readlane_b32 s54, v253, 13
	s_cmpk_gt_u32 s18, 0xff
	v_readlane_b32 s53, v253, 12
	v_readlane_b32 s55, v253, 14
	s_movk_i32 s48, 0x7000
	s_mov_b32 s47, s94
	s_cbranch_scc1 .LBB0_260
	s_barrier

; #define PG8_STAGE(bufoff, gbase, voff) do { _Pragma("unroll") for (int _i = 0; _i < 2; ++_i) \
;         __builtin_amdgcn_global_load_lds((const unsigned*)((const char*)(gbase) + (voff)[_i]), (LAS unsigned*)(lds + (bufoff) + ldsw + _i * 8192), 16, 0, 0); } while (0)
; #define PG8_STAGE_A(bufoff, gbase, h, vv) do { if constexpr (GATHER) { _Pragma("unroll") for (int _i = 0; _i < 2; ++_i) \
;         __builtin_amdgcn_global_load_lds((const unsigned*)((const char*)(gbase) + (vv)[h][_i]), (LAS unsigned*)(lds + (bufoff) + ldsw + _i * 8192), 16, 0, 0); } \
;         else { PG8_STAGE(bufoff, (gbase) + (h) * hstepA, voffA); } } while (0)
; #define PG8_LDA(dst, b, h) do { _Pragma("unroll") for (int m = 0; m < 4; ++m) _Pragma("unroll") for (int k = 0; k < 2; ++k) dst[m][k] = *(const LAS bf16x8*)(lds + PG8_SA(b, h) + aoff + m * 2048 + k * 1024); } while (0)
; #define PG8_LDB(dst, b, h) do { _Pragma("unroll") for (int n = 0; n < 2; ++n) _Pragma("unroll") for (int k = 0; k < 2; ++k) dst[n][k] = *(const LAS bf16x8*)(lds + PG8_SB(b, h) + boff + n * 2048 + k * 1024); } while (0)
; #define PG8_WAIT_L(n) asm volatile("s_waitcnt lgkmcnt(" #n ")" ::: "memory")
; template <class Epi, class Sched>
; __device__ __forceinline__ void gemm_phase(LAS unsigned char* lds, const int K, const int lda, const int ldb, const Sched& S, const Epi& E) {
;     ...
;         for (int t = 0; t < nt; t += 2) {
;             const bool last = (t == nt - 2);
;             const char* a1 = cA + (size_t)(t + 1) * kstep;
;             const char* a2 = last ? nA : cA + (size_t)(t + 2) * kstep; const char* b2 = last ? nB : cB + (size_t)(t + 2) * kstep;
;             const char* a3 = a2 + kstep; const char* b3 = b2 + kstep;
;             PG8_LDB(B0, 0, 0); PG8_SCHED; PG8_LDA(At, 0, 0); PG8_STAGE_A(PG8_SA(1, 1), a1, 1, vcur);
;             if constexpr (GATHER) { if (last) {
; #pragma unroll
;                 for (int h = 0; h < 2; ++h)
; #pragma unroll
;                     for (int i = 0; i < 2; ++i) vcur[h][i] = vnxt[h][i]; } }
;             PG8_WAIT_L(8); PG8_BAR; PG8_WAIT_L(0); PG8_MMA(0, 0, At, B0); PG8_BAR; PG8_SCHED;
;             PG8_LDB(B1, 0, 1); PG8_STAGE(PG8_SB(0, 0), b2, voffB);
;             PG8_BAR; PG8_WAIT_L(0); PG8_MMA(0, 1, At, B1); PG8_BAR;
;             PG8_LDA(At, 0, 1); PG8_STAGE_A(PG8_SA(0, 0), a2, 0, vcur);
;             PG8_BAR; PG8_WAIT_L(0); PG8_MMA(1, 0, At, B0); PG8_BAR; PG8_SCHED;
.LBB0_270:
	s_add_u32 s2, s10, 0xfffe0080
	s_addc_u32 s3, s11, -1
	s_add_i32 s20, 0, 0x10000
	v_add_u32_e32 v163, s20, v160
	ds_read_b128 v[152:155], v163
	ds_read_b128 v[156:159], v163 offset:1024
	ds_read_b128 v[164:167], v163 offset:2048
	ds_read_b128 v[168:171], v163 offset:3072
	s_cmp_eq_u32 s43, 4
	s_cselect_b32 s15, s7, s3
	s_cselect_b32 s14, s6, s2
	s_cselect_b32 s13, s9, s42
	s_cselect_b32 s12, s8, s41
	v_lshl_add_u64 v[214:215], s[10:11], 0, v[148:149]
	s_add_i32 m0, s19, 0xc000
	ds_read_b128 v[172:175], v162
	ds_read_b128 v[176:179], v162 offset:1024
	ds_read_b128 v[180:183], v162 offset:2048
	ds_read_b128 v[184:187], v162 offset:3072
	ds_read_b128 v[188:191], v162 offset:4096
	ds_read_b128 v[192:195], v162 offset:5120
	ds_read_b128 v[216:219], v162 offset:6144
	ds_read_b128 v[220:223], v162 offset:7168
	global_load_lds_dwordx4 v[214:215], off
	v_lshl_add_u64 v[214:215], s[10:11], 0, v[150:151]
	s_add_i32 m0, s19, 0xe000
	s_nop 0
	global_load_lds_dwordx4 v[214:215], off
	s_waitcnt lgkmcnt(8)
	s_barrier
	s_waitcnt lgkmcnt(0)
	s_setprio 1
	v_mfma_f32_16x16x32_bf16 v[126:129], v[152:155], v[172:175], v[126:129]
	v_mfma_f32_16x16x32_bf16 v[98:101], v[164:167], v[172:175], v[98:101]
	v_mfma_f32_16x16x32_bf16 v[122:125], v[152:155], v[180:183], v[122:125]
	v_mfma_f32_16x16x32_bf16 v[90:93], v[164:167], v[180:183], v[90:93]
	v_mfma_f32_16x16x32_bf16 v[118:121], v[152:155], v[188:191], v[118:121]
	v_mfma_f32_16x16x32_bf16 v[86:89], v[164:167], v[188:191], v[86:89]
	v_mfma_f32_16x16x32_bf16 v[114:117], v[152:155], v[216:219], v[114:117]
	v_mfma_f32_16x16x32_bf16 v[82:85], v[164:167], v[216:219], v[82:85]
	v_mfma_f32_16x16x32_bf16 v[126:129], v[156:159], v[176:179], v[126:129]
	v_mfma_f32_16x16x32_bf16 v[98:101], v[168:171], v[176:179], v[98:101]
	v_mfma_f32_16x16x32_bf16 v[122:125], v[156:159], v[184:187], v[122:125]
	v_mfma_f32_16x16x32_bf16 v[90:93], v[168:171], v[184:187], v[90:93]
	v_mfma_f32_16x16x32_bf16 v[118:121], v[156:159], v[192:195], v[118:121]
	v_mfma_f32_16x16x32_bf16 v[86:89], v[168:171], v[192:195], v[86:89]
	v_mfma_f32_16x16x32_bf16 v[114:117], v[156:159], v[220:223], v[114:117]
	v_mfma_f32_16x16x32_bf16 v[82:85], v[168:171], v[220:223], v[82:85]
	s_setprio 0
	s_barrier
	s_add_i32 s2, 0, 0x14000
	s_add_i32 s3, s20, s18
	v_add_u32_e32 v163, s2, v160
	v_lshl_add_u64 v[214:215], s[12:13], 0, v[0:1]
	s_mov_b32 m0, s3
	ds_read_b128 v[224:227], v163
	ds_read_b128 v[228:231], v163 offset:1024
	ds_read_b128 v[232:235], v163 offset:2048
	ds_read_b128 v[236:239], v163 offset:3072
	global_load_lds_dwordx4 v[214:215], off
	v_lshl_add_u64 v[240:241], s[12:13], 0, v[130:131]
	s_add_i32 m0, s3, 0x2000
	s_nop 0
	global_load_lds_dwordx4 v[240:241], off
	s_barrier
	s_waitcnt lgkmcnt(0)
	s_setprio 1
	v_mfma_f32_16x16x32_bf16 v[66:69], v[224:227], v[172:175], v[66:69]
	v_mfma_f32_16x16x32_bf16 v[34:37], v[232:235], v[172:175], v[34:37]
	v_mfma_f32_16x16x32_bf16 v[58:61], v[224:227], v[180:183], v[58:61]
	v_mfma_f32_16x16x32_bf16 v[26:29], v[232:235], v[180:183], v[26:29]
	v_mfma_f32_16x16x32_bf16 v[54:57], v[224:227], v[188:191], v[54:57]
	v_mfma_f32_16x16x32_bf16 v[22:25], v[232:235], v[188:191], v[22:25]
	v_mfma_f32_16x16x32_bf16 v[50:53], v[224:227], v[216:219], v[50:53]
	v_mfma_f32_16x16x32_bf16 v[18:21], v[232:235], v[216:219], v[18:21]
	v_mfma_f32_16x16x32_bf16 v[66:69], v[228:231], v[176:179], v[66:69]
	v_mfma_f32_16x16x32_bf16 v[34:37], v[236:239], v[176:179], v[34:37]
	v_mfma_f32_16x16x32_bf16 v[58:61], v[228:231], v[184:187], v[58:61]
	v_mfma_f32_16x16x32_bf16 v[26:29], v[236:239], v[184:187], v[26:29]
	v_mfma_f32_16x16x32_bf16 v[54:57], v[228:231], v[192:195], v[54:57]
	v_mfma_f32_16x16x32_bf16 v[22:25], v[236:239], v[192:195], v[22:25]
	v_mfma_f32_16x16x32_bf16 v[50:53], v[228:231], v[220:223], v[50:53]
	v_mfma_f32_16x16x32_bf16 v[18:21], v[236:239], v[220:223], v[18:21]
	s_setprio 0
	s_mov_b32 m0, s19
	v_lshl_add_u64 v[242:243], s[14:15], 0, v[0:1]
	s_barrier
	ds_read_b128 v[172:175], v162 offset:16384
	ds_read_b128 v[176:179], v162 offset:17408
	ds_read_b128 v[180:183], v162 offset:18432
	ds_read_b128 v[184:187], v162 offset:19456
	ds_read_b128 v[188:191], v162 offset:20480
	ds_read_b128 v[192:195], v162 offset:21504
	ds_read_b128 v[216:219], v162 offset:22528
	ds_read_b128 v[220:223], v162 offset:23552
	global_load_lds_dwordx4 v[242:243], off
	v_lshl_add_u64 v[244:245], s[14:15], 0, v[130:131]
	s_mov_b32 m0, s30
	s_nop 0
	global_load_lds_dwordx4 v[244:245], off
	s_barrier
	s_waitcnt lgkmcnt(0)
	s_setprio 1
	v_mfma_f32_16x16x32_bf16 v[110:113], v[152:155], v[172:175], v[110:113]
	v_mfma_f32_16x16x32_bf16 v[78:81], v[164:167], v[172:175], v[78:81]
	v_mfma_f32_16x16x32_bf16 v[106:109], v[152:155], v[180:183], v[106:109]
	v_mfma_f32_16x16x32_bf16 v[74:77], v[164:167], v[180:183], v[74:77]
	v_mfma_f32_16x16x32_bf16 v[102:105], v[152:155], v[188:191], v[102:105]
	v_mfma_f32_16x16x32_bf16 v[70:73], v[164:167], v[188:191], v[70:73]
	v_mfma_f32_16x16x32_bf16 v[94:97], v[152:155], v[216:219], v[94:97]
	v_mfma_f32_16x16x32_bf16 v[62:65], v[164:167], v[216:219], v[62:65]
	v_mfma_f32_16x16x32_bf16 v[110:113], v[156:159], v[176:179], v[110:113]
	v_mfma_f32_16x16x32_bf16 v[78:81], v[168:171], v[176:179], v[78:81]
	v_mfma_f32_16x16x32_bf16 v[106:109], v[156:159], v[184:187], v[106:109]
	v_mfma_f32_16x16x32_bf16 v[74:77], v[168:171], v[184:187], v[74:77]
	v_mfma_f32_16x16x32_bf16 v[102:105], v[156:159], v[192:195], v[102:105]
	v_mfma_f32_16x16x32_bf16 v[70:73], v[168:171], v[192:195], v[70:73]
	v_mfma_f32_16x16x32_bf16 v[94:97], v[156:159], v[220:223], v[94:97]
	v_mfma_f32_16x16x32_bf16 v[62:65], v[168:171], v[220:223], v[62:65]
	s_setprio 0
	s_barrier
; #define PG8_STAGE(bufoff, gbase, voff) do { _Pragma("unroll") for (int _i = 0; _i < 2; ++_i) \
;         __builtin_amdgcn_global_load_lds((const unsigned*)((const char*)(gbase) + (voff)[_i]), (LAS unsigned*)(lds + (bufoff) + ldsw + _i * 8192), 16, 0, 0); } while (0)
; #define PG8_STAGE_A(bufoff, gbase, h, vv) do { if constexpr (GATHER) { _Pragma("unroll") for (int _i = 0; _i < 2; ++_i) \
;         __builtin_amdgcn_global_load_lds((const unsigned*)((const char*)(gbase) + (vv)[h][_i]), (LAS unsigned*)(lds + (bufoff) + ldsw + _i * 8192), 16, 0, 0); } \
;         else { PG8_STAGE(bufoff, (gbase) + (h) * hstepA, voffA); } } while (0)
; #define PG8_LDA(dst, b, h) do { _Pragma("unroll") for (int m = 0; m < 4; ++m) _Pragma("unroll") for (int k = 0; k < 2; ++k) dst[m][k] = *(const LAS bf16x8*)(lds + PG8_SA(b, h) + aoff + m * 2048 + k * 1024); } while (0)
; #define PG8_LDB(dst, b, h) do { _Pragma("unroll") for (int n = 0; n < 2; ++n) _Pragma("unroll") for (int k = 0; k < 2; ++k) dst[n][k] = *(const LAS bf16x8*)(lds + PG8_SB(b, h) + boff + n * 2048 + k * 1024); } while (0)
; #define PG8_MMA(ai, bj, At, Bt) do { __builtin_amdgcn_s_setprio(1); _Pragma("unroll") for (int m = 0; m < 4; ++m) _Pragma("unroll") for (int n = 0; n < 2; ++n) _Pragma("unroll") for (int k = 0; k < 2; ++k) \
;         acc[ai][bj][m][n] = __builtin_amdgcn_mfma_f32_16x16x32_bf16(Bt[n][k], At[m][k], acc[ai][bj][m][n], 0, 0, 0); __builtin_amdgcn_s_setprio(0); } while (0)
; #define PG8_WAIT_V(n) asm volatile("s_waitcnt vmcnt(" #n ")" ::: "memory")
; #define PG8_WAIT_L(n) asm volatile("s_waitcnt lgkmcnt(" #n ")" ::: "memory")
; #define PG8_BAR __builtin_amdgcn_s_barrier()
; template <class Epi, class Sched>
; __device__ __forceinline__ void gemm_phase(LAS unsigned char* lds, const int K, const int lda, const int ldb, const Sched& S, const Epi& E) {
;     ...
;             PG8_STAGE(PG8_SB(0, 1), b2 + hstepB, voffB);
;             PG8_WAIT_V(6); PG8_BAR; PG8_MMA(1, 1, At, B1); PG8_BAR;
;             PG8_LDB(B0, 1, 0); PG8_SCHED; PG8_LDA(At, 1, 0); PG8_STAGE_A(PG8_SA(0, 1), a2, 1, vcur);
;             PG8_WAIT_L(8); PG8_BAR; PG8_WAIT_L(0); PG8_MMA(0, 0, At, B0); PG8_BAR; PG8_SCHED;
;             PG8_LDB(B1, 1, 1); PG8_STAGE(PG8_SB(1, 0), b3, voffB);
;             PG8_BAR; PG8_WAIT_L(0); PG8_MMA(0, 1, At, B1); PG8_BAR;
;             PG8_LDA(At, 1, 1); PG8_STAGE_A(PG8_SA(1, 0), a3, 0, vcur);
	s_add_u32 s44, s12, 0x20000
	s_addc_u32 s45, s13, 0
	s_add_i32 s2, s2, s18
	v_lshl_add_u64 v[152:153], s[44:45], 0, v[0:1]
	s_mov_b32 m0, s2
	s_nop 0
	global_load_lds_dwordx4 v[152:153], off
	v_lshl_add_u64 v[152:153], s[44:45], 0, v[130:131]
	s_add_i32 m0, s2, 0x2000
	s_nop 0
	global_load_lds_dwordx4 v[152:153], off
	s_waitcnt vmcnt(6)
	s_barrier
	s_setprio 1
	v_mfma_f32_16x16x32_bf16 v[46:49], v[224:227], v[172:175], v[46:49]
	v_mfma_f32_16x16x32_bf16 v[14:17], v[232:235], v[172:175], v[14:17]
	v_mfma_f32_16x16x32_bf16 v[42:45], v[224:227], v[180:183], v[42:45]
	v_mfma_f32_16x16x32_bf16 v[10:13], v[232:235], v[180:183], v[10:13]
	v_mfma_f32_16x16x32_bf16 v[38:41], v[224:227], v[188:191], v[38:41]
	v_mfma_f32_16x16x32_bf16 v[6:9], v[232:235], v[188:191], v[6:9]
	v_mfma_f32_16x16x32_bf16 v[30:33], v[224:227], v[216:219], v[30:33]
	v_mfma_f32_16x16x32_bf16 v[2:5], v[232:235], v[216:219], v[2:5]
	v_mfma_f32_16x16x32_bf16 v[46:49], v[228:231], v[176:179], v[46:49]
	v_mfma_f32_16x16x32_bf16 v[14:17], v[236:239], v[176:179], v[14:17]
	v_mfma_f32_16x16x32_bf16 v[42:45], v[228:231], v[184:187], v[42:45]
	v_mfma_f32_16x16x32_bf16 v[10:13], v[236:239], v[184:187], v[10:13]
	v_mfma_f32_16x16x32_bf16 v[38:41], v[228:231], v[192:195], v[38:41]
	v_mfma_f32_16x16x32_bf16 v[6:9], v[236:239], v[192:195], v[6:9]
	v_mfma_f32_16x16x32_bf16 v[30:33], v[228:231], v[220:223], v[30:33]
	v_mfma_f32_16x16x32_bf16 v[2:5], v[236:239], v[220:223], v[2:5]
	s_setprio 0
	s_add_i32 s2, 0, 0x18000
	v_add_u32_e32 v163, s2, v160
	s_barrier
	ds_read_b128 v[152:155], v163
	ds_read_b128 v[156:159], v163 offset:1024
	ds_read_b128 v[164:167], v163 offset:2048
	ds_read_b128 v[168:171], v163 offset:3072
	s_add_u32 s14, s14, 0x20000
	s_addc_u32 s15, s15, 0
	s_mov_b32 m0, s34
	v_lshl_add_u64 v[224:225], s[14:15], 0, v[0:1]
	ds_read_b128 v[172:175], v162 offset:32768
	ds_read_b128 v[176:179], v162 offset:33792
	ds_read_b128 v[180:183], v162 offset:34816
	ds_read_b128 v[184:187], v162 offset:35840
	ds_read_b128 v[188:191], v162 offset:36864
	ds_read_b128 v[192:195], v162 offset:37888
	ds_read_b128 v[216:219], v162 offset:38912
	ds_read_b128 v[220:223], v162 offset:39936
	global_load_lds_dwordx4 v[224:225], off
	v_lshl_add_u64 v[224:225], s[14:15], 0, v[130:131]
	s_mov_b32 m0, s35
	s_nop 0
	global_load_lds_dwordx4 v[224:225], off
	s_waitcnt lgkmcnt(8)
	s_barrier
	s_waitcnt lgkmcnt(0)
	s_setprio 1
	v_mfma_f32_16x16x32_bf16 v[126:129], v[152:155], v[172:175], v[126:129]
	v_mfma_f32_16x16x32_bf16 v[98:101], v[164:167], v[172:175], v[98:101]
	v_mfma_f32_16x16x32_bf16 v[122:125], v[152:155], v[180:183], v[122:125]
	v_mfma_f32_16x16x32_bf16 v[90:93], v[164:167], v[180:183], v[90:93]
	v_mfma_f32_16x16x32_bf16 v[118:121], v[152:155], v[188:191], v[118:121]
	v_mfma_f32_16x16x32_bf16 v[86:89], v[164:167], v[188:191], v[86:89]
	v_mfma_f32_16x16x32_bf16 v[114:117], v[152:155], v[216:219], v[114:117]
	v_mfma_f32_16x16x32_bf16 v[82:85], v[164:167], v[216:219], v[82:85]
	v_mfma_f32_16x16x32_bf16 v[126:129], v[156:159], v[176:179], v[126:129]
	v_mfma_f32_16x16x32_bf16 v[98:101], v[168:171], v[176:179], v[98:101]
	v_mfma_f32_16x16x32_bf16 v[122:125], v[156:159], v[184:187], v[122:125]
	v_mfma_f32_16x16x32_bf16 v[90:93], v[168:171], v[184:187], v[90:93]
	v_mfma_f32_16x16x32_bf16 v[118:121], v[156:159], v[192:195], v[118:121]
	v_mfma_f32_16x16x32_bf16 v[86:89], v[168:171], v[192:195], v[86:89]
	v_mfma_f32_16x16x32_bf16 v[114:117], v[156:159], v[220:223], v[114:117]
	v_mfma_f32_16x16x32_bf16 v[82:85], v[168:171], v[220:223], v[82:85]
	s_setprio 0
	s_barrier
	s_add_i32 s3, 0, 0x1c000
	s_add_i32 s2, s2, s18
	v_add_u32_e32 v163, s3, v160
	v_lshl_add_u64 v[214:215], v[214:215], 0, s[64:65]
	s_mov_b32 m0, s2
	ds_read_b128 v[224:227], v163
	ds_read_b128 v[228:231], v163 offset:1024
	ds_read_b128 v[232:235], v163 offset:2048
	ds_read_b128 v[236:239], v163 offset:3072
	global_load_lds_dwordx4 v[214:215], off
	v_lshl_add_u64 v[214:215], v[240:241], 0, s[64:65]
	s_add_i32 m0, s2, 0x2000
	s_nop 0
	global_load_lds_dwordx4 v[214:215], off
	s_barrier
	s_waitcnt lgkmcnt(0)
	s_setprio 1
	v_mfma_f32_16x16x32_bf16 v[66:69], v[224:227], v[172:175], v[66:69]
	v_mfma_f32_16x16x32_bf16 v[34:37], v[232:235], v[172:175], v[34:37]
	v_mfma_f32_16x16x32_bf16 v[58:61], v[224:227], v[180:183], v[58:61]
	v_mfma_f32_16x16x32_bf16 v[26:29], v[232:235], v[180:183], v[26:29]
	v_mfma_f32_16x16x32_bf16 v[54:57], v[224:227], v[188:191], v[54:57]
	v_mfma_f32_16x16x32_bf16 v[22:25], v[232:235], v[188:191], v[22:25]
	v_mfma_f32_16x16x32_bf16 v[50:53], v[224:227], v[216:219], v[50:53]
	v_mfma_f32_16x16x32_bf16 v[18:21], v[232:235], v[216:219], v[18:21]
	v_mfma_f32_16x16x32_bf16 v[66:69], v[228:231], v[176:179], v[66:69]
	v_mfma_f32_16x16x32_bf16 v[34:37], v[236:239], v[176:179], v[34:37]
	v_mfma_f32_16x16x32_bf16 v[58:61], v[228:231], v[184:187], v[58:61]
	v_mfma_f32_16x16x32_bf16 v[26:29], v[236:239], v[184:187], v[26:29]
	v_mfma_f32_16x16x32_bf16 v[54:57], v[228:231], v[192:195], v[54:57]
	v_mfma_f32_16x16x32_bf16 v[22:25], v[236:239], v[192:195], v[22:25]
	v_mfma_f32_16x16x32_bf16 v[50:53], v[228:231], v[220:223], v[50:53]
	v_mfma_f32_16x16x32_bf16 v[18:21], v[236:239], v[220:223], v[18:21]
	s_setprio 0
	s_mov_b32 m0, s36
	v_lshl_add_u64 v[214:215], v[242:243], 0, s[64:65]
	s_barrier
	ds_read_b128 v[172:175], v162 offset:49152
	ds_read_b128 v[176:179], v162 offset:50176
	ds_read_b128 v[180:183], v162 offset:51200
	ds_read_b128 v[184:187], v162 offset:52224
	ds_read_b128 v[188:191], v162 offset:53248
	ds_read_b128 v[192:195], v162 offset:54272
	ds_read_b128 v[216:219], v162 offset:55296
	ds_read_b128 v[220:223], v162 offset:56320
	global_load_lds_dwordx4 v[214:215], off
	v_lshl_add_u64 v[214:215], v[244:245], 0, s[64:65]
	s_mov_b32 m0, s37
	s_nop 0
	global_load_lds_dwordx4 v[214:215], off
	s_barrier
; #define PG8_STAGE(bufoff, gbase, voff) do { _Pragma("unroll") for (int _i = 0; _i < 2; ++_i) \
;         __builtin_amdgcn_global_load_lds((const unsigned*)((const char*)(gbase) + (voff)[_i]), (LAS unsigned*)(lds + (bufoff) + ldsw + _i * 8192), 16, 0, 0); } while (0)
; #define PG8_MMA(ai, bj, At, Bt) do { __builtin_amdgcn_s_setprio(1); _Pragma("unroll") for (int m = 0; m < 4; ++m) _Pragma("unroll") for (int n = 0; n < 2; ++n) _Pragma("unroll") for (int k = 0; k < 2; ++k) \
;         acc[ai][bj][m][n] = __builtin_amdgcn_mfma_f32_16x16x32_bf16(Bt[n][k], At[m][k], acc[ai][bj][m][n], 0, 0, 0); __builtin_amdgcn_s_setprio(0); } while (0)
; #define PG8_WAIT_V(n) asm volatile("s_waitcnt vmcnt(" #n ")" ::: "memory")
; #define PG8_WAIT_L(n) asm volatile("s_waitcnt lgkmcnt(" #n ")" ::: "memory")
; #define PG8_BAR __builtin_amdgcn_s_barrier()
; #define PG8_SCHED __builtin_amdgcn_sched_barrier(0)
; template <class Epi, class Sched>
; __device__ __forceinline__ void gemm_phase(LAS unsigned char* lds, const int K, const int lda, const int ldb, const Sched& S, const Epi& E) {
;     ...
;             PG8_BAR; PG8_WAIT_L(0); PG8_MMA(1, 0, At, B0); PG8_BAR; PG8_SCHED;
;             PG8_STAGE(PG8_SB(1, 1), b3 + hstepB, voffB);
;             PG8_WAIT_V(6); PG8_BAR; PG8_MMA(1, 1, At, B1); PG8_BAR;
;         }
;     __device__ __forceinline__ void operator()(const Acc& acc, const Unit& u, int wr, int wc, int fr, int fq) const {
;         const int row0 = wr * 64 + fr, col0 = u.pn * BM + wc * 32 + 4 * fq;
; #pragma unroll
;         for (int bj = 0; bj < 2; ++bj)
; #pragma unroll
;             for (int n = 0; n < 2; ++n) { const int col = col0 + bj * HALF + n * 16;
;                 const f32x4 g = *(const f32x4*)(gate + col) * (1.f / 256.f);
; #pragma unroll
;                 for (int ai = 0; ai < 2; ++ai)
; #pragma unroll
;                     for (int m = 0; m < 4; ++m) { f32x4* p = (f32x4*)(X + (size_t)(SEQ + row0 + ai * HALF + m * 16) * D + col); *p = *p + g * acc[ai][bj][m][n]; }
;                 __builtin_amdgcn_sched_barrier(0); }
;     }
	s_waitcnt lgkmcnt(0)
	s_setprio 1
	v_mfma_f32_16x16x32_bf16 v[110:113], v[152:155], v[172:175], v[110:113]
	v_mfma_f32_16x16x32_bf16 v[78:81], v[164:167], v[172:175], v[78:81]
	v_mfma_f32_16x16x32_bf16 v[106:109], v[152:155], v[180:183], v[106:109]
	v_mfma_f32_16x16x32_bf16 v[74:77], v[164:167], v[180:183], v[74:77]
	v_mfma_f32_16x16x32_bf16 v[102:105], v[152:155], v[188:191], v[102:105]
	v_mfma_f32_16x16x32_bf16 v[70:73], v[164:167], v[188:191], v[70:73]
	v_mfma_f32_16x16x32_bf16 v[94:97], v[152:155], v[216:219], v[94:97]
	v_mfma_f32_16x16x32_bf16 v[62:65], v[164:167], v[216:219], v[62:65]
	v_mfma_f32_16x16x32_bf16 v[110:113], v[156:159], v[176:179], v[110:113]
	v_mfma_f32_16x16x32_bf16 v[78:81], v[168:171], v[176:179], v[78:81]
	v_mfma_f32_16x16x32_bf16 v[106:109], v[156:159], v[184:187], v[106:109]
	v_mfma_f32_16x16x32_bf16 v[74:77], v[168:171], v[184:187], v[74:77]
	v_mfma_f32_16x16x32_bf16 v[102:105], v[156:159], v[192:195], v[102:105]
	v_mfma_f32_16x16x32_bf16 v[70:73], v[168:171], v[192:195], v[70:73]
	v_mfma_f32_16x16x32_bf16 v[94:97], v[156:159], v[220:223], v[94:97]
	v_mfma_f32_16x16x32_bf16 v[62:65], v[168:171], v[220:223], v[62:65]
	s_setprio 0
	s_barrier
	s_add_u32 s12, s12, 0x20080
	s_addc_u32 s13, s13, 0
	s_add_i32 s2, s3, s18
	v_lshl_add_u64 v[152:153], s[12:13], 0, v[0:1]
	s_mov_b32 m0, s2
	s_nop 0
	global_load_lds_dwordx4 v[152:153], off
	v_lshl_add_u64 v[152:153], s[12:13], 0, v[130:131]
	s_add_i32 m0, s2, 0x2000
	s_nop 0
	global_load_lds_dwordx4 v[152:153], off
	s_waitcnt vmcnt(6)
	s_barrier
	s_setprio 1
	v_mfma_f32_16x16x32_bf16 v[46:49], v[224:227], v[172:175], v[46:49]
	v_mfma_f32_16x16x32_bf16 v[14:17], v[232:235], v[172:175], v[14:17]
	v_mfma_f32_16x16x32_bf16 v[42:45], v[224:227], v[180:183], v[42:45]
	v_mfma_f32_16x16x32_bf16 v[10:13], v[232:235], v[180:183], v[10:13]
	v_mfma_f32_16x16x32_bf16 v[38:41], v[224:227], v[188:191], v[38:41]
	v_mfma_f32_16x16x32_bf16 v[6:9], v[232:235], v[188:191], v[6:9]
	v_mfma_f32_16x16x32_bf16 v[30:33], v[224:227], v[216:219], v[30:33]
	v_mfma_f32_16x16x32_bf16 v[2:5], v[232:235], v[216:219], v[2:5]
	v_mfma_f32_16x16x32_bf16 v[46:49], v[228:231], v[176:179], v[46:49]
	v_mfma_f32_16x16x32_bf16 v[14:17], v[236:239], v[176:179], v[14:17]
	v_mfma_f32_16x16x32_bf16 v[42:45], v[228:231], v[184:187], v[42:45]
	v_mfma_f32_16x16x32_bf16 v[10:13], v[236:239], v[184:187], v[10:13]
	v_mfma_f32_16x16x32_bf16 v[38:41], v[228:231], v[192:195], v[38:41]
	v_mfma_f32_16x16x32_bf16 v[6:9], v[236:239], v[192:195], v[6:9]
	v_mfma_f32_16x16x32_bf16 v[30:33], v[228:231], v[220:223], v[30:33]
	v_mfma_f32_16x16x32_bf16 v[2:5], v[236:239], v[220:223], v[2:5]
	s_setprio 0
	s_add_i32 s43, s43, 2
	s_add_u32 s10, s10, 0x100
	s_addc_u32 s11, s11, 0
	s_add_u32 s41, s41, 0x100
	s_addc_u32 s42, s42, 0
	s_cmp_gt_u32 s43, 5
	s_barrier
	s_cbranch_scc0 .LBB0_270
	v_lshl_or_b32 v154, s40, 8, v161
	v_ashrrev_i32_e32 v155, 31, v154
	v_lshlrev_b64 v[168:169], 2, v[154:155]
	v_lshl_add_u64 v[152:153], s[0:1], 0, v[168:169]
	global_load_dwordx4 v[164:167], v[152:153], off
	s_mov_b32 s2, 0x3b800000
	v_lshl_add_u64 v[152:153], v[132:133], 0, v[168:169]
	s_waitcnt vmcnt(0)
	v_pk_mul_f32 v[156:157], v[166:167], s[2:3] op_sel_hi:[1,0]
	v_pk_mul_f32 v[158:159], v[164:165], s[2:3] op_sel_hi:[1,0]
	global_load_dwordx4 v[172:175], v[152:153], off
	v_lshl_add_u64 v[224:225], v[134:135], 0, v[168:169]
	global_load_dwordx4 v[176:179], v[224:225], off
	v_lshl_add_u64 v[224:225], v[136:137], 0, v[168:169]
	global_load_dwordx4 v[180:183], v[224:225], off
	v_lshl_add_u64 v[224:225], v[138:139], 0, v[168:169]
	global_load_dwordx4 v[184:187], v[224:225], off
	v_lshl_add_u64 v[224:225], v[140:141], 0, v[168:169]
	global_load_dwordx4 v[188:191], v[224:225], off
	v_lshl_add_u64 v[224:225], v[142:143], 0, v[168:169]
	global_load_dwordx4 v[192:195], v[224:225], off
	v_lshl_add_u64 v[224:225], v[144:145], 0, v[168:169]
	global_load_dwordx4 v[216:219], v[224:225], off
	v_lshl_add_u64 v[224:225], v[146:147], 0, v[168:169]
	global_load_dwordx4 v[220:223], v[224:225], off
	s_waitcnt vmcnt(7)
	v_pk_fma_f32 v[128:129], v[128:129], v[156:157], v[174:175]
	v_pk_fma_f32 v[126:127], v[126:127], v[158:159], v[172:173]
	global_store_dwordx4 v[152:153], v[126:129], off
	s_nop 1
	v_lshl_add_u64 v[126:127], v[134:135], 0, v[168:169]
	s_waitcnt vmcnt(7)
	v_pk_fma_f32 v[124:125], v[124:125], v[156:157], v[178:179]
	v_pk_fma_f32 v[122:123], v[122:123], v[158:159], v[176:177]
	global_store_dwordx4 v[126:127], v[122:125], off
	s_nop 1
	v_lshl_add_u64 v[122:123], v[136:137], 0, v[168:169]
	s_waitcnt vmcnt(7)
	v_pk_fma_f32 v[120:121], v[120:121], v[156:157], v[182:183]
	v_pk_fma_f32 v[118:119], v[118:119], v[158:159], v[180:181]
	global_store_dwordx4 v[122:123], v[118:121], off
	s_nop 1
	v_lshl_add_u64 v[118:119], v[138:139], 0, v[168:169]
	s_waitcnt vmcnt(7)
	v_pk_fma_f32 v[116:117], v[116:117], v[156:157], v[186:187]
	v_pk_fma_f32 v[114:115], v[114:115], v[158:159], v[184:185]
	global_store_dwordx4 v[118:119], v[114:117], off
	s_nop 1
	v_lshl_add_u64 v[114:115], v[140:141], 0, v[168:169]
	s_waitcnt vmcnt(7)
	v_pk_fma_f32 v[112:113], v[112:113], v[156:157], v[190:191]
	v_pk_fma_f32 v[110:111], v[110:111], v[158:159], v[188:189]
	global_store_dwordx4 v[114:115], v[110:113], off
	s_nop 1
	v_lshl_add_u64 v[110:111], v[142:143], 0, v[168:169]
	s_waitcnt vmcnt(7)
	v_pk_fma_f32 v[108:109], v[108:109], v[156:157], v[194:195]
	v_pk_fma_f32 v[106:107], v[106:107], v[158:159], v[192:193]
	global_store_dwordx4 v[110:111], v[106:109], off
	s_nop 1
	v_lshl_add_u64 v[106:107], v[144:145], 0, v[168:169]
	s_waitcnt vmcnt(7)
;     __device__ __forceinline__ void operator()(const Acc& acc, const Unit& u, int wr, int wc, int fr, int fq) const {
;     ...
;         for (int bj = 0; bj < 2; ++bj)
; #pragma unroll
;             for (int n = 0; n < 2; ++n) { const int col = col0 + bj * HALF + n * 16;
;                 const f32x4 g = *(const f32x4*)(gate + col) * (1.f / 256.f);
; #pragma unroll
;                 for (int ai = 0; ai < 2; ++ai)
; #pragma unroll
;                     for (int m = 0; m < 4; ++m) { f32x4* p = (f32x4*)(X + (size_t)(SEQ + row0 + ai * HALF + m * 16) * D + col); *p = *p + g * acc[ai][bj][m][n]; }
;                 __builtin_amdgcn_sched_barrier(0); }
	v_pk_fma_f32 v[104:105], v[104:105], v[156:157], v[218:219]
	v_pk_fma_f32 v[102:103], v[102:103], v[158:159], v[216:217]
	global_store_dwordx4 v[106:107], v[102:105], off
	s_nop 1
	v_lshl_add_u64 v[102:103], v[146:147], 0, v[168:169]
	s_waitcnt vmcnt(7)
	v_pk_fma_f32 v[96:97], v[96:97], v[156:157], v[222:223]
	v_pk_fma_f32 v[94:95], v[94:95], v[158:159], v[220:221]
	global_store_dwordx4 v[102:103], v[94:97], off
	s_nop 1
	v_or_b32_e32 v94, 16, v154
	v_ashrrev_i32_e32 v95, 31, v94
	v_lshl_add_u64 v[94:95], v[94:95], 2, s[0:1]
	global_load_dwordx4 v[94:97], v[94:95], off
	s_waitcnt vmcnt(0)
	v_pk_mul_f32 v[104:105], v[96:97], s[2:3] op_sel_hi:[1,0]
	v_pk_mul_f32 v[108:109], v[94:95], s[2:3] op_sel_hi:[1,0]
	global_load_dwordx4 v[172:175], v[152:153], off offset:64
	global_load_dwordx4 v[176:179], v[126:127], off offset:64
	global_load_dwordx4 v[180:183], v[122:123], off offset:64
	global_load_dwordx4 v[184:187], v[118:119], off offset:64
	global_load_dwordx4 v[188:191], v[114:115], off offset:64
	global_load_dwordx4 v[192:195], v[110:111], off offset:64
	global_load_dwordx4 v[216:219], v[106:107], off offset:64
	global_load_dwordx4 v[220:223], v[102:103], off offset:64
	s_waitcnt vmcnt(7)
	v_pk_fma_f32 v[96:97], v[100:101], v[104:105], v[174:175]
	v_pk_fma_f32 v[94:95], v[98:99], v[108:109], v[172:173]
	global_store_dwordx4 v[152:153], v[94:97], off offset:64
	s_waitcnt vmcnt(7)
	v_pk_fma_f32 v[92:93], v[92:93], v[104:105], v[178:179]
	v_pk_fma_f32 v[90:91], v[90:91], v[108:109], v[176:177]
	global_store_dwordx4 v[126:127], v[90:93], off offset:64
	s_waitcnt vmcnt(7)
	v_pk_fma_f32 v[88:89], v[88:89], v[104:105], v[182:183]
	v_pk_fma_f32 v[86:87], v[86:87], v[108:109], v[180:181]
	global_store_dwordx4 v[122:123], v[86:89], off offset:64
	s_waitcnt vmcnt(7)
	v_pk_fma_f32 v[84:85], v[84:85], v[104:105], v[186:187]
	v_pk_fma_f32 v[82:83], v[82:83], v[108:109], v[184:185]
	global_store_dwordx4 v[118:119], v[82:85], off offset:64
	s_waitcnt vmcnt(7)
	v_pk_fma_f32 v[80:81], v[80:81], v[104:105], v[190:191]
	v_pk_fma_f32 v[78:79], v[78:79], v[108:109], v[188:189]
	global_store_dwordx4 v[114:115], v[78:81], off offset:64
	s_waitcnt vmcnt(7)
	v_pk_fma_f32 v[76:77], v[76:77], v[104:105], v[194:195]
	v_pk_fma_f32 v[74:75], v[74:75], v[108:109], v[192:193]
	global_store_dwordx4 v[110:111], v[74:77], off offset:64
	s_waitcnt vmcnt(7)
	v_pk_fma_f32 v[72:73], v[72:73], v[104:105], v[218:219]
	v_pk_fma_f32 v[70:71], v[70:71], v[108:109], v[216:217]
	global_store_dwordx4 v[106:107], v[70:73], off offset:64
	s_waitcnt vmcnt(7)
	v_pk_fma_f32 v[64:65], v[64:65], v[104:105], v[222:223]
	v_pk_fma_f32 v[62:63], v[62:63], v[108:109], v[220:221]
	global_store_dwordx4 v[102:103], v[62:65], off offset:64
	s_nop 1
	v_or_b32_e32 v62, 0x80, v154
	v_ashrrev_i32_e32 v63, 31, v62
	v_lshl_add_u64 v[62:63], v[62:63], 2, s[0:1]
	global_load_dwordx4 v[62:65], v[62:63], off
	s_waitcnt vmcnt(0)
	v_pk_mul_f32 v[70:71], v[64:65], s[2:3] op_sel_hi:[1,0]
	v_pk_mul_f32 v[72:73], v[62:63], s[2:3] op_sel_hi:[1,0]
	global_load_dwordx4 v[172:175], v[152:153], off offset:512
	global_load_dwordx4 v[176:179], v[126:127], off offset:512
	global_load_dwordx4 v[180:183], v[122:123], off offset:512
	global_load_dwordx4 v[184:187], v[118:119], off offset:512
	global_load_dwordx4 v[188:191], v[114:115], off offset:512
	global_load_dwordx4 v[192:195], v[110:111], off offset:512
	global_load_dwordx4 v[216:219], v[106:107], off offset:512
	global_load_dwordx4 v[220:223], v[102:103], off offset:512
	s_waitcnt vmcnt(7)
	v_pk_fma_f32 v[64:65], v[68:69], v[70:71], v[174:175]
	v_pk_fma_f32 v[62:63], v[66:67], v[72:73], v[172:173]
	global_store_dwordx4 v[152:153], v[62:65], off offset:512
	s_waitcnt vmcnt(7)
;     __device__ __forceinline__ void operator()(const Acc& acc, const Unit& u, int wr, int wc, int fr, int fq) const {
;     ...
;         for (int bj = 0; bj < 2; ++bj)
; #pragma unroll
;             for (int n = 0; n < 2; ++n) { const int col = col0 + bj * HALF + n * 16;
;                 const f32x4 g = *(const f32x4*)(gate + col) * (1.f / 256.f);
; #pragma unroll
;                 for (int ai = 0; ai < 2; ++ai)
; #pragma unroll
;                     for (int m = 0; m < 4; ++m) { f32x4* p = (f32x4*)(X + (size_t)(SEQ + row0 + ai * HALF + m * 16) * D + col); *p = *p + g * acc[ai][bj][m][n]; }
;                 __builtin_amdgcn_sched_barrier(0); }
	v_pk_fma_f32 v[60:61], v[60:61], v[70:71], v[178:179]
	v_pk_fma_f32 v[58:59], v[58:59], v[72:73], v[176:177]
	global_store_dwordx4 v[126:127], v[58:61], off offset:512
	s_waitcnt vmcnt(7)
	v_pk_fma_f32 v[56:57], v[56:57], v[70:71], v[182:183]
	v_pk_fma_f32 v[54:55], v[54:55], v[72:73], v[180:181]
	global_store_dwordx4 v[122:123], v[54:57], off offset:512
	s_waitcnt vmcnt(7)
	v_pk_fma_f32 v[52:53], v[52:53], v[70:71], v[186:187]
	v_pk_fma_f32 v[50:51], v[50:51], v[72:73], v[184:185]
	global_store_dwordx4 v[118:119], v[50:53], off offset:512
	s_waitcnt vmcnt(7)
	v_pk_fma_f32 v[48:49], v[48:49], v[70:71], v[190:191]
	v_pk_fma_f32 v[46:47], v[46:47], v[72:73], v[188:189]
	global_store_dwordx4 v[114:115], v[46:49], off offset:512
	s_waitcnt vmcnt(7)
	v_pk_fma_f32 v[44:45], v[44:45], v[70:71], v[194:195]
	v_pk_fma_f32 v[42:43], v[42:43], v[72:73], v[192:193]
	global_store_dwordx4 v[110:111], v[42:45], off offset:512
	s_waitcnt vmcnt(7)
	v_pk_fma_f32 v[40:41], v[40:41], v[70:71], v[218:219]
	v_pk_fma_f32 v[38:39], v[38:39], v[72:73], v[216:217]
	global_store_dwordx4 v[106:107], v[38:41], off offset:512
	s_waitcnt vmcnt(7)
	v_pk_fma_f32 v[32:33], v[32:33], v[70:71], v[222:223]
	v_pk_fma_f32 v[30:31], v[30:31], v[72:73], v[220:221]
	global_store_dwordx4 v[102:103], v[30:33], off offset:512
	s_nop 1
	v_or_b32_e32 v30, 0x90, v154
	v_ashrrev_i32_e32 v31, 31, v30
	v_lshl_add_u64 v[30:31], v[30:31], 2, s[0:1]
	global_load_dwordx4 v[30:33], v[30:31], off
	s_waitcnt vmcnt(0)
	v_pk_mul_f32 v[38:39], v[32:33], s[2:3] op_sel_hi:[1,0]
	v_pk_mul_f32 v[40:41], v[30:31], s[2:3] op_sel_hi:[1,0]
	global_load_dwordx4 v[172:175], v[152:153], off offset:576
	global_load_dwordx4 v[176:179], v[126:127], off offset:576
	global_load_dwordx4 v[180:183], v[122:123], off offset:576
	global_load_dwordx4 v[184:187], v[118:119], off offset:576
	global_load_dwordx4 v[188:191], v[114:115], off offset:576
	global_load_dwordx4 v[192:195], v[110:111], off offset:576
	global_load_dwordx4 v[216:219], v[106:107], off offset:576
	global_load_dwordx4 v[220:223], v[102:103], off offset:576
	s_waitcnt vmcnt(7)
	v_pk_fma_f32 v[32:33], v[36:37], v[38:39], v[174:175]
	v_pk_fma_f32 v[30:31], v[34:35], v[40:41], v[172:173]
	global_store_dwordx4 v[152:153], v[30:33], off offset:576
	s_waitcnt vmcnt(7)
	v_pk_fma_f32 v[28:29], v[28:29], v[38:39], v[178:179]
	v_pk_fma_f32 v[26:27], v[26:27], v[40:41], v[176:177]
	global_store_dwordx4 v[126:127], v[26:29], off offset:576
	s_waitcnt vmcnt(7)
	v_pk_fma_f32 v[24:25], v[24:25], v[38:39], v[182:183]
	v_pk_fma_f32 v[22:23], v[22:23], v[40:41], v[180:181]
	global_store_dwordx4 v[122:123], v[22:25], off offset:576
	s_waitcnt vmcnt(7)
	v_pk_fma_f32 v[20:21], v[20:21], v[38:39], v[186:187]
	v_pk_fma_f32 v[18:19], v[18:19], v[40:41], v[184:185]
	global_store_dwordx4 v[118:119], v[18:21], off offset:576
	s_waitcnt vmcnt(7)
	v_pk_fma_f32 v[16:17], v[16:17], v[38:39], v[190:191]
	v_pk_fma_f32 v[14:15], v[14:15], v[40:41], v[188:189]
	global_store_dwordx4 v[114:115], v[14:17], off offset:576
	s_waitcnt vmcnt(7)
	v_pk_fma_f32 v[12:13], v[12:13], v[38:39], v[194:195]
	v_pk_fma_f32 v[10:11], v[10:11], v[40:41], v[192:193]
	global_store_dwordx4 v[110:111], v[10:13], off offset:576
	s_waitcnt vmcnt(7)
	v_pk_fma_f32 v[8:9], v[8:9], v[38:39], v[218:219]
	v_pk_fma_f32 v[6:7], v[6:7], v[40:41], v[216:217]
	global_store_dwordx4 v[106:107], v[6:9], off offset:576
	s_waitcnt vmcnt(7)
	v_pk_fma_f32 v[4:5], v[4:5], v[38:39], v[222:223]
	v_pk_fma_f32 v[2:3], v[2:3], v[40:41], v[220:221]
	global_store_dwordx4 v[102:103], v[2:5], off offset:576
	s_and_b64 vcc, exec, s[4:5]
	s_mov_b32 s40, s39
	s_mov_b64 s[12:13], s[8:9]
	s_mov_b64 s[10:11], s[6:7]
	s_cbranch_vccz .LBB0_267
	s_waitcnt vmcnt(0)
	s_cmpk_gt_u32 s17, 0xff
	s_cbranch_scc1 .LBB0_274
	s_barrier

; #define PG8_STAGE(bufoff, gbase, voff) do { _Pragma("unroll") for (int _i = 0; _i < 2; ++_i) \
;         __builtin_amdgcn_global_load_lds((const unsigned*)((const char*)(gbase) + (voff)[_i]), (LAS unsigned*)(lds + (bufoff) + ldsw + _i * 8192), 16, 0, 0); } while (0)
; #define PG8_STAGE_A(bufoff, gbase, h, vv) do { if constexpr (GATHER) { _Pragma("unroll") for (int _i = 0; _i < 2; ++_i) \
;         __builtin_amdgcn_global_load_lds((const unsigned*)((const char*)(gbase) + (vv)[h][_i]), (LAS unsigned*)(lds + (bufoff) + ldsw + _i * 8192), 16, 0, 0); } \
;         else { PG8_STAGE(bufoff, (gbase) + (h) * hstepA, voffA); } } while (0)
; #define PG8_WAIT_L(n) asm volatile("s_waitcnt lgkmcnt(" #n ")" ::: "memory")
; #define PG8_BAR __builtin_amdgcn_s_barrier()
; template <class Epi, class Sched>
; __device__ __forceinline__ void gemm_phase(LAS unsigned char* lds, const int K, const int lda, const int ldb, const Sched& S, const Epi& E) {
;     ...
;         const bool has_next = S.next(ui + 1, nxt);
;         const char* nA = has_next ? nxt.a : cA; const char* nB = has_next ? nxt.b : cB;
;         if constexpr (GATHER) {
;             nA = cA;
;             if (has_next) mk_off(ix1, vnxt);
;             else {
; #pragma unroll
;                 for (int h = 0; h < 2; ++h)
; #pragma unroll
;                     for (int i = 0; i < 2; ++i) vnxt[h][i] = vcur[h][i];
;             }
;         }
; #pragma unroll 1
;         for (int t = 0; t < nt; t += 2) {
;             const bool last = (t == nt - 2);
;             const char* a1 = cA + (size_t)(t + 1) * kstep;
;             const char* a2 = last ? nA : cA + (size_t)(t + 2) * kstep; const char* b2 = last ? nB : cB + (size_t)(t + 2) * kstep;
;             const char* a3 = a2 + kstep; const char* b3 = b2 + kstep;
;             PG8_LDB(B0, 0, 0); PG8_SCHED; PG8_LDA(At, 0, 0); PG8_STAGE_A(PG8_SA(1, 1), a1, 1, vcur);
;             if constexpr (GATHER) { if (last) {
; #pragma unroll
;                 for (int h = 0; h < 2; ++h)
; #pragma unroll
;                     for (int i = 0; i < 2; ++i) vcur[h][i] = vnxt[h][i]; } }
;             PG8_WAIT_L(8); PG8_BAR; PG8_WAIT_L(0); PG8_MMA(0, 0, At, B0); PG8_BAR; PG8_SCHED;
;             PG8_LDB(B1, 0, 1); PG8_STAGE(PG8_SB(0, 0), b2, voffB);
;             PG8_BAR; PG8_WAIT_L(0); PG8_MMA(0, 1, At, B1); PG8_BAR;
;             PG8_LDA(At, 0, 1); PG8_STAGE_A(PG8_SA(0, 0), a2, 0, vcur);
.LBB0_286:
	s_add_u32 s11, s6, s42
	s_addc_u32 s13, s7, s43
	s_add_u32 s20, s11, 0x100
	s_addc_u32 s21, s13, 0
	s_and_b64 s[2:3], s[40:41], exec
	s_cselect_b32 s49, s35, s21
	s_cselect_b32 s48, s34, s20
	s_add_u32 s2, s8, s42
	s_addc_u32 s3, s9, s43
	s_add_u32 s20, s2, 0x100
	s_addc_u32 s21, s3, 0
	s_add_i32 s50, 0, 0x10000
	s_and_b64 s[2:3], s[40:41], exec
	s_cselect_b32 s3, s37, s21
	s_cselect_b32 s2, s36, s20
	s_add_u32 s20, s11, 0x10080
	s_addc_u32 s21, s13, 0
	s_add_i32 s57, s50, s19
	s_add_i32 m0, s30, 0xc000
	s_add_i32 s51, s30, 0xe000
	s_add_i32 s56, 0, 0x14000
	s_add_i32 s66, s57, 0x2000
	s_add_u32 s46, s2, 0x10000
	v_add_u32_e32 v146, s50, v132
	s_addc_u32 s47, s3, 0
	s_add_i32 s67, s56, s19
	ds_read_b128 v[134:137], v146
	ds_read_b128 v[138:141], v146 offset:1024
	ds_read_b128 v[142:145], v146 offset:2048
	ds_read_b128 v[150:153], v146 offset:3072
	s_add_i32 s68, s67, 0x2000
	s_add_i32 s69, 0, 0x18000
	s_add_u32 s42, s48, 0x10000
	s_addc_u32 s43, s49, 0
	s_add_i32 s70, s69, s19
	s_add_i32 s63, 0, 0x1c000
	s_add_i32 s62, s70, 0x2000
	s_add_u32 s40, s2, 0x10080
	s_addc_u32 s41, s3, 0
	s_add_i32 s13, s63, s19
	s_add_i32 s11, s13, 0x2000
	v_lshl_add_u64 v[146:147], s[20:21], 0, v[0:1]
	ds_read_b128 v[154:157], v133
	ds_read_b128 v[158:161], v133 offset:1024
	ds_read_b128 v[162:165], v133 offset:2048
	ds_read_b128 v[166:169], v133 offset:3072
	ds_read_b128 v[170:173], v133 offset:4096
	ds_read_b128 v[174:177], v133 offset:5120
	ds_read_b128 v[178:181], v133 offset:6144
	ds_read_b128 v[186:189], v133 offset:7168
	global_load_lds_dwordx4 v[146:147], off
	v_lshl_add_u64 v[146:147], s[20:21], 0, v[130:131]
	s_mov_b32 m0, s51
	s_nop 0
	global_load_lds_dwordx4 v[146:147], off
	s_waitcnt lgkmcnt(8)
	s_barrier
	s_waitcnt lgkmcnt(0)
	s_setprio 1
	v_mfma_f32_16x16x32_bf16 v[126:129], v[134:137], v[154:157], v[126:129]
	v_mfma_f32_16x16x32_bf16 v[98:101], v[142:145], v[154:157], v[98:101]
	v_mfma_f32_16x16x32_bf16 v[122:125], v[134:137], v[162:165], v[122:125]
	v_mfma_f32_16x16x32_bf16 v[94:97], v[142:145], v[162:165], v[94:97]
	v_mfma_f32_16x16x32_bf16 v[118:121], v[134:137], v[170:173], v[118:121]
	v_mfma_f32_16x16x32_bf16 v[78:81], v[142:145], v[170:173], v[78:81]
	v_mfma_f32_16x16x32_bf16 v[106:109], v[134:137], v[178:181], v[106:109]
	v_mfma_f32_16x16x32_bf16 v[74:77], v[142:145], v[178:181], v[74:77]
	v_mfma_f32_16x16x32_bf16 v[126:129], v[138:141], v[158:161], v[126:129]
	v_mfma_f32_16x16x32_bf16 v[98:101], v[150:153], v[158:161], v[98:101]
	v_mfma_f32_16x16x32_bf16 v[122:125], v[138:141], v[166:169], v[122:125]
	v_mfma_f32_16x16x32_bf16 v[94:97], v[150:153], v[166:169], v[94:97]
	v_mfma_f32_16x16x32_bf16 v[118:121], v[138:141], v[174:177], v[118:121]
	v_mfma_f32_16x16x32_bf16 v[78:81], v[150:153], v[174:177], v[78:81]
	v_mfma_f32_16x16x32_bf16 v[106:109], v[138:141], v[186:189], v[106:109]
	v_mfma_f32_16x16x32_bf16 v[74:77], v[150:153], v[186:189], v[74:77]
	s_setprio 0
	s_barrier
	v_add_u32_e32 v146, s56, v132
	s_mov_b32 m0, s57
	ds_read_b128 v[190:193], v146
	ds_read_b128 v[216:219], v146 offset:1024
	ds_read_b128 v[220:223], v146 offset:2048
	ds_read_b128 v[224:227], v146 offset:3072
	v_lshl_add_u64 v[146:147], s[2:3], 0, v[0:1]
	global_load_lds_dwordx4 v[146:147], off
	v_lshl_add_u64 v[182:183], s[2:3], 0, v[130:131]
	s_mov_b32 m0, s66
	s_nop 0
	global_load_lds_dwordx4 v[182:183], off
	s_barrier
	s_waitcnt lgkmcnt(0)
	s_setprio 1
	v_mfma_f32_16x16x32_bf16 v[62:65], v[190:193], v[154:157], v[62:65]
	v_mfma_f32_16x16x32_bf16 v[114:117], v[220:223], v[154:157], v[114:117]
	v_mfma_f32_16x16x32_bf16 v[54:57], v[190:193], v[162:165], v[54:57]
	v_mfma_f32_16x16x32_bf16 v[30:33], v[220:223], v[162:165], v[30:33]
	v_mfma_f32_16x16x32_bf16 v[46:49], v[190:193], v[170:173], v[46:49]
	v_mfma_f32_16x16x32_bf16 v[110:113], v[220:223], v[170:173], v[110:113]
	v_mfma_f32_16x16x32_bf16 v[42:45], v[190:193], v[178:181], v[42:45]
	v_mfma_f32_16x16x32_bf16 v[22:25], v[220:223], v[178:181], v[22:25]
	v_mfma_f32_16x16x32_bf16 v[62:65], v[216:219], v[158:161], v[62:65]
	v_mfma_f32_16x16x32_bf16 v[114:117], v[224:227], v[158:161], v[114:117]
	v_mfma_f32_16x16x32_bf16 v[54:57], v[216:219], v[166:169], v[54:57]
	v_mfma_f32_16x16x32_bf16 v[30:33], v[224:227], v[166:169], v[30:33]
	v_mfma_f32_16x16x32_bf16 v[46:49], v[216:219], v[174:177], v[46:49]
	v_mfma_f32_16x16x32_bf16 v[110:113], v[224:227], v[174:177], v[110:113]
	v_mfma_f32_16x16x32_bf16 v[42:45], v[216:219], v[186:189], v[42:45]
	v_mfma_f32_16x16x32_bf16 v[22:25], v[224:227], v[186:189], v[22:25]
	s_setprio 0
	s_mov_b32 m0, s30
	v_lshl_add_u64 v[194:195], s[48:49], 0, v[0:1]
	s_barrier
	ds_read_b128 v[154:157], v133 offset:16384
	ds_read_b128 v[158:161], v133 offset:17408
	ds_read_b128 v[162:165], v133 offset:18432
	ds_read_b128 v[166:169], v133 offset:19456
	ds_read_b128 v[170:173], v133 offset:20480
	ds_read_b128 v[174:177], v133 offset:21504
	ds_read_b128 v[178:181], v133 offset:22528
	ds_read_b128 v[186:189], v133 offset:23552
	global_load_lds_dwordx4 v[194:195], off
	v_lshl_add_u64 v[214:215], s[48:49], 0, v[130:131]
	s_mov_b32 m0, s44
	s_nop 0
	global_load_lds_dwordx4 v[214:215], off
	s_barrier
; #define PG8_STAGE(bufoff, gbase, voff) do { _Pragma("unroll") for (int _i = 0; _i < 2; ++_i) \
;         __builtin_amdgcn_global_load_lds((const unsigned*)((const char*)(gbase) + (voff)[_i]), (LAS unsigned*)(lds + (bufoff) + ldsw + _i * 8192), 16, 0, 0); } while (0)
; #define PG8_STAGE_A(bufoff, gbase, h, vv) do { if constexpr (GATHER) { _Pragma("unroll") for (int _i = 0; _i < 2; ++_i) \
;         __builtin_amdgcn_global_load_lds((const unsigned*)((const char*)(gbase) + (vv)[h][_i]), (LAS unsigned*)(lds + (bufoff) + ldsw + _i * 8192), 16, 0, 0); } \
;         else { PG8_STAGE(bufoff, (gbase) + (h) * hstepA, voffA); } } while (0)
; #define PG8_LDA(dst, b, h) do { _Pragma("unroll") for (int m = 0; m < 4; ++m) _Pragma("unroll") for (int k = 0; k < 2; ++k) dst[m][k] = *(const LAS bf16x8*)(lds + PG8_SA(b, h) + aoff + m * 2048 + k * 1024); } while (0)
; #define PG8_LDB(dst, b, h) do { _Pragma("unroll") for (int n = 0; n < 2; ++n) _Pragma("unroll") for (int k = 0; k < 2; ++k) dst[n][k] = *(const LAS bf16x8*)(lds + PG8_SB(b, h) + boff + n * 2048 + k * 1024); } while (0)
; #define PG8_MMA(ai, bj, At, Bt) do { __builtin_amdgcn_s_setprio(1); _Pragma("unroll") for (int m = 0; m < 4; ++m) _Pragma("unroll") for (int n = 0; n < 2; ++n) _Pragma("unroll") for (int k = 0; k < 2; ++k) \
;         acc[ai][bj][m][n] = __builtin_amdgcn_mfma_f32_16x16x32_bf16(Bt[n][k], At[m][k], acc[ai][bj][m][n], 0, 0, 0); __builtin_amdgcn_s_setprio(0); } while (0)
; #define PG8_WAIT_V(n) asm volatile("s_waitcnt vmcnt(" #n ")" ::: "memory")
; #define PG8_BAR __builtin_amdgcn_s_barrier()
; template <class Epi, class Sched>
; __device__ __forceinline__ void gemm_phase(LAS unsigned char* lds, const int K, const int lda, const int ldb, const Sched& S, const Epi& E) {
;     ...
;             PG8_BAR; PG8_WAIT_L(0); PG8_MMA(1, 0, At, B0); PG8_BAR; PG8_SCHED;
;             PG8_STAGE(PG8_SB(0, 1), b2 + hstepB, voffB);
;             PG8_WAIT_V(6); PG8_BAR; PG8_MMA(1, 1, At, B1); PG8_BAR;
;             PG8_LDB(B0, 1, 0); PG8_SCHED; PG8_LDA(At, 1, 0); PG8_STAGE_A(PG8_SA(0, 1), a2, 1, vcur);
;             PG8_WAIT_L(8); PG8_BAR; PG8_WAIT_L(0); PG8_MMA(0, 0, At, B0); PG8_BAR; PG8_SCHED;
;             PG8_LDB(B1, 1, 1); PG8_STAGE(PG8_SB(1, 0), b3, voffB);
;             PG8_BAR; PG8_WAIT_L(0); PG8_MMA(0, 1, At, B1); PG8_BAR;
;             PG8_LDA(At, 1, 1); PG8_STAGE_A(PG8_SA(1, 0), a3, 0, vcur);
	s_waitcnt lgkmcnt(0)
	s_setprio 1
	v_mfma_f32_16x16x32_bf16 v[102:105], v[134:137], v[154:157], v[102:105]
	v_mfma_f32_16x16x32_bf16 v[70:73], v[142:145], v[154:157], v[70:73]
	v_mfma_f32_16x16x32_bf16 v[90:93], v[134:137], v[162:165], v[90:93]
	v_mfma_f32_16x16x32_bf16 v[66:69], v[142:145], v[162:165], v[66:69]
	v_mfma_f32_16x16x32_bf16 v[82:85], v[134:137], v[170:173], v[82:85]
	v_mfma_f32_16x16x32_bf16 v[58:61], v[142:145], v[170:173], v[58:61]
	v_mfma_f32_16x16x32_bf16 v[86:89], v[134:137], v[178:181], v[86:89]
	v_mfma_f32_16x16x32_bf16 v[50:53], v[142:145], v[178:181], v[50:53]
	v_mfma_f32_16x16x32_bf16 v[102:105], v[138:141], v[158:161], v[102:105]
	v_mfma_f32_16x16x32_bf16 v[70:73], v[150:153], v[158:161], v[70:73]
	v_mfma_f32_16x16x32_bf16 v[90:93], v[138:141], v[166:169], v[90:93]
	v_mfma_f32_16x16x32_bf16 v[66:69], v[150:153], v[166:169], v[66:69]
	v_mfma_f32_16x16x32_bf16 v[82:85], v[138:141], v[174:177], v[82:85]
	v_mfma_f32_16x16x32_bf16 v[58:61], v[150:153], v[174:177], v[58:61]
	v_mfma_f32_16x16x32_bf16 v[86:89], v[138:141], v[186:189], v[86:89]
	v_mfma_f32_16x16x32_bf16 v[50:53], v[150:153], v[186:189], v[50:53]
	s_setprio 0
	s_barrier
	s_mov_b32 m0, s67
	v_lshl_add_u64 v[134:135], s[46:47], 0, v[0:1]
	global_load_lds_dwordx4 v[134:135], off
	v_lshl_add_u64 v[134:135], s[46:47], 0, v[130:131]
	s_mov_b32 m0, s68
	s_nop 0
	global_load_lds_dwordx4 v[134:135], off
	s_waitcnt vmcnt(6)
	s_barrier
	s_setprio 1
	v_mfma_f32_16x16x32_bf16 v[38:41], v[190:193], v[154:157], v[38:41]
	v_mfma_f32_16x16x32_bf16 v[10:13], v[220:223], v[154:157], v[10:13]
	v_mfma_f32_16x16x32_bf16 v[34:37], v[190:193], v[162:165], v[34:37]
	v_mfma_f32_16x16x32_bf16 v[14:17], v[220:223], v[162:165], v[14:17]
	v_mfma_f32_16x16x32_bf16 v[26:29], v[190:193], v[170:173], v[26:29]
	v_mfma_f32_16x16x32_bf16 v[6:9], v[220:223], v[170:173], v[6:9]
	v_mfma_f32_16x16x32_bf16 v[18:21], v[190:193], v[178:181], v[18:21]
	v_mfma_f32_16x16x32_bf16 v[2:5], v[220:223], v[178:181], v[2:5]
	v_mfma_f32_16x16x32_bf16 v[38:41], v[216:219], v[158:161], v[38:41]
	v_mfma_f32_16x16x32_bf16 v[10:13], v[224:227], v[158:161], v[10:13]
	v_mfma_f32_16x16x32_bf16 v[34:37], v[216:219], v[166:169], v[34:37]
	v_mfma_f32_16x16x32_bf16 v[14:17], v[224:227], v[166:169], v[14:17]
	v_mfma_f32_16x16x32_bf16 v[26:29], v[216:219], v[174:177], v[26:29]
	v_mfma_f32_16x16x32_bf16 v[6:9], v[224:227], v[174:177], v[6:9]
	v_mfma_f32_16x16x32_bf16 v[18:21], v[216:219], v[186:189], v[18:21]
	v_mfma_f32_16x16x32_bf16 v[2:5], v[224:227], v[186:189], v[2:5]
	s_setprio 0
	v_add_u32_e32 v148, s69, v132
	s_barrier
	ds_read_b128 v[134:137], v148
	ds_read_b128 v[138:141], v148 offset:1024
	ds_read_b128 v[142:145], v148 offset:2048
	ds_read_b128 v[150:153], v148 offset:3072
	s_mov_b32 m0, s45
	v_lshl_add_u64 v[190:191], s[42:43], 0, v[0:1]
	ds_read_b128 v[154:157], v133 offset:32768
	ds_read_b128 v[158:161], v133 offset:33792
	ds_read_b128 v[162:165], v133 offset:34816
	ds_read_b128 v[166:169], v133 offset:35840
	ds_read_b128 v[170:173], v133 offset:36864
	ds_read_b128 v[174:177], v133 offset:37888
	ds_read_b128 v[178:181], v133 offset:38912
	ds_read_b128 v[186:189], v133 offset:39936
	global_load_lds_dwordx4 v[190:191], off
	v_lshl_add_u64 v[190:191], s[42:43], 0, v[130:131]
	s_mov_b32 m0, s52
	s_nop 0
	global_load_lds_dwordx4 v[190:191], off
	s_waitcnt lgkmcnt(8)
	s_barrier
	s_waitcnt lgkmcnt(0)
	s_setprio 1
	v_mfma_f32_16x16x32_bf16 v[126:129], v[134:137], v[154:157], v[126:129]
	v_mfma_f32_16x16x32_bf16 v[98:101], v[142:145], v[154:157], v[98:101]
	v_mfma_f32_16x16x32_bf16 v[122:125], v[134:137], v[162:165], v[122:125]
	v_mfma_f32_16x16x32_bf16 v[94:97], v[142:145], v[162:165], v[94:97]
	v_mfma_f32_16x16x32_bf16 v[118:121], v[134:137], v[170:173], v[118:121]
	v_mfma_f32_16x16x32_bf16 v[78:81], v[142:145], v[170:173], v[78:81]
	v_mfma_f32_16x16x32_bf16 v[106:109], v[134:137], v[178:181], v[106:109]
	v_mfma_f32_16x16x32_bf16 v[74:77], v[142:145], v[178:181], v[74:77]
	v_mfma_f32_16x16x32_bf16 v[126:129], v[138:141], v[158:161], v[126:129]
	v_mfma_f32_16x16x32_bf16 v[98:101], v[150:153], v[158:161], v[98:101]
	v_mfma_f32_16x16x32_bf16 v[122:125], v[138:141], v[166:169], v[122:125]
	v_mfma_f32_16x16x32_bf16 v[94:97], v[150:153], v[166:169], v[94:97]
	v_mfma_f32_16x16x32_bf16 v[118:121], v[138:141], v[174:177], v[118:121]
	v_mfma_f32_16x16x32_bf16 v[78:81], v[150:153], v[174:177], v[78:81]
	v_mfma_f32_16x16x32_bf16 v[106:109], v[138:141], v[186:189], v[106:109]
	v_mfma_f32_16x16x32_bf16 v[74:77], v[150:153], v[186:189], v[74:77]
	s_setprio 0
	s_barrier
	s_mov_b32 m0, s70
	v_add_u32_e32 v148, s63, v132
	v_lshl_add_u64 v[146:147], v[146:147], 0, s[64:65]
	ds_read_b128 v[190:193], v148
	ds_read_b128 v[216:219], v148 offset:1024
	ds_read_b128 v[220:223], v148 offset:2048
	ds_read_b128 v[224:227], v148 offset:3072
	global_load_lds_dwordx4 v[146:147], off
	v_lshl_add_u64 v[146:147], v[182:183], 0, s[64:65]
	s_mov_b32 m0, s62
	s_nop 0
	global_load_lds_dwordx4 v[146:147], off
	s_barrier
	s_waitcnt lgkmcnt(0)
	s_setprio 1
	v_mfma_f32_16x16x32_bf16 v[62:65], v[190:193], v[154:157], v[62:65]
	v_mfma_f32_16x16x32_bf16 v[114:117], v[220:223], v[154:157], v[114:117]
	v_mfma_f32_16x16x32_bf16 v[54:57], v[190:193], v[162:165], v[54:57]
	v_mfma_f32_16x16x32_bf16 v[30:33], v[220:223], v[162:165], v[30:33]
	v_mfma_f32_16x16x32_bf16 v[46:49], v[190:193], v[170:173], v[46:49]
	v_mfma_f32_16x16x32_bf16 v[110:113], v[220:223], v[170:173], v[110:113]
	v_mfma_f32_16x16x32_bf16 v[42:45], v[190:193], v[178:181], v[42:45]
	v_mfma_f32_16x16x32_bf16 v[22:25], v[220:223], v[178:181], v[22:25]
	v_mfma_f32_16x16x32_bf16 v[62:65], v[216:219], v[158:161], v[62:65]
	v_mfma_f32_16x16x32_bf16 v[114:117], v[224:227], v[158:161], v[114:117]
	v_mfma_f32_16x16x32_bf16 v[54:57], v[216:219], v[166:169], v[54:57]
	v_mfma_f32_16x16x32_bf16 v[30:33], v[224:227], v[166:169], v[30:33]
	v_mfma_f32_16x16x32_bf16 v[46:49], v[216:219], v[174:177], v[46:49]
	v_mfma_f32_16x16x32_bf16 v[110:113], v[224:227], v[174:177], v[110:113]
	v_mfma_f32_16x16x32_bf16 v[42:45], v[216:219], v[186:189], v[42:45]
	v_mfma_f32_16x16x32_bf16 v[22:25], v[224:227], v[186:189], v[22:25]
	s_setprio 0
	s_mov_b32 m0, s53
	v_lshl_add_u64 v[146:147], v[194:195], 0, s[64:65]
	s_barrier
; #define PG8_STAGE(bufoff, gbase, voff) do { _Pragma("unroll") for (int _i = 0; _i < 2; ++_i) \
;         __builtin_amdgcn_global_load_lds((const unsigned*)((const char*)(gbase) + (voff)[_i]), (LAS unsigned*)(lds + (bufoff) + ldsw + _i * 8192), 16, 0, 0); } while (0)
; #define PG8_STAGE_A(bufoff, gbase, h, vv) do { if constexpr (GATHER) { _Pragma("unroll") for (int _i = 0; _i < 2; ++_i) \
;         __builtin_amdgcn_global_load_lds((const unsigned*)((const char*)(gbase) + (vv)[h][_i]), (LAS unsigned*)(lds + (bufoff) + ldsw + _i * 8192), 16, 0, 0); } \
;         else { PG8_STAGE(bufoff, (gbase) + (h) * hstepA, voffA); } } while (0)
; #define PG8_LDA(dst, b, h) do { _Pragma("unroll") for (int m = 0; m < 4; ++m) _Pragma("unroll") for (int k = 0; k < 2; ++k) dst[m][k] = *(const LAS bf16x8*)(lds + PG8_SA(b, h) + aoff + m * 2048 + k * 1024); } while (0)
; #define PG8_MMA(ai, bj, At, Bt) do { __builtin_amdgcn_s_setprio(1); _Pragma("unroll") for (int m = 0; m < 4; ++m) _Pragma("unroll") for (int n = 0; n < 2; ++n) _Pragma("unroll") for (int k = 0; k < 2; ++k) \
;         acc[ai][bj][m][n] = __builtin_amdgcn_mfma_f32_16x16x32_bf16(Bt[n][k], At[m][k], acc[ai][bj][m][n], 0, 0, 0); __builtin_amdgcn_s_setprio(0); } while (0)
; #define PG8_WAIT_V(n) asm volatile("s_waitcnt vmcnt(" #n ")" ::: "memory")
; #define PG8_WAIT_L(n) asm volatile("s_waitcnt lgkmcnt(" #n ")" ::: "memory")
; #define PG8_BAR __builtin_amdgcn_s_barrier()
; #define PG8_SCHED __builtin_amdgcn_sched_barrier(0)
; template <class Epi, class Sched>
; __device__ __forceinline__ void gemm_phase(LAS unsigned char* lds, const int K, const int lda, const int ldb, const Sched& S, const Epi& E) {
;     ...
;             PG8_LDA(At, 1, 1); PG8_STAGE_A(PG8_SA(1, 0), a3, 0, vcur);
;             PG8_BAR; PG8_WAIT_L(0); PG8_MMA(1, 0, At, B0); PG8_BAR; PG8_SCHED;
;             PG8_STAGE(PG8_SB(1, 1), b3 + hstepB, voffB);
;             PG8_WAIT_V(6); PG8_BAR; PG8_MMA(1, 1, At, B1); PG8_BAR;
;         }
;     ...
; #pragma unroll
;         for (int a = 0; a < 2; ++a)
; #pragma unroll
;             for (int b = 0; b < 2; ++b)
; #pragma unroll
;                 for (int m = 0; m < 4; ++m)
; #pragma unroll
;                     for (int n = 0; n < 2; ++n) acc[a][b][m][n] = (f32x4){0.f, 0.f, 0.f, 0.f};
;         cur = nxt; cA = nA; cB = nB; ++ui;
	ds_read_b128 v[154:157], v133 offset:49152
	ds_read_b128 v[158:161], v133 offset:50176
	ds_read_b128 v[162:165], v133 offset:51200
	ds_read_b128 v[166:169], v133 offset:52224
	ds_read_b128 v[170:173], v133 offset:53248
	ds_read_b128 v[174:177], v133 offset:54272
	ds_read_b128 v[178:181], v133 offset:55296
	ds_read_b128 v[186:189], v133 offset:56320
	global_load_lds_dwordx4 v[146:147], off
	v_lshl_add_u64 v[146:147], v[214:215], 0, s[64:65]
	s_mov_b32 m0, s54
	s_nop 0
	global_load_lds_dwordx4 v[146:147], off
	s_barrier
	s_waitcnt lgkmcnt(0)
	s_setprio 1
	v_mfma_f32_16x16x32_bf16 v[102:105], v[134:137], v[154:157], v[102:105]
	v_mfma_f32_16x16x32_bf16 v[70:73], v[142:145], v[154:157], v[70:73]
	v_mfma_f32_16x16x32_bf16 v[90:93], v[134:137], v[162:165], v[90:93]
	v_mfma_f32_16x16x32_bf16 v[66:69], v[142:145], v[162:165], v[66:69]
	v_mfma_f32_16x16x32_bf16 v[82:85], v[134:137], v[170:173], v[82:85]
	v_mfma_f32_16x16x32_bf16 v[58:61], v[142:145], v[170:173], v[58:61]
	v_mfma_f32_16x16x32_bf16 v[86:89], v[134:137], v[178:181], v[86:89]
	v_mfma_f32_16x16x32_bf16 v[50:53], v[142:145], v[178:181], v[50:53]
	v_mfma_f32_16x16x32_bf16 v[102:105], v[138:141], v[158:161], v[102:105]
	v_mfma_f32_16x16x32_bf16 v[70:73], v[150:153], v[158:161], v[70:73]
	v_mfma_f32_16x16x32_bf16 v[90:93], v[138:141], v[166:169], v[90:93]
	v_mfma_f32_16x16x32_bf16 v[66:69], v[150:153], v[166:169], v[66:69]
	v_mfma_f32_16x16x32_bf16 v[82:85], v[138:141], v[174:177], v[82:85]
	v_mfma_f32_16x16x32_bf16 v[58:61], v[150:153], v[174:177], v[58:61]
	v_mfma_f32_16x16x32_bf16 v[86:89], v[138:141], v[186:189], v[86:89]
	v_mfma_f32_16x16x32_bf16 v[50:53], v[150:153], v[186:189], v[50:53]
	s_setprio 0
	s_barrier
	s_mov_b32 m0, s13
	v_lshl_add_u64 v[134:135], s[40:41], 0, v[0:1]
	global_load_lds_dwordx4 v[134:135], off
	v_lshl_add_u64 v[134:135], s[40:41], 0, v[130:131]
	s_mov_b32 m0, s11
	s_nop 0
	global_load_lds_dwordx4 v[134:135], off
	s_waitcnt vmcnt(6)
	s_barrier
	s_setprio 1
	v_mfma_f32_16x16x32_bf16 v[38:41], v[190:193], v[154:157], v[38:41]
	v_mfma_f32_16x16x32_bf16 v[10:13], v[220:223], v[154:157], v[10:13]
	v_mfma_f32_16x16x32_bf16 v[34:37], v[190:193], v[162:165], v[34:37]
	v_mfma_f32_16x16x32_bf16 v[14:17], v[220:223], v[162:165], v[14:17]
	v_mfma_f32_16x16x32_bf16 v[26:29], v[190:193], v[170:173], v[26:29]
	v_mfma_f32_16x16x32_bf16 v[6:9], v[220:223], v[170:173], v[6:9]
	v_mfma_f32_16x16x32_bf16 v[18:21], v[190:193], v[178:181], v[18:21]
	v_mfma_f32_16x16x32_bf16 v[2:5], v[220:223], v[178:181], v[2:5]
	v_mfma_f32_16x16x32_bf16 v[38:41], v[216:219], v[158:161], v[38:41]
	v_mfma_f32_16x16x32_bf16 v[10:13], v[224:227], v[158:161], v[10:13]
	v_mfma_f32_16x16x32_bf16 v[34:37], v[216:219], v[166:169], v[34:37]
	v_mfma_f32_16x16x32_bf16 v[14:17], v[224:227], v[166:169], v[14:17]
	v_mfma_f32_16x16x32_bf16 v[26:29], v[216:219], v[174:177], v[26:29]
	v_mfma_f32_16x16x32_bf16 v[6:9], v[224:227], v[174:177], v[6:9]
	v_mfma_f32_16x16x32_bf16 v[18:21], v[216:219], v[186:189], v[18:21]
	v_mfma_f32_16x16x32_bf16 v[2:5], v[224:227], v[186:189], v[2:5]
	s_setprio 0
	s_andn2_b64 vcc, exec, s[38:39]
	s_mov_b64 s[40:41], -1
	s_mov_b64 s[38:39], 0
	s_mov_b64 s[42:43], 0x100
	s_barrier
	s_cbranch_vccz .LBB0_286
	s_andn2_b64 vcc, exec, s[16:17]
	s_cbranch_vccnz .LBB0_282
	v_mov_b32_e32 v2, 0
	s_mov_b32 s4, s12
	s_mov_b32 s0, s10
	s_mov_b64 s[8:9], s[36:37]
	s_mov_b64 s[6:7], s[34:35]
	s_mov_b32 s55, s60
	v_mov_b32_e32 v3, v2
	v_mov_b64_e32 v[4:5], 0
	v_mov_b64_e32 v[18:19], 0
	v_mov_b64_e32 v[20:21], 0
	v_mov_b64_e32 v[6:7], 0
	v_mov_b64_e32 v[8:9], 0
	v_mov_b64_e32 v[26:27], 0
	v_mov_b64_e32 v[28:29], 0
	v_mov_b64_e32 v[14:15], 0
	v_mov_b64_e32 v[16:17], 0
	v_mov_b64_e32 v[34:35], 0
	v_mov_b64_e32 v[36:37], 0
	v_mov_b64_e32 v[10:11], 0
	v_mov_b64_e32 v[12:13], 0
	v_mov_b64_e32 v[38:39], 0
	v_mov_b64_e32 v[40:41], 0
	v_mov_b64_e32 v[50:51], 0
	v_mov_b64_e32 v[52:53], 0
	v_mov_b64_e32 v[86:87], 0
	v_mov_b64_e32 v[88:89], 0
	v_mov_b64_e32 v[58:59], 0
	v_mov_b64_e32 v[60:61], 0
	v_mov_b64_e32 v[82:83], 0
	v_mov_b64_e32 v[84:85], 0
	v_mov_b64_e32 v[66:67], 0
	v_mov_b64_e32 v[68:69], 0
	v_mov_b64_e32 v[90:91], 0
	v_mov_b64_e32 v[92:93], 0
	v_mov_b64_e32 v[70:71], 0
	v_mov_b64_e32 v[72:73], 0
	v_mov_b64_e32 v[102:103], 0
	v_mov_b64_e32 v[104:105], 0
	v_mov_b64_e32 v[22:23], 0
	v_mov_b64_e32 v[24:25], 0
	v_mov_b64_e32 v[42:43], 0
	v_mov_b64_e32 v[44:45], 0
	v_mov_b64_e32 v[110:111], 0
	v_mov_b64_e32 v[112:113], 0
	v_mov_b64_e32 v[46:47], 0
	v_mov_b64_e32 v[48:49], 0
	v_mov_b64_e32 v[30:31], 0
	v_mov_b64_e32 v[32:33], 0
	v_mov_b64_e32 v[54:55], 0
	v_mov_b64_e32 v[56:57], 0
	v_mov_b64_e32 v[114:115], 0
	v_mov_b64_e32 v[116:117], 0
	v_mov_b64_e32 v[62:63], 0
	v_mov_b64_e32 v[64:65], 0
	v_mov_b64_e32 v[74:75], 0
	v_mov_b64_e32 v[76:77], 0
	v_mov_b64_e32 v[106:107], 0
	v_mov_b64_e32 v[108:109], 0
	v_mov_b64_e32 v[78:79], 0
	v_mov_b64_e32 v[80:81], 0
	v_mov_b64_e32 v[118:119], 0
	v_mov_b64_e32 v[120:121], 0
	v_mov_b64_e32 v[94:95], 0
	v_mov_b64_e32 v[96:97], 0
	v_mov_b64_e32 v[122:123], 0
	v_mov_b64_e32 v[124:125], 0
	v_mov_b64_e32 v[98:99], 0
	v_mov_b64_e32 v[100:101], 0
	v_mov_b64_e32 v[126:127], 0
	v_mov_b64_e32 v[128:129], 0
	s_branch .LBB0_282

; #define PG8_STAGE(bufoff, gbase, voff) do { _Pragma("unroll") for (int _i = 0; _i < 2; ++_i) \
;         __builtin_amdgcn_global_load_lds((const unsigned*)((const char*)(gbase) + (voff)[_i]), (LAS unsigned*)(lds + (bufoff) + ldsw + _i * 8192), 16, 0, 0); } while (0)
; #define PG8_STAGE_A(bufoff, gbase, h, vv) do { if constexpr (GATHER) { _Pragma("unroll") for (int _i = 0; _i < 2; ++_i) \
;         __builtin_amdgcn_global_load_lds((const unsigned*)((const char*)(gbase) + (vv)[h][_i]), (LAS unsigned*)(lds + (bufoff) + ldsw + _i * 8192), 16, 0, 0); } \
;         else { PG8_STAGE(bufoff, (gbase) + (h) * hstepA, voffA); } } while (0)
; #define PG8_LDA(dst, b, h) do { _Pragma("unroll") for (int m = 0; m < 4; ++m) _Pragma("unroll") for (int k = 0; k < 2; ++k) dst[m][k] = *(const LAS bf16x8*)(lds + PG8_SA(b, h) + aoff + m * 2048 + k * 1024); } while (0)
; #define PG8_LDB(dst, b, h) do { _Pragma("unroll") for (int n = 0; n < 2; ++n) _Pragma("unroll") for (int k = 0; k < 2; ++k) dst[n][k] = *(const LAS bf16x8*)(lds + PG8_SB(b, h) + boff + n * 2048 + k * 1024); } while (0)
; #define PG8_WAIT_L(n) asm volatile("s_waitcnt lgkmcnt(" #n ")" ::: "memory")
; template <class Epi, class Sched>
; __device__ __forceinline__ void gemm_phase(LAS unsigned char* lds, const int K, const int lda, const int ldb, const Sched& S, const Epi& E) {
;     ...
;         for (int t = 0; t < nt; t += 2) {
;             const bool last = (t == nt - 2);
;             const char* a1 = cA + (size_t)(t + 1) * kstep;
;             const char* a2 = last ? nA : cA + (size_t)(t + 2) * kstep; const char* b2 = last ? nB : cB + (size_t)(t + 2) * kstep;
;             const char* a3 = a2 + kstep; const char* b3 = b2 + kstep;
;             PG8_LDB(B0, 0, 0); PG8_SCHED; PG8_LDA(At, 0, 0); PG8_STAGE_A(PG8_SA(1, 1), a1, 1, vcur);
;             if constexpr (GATHER) { if (last) {
; #pragma unroll
;                 for (int h = 0; h < 2; ++h)
; #pragma unroll
;                     for (int i = 0; i < 2; ++i) vcur[h][i] = vnxt[h][i]; } }
;             PG8_WAIT_L(8); PG8_BAR; PG8_WAIT_L(0); PG8_MMA(0, 0, At, B0); PG8_BAR; PG8_SCHED;
;             PG8_LDB(B1, 0, 1); PG8_STAGE(PG8_SB(0, 0), b2, voffB);
;             PG8_BAR; PG8_WAIT_L(0); PG8_MMA(0, 1, At, B1); PG8_BAR;
;             PG8_LDA(At, 0, 1); PG8_STAGE_A(PG8_SA(0, 0), a2, 0, vcur);
;             PG8_BAR; PG8_WAIT_L(0); PG8_MMA(1, 0, At, B0); PG8_BAR; PG8_SCHED;
.LBB0_392:
	s_add_u32 s2, s0, s12
	s_addc_u32 s3, s1, s13
	s_add_u32 s2, s2, 0x100
	s_addc_u32 s3, s3, 0
	s_add_u32 s14, s78, s12
	s_addc_u32 s15, s79, s13
	s_add_i32 s20, 0, 0x10000
	v_add_u32_e32 v160, s20, v145
	ds_read_b128 v[148:151], v160
	ds_read_b128 v[152:155], v160 offset:1024
	ds_read_b128 v[156:159], v160 offset:2048
	ds_read_b128 v[160:163], v160 offset:3072
	s_cmpk_eq_i32 s12, 0x1b00
	s_cselect_b32 s17, s11, s3
	s_cselect_b32 s16, s10, s2
	s_cselect_b32 s15, s5, s15
	s_cselect_b32 s14, s4, s14
	v_lshl_add_u64 v[214:215], v[140:141], 0, s[12:13]
	s_add_i32 m0, s54, 0xc000
	ds_read_b128 v[164:167], v147
	ds_read_b128 v[168:171], v147 offset:1024
	ds_read_b128 v[172:175], v147 offset:2048
	ds_read_b128 v[176:179], v147 offset:3072
	ds_read_b128 v[180:183], v147 offset:4096
	ds_read_b128 v[184:187], v147 offset:5120
	ds_read_b128 v[188:191], v147 offset:6144
	ds_read_b128 v[192:195], v147 offset:7168
	global_load_lds_dwordx4 v[214:215], off
	v_lshl_add_u64 v[214:215], v[142:143], 0, s[12:13]
	s_add_i32 m0, s54, 0xe000
	s_nop 0
	global_load_lds_dwordx4 v[214:215], off
	s_waitcnt lgkmcnt(8)
	s_barrier
	s_waitcnt lgkmcnt(0)
	s_setprio 1
	v_mfma_f32_16x16x32_bf16 v[126:129], v[148:151], v[164:167], v[126:129]
	v_mfma_f32_16x16x32_bf16 v[122:125], v[156:159], v[164:167], v[122:125]
	v_mfma_f32_16x16x32_bf16 v[118:121], v[148:151], v[172:175], v[118:121]
	v_mfma_f32_16x16x32_bf16 v[114:117], v[156:159], v[172:175], v[114:117]
	v_mfma_f32_16x16x32_bf16 v[110:113], v[148:151], v[180:183], v[110:113]
	v_mfma_f32_16x16x32_bf16 v[106:109], v[156:159], v[180:183], v[106:109]
	v_mfma_f32_16x16x32_bf16 v[102:105], v[148:151], v[188:191], v[102:105]
	v_mfma_f32_16x16x32_bf16 v[98:101], v[156:159], v[188:191], v[98:101]
	v_mfma_f32_16x16x32_bf16 v[126:129], v[152:155], v[168:171], v[126:129]
	v_mfma_f32_16x16x32_bf16 v[122:125], v[160:163], v[168:171], v[122:125]
	v_mfma_f32_16x16x32_bf16 v[118:121], v[152:155], v[176:179], v[118:121]
	v_mfma_f32_16x16x32_bf16 v[114:117], v[160:163], v[176:179], v[114:117]
	v_mfma_f32_16x16x32_bf16 v[110:113], v[152:155], v[184:187], v[110:113]
	v_mfma_f32_16x16x32_bf16 v[106:109], v[160:163], v[184:187], v[106:109]
	v_mfma_f32_16x16x32_bf16 v[102:105], v[152:155], v[192:195], v[102:105]
	v_mfma_f32_16x16x32_bf16 v[98:101], v[160:163], v[192:195], v[98:101]
	s_setprio 0
	s_barrier
	s_add_i32 s21, 0, 0x14000
	v_add_u32_e32 v214, s21, v145
	s_add_i32 s2, s20, s63
	ds_read_b128 v[216:219], v214
	ds_read_b128 v[220:223], v214 offset:1024
	ds_read_b128 v[224:227], v214 offset:2048
	ds_read_b128 v[228:231], v214 offset:3072
	v_lshl_add_u64 v[214:215], s[14:15], 0, v[0:1]
	s_mov_b32 m0, s2
	v_lshl_add_u64 v[232:233], s[14:15], 0, v[134:135]
	global_load_lds_dwordx4 v[214:215], off
	s_add_i32 m0, s2, 0x2000
	s_nop 0
	global_load_lds_dwordx4 v[232:233], off
	s_barrier
	s_waitcnt lgkmcnt(0)
	s_setprio 1
	v_mfma_f32_16x16x32_bf16 v[94:97], v[216:219], v[164:167], v[94:97]
	v_mfma_f32_16x16x32_bf16 v[90:93], v[224:227], v[164:167], v[90:93]
	v_mfma_f32_16x16x32_bf16 v[86:89], v[216:219], v[172:175], v[86:89]
	v_mfma_f32_16x16x32_bf16 v[82:85], v[224:227], v[172:175], v[82:85]
	v_mfma_f32_16x16x32_bf16 v[78:81], v[216:219], v[180:183], v[78:81]
	v_mfma_f32_16x16x32_bf16 v[74:77], v[224:227], v[180:183], v[74:77]
	v_mfma_f32_16x16x32_bf16 v[70:73], v[216:219], v[188:191], v[70:73]
	v_mfma_f32_16x16x32_bf16 v[66:69], v[224:227], v[188:191], v[66:69]
	v_mfma_f32_16x16x32_bf16 v[94:97], v[220:223], v[168:171], v[94:97]
	v_mfma_f32_16x16x32_bf16 v[90:93], v[228:231], v[168:171], v[90:93]
	v_mfma_f32_16x16x32_bf16 v[86:89], v[220:223], v[176:179], v[86:89]
	v_mfma_f32_16x16x32_bf16 v[82:85], v[228:231], v[176:179], v[82:85]
	v_mfma_f32_16x16x32_bf16 v[78:81], v[220:223], v[184:187], v[78:81]
	v_mfma_f32_16x16x32_bf16 v[74:77], v[228:231], v[184:187], v[74:77]
	v_mfma_f32_16x16x32_bf16 v[70:73], v[220:223], v[192:195], v[70:73]
	v_mfma_f32_16x16x32_bf16 v[66:69], v[228:231], v[192:195], v[66:69]
	s_setprio 0
	s_mov_b32 m0, s54
	v_lshl_add_u64 v[234:235], s[16:17], 0, v[130:131]
	s_barrier
	ds_read_b128 v[164:167], v147 offset:16384
	ds_read_b128 v[168:171], v147 offset:17408
	ds_read_b128 v[172:175], v147 offset:18432
	ds_read_b128 v[176:179], v147 offset:19456
	ds_read_b128 v[180:183], v147 offset:20480
	ds_read_b128 v[184:187], v147 offset:21504
	ds_read_b128 v[188:191], v147 offset:22528
	ds_read_b128 v[192:195], v147 offset:23552
	global_load_lds_dwordx4 v[234:235], off
	v_lshl_add_u64 v[236:237], s[16:17], 0, v[132:133]
	s_mov_b32 m0, s55
	s_nop 0
	global_load_lds_dwordx4 v[236:237], off
	s_barrier
	s_waitcnt lgkmcnt(0)
	s_setprio 1
	v_mfma_f32_16x16x32_bf16 v[62:65], v[148:151], v[164:167], v[62:65]
	v_mfma_f32_16x16x32_bf16 v[58:61], v[156:159], v[164:167], v[58:61]
	v_mfma_f32_16x16x32_bf16 v[54:57], v[148:151], v[172:175], v[54:57]
	v_mfma_f32_16x16x32_bf16 v[50:53], v[156:159], v[172:175], v[50:53]
	v_mfma_f32_16x16x32_bf16 v[46:49], v[148:151], v[180:183], v[46:49]
	v_mfma_f32_16x16x32_bf16 v[42:45], v[156:159], v[180:183], v[42:45]
	v_mfma_f32_16x16x32_bf16 v[38:41], v[148:151], v[188:191], v[38:41]
	v_mfma_f32_16x16x32_bf16 v[34:37], v[156:159], v[188:191], v[34:37]
	v_mfma_f32_16x16x32_bf16 v[62:65], v[152:155], v[168:171], v[62:65]
	v_mfma_f32_16x16x32_bf16 v[58:61], v[160:163], v[168:171], v[58:61]
	v_mfma_f32_16x16x32_bf16 v[54:57], v[152:155], v[176:179], v[54:57]
	v_mfma_f32_16x16x32_bf16 v[50:53], v[160:163], v[176:179], v[50:53]
	v_mfma_f32_16x16x32_bf16 v[46:49], v[152:155], v[184:187], v[46:49]
	v_mfma_f32_16x16x32_bf16 v[42:45], v[160:163], v[184:187], v[42:45]
	v_mfma_f32_16x16x32_bf16 v[38:41], v[152:155], v[192:195], v[38:41]
	v_mfma_f32_16x16x32_bf16 v[34:37], v[160:163], v[192:195], v[34:37]
	s_setprio 0
	s_barrier
; #define PG8_STAGE(bufoff, gbase, voff) do { _Pragma("unroll") for (int _i = 0; _i < 2; ++_i) \
;         __builtin_amdgcn_global_load_lds((const unsigned*)((const char*)(gbase) + (voff)[_i]), (LAS unsigned*)(lds + (bufoff) + ldsw + _i * 8192), 16, 0, 0); } while (0)
; #define PG8_STAGE_A(bufoff, gbase, h, vv) do { if constexpr (GATHER) { _Pragma("unroll") for (int _i = 0; _i < 2; ++_i) \
;         __builtin_amdgcn_global_load_lds((const unsigned*)((const char*)(gbase) + (vv)[h][_i]), (LAS unsigned*)(lds + (bufoff) + ldsw + _i * 8192), 16, 0, 0); } \
;         else { PG8_STAGE(bufoff, (gbase) + (h) * hstepA, voffA); } } while (0)
; #define PG8_LDA(dst, b, h) do { _Pragma("unroll") for (int m = 0; m < 4; ++m) _Pragma("unroll") for (int k = 0; k < 2; ++k) dst[m][k] = *(const LAS bf16x8*)(lds + PG8_SA(b, h) + aoff + m * 2048 + k * 1024); } while (0)
; #define PG8_LDB(dst, b, h) do { _Pragma("unroll") for (int n = 0; n < 2; ++n) _Pragma("unroll") for (int k = 0; k < 2; ++k) dst[n][k] = *(const LAS bf16x8*)(lds + PG8_SB(b, h) + boff + n * 2048 + k * 1024); } while (0)
; #define PG8_MMA(ai, bj, At, Bt) do { __builtin_amdgcn_s_setprio(1); _Pragma("unroll") for (int m = 0; m < 4; ++m) _Pragma("unroll") for (int n = 0; n < 2; ++n) _Pragma("unroll") for (int k = 0; k < 2; ++k) \
;         acc[ai][bj][m][n] = __builtin_amdgcn_mfma_f32_16x16x32_bf16(Bt[n][k], At[m][k], acc[ai][bj][m][n], 0, 0, 0); __builtin_amdgcn_s_setprio(0); } while (0)
; #define PG8_WAIT_V(n) asm volatile("s_waitcnt vmcnt(" #n ")" ::: "memory")
; #define PG8_WAIT_L(n) asm volatile("s_waitcnt lgkmcnt(" #n ")" ::: "memory")
; #define PG8_BAR __builtin_amdgcn_s_barrier()
; #define PG8_SCHED __builtin_amdgcn_sched_barrier(0)
; template <class Epi, class Sched>
; __device__ __forceinline__ void gemm_phase(LAS unsigned char* lds, const int K, const int lda, const int ldb, const Sched& S, const Epi& E) {
;     ...
;             PG8_STAGE(PG8_SB(0, 1), b2 + hstepB, voffB);
;             PG8_WAIT_V(6); PG8_BAR; PG8_MMA(1, 1, At, B1); PG8_BAR;
;             PG8_LDB(B0, 1, 0); PG8_SCHED; PG8_LDA(At, 1, 0); PG8_STAGE_A(PG8_SA(0, 1), a2, 1, vcur);
;             PG8_WAIT_L(8); PG8_BAR; PG8_WAIT_L(0); PG8_MMA(0, 0, At, B0); PG8_BAR; PG8_SCHED;
;             PG8_LDB(B1, 1, 1); PG8_STAGE(PG8_SB(1, 0), b3, voffB);
	s_add_u32 s2, s14, 0xe0000
	s_addc_u32 s3, s15, 0
	s_add_i32 s20, s21, s63
	v_lshl_add_u64 v[148:149], s[2:3], 0, v[0:1]
	s_mov_b32 m0, s20
	s_nop 0
	global_load_lds_dwordx4 v[148:149], off
	v_lshl_add_u64 v[148:149], s[2:3], 0, v[134:135]
	s_add_i32 m0, s20, 0x2000
	s_nop 0
	global_load_lds_dwordx4 v[148:149], off
	s_waitcnt vmcnt(6)
	s_barrier
	s_setprio 1
	v_mfma_f32_16x16x32_bf16 v[30:33], v[216:219], v[164:167], v[30:33]
	v_mfma_f32_16x16x32_bf16 v[26:29], v[224:227], v[164:167], v[26:29]
	v_mfma_f32_16x16x32_bf16 v[22:25], v[216:219], v[172:175], v[22:25]
	v_mfma_f32_16x16x32_bf16 v[18:21], v[224:227], v[172:175], v[18:21]
	v_mfma_f32_16x16x32_bf16 v[14:17], v[216:219], v[180:183], v[14:17]
	v_mfma_f32_16x16x32_bf16 v[10:13], v[224:227], v[180:183], v[10:13]
	v_mfma_f32_16x16x32_bf16 v[6:9], v[216:219], v[188:191], v[6:9]
	v_mfma_f32_16x16x32_bf16 v[2:5], v[224:227], v[188:191], v[2:5]
	v_mfma_f32_16x16x32_bf16 v[30:33], v[220:223], v[168:171], v[30:33]
	v_mfma_f32_16x16x32_bf16 v[26:29], v[228:231], v[168:171], v[26:29]
	v_mfma_f32_16x16x32_bf16 v[22:25], v[220:223], v[176:179], v[22:25]
	v_mfma_f32_16x16x32_bf16 v[18:21], v[228:231], v[176:179], v[18:21]
	v_mfma_f32_16x16x32_bf16 v[14:17], v[220:223], v[184:187], v[14:17]
	v_mfma_f32_16x16x32_bf16 v[10:13], v[228:231], v[184:187], v[10:13]
	v_mfma_f32_16x16x32_bf16 v[6:9], v[220:223], v[192:195], v[6:9]
	v_mfma_f32_16x16x32_bf16 v[2:5], v[228:231], v[192:195], v[2:5]
	s_setprio 0
	s_add_i32 s20, 0, 0x18000
	v_add_u32_e32 v160, s20, v145
	s_barrier
	ds_read_b128 v[148:151], v160
	ds_read_b128 v[152:155], v160 offset:1024
	ds_read_b128 v[156:159], v160 offset:2048
	ds_read_b128 v[160:163], v160 offset:3072
	s_add_u32 s2, s16, 0xe0000
	s_addc_u32 s3, s17, 0
	s_mov_b32 m0, s69
	v_lshl_add_u64 v[216:217], s[2:3], 0, v[130:131]
	ds_read_b128 v[164:167], v147 offset:32768
	ds_read_b128 v[168:171], v147 offset:33792
	ds_read_b128 v[172:175], v147 offset:34816
	ds_read_b128 v[176:179], v147 offset:35840
	ds_read_b128 v[180:183], v147 offset:36864
	ds_read_b128 v[184:187], v147 offset:37888
	ds_read_b128 v[188:191], v147 offset:38912
	ds_read_b128 v[192:195], v147 offset:39936
	global_load_lds_dwordx4 v[216:217], off
	v_lshl_add_u64 v[216:217], s[2:3], 0, v[132:133]
	s_mov_b32 m0, s70
	s_nop 0
	global_load_lds_dwordx4 v[216:217], off
	s_waitcnt lgkmcnt(8)
	s_barrier
	s_waitcnt lgkmcnt(0)
	s_setprio 1
	v_mfma_f32_16x16x32_bf16 v[126:129], v[148:151], v[164:167], v[126:129]
	v_mfma_f32_16x16x32_bf16 v[122:125], v[156:159], v[164:167], v[122:125]
	v_mfma_f32_16x16x32_bf16 v[118:121], v[148:151], v[172:175], v[118:121]
	v_mfma_f32_16x16x32_bf16 v[114:117], v[156:159], v[172:175], v[114:117]
	v_mfma_f32_16x16x32_bf16 v[110:113], v[148:151], v[180:183], v[110:113]
	v_mfma_f32_16x16x32_bf16 v[106:109], v[156:159], v[180:183], v[106:109]
	v_mfma_f32_16x16x32_bf16 v[102:105], v[148:151], v[188:191], v[102:105]
	v_mfma_f32_16x16x32_bf16 v[98:101], v[156:159], v[188:191], v[98:101]
	v_mfma_f32_16x16x32_bf16 v[126:129], v[152:155], v[168:171], v[126:129]
	v_mfma_f32_16x16x32_bf16 v[122:125], v[160:163], v[168:171], v[122:125]
	v_mfma_f32_16x16x32_bf16 v[118:121], v[152:155], v[176:179], v[118:121]
	v_mfma_f32_16x16x32_bf16 v[114:117], v[160:163], v[176:179], v[114:117]
	v_mfma_f32_16x16x32_bf16 v[110:113], v[152:155], v[184:187], v[110:113]
	v_mfma_f32_16x16x32_bf16 v[106:109], v[160:163], v[184:187], v[106:109]
	v_mfma_f32_16x16x32_bf16 v[102:105], v[152:155], v[192:195], v[102:105]
	v_mfma_f32_16x16x32_bf16 v[98:101], v[160:163], v[192:195], v[98:101]
	s_setprio 0
	s_barrier
	s_add_i32 s16, 0, 0x1c000
	s_add_i32 s2, s20, s63
	v_add_u32_e32 v228, s16, v145
	v_lshl_add_u64 v[214:215], v[214:215], 0, s[64:65]
	s_mov_b32 m0, s2
	ds_read_b128 v[216:219], v228
	ds_read_b128 v[220:223], v228 offset:1024
	ds_read_b128 v[224:227], v228 offset:2048
	ds_read_b128 v[228:231], v228 offset:3072
	global_load_lds_dwordx4 v[214:215], off
	v_lshl_add_u64 v[214:215], v[232:233], 0, s[64:65]
	s_add_i32 m0, s2, 0x2000
	s_nop 0
	global_load_lds_dwordx4 v[214:215], off
	s_barrier
; #define PG8_STAGE(bufoff, gbase, voff) do { _Pragma("unroll") for (int _i = 0; _i < 2; ++_i) \
;         __builtin_amdgcn_global_load_lds((const unsigned*)((const char*)(gbase) + (voff)[_i]), (LAS unsigned*)(lds + (bufoff) + ldsw + _i * 8192), 16, 0, 0); } while (0)
; #define PG8_STAGE_A(bufoff, gbase, h, vv) do { if constexpr (GATHER) { _Pragma("unroll") for (int _i = 0; _i < 2; ++_i) \
;         __builtin_amdgcn_global_load_lds((const unsigned*)((const char*)(gbase) + (vv)[h][_i]), (LAS unsigned*)(lds + (bufoff) + ldsw + _i * 8192), 16, 0, 0); } \
;         else { PG8_STAGE(bufoff, (gbase) + (h) * hstepA, voffA); } } while (0)
; #define PG8_LDA(dst, b, h) do { _Pragma("unroll") for (int m = 0; m < 4; ++m) _Pragma("unroll") for (int k = 0; k < 2; ++k) dst[m][k] = *(const LAS bf16x8*)(lds + PG8_SA(b, h) + aoff + m * 2048 + k * 1024); } while (0)
; #define PG8_MMA(ai, bj, At, Bt) do { __builtin_amdgcn_s_setprio(1); _Pragma("unroll") for (int m = 0; m < 4; ++m) _Pragma("unroll") for (int n = 0; n < 2; ++n) _Pragma("unroll") for (int k = 0; k < 2; ++k) \
;         acc[ai][bj][m][n] = __builtin_amdgcn_mfma_f32_16x16x32_bf16(Bt[n][k], At[m][k], acc[ai][bj][m][n], 0, 0, 0); __builtin_amdgcn_s_setprio(0); } while (0)
; template <class Epi, class Sched>
; __device__ __forceinline__ void gemm_phase(LAS unsigned char* lds, const int K, const int lda, const int ldb, const Sched& S, const Epi& E) {
;     ...
;             PG8_BAR; PG8_WAIT_L(0); PG8_MMA(0, 1, At, B1); PG8_BAR;
;             PG8_LDA(At, 1, 1); PG8_STAGE_A(PG8_SA(1, 0), a3, 0, vcur);
;             PG8_BAR; PG8_WAIT_L(0); PG8_MMA(1, 0, At, B0); PG8_BAR; PG8_SCHED;
;             PG8_STAGE(PG8_SB(1, 1), b3 + hstepB, voffB);
;             PG8_WAIT_V(6); PG8_BAR; PG8_MMA(1, 1, At, B1); PG8_BAR;
;         }
;         if constexpr (GATHER) { Unit n2; if (has_next && S.next(ui + 2, n2)) ld_ix(n2.pm, ix1); }
;         if constexpr (!Epi::AFTER_DRAIN) E(acc, cur, wr, wc, fr, fq);
;         if (!has_next) break;
; #pragma unroll
;         for (int a = 0; a < 2; ++a)
; #pragma unroll
;             for (int b = 0; b < 2; ++b)
; #pragma unroll
;                 for (int m = 0; m < 4; ++m)
; #pragma unroll
;                     for (int n = 0; n < 2; ++n) acc[a][b][m][n] = (f32x4){0.f, 0.f, 0.f, 0.f};
;         cur = nxt; cA = nA; cB = nB; ++ui;
;     }
;     PG8_WAIT_V(0);
;     if (wr == 0) PG8_BAR;
;     PG8_BAR;
	s_waitcnt lgkmcnt(0)
	s_setprio 1
	v_mfma_f32_16x16x32_bf16 v[94:97], v[216:219], v[164:167], v[94:97]
	v_mfma_f32_16x16x32_bf16 v[90:93], v[224:227], v[164:167], v[90:93]
	v_mfma_f32_16x16x32_bf16 v[86:89], v[216:219], v[172:175], v[86:89]
	v_mfma_f32_16x16x32_bf16 v[82:85], v[224:227], v[172:175], v[82:85]
	v_mfma_f32_16x16x32_bf16 v[78:81], v[216:219], v[180:183], v[78:81]
	v_mfma_f32_16x16x32_bf16 v[74:77], v[224:227], v[180:183], v[74:77]
	v_mfma_f32_16x16x32_bf16 v[70:73], v[216:219], v[188:191], v[70:73]
	v_mfma_f32_16x16x32_bf16 v[66:69], v[224:227], v[188:191], v[66:69]
	v_mfma_f32_16x16x32_bf16 v[94:97], v[220:223], v[168:171], v[94:97]
	v_mfma_f32_16x16x32_bf16 v[90:93], v[228:231], v[168:171], v[90:93]
	v_mfma_f32_16x16x32_bf16 v[86:89], v[220:223], v[176:179], v[86:89]
	v_mfma_f32_16x16x32_bf16 v[82:85], v[228:231], v[176:179], v[82:85]
	v_mfma_f32_16x16x32_bf16 v[78:81], v[220:223], v[184:187], v[78:81]
	v_mfma_f32_16x16x32_bf16 v[74:77], v[228:231], v[184:187], v[74:77]
	v_mfma_f32_16x16x32_bf16 v[70:73], v[220:223], v[192:195], v[70:73]
	v_mfma_f32_16x16x32_bf16 v[66:69], v[228:231], v[192:195], v[66:69]
	s_setprio 0
	s_mov_b32 m0, s71
	v_lshl_add_u64 v[214:215], v[234:235], 0, s[64:65]
	s_barrier
	ds_read_b128 v[164:167], v147 offset:49152
	ds_read_b128 v[168:171], v147 offset:50176
	ds_read_b128 v[172:175], v147 offset:51200
	ds_read_b128 v[176:179], v147 offset:52224
	ds_read_b128 v[180:183], v147 offset:53248
	ds_read_b128 v[184:187], v147 offset:54272
	ds_read_b128 v[188:191], v147 offset:55296
	ds_read_b128 v[192:195], v147 offset:56320
	global_load_lds_dwordx4 v[214:215], off
	v_lshl_add_u64 v[214:215], v[236:237], 0, s[64:65]
	s_mov_b32 m0, s72
	s_nop 0
	global_load_lds_dwordx4 v[214:215], off
	s_barrier
	s_waitcnt lgkmcnt(0)
	s_setprio 1
	v_mfma_f32_16x16x32_bf16 v[62:65], v[148:151], v[164:167], v[62:65]
	v_mfma_f32_16x16x32_bf16 v[58:61], v[156:159], v[164:167], v[58:61]
	v_mfma_f32_16x16x32_bf16 v[54:57], v[148:151], v[172:175], v[54:57]
	v_mfma_f32_16x16x32_bf16 v[50:53], v[156:159], v[172:175], v[50:53]
	v_mfma_f32_16x16x32_bf16 v[46:49], v[148:151], v[180:183], v[46:49]
	v_mfma_f32_16x16x32_bf16 v[42:45], v[156:159], v[180:183], v[42:45]
	v_mfma_f32_16x16x32_bf16 v[38:41], v[148:151], v[188:191], v[38:41]
	v_mfma_f32_16x16x32_bf16 v[34:37], v[156:159], v[188:191], v[34:37]
	v_mfma_f32_16x16x32_bf16 v[62:65], v[152:155], v[168:171], v[62:65]
	v_mfma_f32_16x16x32_bf16 v[58:61], v[160:163], v[168:171], v[58:61]
	v_mfma_f32_16x16x32_bf16 v[54:57], v[152:155], v[176:179], v[54:57]
	v_mfma_f32_16x16x32_bf16 v[50:53], v[160:163], v[176:179], v[50:53]
	v_mfma_f32_16x16x32_bf16 v[46:49], v[152:155], v[184:187], v[46:49]
	v_mfma_f32_16x16x32_bf16 v[42:45], v[160:163], v[184:187], v[42:45]
	v_mfma_f32_16x16x32_bf16 v[38:41], v[152:155], v[192:195], v[38:41]
	v_mfma_f32_16x16x32_bf16 v[34:37], v[160:163], v[192:195], v[34:37]
	s_setprio 0
	s_barrier
	s_add_u32 s2, s14, 0xe0080
	s_addc_u32 s3, s15, 0
	s_add_i32 s14, s16, s63
	v_lshl_add_u64 v[148:149], s[2:3], 0, v[0:1]
	s_mov_b32 m0, s14
	s_nop 0
	global_load_lds_dwordx4 v[148:149], off
	v_lshl_add_u64 v[148:149], s[2:3], 0, v[134:135]
	s_add_i32 m0, s14, 0x2000
	s_nop 0
	global_load_lds_dwordx4 v[148:149], off
	s_waitcnt vmcnt(6)
	s_barrier
	s_setprio 1
	v_mfma_f32_16x16x32_bf16 v[30:33], v[216:219], v[164:167], v[30:33]
	v_mfma_f32_16x16x32_bf16 v[26:29], v[224:227], v[164:167], v[26:29]
	v_mfma_f32_16x16x32_bf16 v[22:25], v[216:219], v[172:175], v[22:25]
	v_mfma_f32_16x16x32_bf16 v[18:21], v[224:227], v[172:175], v[18:21]
	v_mfma_f32_16x16x32_bf16 v[14:17], v[216:219], v[180:183], v[14:17]
	v_mfma_f32_16x16x32_bf16 v[10:13], v[224:227], v[180:183], v[10:13]
	v_mfma_f32_16x16x32_bf16 v[6:9], v[216:219], v[188:191], v[6:9]
	v_mfma_f32_16x16x32_bf16 v[2:5], v[224:227], v[188:191], v[2:5]
	v_mfma_f32_16x16x32_bf16 v[30:33], v[220:223], v[168:171], v[30:33]
	v_mfma_f32_16x16x32_bf16 v[26:29], v[228:231], v[168:171], v[26:29]
	v_mfma_f32_16x16x32_bf16 v[22:25], v[220:223], v[176:179], v[22:25]
	v_mfma_f32_16x16x32_bf16 v[18:21], v[228:231], v[176:179], v[18:21]
	v_mfma_f32_16x16x32_bf16 v[14:17], v[220:223], v[184:187], v[14:17]
	v_mfma_f32_16x16x32_bf16 v[10:13], v[228:231], v[184:187], v[10:13]
	v_mfma_f32_16x16x32_bf16 v[6:9], v[220:223], v[192:195], v[6:9]
	v_mfma_f32_16x16x32_bf16 v[2:5], v[228:231], v[192:195], v[2:5]
	s_setprio 0
	s_add_i32 vcc_lo, vcc_lo, 2
	s_add_u32 s12, s12, 0x100
	s_addc_u32 s13, s13, 0
	s_cmp_gt_u32 vcc_lo, 53
	s_barrier
	s_cbranch_scc0 .LBB0_392
	s_cmpk_gt_u32 s85, 0xff
	s_cbranch_scc1 .Lgx_g_pre
	s_barrier

; #define PG8_STAGE(bufoff, gbase, voff) do { _Pragma("unroll") for (int _i = 0; _i < 2; ++_i) \
;         __builtin_amdgcn_global_load_lds((const unsigned*)((const char*)(gbase) + (voff)[_i]), (LAS unsigned*)(lds + (bufoff) + ldsw + _i * 8192), 16, 0, 0); } while (0)
; #define PG8_STAGE_A(bufoff, gbase, h, vv) do { if constexpr (GATHER) { _Pragma("unroll") for (int _i = 0; _i < 2; ++_i) \
;         __builtin_amdgcn_global_load_lds((const unsigned*)((const char*)(gbase) + (vv)[h][_i]), (LAS unsigned*)(lds + (bufoff) + ldsw + _i * 8192), 16, 0, 0); } \
;         else { PG8_STAGE(bufoff, (gbase) + (h) * hstepA, voffA); } } while (0)
; #define PG8_LDA(dst, b, h) do { _Pragma("unroll") for (int m = 0; m < 4; ++m) _Pragma("unroll") for (int k = 0; k < 2; ++k) dst[m][k] = *(const LAS bf16x8*)(lds + PG8_SA(b, h) + aoff + m * 2048 + k * 1024); } while (0)
; #define PG8_LDB(dst, b, h) do { _Pragma("unroll") for (int n = 0; n < 2; ++n) _Pragma("unroll") for (int k = 0; k < 2; ++k) dst[n][k] = *(const LAS bf16x8*)(lds + PG8_SB(b, h) + boff + n * 2048 + k * 1024); } while (0)
; #define PG8_MMA(ai, bj, At, Bt) do { __builtin_amdgcn_s_setprio(1); _Pragma("unroll") for (int m = 0; m < 4; ++m) _Pragma("unroll") for (int n = 0; n < 2; ++n) _Pragma("unroll") for (int k = 0; k < 2; ++k) \
;         acc[ai][bj][m][n] = __builtin_amdgcn_mfma_f32_16x16x32_bf16(Bt[n][k], At[m][k], acc[ai][bj][m][n], 0, 0, 0); __builtin_amdgcn_s_setprio(0); } while (0)
; #define PG8_WAIT_V(n) asm volatile("s_waitcnt vmcnt(" #n ")" ::: "memory")
; #define PG8_WAIT_L(n) asm volatile("s_waitcnt lgkmcnt(" #n ")" ::: "memory")
; #define PG8_BAR __builtin_amdgcn_s_barrier()
; template <class Epi, class Sched>
; __device__ __forceinline__ void gemm_phase(LAS unsigned char* lds, const int K, const int lda, const int ldb, const Sched& S, const Epi& E) {
;     ...
;             PG8_WAIT_L(8); PG8_BAR; PG8_WAIT_L(0); PG8_MMA(0, 0, At, B0); PG8_BAR; PG8_SCHED;
;             PG8_LDB(B1, 0, 1); PG8_STAGE(PG8_SB(0, 0), b2, voffB);
;             PG8_BAR; PG8_WAIT_L(0); PG8_MMA(0, 1, At, B1); PG8_BAR;
;             PG8_LDA(At, 0, 1); PG8_STAGE_A(PG8_SA(0, 0), a2, 0, vcur);
;             PG8_BAR; PG8_WAIT_L(0); PG8_MMA(1, 0, At, B0); PG8_BAR; PG8_SCHED;
;             PG8_STAGE(PG8_SB(0, 1), b2 + hstepB, voffB);
;             PG8_WAIT_V(6); PG8_BAR; PG8_MMA(1, 1, At, B1); PG8_BAR;
.LBB0_485:
	s_add_u32 s2, s28, s12
	s_addc_u32 s3, s29, s13
	s_add_u32 s2, s2, 0x1c9b9100
	s_addc_u32 s3, s3, 0
	s_and_b64 s[34:35], s[16:17], exec
	s_cselect_b32 s35, s97, s3
	s_cselect_b32 s34, s96, s2
	s_add_u32 s2, s7, s12
	s_waitcnt lgkmcnt(8)
	s_barrier
	s_waitcnt lgkmcnt(0)
	s_addc_u32 s3, s55, s13
	s_and_b64 s[16:17], s[16:17], exec
	s_cselect_b32 s17, s11, s3
	s_cselect_b32 s16, s10, s2
	s_setprio 1
	s_waitcnt lgkmcnt(0)
	v_mfma_f32_16x16x32_bf16 v[126:129], v[130:133], v[170:173], v[126:129]
	v_mfma_f32_16x16x32_bf16 v[122:125], v[138:141], v[170:173], v[122:125]
	v_mfma_f32_16x16x32_bf16 v[118:121], v[130:133], v[162:165], v[118:121]
	v_mfma_f32_16x16x32_bf16 v[114:117], v[138:141], v[162:165], v[114:117]
	v_mfma_f32_16x16x32_bf16 v[110:113], v[130:133], v[154:157], v[110:113]
	v_mfma_f32_16x16x32_bf16 v[106:109], v[138:141], v[154:157], v[106:109]
	v_mfma_f32_16x16x32_bf16 v[102:105], v[130:133], v[146:149], v[102:105]
	v_mfma_f32_16x16x32_bf16 v[98:101], v[138:141], v[146:149], v[98:101]
	v_mfma_f32_16x16x32_bf16 v[126:129], v[134:137], v[174:177], v[126:129]
	v_mfma_f32_16x16x32_bf16 v[122:125], v[142:145], v[174:177], v[122:125]
	v_mfma_f32_16x16x32_bf16 v[118:121], v[134:137], v[166:169], v[118:121]
	v_mfma_f32_16x16x32_bf16 v[114:117], v[142:145], v[166:169], v[114:117]
	v_mfma_f32_16x16x32_bf16 v[110:113], v[134:137], v[158:161], v[110:113]
	v_mfma_f32_16x16x32_bf16 v[106:109], v[142:145], v[158:161], v[106:109]
	v_mfma_f32_16x16x32_bf16 v[102:105], v[134:137], v[150:153], v[102:105]
	v_mfma_f32_16x16x32_bf16 v[98:101], v[142:145], v[150:153], v[98:101]
	s_setprio 0
	s_barrier
	s_add_i32 s2, 0, 0x14000
	s_mov_b32 m0, s67
	v_add_u32_e32 v179, s2, v221
	v_lshl_add_u64 v[214:215], s[16:17], 0, v[184:185]
	ds_read_b128 v[226:229], v179
	ds_read_b128 v[230:233], v179 offset:1024
	ds_read_b128 v[234:237], v179 offset:2048
	ds_read_b128 v[238:241], v179 offset:3072
	global_load_lds_dwordx4 v[214:215], off
	v_lshl_add_u64 v[242:243], s[16:17], 0, v[186:187]
	s_mov_b32 m0, s62
	s_nop 0
	global_load_lds_dwordx4 v[242:243], off
	s_barrier
	s_waitcnt lgkmcnt(0)
	s_setprio 1
	v_mfma_f32_16x16x32_bf16 v[94:97], v[226:229], v[170:173], v[94:97]
	v_mfma_f32_16x16x32_bf16 v[90:93], v[234:237], v[170:173], v[90:93]
	v_mfma_f32_16x16x32_bf16 v[86:89], v[226:229], v[162:165], v[86:89]
	v_mfma_f32_16x16x32_bf16 v[82:85], v[234:237], v[162:165], v[82:85]
	v_mfma_f32_16x16x32_bf16 v[78:81], v[226:229], v[154:157], v[78:81]
	v_mfma_f32_16x16x32_bf16 v[74:77], v[234:237], v[154:157], v[74:77]
	v_mfma_f32_16x16x32_bf16 v[70:73], v[226:229], v[146:149], v[70:73]
	v_mfma_f32_16x16x32_bf16 v[66:69], v[234:237], v[146:149], v[66:69]
	v_mfma_f32_16x16x32_bf16 v[94:97], v[230:233], v[174:177], v[94:97]
	v_mfma_f32_16x16x32_bf16 v[90:93], v[238:241], v[174:177], v[90:93]
	v_mfma_f32_16x16x32_bf16 v[86:89], v[230:233], v[166:169], v[86:89]
	v_mfma_f32_16x16x32_bf16 v[82:85], v[238:241], v[166:169], v[82:85]
	v_mfma_f32_16x16x32_bf16 v[78:81], v[230:233], v[158:161], v[78:81]
	v_mfma_f32_16x16x32_bf16 v[74:77], v[238:241], v[158:161], v[74:77]
	v_mfma_f32_16x16x32_bf16 v[70:73], v[230:233], v[150:153], v[70:73]
	v_mfma_f32_16x16x32_bf16 v[66:69], v[238:241], v[150:153], v[66:69]
	s_setprio 0
	s_mov_b32 m0, s19
	s_barrier
	ds_read_b128 v[146:149], v223 offset:16384
	ds_read_b128 v[150:153], v223 offset:17408
	ds_read_b128 v[154:157], v223 offset:18432
	ds_read_b128 v[158:161], v223 offset:19456
	ds_read_b128 v[162:165], v223 offset:20480
	ds_read_b128 v[166:169], v223 offset:21504
	ds_read_b128 v[170:173], v223 offset:22528
	ds_read_b128 v[174:177], v223 offset:23552
	global_load_lds_dwordx4 v178, s[34:35]
	s_mov_b32 m0, s44
	v_mov_b32_e32 v179, v1
	global_load_lds_dwordx4 v180, s[34:35]
	s_barrier
	s_waitcnt lgkmcnt(0)
	v_mov_b32_e32 v181, v1
	v_lshl_add_u64 v[244:245], s[34:35], 0, v[178:179]
	v_lshl_add_u64 v[246:247], s[34:35], 0, v[180:181]
	s_setprio 1
	s_waitcnt lgkmcnt(0)
	v_mfma_f32_16x16x32_bf16 v[62:65], v[130:133], v[146:149], v[62:65]
	v_mfma_f32_16x16x32_bf16 v[58:61], v[138:141], v[146:149], v[58:61]
	v_mfma_f32_16x16x32_bf16 v[54:57], v[130:133], v[154:157], v[54:57]
	v_mfma_f32_16x16x32_bf16 v[50:53], v[138:141], v[154:157], v[50:53]
	v_mfma_f32_16x16x32_bf16 v[46:49], v[130:133], v[162:165], v[46:49]
	v_mfma_f32_16x16x32_bf16 v[42:45], v[138:141], v[162:165], v[42:45]
	v_mfma_f32_16x16x32_bf16 v[38:41], v[130:133], v[170:173], v[38:41]
	v_mfma_f32_16x16x32_bf16 v[34:37], v[138:141], v[170:173], v[34:37]
	v_mfma_f32_16x16x32_bf16 v[62:65], v[134:137], v[150:153], v[62:65]
	v_mfma_f32_16x16x32_bf16 v[58:61], v[142:145], v[150:153], v[58:61]
	v_mfma_f32_16x16x32_bf16 v[54:57], v[134:137], v[158:161], v[54:57]
	v_mfma_f32_16x16x32_bf16 v[50:53], v[142:145], v[158:161], v[50:53]
	v_mfma_f32_16x16x32_bf16 v[46:49], v[134:137], v[166:169], v[46:49]
	v_mfma_f32_16x16x32_bf16 v[42:45], v[142:145], v[166:169], v[42:45]
	v_mfma_f32_16x16x32_bf16 v[38:41], v[134:137], v[174:177], v[38:41]
	v_mfma_f32_16x16x32_bf16 v[34:37], v[142:145], v[174:177], v[34:37]
	s_setprio 0
	s_barrier
	s_add_u32 s56, s16, 0x40000
	s_addc_u32 s57, s17, 0
	s_add_i32 s2, s2, s5
	v_lshl_add_u64 v[130:131], s[56:57], 0, v[184:185]
	s_mov_b32 m0, s2
	s_nop 0
	global_load_lds_dwordx4 v[130:131], off
	v_lshl_add_u64 v[130:131], s[56:57], 0, v[186:187]
	s_add_i32 m0, s2, 0x2000
	s_nop 0
	global_load_lds_dwordx4 v[130:131], off
	s_waitcnt vmcnt(6)
	s_barrier
; #define PG8_STAGE(bufoff, gbase, voff) do { _Pragma("unroll") for (int _i = 0; _i < 2; ++_i) \
;         __builtin_amdgcn_global_load_lds((const unsigned*)((const char*)(gbase) + (voff)[_i]), (LAS unsigned*)(lds + (bufoff) + ldsw + _i * 8192), 16, 0, 0); } while (0)
; #define PG8_STAGE_A(bufoff, gbase, h, vv) do { if constexpr (GATHER) { _Pragma("unroll") for (int _i = 0; _i < 2; ++_i) \
;         __builtin_amdgcn_global_load_lds((const unsigned*)((const char*)(gbase) + (vv)[h][_i]), (LAS unsigned*)(lds + (bufoff) + ldsw + _i * 8192), 16, 0, 0); } \
;         else { PG8_STAGE(bufoff, (gbase) + (h) * hstepA, voffA); } } while (0)
; #define PG8_LDA(dst, b, h) do { _Pragma("unroll") for (int m = 0; m < 4; ++m) _Pragma("unroll") for (int k = 0; k < 2; ++k) dst[m][k] = *(const LAS bf16x8*)(lds + PG8_SA(b, h) + aoff + m * 2048 + k * 1024); } while (0)
; #define PG8_LDB(dst, b, h) do { _Pragma("unroll") for (int n = 0; n < 2; ++n) _Pragma("unroll") for (int k = 0; k < 2; ++k) dst[n][k] = *(const LAS bf16x8*)(lds + PG8_SB(b, h) + boff + n * 2048 + k * 1024); } while (0)
; #define PG8_MMA(ai, bj, At, Bt) do { __builtin_amdgcn_s_setprio(1); _Pragma("unroll") for (int m = 0; m < 4; ++m) _Pragma("unroll") for (int n = 0; n < 2; ++n) _Pragma("unroll") for (int k = 0; k < 2; ++k) \
;         acc[ai][bj][m][n] = __builtin_amdgcn_mfma_f32_16x16x32_bf16(Bt[n][k], At[m][k], acc[ai][bj][m][n], 0, 0, 0); __builtin_amdgcn_s_setprio(0); } while (0)
; #define PG8_WAIT_V(n) asm volatile("s_waitcnt vmcnt(" #n ")" ::: "memory")
; #define PG8_WAIT_L(n) asm volatile("s_waitcnt lgkmcnt(" #n ")" ::: "memory")
; #define PG8_BAR __builtin_amdgcn_s_barrier()
; #define PG8_SCHED __builtin_amdgcn_sched_barrier(0)
; template <class Epi, class Sched>
; __device__ __forceinline__ void gemm_phase(LAS unsigned char* lds, const int K, const int lda, const int ldb, const Sched& S, const Epi& E) {
;     ...
;             PG8_WAIT_V(6); PG8_BAR; PG8_MMA(1, 1, At, B1); PG8_BAR;
;             PG8_LDB(B0, 1, 0); PG8_SCHED; PG8_LDA(At, 1, 0); PG8_STAGE_A(PG8_SA(0, 1), a2, 1, vcur);
;             PG8_WAIT_L(8); PG8_BAR; PG8_WAIT_L(0); PG8_MMA(0, 0, At, B0); PG8_BAR; PG8_SCHED;
;             PG8_LDB(B1, 1, 1); PG8_STAGE(PG8_SB(1, 0), b3, voffB);
	s_setprio 1
	v_mfma_f32_16x16x32_bf16 v[30:33], v[226:229], v[146:149], v[30:33]
	v_mfma_f32_16x16x32_bf16 v[26:29], v[234:237], v[146:149], v[26:29]
	v_mfma_f32_16x16x32_bf16 v[22:25], v[226:229], v[154:157], v[22:25]
	v_mfma_f32_16x16x32_bf16 v[18:21], v[234:237], v[154:157], v[18:21]
	v_mfma_f32_16x16x32_bf16 v[14:17], v[226:229], v[162:165], v[14:17]
	v_mfma_f32_16x16x32_bf16 v[10:13], v[234:237], v[162:165], v[10:13]
	v_mfma_f32_16x16x32_bf16 v[6:9], v[226:229], v[170:173], v[6:9]
	v_mfma_f32_16x16x32_bf16 v[2:5], v[234:237], v[170:173], v[2:5]
	v_mfma_f32_16x16x32_bf16 v[30:33], v[230:233], v[150:153], v[30:33]
	v_mfma_f32_16x16x32_bf16 v[26:29], v[238:241], v[150:153], v[26:29]
	v_mfma_f32_16x16x32_bf16 v[22:25], v[230:233], v[158:161], v[22:25]
	v_mfma_f32_16x16x32_bf16 v[18:21], v[238:241], v[158:161], v[18:21]
	v_mfma_f32_16x16x32_bf16 v[14:17], v[230:233], v[166:169], v[14:17]
	v_mfma_f32_16x16x32_bf16 v[10:13], v[238:241], v[166:169], v[10:13]
	v_mfma_f32_16x16x32_bf16 v[6:9], v[230:233], v[174:177], v[6:9]
	v_mfma_f32_16x16x32_bf16 v[2:5], v[238:241], v[174:177], v[2:5]
	s_setprio 0
	s_add_i32 s2, 0, 0x18000
	v_add_u32_e32 v142, s2, v221
	s_barrier
	ds_read_b128 v[130:133], v142
	ds_read_b128 v[134:137], v142 offset:1024
	ds_read_b128 v[138:141], v142 offset:2048
	ds_read_b128 v[142:145], v142 offset:3072
	s_mov_b32 m0, s45
	v_lshl_add_u64 v[194:195], s[34:35], 0, v[194:195]
	ds_read_b128 v[146:149], v223 offset:32768
	ds_read_b128 v[150:153], v223 offset:33792
	ds_read_b128 v[154:157], v223 offset:34816
	ds_read_b128 v[158:161], v223 offset:35840
	ds_read_b128 v[162:165], v223 offset:36864
	ds_read_b128 v[166:169], v223 offset:37888
	ds_read_b128 v[170:173], v223 offset:38912
	ds_read_b128 v[174:177], v223 offset:39936
	global_load_lds_dwordx4 v[194:195], off
	v_lshl_add_u64 v[192:193], s[34:35], 0, v[192:193]
	s_mov_b32 m0, s39
	s_nop 0
	global_load_lds_dwordx4 v[192:193], off
	s_waitcnt lgkmcnt(8)
	s_barrier
	s_waitcnt lgkmcnt(0)
	s_setprio 1
	v_mfma_f32_16x16x32_bf16 v[126:129], v[130:133], v[146:149], v[126:129]
	v_mfma_f32_16x16x32_bf16 v[122:125], v[138:141], v[146:149], v[122:125]
	v_mfma_f32_16x16x32_bf16 v[118:121], v[130:133], v[154:157], v[118:121]
	v_mfma_f32_16x16x32_bf16 v[114:117], v[138:141], v[154:157], v[114:117]
	v_mfma_f32_16x16x32_bf16 v[110:113], v[130:133], v[162:165], v[110:113]
	v_mfma_f32_16x16x32_bf16 v[106:109], v[138:141], v[162:165], v[106:109]
	v_mfma_f32_16x16x32_bf16 v[102:105], v[130:133], v[170:173], v[102:105]
	v_mfma_f32_16x16x32_bf16 v[98:101], v[138:141], v[170:173], v[98:101]
	v_mfma_f32_16x16x32_bf16 v[126:129], v[134:137], v[150:153], v[126:129]
	v_mfma_f32_16x16x32_bf16 v[122:125], v[142:145], v[150:153], v[122:125]
	v_mfma_f32_16x16x32_bf16 v[118:121], v[134:137], v[158:161], v[118:121]
	v_mfma_f32_16x16x32_bf16 v[114:117], v[142:145], v[158:161], v[114:117]
	v_mfma_f32_16x16x32_bf16 v[110:113], v[134:137], v[166:169], v[110:113]
	v_mfma_f32_16x16x32_bf16 v[106:109], v[142:145], v[166:169], v[106:109]
	v_mfma_f32_16x16x32_bf16 v[102:105], v[134:137], v[174:177], v[102:105]
	v_mfma_f32_16x16x32_bf16 v[98:101], v[142:145], v[174:177], v[98:101]
	s_setprio 0
	s_barrier
	s_add_i32 s3, 0, 0x1c000
	s_add_i32 s2, s2, s5
	v_add_u32_e32 v179, s3, v221
	v_lshl_add_u64 v[214:215], v[214:215], 0, s[64:65]
	s_mov_b32 m0, s2
	ds_read_b128 v[192:195], v179
	ds_read_b128 v[226:229], v179 offset:1024
	ds_read_b128 v[230:233], v179 offset:2048
	ds_read_b128 v[234:237], v179 offset:3072
	global_load_lds_dwordx4 v[214:215], off
	v_lshl_add_u64 v[214:215], v[242:243], 0, s[64:65]
	s_add_i32 m0, s2, 0x2000
	s_nop 0
	global_load_lds_dwordx4 v[214:215], off
	s_barrier
; #define PG8_STAGE(bufoff, gbase, voff) do { _Pragma("unroll") for (int _i = 0; _i < 2; ++_i) \
;         __builtin_amdgcn_global_load_lds((const unsigned*)((const char*)(gbase) + (voff)[_i]), (LAS unsigned*)(lds + (bufoff) + ldsw + _i * 8192), 16, 0, 0); } while (0)
; #define PG8_STAGE_A(bufoff, gbase, h, vv) do { if constexpr (GATHER) { _Pragma("unroll") for (int _i = 0; _i < 2; ++_i) \
;         __builtin_amdgcn_global_load_lds((const unsigned*)((const char*)(gbase) + (vv)[h][_i]), (LAS unsigned*)(lds + (bufoff) + ldsw + _i * 8192), 16, 0, 0); } \
;         else { PG8_STAGE(bufoff, (gbase) + (h) * hstepA, voffA); } } while (0)
; #define PG8_LDA(dst, b, h) do { _Pragma("unroll") for (int m = 0; m < 4; ++m) _Pragma("unroll") for (int k = 0; k < 2; ++k) dst[m][k] = *(const LAS bf16x8*)(lds + PG8_SA(b, h) + aoff + m * 2048 + k * 1024); } while (0)
; #define PG8_LDB(dst, b, h) do { _Pragma("unroll") for (int n = 0; n < 2; ++n) _Pragma("unroll") for (int k = 0; k < 2; ++k) dst[n][k] = *(const LAS bf16x8*)(lds + PG8_SB(b, h) + boff + n * 2048 + k * 1024); } while (0)
; #define PG8_MMA(ai, bj, At, Bt) do { __builtin_amdgcn_s_setprio(1); _Pragma("unroll") for (int m = 0; m < 4; ++m) _Pragma("unroll") for (int n = 0; n < 2; ++n) _Pragma("unroll") for (int k = 0; k < 2; ++k) \
;         acc[ai][bj][m][n] = __builtin_amdgcn_mfma_f32_16x16x32_bf16(Bt[n][k], At[m][k], acc[ai][bj][m][n], 0, 0, 0); __builtin_amdgcn_s_setprio(0); } while (0)
; #define PG8_BAR __builtin_amdgcn_s_barrier()
; template <class Epi, class Sched>
; __device__ __forceinline__ void gemm_phase(LAS unsigned char* lds, const int K, const int lda, const int ldb, const Sched& S, const Epi& E) {
;     ...
;             PG8_WAIT_V(6); PG8_BAR; PG8_MMA(1, 1, At, B1); PG8_BAR;
;             PG8_LDB(B0, 1, 0); PG8_SCHED; PG8_LDA(At, 1, 0); PG8_STAGE_A(PG8_SA(0, 1), a2, 1, vcur);
;             PG8_WAIT_L(8); PG8_BAR; PG8_WAIT_L(0); PG8_MMA(0, 0, At, B0); PG8_BAR; PG8_SCHED;
;             PG8_LDB(B1, 1, 1); PG8_STAGE(PG8_SB(1, 0), b3, voffB);
;             PG8_BAR; PG8_WAIT_L(0); PG8_MMA(0, 1, At, B1); PG8_BAR;
;             PG8_LDA(At, 1, 1); PG8_STAGE_A(PG8_SA(1, 0), a3, 0, vcur);
;             PG8_BAR; PG8_WAIT_L(0); PG8_MMA(1, 0, At, B0); PG8_BAR; PG8_SCHED;
;             PG8_STAGE(PG8_SB(1, 1), b3 + hstepB, voffB);
;             PG8_WAIT_V(6); PG8_BAR; PG8_MMA(1, 1, At, B1); PG8_BAR;
;         }
	s_waitcnt lgkmcnt(0)
	s_setprio 1
	v_mfma_f32_16x16x32_bf16 v[94:97], v[192:195], v[146:149], v[94:97]
	v_mfma_f32_16x16x32_bf16 v[90:93], v[230:233], v[146:149], v[90:93]
	v_mfma_f32_16x16x32_bf16 v[86:89], v[192:195], v[154:157], v[86:89]
	v_mfma_f32_16x16x32_bf16 v[82:85], v[230:233], v[154:157], v[82:85]
	v_mfma_f32_16x16x32_bf16 v[78:81], v[192:195], v[162:165], v[78:81]
	v_mfma_f32_16x16x32_bf16 v[74:77], v[230:233], v[162:165], v[74:77]
	v_mfma_f32_16x16x32_bf16 v[70:73], v[192:195], v[170:173], v[70:73]
	v_mfma_f32_16x16x32_bf16 v[66:69], v[230:233], v[170:173], v[66:69]
	v_mfma_f32_16x16x32_bf16 v[94:97], v[226:229], v[150:153], v[94:97]
	v_mfma_f32_16x16x32_bf16 v[90:93], v[234:237], v[150:153], v[90:93]
	v_mfma_f32_16x16x32_bf16 v[86:89], v[226:229], v[158:161], v[86:89]
	v_mfma_f32_16x16x32_bf16 v[82:85], v[234:237], v[158:161], v[82:85]
	v_mfma_f32_16x16x32_bf16 v[78:81], v[226:229], v[166:169], v[78:81]
	v_mfma_f32_16x16x32_bf16 v[74:77], v[234:237], v[166:169], v[74:77]
	v_mfma_f32_16x16x32_bf16 v[70:73], v[226:229], v[174:177], v[70:73]
	v_mfma_f32_16x16x32_bf16 v[66:69], v[234:237], v[174:177], v[66:69]
	s_setprio 0
	s_mov_b32 m0, s41
	v_lshl_add_u64 v[214:215], v[244:245], 0, s[64:65]
	s_barrier
	ds_read_b128 v[146:149], v223 offset:49152
	ds_read_b128 v[150:153], v223 offset:50176
	ds_read_b128 v[154:157], v223 offset:51200
	ds_read_b128 v[158:161], v223 offset:52224
	ds_read_b128 v[162:165], v223 offset:53248
	ds_read_b128 v[166:169], v223 offset:54272
	ds_read_b128 v[170:173], v223 offset:55296
	ds_read_b128 v[174:177], v223 offset:56320
	global_load_lds_dwordx4 v[214:215], off
	v_lshl_add_u64 v[214:215], v[246:247], 0, s[64:65]
	s_mov_b32 m0, s43
	s_nop 0
	global_load_lds_dwordx4 v[214:215], off
	s_barrier
	s_waitcnt lgkmcnt(0)
	s_setprio 1
	v_mfma_f32_16x16x32_bf16 v[62:65], v[130:133], v[146:149], v[62:65]
	v_mfma_f32_16x16x32_bf16 v[58:61], v[138:141], v[146:149], v[58:61]
	v_mfma_f32_16x16x32_bf16 v[54:57], v[130:133], v[154:157], v[54:57]
	v_mfma_f32_16x16x32_bf16 v[50:53], v[138:141], v[154:157], v[50:53]
	v_mfma_f32_16x16x32_bf16 v[46:49], v[130:133], v[162:165], v[46:49]
	v_mfma_f32_16x16x32_bf16 v[42:45], v[138:141], v[162:165], v[42:45]
	v_mfma_f32_16x16x32_bf16 v[38:41], v[130:133], v[170:173], v[38:41]
	v_mfma_f32_16x16x32_bf16 v[34:37], v[138:141], v[170:173], v[34:37]
	v_mfma_f32_16x16x32_bf16 v[62:65], v[134:137], v[150:153], v[62:65]
	v_mfma_f32_16x16x32_bf16 v[58:61], v[142:145], v[150:153], v[58:61]
	v_mfma_f32_16x16x32_bf16 v[54:57], v[134:137], v[158:161], v[54:57]
	v_mfma_f32_16x16x32_bf16 v[50:53], v[142:145], v[158:161], v[50:53]
	v_mfma_f32_16x16x32_bf16 v[46:49], v[134:137], v[166:169], v[46:49]
	v_mfma_f32_16x16x32_bf16 v[42:45], v[142:145], v[166:169], v[42:45]
	v_mfma_f32_16x16x32_bf16 v[38:41], v[134:137], v[174:177], v[38:41]
	v_mfma_f32_16x16x32_bf16 v[34:37], v[142:145], v[174:177], v[34:37]
	s_setprio 0
	s_barrier
	s_add_u32 s16, s16, 0x40080
	s_addc_u32 s17, s17, 0
	s_add_i32 s2, s3, s5
	v_lshl_add_u64 v[130:131], s[16:17], 0, v[184:185]
	s_mov_b32 m0, s2
	s_nop 0
	global_load_lds_dwordx4 v[130:131], off
	v_lshl_add_u64 v[130:131], s[16:17], 0, v[186:187]
	s_add_i32 m0, s2, 0x2000
	s_nop 0
	global_load_lds_dwordx4 v[130:131], off
	s_waitcnt vmcnt(6)
	s_barrier
	s_setprio 1
	v_mfma_f32_16x16x32_bf16 v[30:33], v[192:195], v[146:149], v[30:33]
	v_mfma_f32_16x16x32_bf16 v[26:29], v[230:233], v[146:149], v[26:29]
	v_mfma_f32_16x16x32_bf16 v[22:25], v[192:195], v[154:157], v[22:25]
	v_mfma_f32_16x16x32_bf16 v[18:21], v[230:233], v[154:157], v[18:21]
	v_mfma_f32_16x16x32_bf16 v[14:17], v[192:195], v[162:165], v[14:17]
	v_mfma_f32_16x16x32_bf16 v[10:13], v[230:233], v[162:165], v[10:13]
	v_mfma_f32_16x16x32_bf16 v[6:9], v[192:195], v[170:173], v[6:9]
	v_mfma_f32_16x16x32_bf16 v[2:5], v[230:233], v[170:173], v[2:5]
	v_mfma_f32_16x16x32_bf16 v[30:33], v[226:229], v[150:153], v[30:33]
	v_mfma_f32_16x16x32_bf16 v[26:29], v[234:237], v[150:153], v[26:29]
	v_mfma_f32_16x16x32_bf16 v[22:25], v[226:229], v[158:161], v[22:25]
	v_mfma_f32_16x16x32_bf16 v[18:21], v[234:237], v[158:161], v[18:21]
	v_mfma_f32_16x16x32_bf16 v[14:17], v[226:229], v[166:169], v[14:17]
	v_mfma_f32_16x16x32_bf16 v[10:13], v[234:237], v[166:169], v[10:13]
	v_mfma_f32_16x16x32_bf16 v[6:9], v[226:229], v[174:177], v[6:9]
	v_mfma_f32_16x16x32_bf16 v[2:5], v[234:237], v[174:177], v[2:5]
	s_setprio 0
	s_add_i32 vcc_lo, vcc_lo, 2
	s_add_u32 s12, s12, 0x100
	s_addc_u32 s13, s13, 0
	s_cmp_gt_u32 vcc_lo, 13
	s_barrier
	s_cbranch_scc1 .LBB0_488

; #define PG8_STAGE(bufoff, gbase, voff) do { _Pragma("unroll") for (int _i = 0; _i < 2; ++_i) \
;         __builtin_amdgcn_global_load_lds((const unsigned*)((const char*)(gbase) + (voff)[_i]), (LAS unsigned*)(lds + (bufoff) + ldsw + _i * 8192), 16, 0, 0); } while (0)
; #define PG8_STAGE_A(bufoff, gbase, h, vv) do { if constexpr (GATHER) { _Pragma("unroll") for (int _i = 0; _i < 2; ++_i) \
;         __builtin_amdgcn_global_load_lds((const unsigned*)((const char*)(gbase) + (vv)[h][_i]), (LAS unsigned*)(lds + (bufoff) + ldsw + _i * 8192), 16, 0, 0); } \
;         else { PG8_STAGE(bufoff, (gbase) + (h) * hstepA, voffA); } } while (0)
; #define PG8_LDA(dst, b, h) do { _Pragma("unroll") for (int m = 0; m < 4; ++m) _Pragma("unroll") for (int k = 0; k < 2; ++k) dst[m][k] = *(const LAS bf16x8*)(lds + PG8_SA(b, h) + aoff + m * 2048 + k * 1024); } while (0)
; #define PG8_LDB(dst, b, h) do { _Pragma("unroll") for (int n = 0; n < 2; ++n) _Pragma("unroll") for (int k = 0; k < 2; ++k) dst[n][k] = *(const LAS bf16x8*)(lds + PG8_SB(b, h) + boff + n * 2048 + k * 1024); } while (0)
; #define PG8_WAIT_L(n) asm volatile("s_waitcnt lgkmcnt(" #n ")" ::: "memory")
; template <class Epi, class Sched>
; __device__ __forceinline__ void gemm_phase(LAS unsigned char* lds, const int K, const int lda, const int ldb, const Sched& S, const Epi& E) {
;     ...
;         for (int t = 0; t < nt; t += 2) {
;             const bool last = (t == nt - 2);
;             const char* a1 = cA + (size_t)(t + 1) * kstep;
;             const char* a2 = last ? nA : cA + (size_t)(t + 2) * kstep; const char* b2 = last ? nB : cB + (size_t)(t + 2) * kstep;
;             const char* a3 = a2 + kstep; const char* b3 = b2 + kstep;
;             PG8_LDB(B0, 0, 0); PG8_SCHED; PG8_LDA(At, 0, 0); PG8_STAGE_A(PG8_SA(1, 1), a1, 1, vcur);
;             if constexpr (GATHER) { if (last) {
; #pragma unroll
;                 for (int h = 0; h < 2; ++h)
; #pragma unroll
;                     for (int i = 0; i < 2; ++i) vcur[h][i] = vnxt[h][i]; } }
;             PG8_WAIT_L(8); PG8_BAR; PG8_WAIT_L(0); PG8_MMA(0, 0, At, B0); PG8_BAR; PG8_SCHED;
;             PG8_LDB(B1, 0, 1); PG8_STAGE(PG8_SB(0, 0), b2, voffB);
;             PG8_BAR; PG8_WAIT_L(0); PG8_MMA(0, 1, At, B1); PG8_BAR;
;             PG8_LDA(At, 0, 1); PG8_STAGE_A(PG8_SA(0, 0), a2, 0, vcur);
;             PG8_BAR; PG8_WAIT_L(0); PG8_MMA(1, 0, At, B0); PG8_BAR; PG8_SCHED;
.LBB0_711:
	s_add_u32 s2, s12, 0xfffc0080
	s_addc_u32 s3, s13, -1
	s_add_i32 s20, 0, 0x10000
	v_add_u32_e32 v148, s20, v177
	ds_read_b128 v[130:133], v148
	ds_read_b128 v[134:137], v148 offset:1024
	ds_read_b128 v[144:147], v148 offset:2048
	ds_read_b128 v[148:151], v148 offset:3072
	s_cmp_eq_u32 s43, 12
	s_cselect_b32 s17, s5, s3
	s_cselect_b32 s16, s4, s2
	s_cselect_b32 s15, s7, s42
	s_cselect_b32 s14, s6, s1
	v_lshl_add_u64 v[188:189], s[12:13], 0, v[140:141]
	s_add_i32 m0, s11, 0xc000
	ds_read_b128 v[152:155], v179
	ds_read_b128 v[156:159], v179 offset:1024
	ds_read_b128 v[160:163], v179 offset:2048
	ds_read_b128 v[164:167], v179 offset:3072
	ds_read_b128 v[168:171], v179 offset:4096
	ds_read_b128 v[172:175], v179 offset:5120
	ds_read_b128 v[180:183], v179 offset:6144
	ds_read_b128 v[184:187], v179 offset:7168
	global_load_lds_dwordx4 v[188:189], off
	v_lshl_add_u64 v[188:189], s[12:13], 0, v[142:143]
	s_add_i32 m0, s11, 0xe000
	s_nop 0
	global_load_lds_dwordx4 v[188:189], off
	s_waitcnt lgkmcnt(8)
	s_barrier
	s_waitcnt lgkmcnt(0)
	s_setprio 1
	v_mfma_f32_16x16x32_bf16 v[126:129], v[130:133], v[152:155], v[126:129]
	v_mfma_f32_16x16x32_bf16 v[110:113], v[144:147], v[152:155], v[110:113]
	v_mfma_f32_16x16x32_bf16 v[122:125], v[130:133], v[160:163], v[122:125]
	v_mfma_f32_16x16x32_bf16 v[106:109], v[144:147], v[160:163], v[106:109]
	v_mfma_f32_16x16x32_bf16 v[118:121], v[130:133], v[168:171], v[118:121]
	v_mfma_f32_16x16x32_bf16 v[94:97], v[144:147], v[168:171], v[94:97]
	v_mfma_f32_16x16x32_bf16 v[114:117], v[130:133], v[180:183], v[114:117]
	v_mfma_f32_16x16x32_bf16 v[82:85], v[144:147], v[180:183], v[82:85]
	v_mfma_f32_16x16x32_bf16 v[126:129], v[134:137], v[156:159], v[126:129]
	v_mfma_f32_16x16x32_bf16 v[110:113], v[148:151], v[156:159], v[110:113]
	v_mfma_f32_16x16x32_bf16 v[122:125], v[134:137], v[164:167], v[122:125]
	v_mfma_f32_16x16x32_bf16 v[106:109], v[148:151], v[164:167], v[106:109]
	v_mfma_f32_16x16x32_bf16 v[118:121], v[134:137], v[172:175], v[118:121]
	v_mfma_f32_16x16x32_bf16 v[94:97], v[148:151], v[172:175], v[94:97]
	v_mfma_f32_16x16x32_bf16 v[114:117], v[134:137], v[184:187], v[114:117]
	v_mfma_f32_16x16x32_bf16 v[82:85], v[148:151], v[184:187], v[82:85]
	s_setprio 0
	s_barrier
	s_add_i32 s2, 0, 0x14000
	v_add_u32_e32 v214, s2, v177
	s_add_i32 s3, s20, s30
	ds_read_b128 v[188:191], v214
	ds_read_b128 v[192:195], v214 offset:1024
	ds_read_b128 v[216:219], v214 offset:2048
	ds_read_b128 v[220:223], v214 offset:3072
	v_lshl_add_u64 v[214:215], s[14:15], 0, v[0:1]
	s_mov_b32 m0, s3
	v_lshl_add_u64 v[224:225], s[14:15], 0, v[138:139]
	global_load_lds_dwordx4 v[214:215], off
	s_add_i32 m0, s3, 0x2000
	s_nop 0
	global_load_lds_dwordx4 v[224:225], off
	s_barrier
	s_waitcnt lgkmcnt(0)
	s_setprio 1
	v_mfma_f32_16x16x32_bf16 v[70:73], v[188:191], v[152:155], v[70:73]
	v_mfma_f32_16x16x32_bf16 v[42:45], v[216:219], v[152:155], v[42:45]
	v_mfma_f32_16x16x32_bf16 v[62:65], v[188:191], v[160:163], v[62:65]
	v_mfma_f32_16x16x32_bf16 v[34:37], v[216:219], v[160:163], v[34:37]
	v_mfma_f32_16x16x32_bf16 v[54:57], v[188:191], v[168:171], v[54:57]
	v_mfma_f32_16x16x32_bf16 v[26:29], v[216:219], v[168:171], v[26:29]
	v_mfma_f32_16x16x32_bf16 v[50:53], v[188:191], v[180:183], v[50:53]
	v_mfma_f32_16x16x32_bf16 v[18:21], v[216:219], v[180:183], v[18:21]
	v_mfma_f32_16x16x32_bf16 v[70:73], v[192:195], v[156:159], v[70:73]
	v_mfma_f32_16x16x32_bf16 v[42:45], v[220:223], v[156:159], v[42:45]
	v_mfma_f32_16x16x32_bf16 v[62:65], v[192:195], v[164:167], v[62:65]
	v_mfma_f32_16x16x32_bf16 v[34:37], v[220:223], v[164:167], v[34:37]
	v_mfma_f32_16x16x32_bf16 v[54:57], v[192:195], v[172:175], v[54:57]
	v_mfma_f32_16x16x32_bf16 v[26:29], v[220:223], v[172:175], v[26:29]
	v_mfma_f32_16x16x32_bf16 v[50:53], v[192:195], v[184:187], v[50:53]
	v_mfma_f32_16x16x32_bf16 v[18:21], v[220:223], v[184:187], v[18:21]
	s_setprio 0
	s_mov_b32 m0, s11
	v_lshl_add_u64 v[226:227], s[16:17], 0, v[0:1]
	s_barrier
	ds_read_b128 v[152:155], v179 offset:16384
	ds_read_b128 v[156:159], v179 offset:17408
	ds_read_b128 v[160:163], v179 offset:18432
	ds_read_b128 v[164:167], v179 offset:19456
	ds_read_b128 v[168:171], v179 offset:20480
	ds_read_b128 v[172:175], v179 offset:21504
	ds_read_b128 v[180:183], v179 offset:22528
	ds_read_b128 v[184:187], v179 offset:23552
	global_load_lds_dwordx4 v[226:227], off
	v_lshl_add_u64 v[228:229], s[16:17], 0, v[138:139]
	s_mov_b32 m0, s34
	s_nop 0
	global_load_lds_dwordx4 v[228:229], off
	s_barrier
	s_waitcnt lgkmcnt(0)
	s_setprio 1
	v_mfma_f32_16x16x32_bf16 v[102:105], v[130:133], v[152:155], v[102:105]
	v_mfma_f32_16x16x32_bf16 v[78:81], v[144:147], v[152:155], v[78:81]
	v_mfma_f32_16x16x32_bf16 v[98:101], v[130:133], v[160:163], v[98:101]
	v_mfma_f32_16x16x32_bf16 v[74:77], v[144:147], v[160:163], v[74:77]
	v_mfma_f32_16x16x32_bf16 v[90:93], v[130:133], v[168:171], v[90:93]
	v_mfma_f32_16x16x32_bf16 v[66:69], v[144:147], v[168:171], v[66:69]
	v_mfma_f32_16x16x32_bf16 v[86:89], v[130:133], v[180:183], v[86:89]
	v_mfma_f32_16x16x32_bf16 v[58:61], v[144:147], v[180:183], v[58:61]
	v_mfma_f32_16x16x32_bf16 v[102:105], v[134:137], v[156:159], v[102:105]
	v_mfma_f32_16x16x32_bf16 v[78:81], v[148:151], v[156:159], v[78:81]
	v_mfma_f32_16x16x32_bf16 v[98:101], v[134:137], v[164:167], v[98:101]
	v_mfma_f32_16x16x32_bf16 v[74:77], v[148:151], v[164:167], v[74:77]
	v_mfma_f32_16x16x32_bf16 v[90:93], v[134:137], v[172:175], v[90:93]
	v_mfma_f32_16x16x32_bf16 v[66:69], v[148:151], v[172:175], v[66:69]
	v_mfma_f32_16x16x32_bf16 v[86:89], v[134:137], v[184:187], v[86:89]
	v_mfma_f32_16x16x32_bf16 v[58:61], v[148:151], v[184:187], v[58:61]
	s_setprio 0
	s_barrier
; #define PG8_STAGE(bufoff, gbase, voff) do { _Pragma("unroll") for (int _i = 0; _i < 2; ++_i) \
;         __builtin_amdgcn_global_load_lds((const unsigned*)((const char*)(gbase) + (voff)[_i]), (LAS unsigned*)(lds + (bufoff) + ldsw + _i * 8192), 16, 0, 0); } while (0)
; #define PG8_STAGE_A(bufoff, gbase, h, vv) do { if constexpr (GATHER) { _Pragma("unroll") for (int _i = 0; _i < 2; ++_i) \
;         __builtin_amdgcn_global_load_lds((const unsigned*)((const char*)(gbase) + (vv)[h][_i]), (LAS unsigned*)(lds + (bufoff) + ldsw + _i * 8192), 16, 0, 0); } \
;         else { PG8_STAGE(bufoff, (gbase) + (h) * hstepA, voffA); } } while (0)
; #define PG8_LDA(dst, b, h) do { _Pragma("unroll") for (int m = 0; m < 4; ++m) _Pragma("unroll") for (int k = 0; k < 2; ++k) dst[m][k] = *(const LAS bf16x8*)(lds + PG8_SA(b, h) + aoff + m * 2048 + k * 1024); } while (0)
; #define PG8_LDB(dst, b, h) do { _Pragma("unroll") for (int n = 0; n < 2; ++n) _Pragma("unroll") for (int k = 0; k < 2; ++k) dst[n][k] = *(const LAS bf16x8*)(lds + PG8_SB(b, h) + boff + n * 2048 + k * 1024); } while (0)
; #define PG8_MMA(ai, bj, At, Bt) do { __builtin_amdgcn_s_setprio(1); _Pragma("unroll") for (int m = 0; m < 4; ++m) _Pragma("unroll") for (int n = 0; n < 2; ++n) _Pragma("unroll") for (int k = 0; k < 2; ++k) \
;         acc[ai][bj][m][n] = __builtin_amdgcn_mfma_f32_16x16x32_bf16(Bt[n][k], At[m][k], acc[ai][bj][m][n], 0, 0, 0); __builtin_amdgcn_s_setprio(0); } while (0)
; #define PG8_WAIT_V(n) asm volatile("s_waitcnt vmcnt(" #n ")" ::: "memory")
; #define PG8_WAIT_L(n) asm volatile("s_waitcnt lgkmcnt(" #n ")" ::: "memory")
; #define PG8_BAR __builtin_amdgcn_s_barrier()
; template <class Epi, class Sched>
; __device__ __forceinline__ void gemm_phase(LAS unsigned char* lds, const int K, const int lda, const int ldb, const Sched& S, const Epi& E) {
;     ...
;             PG8_BAR; PG8_WAIT_L(0); PG8_MMA(1, 0, At, B0); PG8_BAR; PG8_SCHED;
;             PG8_STAGE(PG8_SB(0, 1), b2 + hstepB, voffB);
;             PG8_WAIT_V(6); PG8_BAR; PG8_MMA(1, 1, At, B1); PG8_BAR;
;             PG8_LDB(B0, 1, 0); PG8_SCHED; PG8_LDA(At, 1, 0); PG8_STAGE_A(PG8_SA(0, 1), a2, 1, vcur);
;             PG8_WAIT_L(8); PG8_BAR; PG8_WAIT_L(0); PG8_MMA(0, 0, At, B0); PG8_BAR; PG8_SCHED;
;             PG8_LDB(B1, 1, 1); PG8_STAGE(PG8_SB(1, 0), b3, voffB);
;             PG8_BAR; PG8_WAIT_L(0); PG8_MMA(0, 1, At, B1); PG8_BAR;
	s_add_u32 s44, s14, 0x40000
	s_addc_u32 s45, s15, 0
	s_add_i32 s2, s2, s30
	v_lshl_add_u64 v[130:131], s[44:45], 0, v[0:1]
	s_mov_b32 m0, s2
	s_nop 0
	global_load_lds_dwordx4 v[130:131], off
	v_lshl_add_u64 v[130:131], s[44:45], 0, v[138:139]
	s_add_i32 m0, s2, 0x2000
	s_nop 0
	global_load_lds_dwordx4 v[130:131], off
	s_waitcnt vmcnt(6)
	s_barrier
	s_setprio 1
	v_mfma_f32_16x16x32_bf16 v[46:49], v[188:191], v[152:155], v[46:49]
	v_mfma_f32_16x16x32_bf16 v[14:17], v[216:219], v[152:155], v[14:17]
	v_mfma_f32_16x16x32_bf16 v[38:41], v[188:191], v[160:163], v[38:41]
	v_mfma_f32_16x16x32_bf16 v[10:13], v[216:219], v[160:163], v[10:13]
	v_mfma_f32_16x16x32_bf16 v[30:33], v[188:191], v[168:171], v[30:33]
	v_mfma_f32_16x16x32_bf16 v[6:9], v[216:219], v[168:171], v[6:9]
	v_mfma_f32_16x16x32_bf16 v[22:25], v[188:191], v[180:183], v[22:25]
	v_mfma_f32_16x16x32_bf16 v[2:5], v[216:219], v[180:183], v[2:5]
	v_mfma_f32_16x16x32_bf16 v[46:49], v[192:195], v[156:159], v[46:49]
	v_mfma_f32_16x16x32_bf16 v[14:17], v[220:223], v[156:159], v[14:17]
	v_mfma_f32_16x16x32_bf16 v[38:41], v[192:195], v[164:167], v[38:41]
	v_mfma_f32_16x16x32_bf16 v[10:13], v[220:223], v[164:167], v[10:13]
	v_mfma_f32_16x16x32_bf16 v[30:33], v[192:195], v[172:175], v[30:33]
	v_mfma_f32_16x16x32_bf16 v[6:9], v[220:223], v[172:175], v[6:9]
	v_mfma_f32_16x16x32_bf16 v[22:25], v[192:195], v[184:187], v[22:25]
	v_mfma_f32_16x16x32_bf16 v[2:5], v[220:223], v[184:187], v[2:5]
	s_setprio 0
	s_add_i32 s2, 0, 0x18000
	v_add_u32_e32 v148, s2, v177
	s_barrier
	ds_read_b128 v[130:133], v148
	ds_read_b128 v[134:137], v148 offset:1024
	ds_read_b128 v[144:147], v148 offset:2048
	ds_read_b128 v[148:151], v148 offset:3072
	s_add_u32 s16, s16, 0x40000
	s_addc_u32 s17, s17, 0
	s_mov_b32 m0, s35
	v_lshl_add_u64 v[188:189], s[16:17], 0, v[0:1]
	ds_read_b128 v[152:155], v179 offset:32768
	ds_read_b128 v[156:159], v179 offset:33792
	ds_read_b128 v[160:163], v179 offset:34816
	ds_read_b128 v[164:167], v179 offset:35840
	ds_read_b128 v[168:171], v179 offset:36864
	ds_read_b128 v[172:175], v179 offset:37888
	ds_read_b128 v[180:183], v179 offset:38912
	ds_read_b128 v[184:187], v179 offset:39936
	global_load_lds_dwordx4 v[188:189], off
	v_lshl_add_u64 v[188:189], s[16:17], 0, v[138:139]
	s_mov_b32 m0, s36
	s_nop 0
	global_load_lds_dwordx4 v[188:189], off
	s_waitcnt lgkmcnt(8)
	s_barrier
	s_waitcnt lgkmcnt(0)
	s_setprio 1
	v_mfma_f32_16x16x32_bf16 v[126:129], v[130:133], v[152:155], v[126:129]
	v_mfma_f32_16x16x32_bf16 v[110:113], v[144:147], v[152:155], v[110:113]
	v_mfma_f32_16x16x32_bf16 v[122:125], v[130:133], v[160:163], v[122:125]
	v_mfma_f32_16x16x32_bf16 v[106:109], v[144:147], v[160:163], v[106:109]
	v_mfma_f32_16x16x32_bf16 v[118:121], v[130:133], v[168:171], v[118:121]
	v_mfma_f32_16x16x32_bf16 v[94:97], v[144:147], v[168:171], v[94:97]
	v_mfma_f32_16x16x32_bf16 v[114:117], v[130:133], v[180:183], v[114:117]
	v_mfma_f32_16x16x32_bf16 v[82:85], v[144:147], v[180:183], v[82:85]
	v_mfma_f32_16x16x32_bf16 v[126:129], v[134:137], v[156:159], v[126:129]
	v_mfma_f32_16x16x32_bf16 v[110:113], v[148:151], v[156:159], v[110:113]
	v_mfma_f32_16x16x32_bf16 v[122:125], v[134:137], v[164:167], v[122:125]
	v_mfma_f32_16x16x32_bf16 v[106:109], v[148:151], v[164:167], v[106:109]
	v_mfma_f32_16x16x32_bf16 v[118:121], v[134:137], v[172:175], v[118:121]
	v_mfma_f32_16x16x32_bf16 v[94:97], v[148:151], v[172:175], v[94:97]
	v_mfma_f32_16x16x32_bf16 v[114:117], v[134:137], v[184:187], v[114:117]
	v_mfma_f32_16x16x32_bf16 v[82:85], v[148:151], v[184:187], v[82:85]
	s_setprio 0
	s_barrier
	s_add_i32 s3, 0, 0x1c000
	s_add_i32 s2, s2, s30
	v_add_u32_e32 v220, s3, v177
	v_lshl_add_u64 v[214:215], v[214:215], 0, s[64:65]
	s_mov_b32 m0, s2
	ds_read_b128 v[188:191], v220
	ds_read_b128 v[192:195], v220 offset:1024
	ds_read_b128 v[216:219], v220 offset:2048
	ds_read_b128 v[220:223], v220 offset:3072
	global_load_lds_dwordx4 v[214:215], off
	v_lshl_add_u64 v[214:215], v[224:225], 0, s[64:65]
	s_add_i32 m0, s2, 0x2000
	s_nop 0
	global_load_lds_dwordx4 v[214:215], off
	s_barrier
	s_waitcnt lgkmcnt(0)
	s_setprio 1
	v_mfma_f32_16x16x32_bf16 v[70:73], v[188:191], v[152:155], v[70:73]
	v_mfma_f32_16x16x32_bf16 v[42:45], v[216:219], v[152:155], v[42:45]
	v_mfma_f32_16x16x32_bf16 v[62:65], v[188:191], v[160:163], v[62:65]
	v_mfma_f32_16x16x32_bf16 v[34:37], v[216:219], v[160:163], v[34:37]
	v_mfma_f32_16x16x32_bf16 v[54:57], v[188:191], v[168:171], v[54:57]
	v_mfma_f32_16x16x32_bf16 v[26:29], v[216:219], v[168:171], v[26:29]
	v_mfma_f32_16x16x32_bf16 v[50:53], v[188:191], v[180:183], v[50:53]
	v_mfma_f32_16x16x32_bf16 v[18:21], v[216:219], v[180:183], v[18:21]
	v_mfma_f32_16x16x32_bf16 v[70:73], v[192:195], v[156:159], v[70:73]
	v_mfma_f32_16x16x32_bf16 v[42:45], v[220:223], v[156:159], v[42:45]
	v_mfma_f32_16x16x32_bf16 v[62:65], v[192:195], v[164:167], v[62:65]
	v_mfma_f32_16x16x32_bf16 v[34:37], v[220:223], v[164:167], v[34:37]
	v_mfma_f32_16x16x32_bf16 v[54:57], v[192:195], v[172:175], v[54:57]
	v_mfma_f32_16x16x32_bf16 v[26:29], v[220:223], v[172:175], v[26:29]
	v_mfma_f32_16x16x32_bf16 v[50:53], v[192:195], v[184:187], v[50:53]
	v_mfma_f32_16x16x32_bf16 v[18:21], v[220:223], v[184:187], v[18:21]
	s_setprio 0
	s_mov_b32 m0, s37
	v_lshl_add_u64 v[214:215], v[226:227], 0, s[64:65]
	s_barrier
	ds_read_b128 v[152:155], v179 offset:49152
	ds_read_b128 v[156:159], v179 offset:50176
	ds_read_b128 v[160:163], v179 offset:51200
	ds_read_b128 v[164:167], v179 offset:52224
	ds_read_b128 v[168:171], v179 offset:53248
	ds_read_b128 v[172:175], v179 offset:54272
	ds_read_b128 v[180:183], v179 offset:55296
	ds_read_b128 v[184:187], v179 offset:56320
	global_load_lds_dwordx4 v[214:215], off
	v_lshl_add_u64 v[214:215], v[228:229], 0, s[64:65]
	s_mov_b32 m0, s38
	s_nop 0
	global_load_lds_dwordx4 v[214:215], off
	s_barrier
; #define PG8_STAGE(bufoff, gbase, voff) do { _Pragma("unroll") for (int _i = 0; _i < 2; ++_i) \
;         __builtin_amdgcn_global_load_lds((const unsigned*)((const char*)(gbase) + (voff)[_i]), (LAS unsigned*)(lds + (bufoff) + ldsw + _i * 8192), 16, 0, 0); } while (0)
; #define PG8_STAGE_A(bufoff, gbase, h, vv) do { if constexpr (GATHER) { _Pragma("unroll") for (int _i = 0; _i < 2; ++_i) \
;         __builtin_amdgcn_global_load_lds((const unsigned*)((const char*)(gbase) + (vv)[h][_i]), (LAS unsigned*)(lds + (bufoff) + ldsw + _i * 8192), 16, 0, 0); } \
;         else { PG8_STAGE(bufoff, (gbase) + (h) * hstepA, voffA); } } while (0)
; #define PG8_LDA(dst, b, h) do { _Pragma("unroll") for (int m = 0; m < 4; ++m) _Pragma("unroll") for (int k = 0; k < 2; ++k) dst[m][k] = *(const LAS bf16x8*)(lds + PG8_SA(b, h) + aoff + m * 2048 + k * 1024); } while (0)
; #define PG8_MMA(ai, bj, At, Bt) do { __builtin_amdgcn_s_setprio(1); _Pragma("unroll") for (int m = 0; m < 4; ++m) _Pragma("unroll") for (int n = 0; n < 2; ++n) _Pragma("unroll") for (int k = 0; k < 2; ++k) \
;         acc[ai][bj][m][n] = __builtin_amdgcn_mfma_f32_16x16x32_bf16(Bt[n][k], At[m][k], acc[ai][bj][m][n], 0, 0, 0); __builtin_amdgcn_s_setprio(0); } while (0)
; #define PG8_WAIT_V(n) asm volatile("s_waitcnt vmcnt(" #n ")" ::: "memory")
; #define PG8_BAR __builtin_amdgcn_s_barrier()
; template <class Epi, class Sched>
; __device__ __forceinline__ void gemm_phase(LAS unsigned char* lds, const int K, const int lda, const int ldb, const Sched& S, const Epi& E) {
;     ...
;             PG8_BAR; PG8_WAIT_L(0); PG8_MMA(0, 1, At, B1); PG8_BAR;
;             PG8_LDA(At, 1, 1); PG8_STAGE_A(PG8_SA(1, 0), a3, 0, vcur);
;             PG8_BAR; PG8_WAIT_L(0); PG8_MMA(1, 0, At, B0); PG8_BAR; PG8_SCHED;
;             PG8_STAGE(PG8_SB(1, 1), b3 + hstepB, voffB);
;             PG8_WAIT_V(6); PG8_BAR; PG8_MMA(1, 1, At, B1); PG8_BAR;
;         }
;     __device__ __forceinline__ void operator()(const Acc& acc, const Unit& u, int wr, int wc, int fr, int fq) const {
;         const int row0 = u.pm * BM + wr * 64 + fr, col0 = u.pn * BM + wc * 32 + 4 * fq;
;         const float* gp = (u.pm < SEQ / BM) ? gate_x : gate_c;
;         f32x4 gv[2][2];
; #pragma unroll
;         for (int bj = 0; bj < 2; ++bj)
; #pragma unroll
;             for (int n = 0; n < 2; ++n) gv[bj][n] = *(const f32x4*)(gp + col0 + bj * HALF + n * 16);
	s_waitcnt lgkmcnt(0)
	s_setprio 1
	v_mfma_f32_16x16x32_bf16 v[102:105], v[130:133], v[152:155], v[102:105]
	v_mfma_f32_16x16x32_bf16 v[78:81], v[144:147], v[152:155], v[78:81]
	v_mfma_f32_16x16x32_bf16 v[98:101], v[130:133], v[160:163], v[98:101]
	v_mfma_f32_16x16x32_bf16 v[74:77], v[144:147], v[160:163], v[74:77]
	v_mfma_f32_16x16x32_bf16 v[90:93], v[130:133], v[168:171], v[90:93]
	v_mfma_f32_16x16x32_bf16 v[66:69], v[144:147], v[168:171], v[66:69]
	v_mfma_f32_16x16x32_bf16 v[86:89], v[130:133], v[180:183], v[86:89]
	v_mfma_f32_16x16x32_bf16 v[58:61], v[144:147], v[180:183], v[58:61]
	v_mfma_f32_16x16x32_bf16 v[102:105], v[134:137], v[156:159], v[102:105]
	v_mfma_f32_16x16x32_bf16 v[78:81], v[148:151], v[156:159], v[78:81]
	v_mfma_f32_16x16x32_bf16 v[98:101], v[134:137], v[164:167], v[98:101]
	v_mfma_f32_16x16x32_bf16 v[74:77], v[148:151], v[164:167], v[74:77]
	v_mfma_f32_16x16x32_bf16 v[90:93], v[134:137], v[172:175], v[90:93]
	v_mfma_f32_16x16x32_bf16 v[66:69], v[148:151], v[172:175], v[66:69]
	v_mfma_f32_16x16x32_bf16 v[86:89], v[134:137], v[184:187], v[86:89]
	v_mfma_f32_16x16x32_bf16 v[58:61], v[148:151], v[184:187], v[58:61]
	s_setprio 0
	s_barrier
	s_add_u32 s14, s14, 0x40080
	s_addc_u32 s15, s15, 0
	s_add_i32 s2, s3, s30
	v_lshl_add_u64 v[130:131], s[14:15], 0, v[0:1]
	s_mov_b32 m0, s2
	s_nop 0
	global_load_lds_dwordx4 v[130:131], off
	v_lshl_add_u64 v[130:131], s[14:15], 0, v[138:139]
	s_add_i32 m0, s2, 0x2000
	s_nop 0
	global_load_lds_dwordx4 v[130:131], off
	s_waitcnt vmcnt(6)
	s_barrier
	s_setprio 1
	v_mfma_f32_16x16x32_bf16 v[46:49], v[188:191], v[152:155], v[46:49]
	v_mfma_f32_16x16x32_bf16 v[14:17], v[216:219], v[152:155], v[14:17]
	v_mfma_f32_16x16x32_bf16 v[38:41], v[188:191], v[160:163], v[38:41]
	v_mfma_f32_16x16x32_bf16 v[10:13], v[216:219], v[160:163], v[10:13]
	v_mfma_f32_16x16x32_bf16 v[30:33], v[188:191], v[168:171], v[30:33]
	v_mfma_f32_16x16x32_bf16 v[6:9], v[216:219], v[168:171], v[6:9]
	v_mfma_f32_16x16x32_bf16 v[22:25], v[188:191], v[180:183], v[22:25]
	v_mfma_f32_16x16x32_bf16 v[2:5], v[216:219], v[180:183], v[2:5]
	v_mfma_f32_16x16x32_bf16 v[46:49], v[192:195], v[156:159], v[46:49]
	v_mfma_f32_16x16x32_bf16 v[14:17], v[220:223], v[156:159], v[14:17]
	v_mfma_f32_16x16x32_bf16 v[38:41], v[192:195], v[164:167], v[38:41]
	v_mfma_f32_16x16x32_bf16 v[10:13], v[220:223], v[164:167], v[10:13]
	v_mfma_f32_16x16x32_bf16 v[30:33], v[192:195], v[172:175], v[30:33]
	v_mfma_f32_16x16x32_bf16 v[6:9], v[220:223], v[172:175], v[6:9]
	v_mfma_f32_16x16x32_bf16 v[22:25], v[192:195], v[184:187], v[22:25]
	v_mfma_f32_16x16x32_bf16 v[2:5], v[220:223], v[184:187], v[2:5]
	s_setprio 0
	s_add_i32 s43, s43, 2
	s_add_u32 s12, s12, 0x100
	s_addc_u32 s13, s13, 0
	s_add_u32 s1, s1, 0x100
	s_addc_u32 s42, s42, 0
	s_cmp_gt_u32 s43, 13
	s_barrier
	s_cbranch_scc0 .LBB0_711
	v_lshl_add_u32 v132, s10, 8, v176
	v_ashrrev_i32_e32 v133, 31, v132
	v_or_b32_e32 v136, 16, v132
	v_lshl_or_b32 v130, s41, 8, v178
	v_lshlrev_b64 v[144:145], 12, v[132:133]
	v_ashrrev_i32_e32 v137, 31, v136
	s_mov_b64 s[2:3], 0x80000
	v_ashrrev_i32_e32 v131, 31, v130
	v_lshlrev_b64 v[164:165], 12, v[136:137]
	v_or_b32_e32 v136, 32, v132
	v_lshl_add_u64 v[170:171], v[144:145], 0, s[2:3]
	s_mov_b64 s[2:3], 0x90000
	v_lshlrev_b64 v[162:163], 2, v[130:131]
	v_ashrrev_i32_e32 v137, 31, v136
	v_or_b32_e32 v132, 48, v132
	v_lshl_add_u64 v[172:173], v[144:145], 0, s[2:3]
	s_mov_b64 s[2:3], 0xa0000
	v_lshl_add_u64 v[130:131], s[92:93], 0, v[162:163]
	v_lshl_add_u64 v[134:135], s[22:23], 0, v[162:163]
	v_lshlrev_b64 v[166:167], 12, v[136:137]
	v_ashrrev_i32_e32 v133, 31, v132
	v_lshl_add_u64 v[174:175], v[144:145], 0, s[2:3]
	global_load_dwordx4 v[180:183], v[130:131], off
	v_lshl_add_u64 v[146:147], v[134:135], 0, v[144:145]
	v_lshl_add_u64 v[150:151], v[134:135], 0, v[166:167]
	v_lshlrev_b64 v[168:169], 12, v[132:133]
	v_lshl_add_u64 v[154:155], v[134:135], 0, v[170:171]
	v_lshl_add_u64 v[158:159], v[134:135], 0, v[174:175]
	v_lshl_add_u64 v[148:149], v[134:135], 0, v[164:165]
	global_load_dwordx4 v[184:187], v[146:147], off
	global_load_dwordx4 v[188:191], v[148:149], off
	v_lshl_add_u64 v[152:153], v[134:135], 0, v[168:169]
	global_load_dwordx4 v[192:195], v[150:151], off
	global_load_dwordx4 v[216:219], v[152:153], off
	v_lshl_add_u64 v[156:157], v[134:135], 0, v[172:173]
	global_load_dwordx4 v[220:223], v[154:155], off
	global_load_dwordx4 v[224:227], v[156:157], off
	global_load_dwordx4 v[228:231], v[158:159], off
	s_mov_b64 s[2:3], 0xb0000
	v_lshl_add_u64 v[214:215], v[144:145], 0, s[2:3]
	v_lshl_add_u64 v[160:161], v[134:135], 0, v[214:215]
	global_load_dwordx4 v[232:235], v[160:161], off
	global_load_dwordx4 v[236:239], v[130:131], off offset:64
	global_load_dwordx4 v[134:137], v[130:131], off offset:512
	s_nop 0
	global_load_dwordx4 v[130:133], v[130:131], off offset:576
	v_lshl_add_u64 v[144:145], s[22:23], 0, v[144:145]
	v_lshl_add_u64 v[144:145], v[144:145], 0, v[162:163]
	v_lshl_add_u64 v[164:165], s[22:23], 0, v[164:165]
	v_lshl_add_u64 v[166:167], s[22:23], 0, v[166:167]
	v_lshl_add_u64 v[168:169], s[22:23], 0, v[168:169]
	v_lshl_add_u64 v[170:171], s[22:23], 0, v[170:171]
	v_lshl_add_u64 v[172:173], s[22:23], 0, v[172:173]
	v_lshl_add_u64 v[174:175], s[22:23], 0, v[174:175]
	v_lshl_add_u64 v[214:215], s[22:23], 0, v[214:215]
	v_lshl_add_u64 v[164:165], v[164:165], 0, v[162:163]
	v_lshl_add_u64 v[166:167], v[166:167], 0, v[162:163]
	v_lshl_add_u64 v[168:169], v[168:169], 0, v[162:163]
	v_lshl_add_u64 v[170:171], v[170:171], 0, v[162:163]
	v_lshl_add_u64 v[172:173], v[172:173], 0, v[162:163]
	v_lshl_add_u64 v[174:175], v[174:175], 0, v[162:163]
	v_lshl_add_u64 v[162:163], v[214:215], 0, v[162:163]
	s_waitcnt vmcnt(0)
;     __device__ __forceinline__ void operator()(const Acc& acc, const Unit& u, int wr, int wc, int fr, int fq) const {
;     ...
; #pragma unroll
;         for (int bj = 0; bj < 2; ++bj)
; #pragma unroll
;             for (int n = 0; n < 2; ++n) { f32x4 xin[2][4];
; #pragma unroll
;                 for (int ai = 0; ai < 2; ++ai)
; #pragma unroll
;                     for (int m = 0; m < 4; ++m) xin[ai][m] = *(const f32x4*)(X + (size_t)(row0 + ai * HALF + m * 16) * D + col0 + bj * HALF + n * 16);
; #pragma unroll
;                 for (int ai = 0; ai < 2; ++ai)
; #pragma unroll
;                     for (int m = 0; m < 4; ++m) *(f32x4*)(X + (size_t)(row0 + ai * HALF + m * 16) * D + col0 + bj * HALF + n * 16) = xin[ai][m] + gv[bj][n] * acc[ai][bj][m][n];
;                 __builtin_amdgcn_sched_barrier(0); }
	v_pk_fma_f32 v[128:129], v[128:129], v[182:183], v[186:187]
	v_pk_fma_f32 v[126:127], v[126:127], v[180:181], v[184:185]
	v_pk_fma_f32 v[124:125], v[124:125], v[182:183], v[190:191]
	v_pk_fma_f32 v[122:123], v[122:123], v[180:181], v[188:189]
	v_pk_fma_f32 v[120:121], v[120:121], v[182:183], v[194:195]
	v_pk_fma_f32 v[118:119], v[118:119], v[180:181], v[192:193]
	v_pk_fma_f32 v[116:117], v[116:117], v[182:183], v[218:219]
	v_pk_fma_f32 v[114:115], v[114:115], v[180:181], v[216:217]
	v_pk_fma_f32 v[104:105], v[104:105], v[182:183], v[222:223]
	v_pk_fma_f32 v[102:103], v[102:103], v[180:181], v[220:221]
	v_pk_fma_f32 v[100:101], v[100:101], v[182:183], v[226:227]
	v_pk_fma_f32 v[98:99], v[98:99], v[180:181], v[224:225]
	v_pk_fma_f32 v[92:93], v[92:93], v[182:183], v[230:231]
	v_pk_fma_f32 v[90:91], v[90:91], v[180:181], v[228:229]
	v_pk_fma_f32 v[88:89], v[88:89], v[182:183], v[234:235]
	v_pk_fma_f32 v[86:87], v[86:87], v[180:181], v[232:233]
	global_store_dwordx4 v[144:145], v[126:129], off
	global_store_dwordx4 v[164:165], v[122:125], off
	global_store_dwordx4 v[166:167], v[118:121], off
	global_store_dwordx4 v[168:169], v[114:117], off
	global_store_dwordx4 v[170:171], v[102:105], off
	global_store_dwordx4 v[172:173], v[98:101], off
	global_store_dwordx4 v[174:175], v[90:93], off
	global_store_dwordx4 v[162:163], v[86:89], off
	global_load_dwordx4 v[86:89], v[146:147], off offset:64
	s_nop 0
	global_load_dwordx4 v[90:93], v[148:149], off offset:64
	global_load_dwordx4 v[98:101], v[150:151], off offset:64
	global_load_dwordx4 v[102:105], v[152:153], off offset:64
	global_load_dwordx4 v[114:117], v[154:155], off offset:64
	global_load_dwordx4 v[118:121], v[156:157], off offset:64
	global_load_dwordx4 v[122:125], v[158:159], off offset:64
	global_load_dwordx4 v[126:129], v[160:161], off offset:64
	s_waitcnt vmcnt(0)
	v_pk_fma_f32 v[88:89], v[112:113], v[238:239], v[88:89]
	v_pk_fma_f32 v[86:87], v[110:111], v[236:237], v[86:87]
	v_pk_fma_f32 v[92:93], v[108:109], v[238:239], v[92:93]
	v_pk_fma_f32 v[90:91], v[106:107], v[236:237], v[90:91]
	v_pk_fma_f32 v[96:97], v[96:97], v[238:239], v[100:101]
	v_pk_fma_f32 v[94:95], v[94:95], v[236:237], v[98:99]
	v_pk_fma_f32 v[84:85], v[84:85], v[238:239], v[104:105]
	v_pk_fma_f32 v[82:83], v[82:83], v[236:237], v[102:103]
	v_pk_fma_f32 v[80:81], v[80:81], v[238:239], v[116:117]
	v_pk_fma_f32 v[78:79], v[78:79], v[236:237], v[114:115]
	v_pk_fma_f32 v[76:77], v[76:77], v[238:239], v[120:121]
	v_pk_fma_f32 v[74:75], v[74:75], v[236:237], v[118:119]
	v_pk_fma_f32 v[68:69], v[68:69], v[238:239], v[124:125]
	v_pk_fma_f32 v[66:67], v[66:67], v[236:237], v[122:123]
	v_pk_fma_f32 v[60:61], v[60:61], v[238:239], v[128:129]
	v_pk_fma_f32 v[58:59], v[58:59], v[236:237], v[126:127]
	global_store_dwordx4 v[144:145], v[86:89], off offset:64
	global_store_dwordx4 v[164:165], v[90:93], off offset:64
	global_store_dwordx4 v[166:167], v[94:97], off offset:64
	global_store_dwordx4 v[168:169], v[82:85], off offset:64
	global_store_dwordx4 v[170:171], v[78:81], off offset:64
	global_store_dwordx4 v[172:173], v[74:77], off offset:64
	global_store_dwordx4 v[174:175], v[66:69], off offset:64
	global_store_dwordx4 v[162:163], v[58:61], off offset:64
	global_load_dwordx4 v[58:61], v[146:147], off offset:512
	s_nop 0
	global_load_dwordx4 v[66:69], v[148:149], off offset:512
	global_load_dwordx4 v[74:77], v[150:151], off offset:512
	global_load_dwordx4 v[78:81], v[152:153], off offset:512
	global_load_dwordx4 v[82:85], v[154:155], off offset:512
	global_load_dwordx4 v[86:89], v[156:157], off offset:512
	global_load_dwordx4 v[90:93], v[158:159], off offset:512
	global_load_dwordx4 v[94:97], v[160:161], off offset:512
	s_waitcnt vmcnt(0)
	v_pk_fma_f32 v[60:61], v[72:73], v[136:137], v[60:61]
	v_pk_fma_f32 v[58:59], v[70:71], v[134:135], v[58:59]
	v_pk_fma_f32 v[64:65], v[64:65], v[136:137], v[68:69]
	v_pk_fma_f32 v[62:63], v[62:63], v[134:135], v[66:67]
	v_pk_fma_f32 v[56:57], v[56:57], v[136:137], v[76:77]
	v_pk_fma_f32 v[54:55], v[54:55], v[134:135], v[74:75]
	v_pk_fma_f32 v[52:53], v[52:53], v[136:137], v[80:81]
	v_pk_fma_f32 v[50:51], v[50:51], v[134:135], v[78:79]
	v_pk_fma_f32 v[48:49], v[48:49], v[136:137], v[84:85]
	v_pk_fma_f32 v[46:47], v[46:47], v[134:135], v[82:83]
	v_pk_fma_f32 v[40:41], v[40:41], v[136:137], v[88:89]
	v_pk_fma_f32 v[38:39], v[38:39], v[134:135], v[86:87]
	v_pk_fma_f32 v[32:33], v[32:33], v[136:137], v[92:93]
	v_pk_fma_f32 v[30:31], v[30:31], v[134:135], v[90:91]
	v_pk_fma_f32 v[24:25], v[24:25], v[136:137], v[96:97]
	v_pk_fma_f32 v[22:23], v[22:23], v[134:135], v[94:95]
	global_store_dwordx4 v[144:145], v[58:61], off offset:512
	global_store_dwordx4 v[164:165], v[62:65], off offset:512
	global_store_dwordx4 v[166:167], v[54:57], off offset:512
	global_store_dwordx4 v[168:169], v[50:53], off offset:512
	global_store_dwordx4 v[170:171], v[46:49], off offset:512
	global_store_dwordx4 v[172:173], v[38:41], off offset:512
	global_store_dwordx4 v[174:175], v[30:33], off offset:512
	global_store_dwordx4 v[162:163], v[22:25], off offset:512
	global_load_dwordx4 v[22:25], v[146:147], off offset:576
	s_nop 0
	global_load_dwordx4 v[30:33], v[148:149], off offset:576
	global_load_dwordx4 v[38:41], v[150:151], off offset:576
	global_load_dwordx4 v[46:49], v[152:153], off offset:576
	global_load_dwordx4 v[50:53], v[154:155], off offset:576
	global_load_dwordx4 v[54:57], v[156:157], off offset:576
	global_load_dwordx4 v[58:61], v[158:159], off offset:576
	global_load_dwordx4 v[62:65], v[160:161], off offset:576
	s_waitcnt vmcnt(0)
	v_pk_fma_f32 v[24:25], v[44:45], v[132:133], v[24:25]
	v_pk_fma_f32 v[22:23], v[42:43], v[130:131], v[22:23]
	v_pk_fma_f32 v[32:33], v[36:37], v[132:133], v[32:33]
	v_pk_fma_f32 v[30:31], v[34:35], v[130:131], v[30:31]
	v_pk_fma_f32 v[28:29], v[28:29], v[132:133], v[40:41]
	v_pk_fma_f32 v[26:27], v[26:27], v[130:131], v[38:39]
	v_pk_fma_f32 v[20:21], v[20:21], v[132:133], v[48:49]
	v_pk_fma_f32 v[18:19], v[18:19], v[130:131], v[46:47]
	v_pk_fma_f32 v[16:17], v[16:17], v[132:133], v[52:53]
	v_pk_fma_f32 v[14:15], v[14:15], v[130:131], v[50:51]
	v_pk_fma_f32 v[12:13], v[12:13], v[132:133], v[56:57]
	v_pk_fma_f32 v[10:11], v[10:11], v[130:131], v[54:55]
	v_pk_fma_f32 v[8:9], v[8:9], v[132:133], v[60:61]
	v_pk_fma_f32 v[6:7], v[6:7], v[130:131], v[58:59]
	v_pk_fma_f32 v[4:5], v[4:5], v[132:133], v[64:65]
	v_pk_fma_f32 v[2:3], v[2:3], v[130:131], v[62:63]
	global_store_dwordx4 v[144:145], v[22:25], off offset:576
	global_store_dwordx4 v[164:165], v[30:33], off offset:576
	global_store_dwordx4 v[166:167], v[26:29], off offset:576
	global_store_dwordx4 v[168:169], v[18:21], off offset:576
	global_store_dwordx4 v[170:171], v[14:17], off offset:576
	global_store_dwordx4 v[172:173], v[10:13], off offset:576
	global_store_dwordx4 v[174:175], v[6:9], off offset:576
	global_store_dwordx4 v[162:163], v[2:5], off offset:576
	s_and_b64 vcc, exec, s[8:9]
	s_mov_b32 s41, s40
	s_mov_b32 s10, s0
	s_mov_b64 s[14:15], s[6:7]
	s_mov_b64 s[12:13], s[4:5]
	s_cbranch_vccz .LBB0_708
; #define PG8_WAIT_V(n) asm volatile("s_waitcnt vmcnt(" #n ")" ::: "memory")
; #define PG8_BAR __builtin_amdgcn_s_barrier()
; template <class Epi, class Sched>
; __device__ __forceinline__ void gemm_phase(LAS unsigned char* lds, const int K, const int lda, const int ldb, const Sched& S, const Epi& E) {
;     ...
;     PG8_WAIT_V(0);
;     if (wr == 0) PG8_BAR;
;     PG8_BAR;
	s_waitcnt vmcnt(0)
	s_cmpk_gt_u32 s19, 0xff
	s_cbranch_scc1 .LBB0_715
	s_barrier

; #define PG8_STAGE(bufoff, gbase, voff) do { _Pragma("unroll") for (int _i = 0; _i < 2; ++_i) \
;         __builtin_amdgcn_global_load_lds((const unsigned*)((const char*)(gbase) + (voff)[_i]), (LAS unsigned*)(lds + (bufoff) + ldsw + _i * 8192), 16, 0, 0); } while (0)
; #define PG8_STAGE_A(bufoff, gbase, h, vv) do { if constexpr (GATHER) { _Pragma("unroll") for (int _i = 0; _i < 2; ++_i) \
;         __builtin_amdgcn_global_load_lds((const unsigned*)((const char*)(gbase) + (vv)[h][_i]), (LAS unsigned*)(lds + (bufoff) + ldsw + _i * 8192), 16, 0, 0); } \
;         else { PG8_STAGE(bufoff, (gbase) + (h) * hstepA, voffA); } } while (0)
; #define PG8_LDA(dst, b, h) do { _Pragma("unroll") for (int m = 0; m < 4; ++m) _Pragma("unroll") for (int k = 0; k < 2; ++k) dst[m][k] = *(const LAS bf16x8*)(lds + PG8_SA(b, h) + aoff + m * 2048 + k * 1024); } while (0)
; #define PG8_LDB(dst, b, h) do { _Pragma("unroll") for (int n = 0; n < 2; ++n) _Pragma("unroll") for (int k = 0; k < 2; ++k) dst[n][k] = *(const LAS bf16x8*)(lds + PG8_SB(b, h) + boff + n * 2048 + k * 1024); } while (0)
; #define PG8_WAIT_L(n) asm volatile("s_waitcnt lgkmcnt(" #n ")" ::: "memory")
; template <class Epi, class Sched>
; __device__ __forceinline__ void gemm_phase(LAS unsigned char* lds, const int K, const int lda, const int ldb, const Sched& S, const Epi& E) {
;     ...
;         for (int t = 0; t < nt; t += 2) {
;             const bool last = (t == nt - 2);
;             const char* a1 = cA + (size_t)(t + 1) * kstep;
;             const char* a2 = last ? nA : cA + (size_t)(t + 2) * kstep; const char* b2 = last ? nB : cB + (size_t)(t + 2) * kstep;
;             const char* a3 = a2 + kstep; const char* b3 = b2 + kstep;
;             PG8_LDB(B0, 0, 0); PG8_SCHED; PG8_LDA(At, 0, 0); PG8_STAGE_A(PG8_SA(1, 1), a1, 1, vcur);
;             if constexpr (GATHER) { if (last) {
; #pragma unroll
;                 for (int h = 0; h < 2; ++h)
; #pragma unroll
;                     for (int i = 0; i < 2; ++i) vcur[h][i] = vnxt[h][i]; } }
;             PG8_WAIT_L(8); PG8_BAR; PG8_WAIT_L(0); PG8_MMA(0, 0, At, B0); PG8_BAR; PG8_SCHED;
;             PG8_LDB(B1, 0, 1); PG8_STAGE(PG8_SB(0, 0), b2, voffB);
;             PG8_BAR; PG8_WAIT_L(0); PG8_MMA(0, 1, At, B1); PG8_BAR;
;             PG8_LDA(At, 0, 1); PG8_STAGE_A(PG8_SA(0, 0), a2, 0, vcur);
;             PG8_BAR; PG8_WAIT_L(0); PG8_MMA(1, 0, At, B0); PG8_BAR; PG8_SCHED;
.LBB0_761:
	s_add_u32 s2, s16, 0xfffc0080
	s_addc_u32 s3, s17, -1
	s_add_i32 s20, 0, 0x10000
	v_add_u32_e32 v140, s20, v143
	ds_read_b128 v[146:149], v140
	ds_read_b128 v[150:153], v140 offset:1024
	ds_read_b128 v[154:157], v140 offset:2048
	ds_read_b128 v[158:161], v140 offset:3072
	s_cmp_eq_u32 s68, 12
	s_cselect_b32 s37, s13, s3
	s_cselect_b32 s36, s12, s2
	s_cselect_b32 s35, s15, s11
	s_cselect_b32 s34, s14, s7
	v_lshl_add_u64 v[140:141], s[16:17], 0, v[136:137]
	s_add_i32 m0, s9, 0xc000
	ds_read_b128 v[162:165], v145
	ds_read_b128 v[166:169], v145 offset:1024
	ds_read_b128 v[170:173], v145 offset:2048
	ds_read_b128 v[174:177], v145 offset:3072
	ds_read_b128 v[178:181], v145 offset:4096
	ds_read_b128 v[182:185], v145 offset:5120
	ds_read_b128 v[186:189], v145 offset:6144
	ds_read_b128 v[190:193], v145 offset:7168
	global_load_lds_dwordx4 v[140:141], off
	v_lshl_add_u64 v[140:141], s[16:17], 0, v[138:139]
	s_add_i32 m0, s9, 0xe000
	s_nop 0
	global_load_lds_dwordx4 v[140:141], off
	s_waitcnt lgkmcnt(8)
	s_barrier
	s_waitcnt lgkmcnt(0)
	s_setprio 1
	v_mfma_f32_16x16x32_bf16 v[126:129], v[146:149], v[162:165], v[126:129]
	v_mfma_f32_16x16x32_bf16 v[122:125], v[154:157], v[162:165], v[122:125]
	v_mfma_f32_16x16x32_bf16 v[118:121], v[146:149], v[170:173], v[118:121]
	v_mfma_f32_16x16x32_bf16 v[110:113], v[154:157], v[170:173], v[110:113]
	v_mfma_f32_16x16x32_bf16 v[102:105], v[146:149], v[178:181], v[102:105]
	v_mfma_f32_16x16x32_bf16 v[94:97], v[154:157], v[178:181], v[94:97]
	v_mfma_f32_16x16x32_bf16 v[86:89], v[146:149], v[186:189], v[86:89]
	v_mfma_f32_16x16x32_bf16 v[78:81], v[154:157], v[186:189], v[78:81]
	v_mfma_f32_16x16x32_bf16 v[126:129], v[150:153], v[166:169], v[126:129]
	v_mfma_f32_16x16x32_bf16 v[122:125], v[158:161], v[166:169], v[122:125]
	v_mfma_f32_16x16x32_bf16 v[118:121], v[150:153], v[174:177], v[118:121]
	v_mfma_f32_16x16x32_bf16 v[110:113], v[158:161], v[174:177], v[110:113]
	v_mfma_f32_16x16x32_bf16 v[102:105], v[150:153], v[182:185], v[102:105]
	v_mfma_f32_16x16x32_bf16 v[94:97], v[158:161], v[182:185], v[94:97]
	v_mfma_f32_16x16x32_bf16 v[86:89], v[150:153], v[190:193], v[86:89]
	v_mfma_f32_16x16x32_bf16 v[78:81], v[158:161], v[190:193], v[78:81]
	s_setprio 0
	s_barrier
	s_add_i32 s2, 0, 0x14000
	v_add_u32_e32 v140, s2, v143
	s_add_i32 s3, s20, s49
	ds_read_b128 v[216:219], v140
	ds_read_b128 v[220:223], v140 offset:1024
	ds_read_b128 v[224:227], v140 offset:2048
	ds_read_b128 v[228:231], v140 offset:3072
	v_lshl_add_u64 v[140:141], s[34:35], 0, v[0:1]
	s_mov_b32 m0, s3
	v_lshl_add_u64 v[194:195], s[34:35], 0, v[134:135]
	global_load_lds_dwordx4 v[140:141], off
	s_add_i32 m0, s3, 0x2000
	s_nop 0
	global_load_lds_dwordx4 v[194:195], off
	s_barrier
	s_waitcnt lgkmcnt(0)
	s_setprio 1
	v_mfma_f32_16x16x32_bf16 v[114:117], v[216:219], v[162:165], v[114:117]
	v_mfma_f32_16x16x32_bf16 v[106:109], v[224:227], v[162:165], v[106:109]
	v_mfma_f32_16x16x32_bf16 v[98:101], v[216:219], v[170:173], v[98:101]
	v_mfma_f32_16x16x32_bf16 v[90:93], v[224:227], v[170:173], v[90:93]
	v_mfma_f32_16x16x32_bf16 v[82:85], v[216:219], v[178:181], v[82:85]
	v_mfma_f32_16x16x32_bf16 v[74:77], v[224:227], v[178:181], v[74:77]
	v_mfma_f32_16x16x32_bf16 v[70:73], v[216:219], v[186:189], v[70:73]
	v_mfma_f32_16x16x32_bf16 v[66:69], v[224:227], v[186:189], v[66:69]
	v_mfma_f32_16x16x32_bf16 v[114:117], v[220:223], v[166:169], v[114:117]
	v_mfma_f32_16x16x32_bf16 v[106:109], v[228:231], v[166:169], v[106:109]
	v_mfma_f32_16x16x32_bf16 v[98:101], v[220:223], v[174:177], v[98:101]
	v_mfma_f32_16x16x32_bf16 v[90:93], v[228:231], v[174:177], v[90:93]
	v_mfma_f32_16x16x32_bf16 v[82:85], v[220:223], v[182:185], v[82:85]
	v_mfma_f32_16x16x32_bf16 v[74:77], v[228:231], v[182:185], v[74:77]
	v_mfma_f32_16x16x32_bf16 v[70:73], v[220:223], v[190:193], v[70:73]
	v_mfma_f32_16x16x32_bf16 v[66:69], v[228:231], v[190:193], v[66:69]
	s_setprio 0
	s_mov_b32 m0, s9
	v_lshl_add_u64 v[214:215], s[36:37], 0, v[130:131]
	s_barrier
	ds_read_b128 v[162:165], v145 offset:16384
	ds_read_b128 v[166:169], v145 offset:17408
	ds_read_b128 v[170:173], v145 offset:18432
	ds_read_b128 v[174:177], v145 offset:19456
	ds_read_b128 v[178:181], v145 offset:20480
	ds_read_b128 v[182:185], v145 offset:21504
	ds_read_b128 v[186:189], v145 offset:22528
	ds_read_b128 v[190:193], v145 offset:23552
	global_load_lds_dwordx4 v[214:215], off
	v_lshl_add_u64 v[232:233], s[36:37], 0, v[132:133]
	s_mov_b32 m0, s53
	s_nop 0
	global_load_lds_dwordx4 v[232:233], off
	s_barrier
	s_waitcnt lgkmcnt(0)
	s_setprio 1
	v_mfma_f32_16x16x32_bf16 v[62:65], v[146:149], v[162:165], v[62:65]
	v_mfma_f32_16x16x32_bf16 v[58:61], v[154:157], v[162:165], v[58:61]
	v_mfma_f32_16x16x32_bf16 v[54:57], v[146:149], v[170:173], v[54:57]
	v_mfma_f32_16x16x32_bf16 v[46:49], v[154:157], v[170:173], v[46:49]
	v_mfma_f32_16x16x32_bf16 v[38:41], v[146:149], v[178:181], v[38:41]
	v_mfma_f32_16x16x32_bf16 v[30:33], v[154:157], v[178:181], v[30:33]
	v_mfma_f32_16x16x32_bf16 v[22:25], v[146:149], v[186:189], v[22:25]
	v_mfma_f32_16x16x32_bf16 v[14:17], v[154:157], v[186:189], v[14:17]
	v_mfma_f32_16x16x32_bf16 v[62:65], v[150:153], v[166:169], v[62:65]
	v_mfma_f32_16x16x32_bf16 v[58:61], v[158:161], v[166:169], v[58:61]
	v_mfma_f32_16x16x32_bf16 v[54:57], v[150:153], v[174:177], v[54:57]
	v_mfma_f32_16x16x32_bf16 v[46:49], v[158:161], v[174:177], v[46:49]
	v_mfma_f32_16x16x32_bf16 v[38:41], v[150:153], v[182:185], v[38:41]
	v_mfma_f32_16x16x32_bf16 v[30:33], v[158:161], v[182:185], v[30:33]
	v_mfma_f32_16x16x32_bf16 v[22:25], v[150:153], v[190:193], v[22:25]
	v_mfma_f32_16x16x32_bf16 v[14:17], v[158:161], v[190:193], v[14:17]
	s_setprio 0
	s_barrier
; #define PG8_STAGE(bufoff, gbase, voff) do { _Pragma("unroll") for (int _i = 0; _i < 2; ++_i) \
;         __builtin_amdgcn_global_load_lds((const unsigned*)((const char*)(gbase) + (voff)[_i]), (LAS unsigned*)(lds + (bufoff) + ldsw + _i * 8192), 16, 0, 0); } while (0)
; #define PG8_STAGE_A(bufoff, gbase, h, vv) do { if constexpr (GATHER) { _Pragma("unroll") for (int _i = 0; _i < 2; ++_i) \
;         __builtin_amdgcn_global_load_lds((const unsigned*)((const char*)(gbase) + (vv)[h][_i]), (LAS unsigned*)(lds + (bufoff) + ldsw + _i * 8192), 16, 0, 0); } \
;         else { PG8_STAGE(bufoff, (gbase) + (h) * hstepA, voffA); } } while (0)
; #define PG8_LDA(dst, b, h) do { _Pragma("unroll") for (int m = 0; m < 4; ++m) _Pragma("unroll") for (int k = 0; k < 2; ++k) dst[m][k] = *(const LAS bf16x8*)(lds + PG8_SA(b, h) + aoff + m * 2048 + k * 1024); } while (0)
; #define PG8_LDB(dst, b, h) do { _Pragma("unroll") for (int n = 0; n < 2; ++n) _Pragma("unroll") for (int k = 0; k < 2; ++k) dst[n][k] = *(const LAS bf16x8*)(lds + PG8_SB(b, h) + boff + n * 2048 + k * 1024); } while (0)
; #define PG8_MMA(ai, bj, At, Bt) do { __builtin_amdgcn_s_setprio(1); _Pragma("unroll") for (int m = 0; m < 4; ++m) _Pragma("unroll") for (int n = 0; n < 2; ++n) _Pragma("unroll") for (int k = 0; k < 2; ++k) \
;         acc[ai][bj][m][n] = __builtin_amdgcn_mfma_f32_16x16x32_bf16(Bt[n][k], At[m][k], acc[ai][bj][m][n], 0, 0, 0); __builtin_amdgcn_s_setprio(0); } while (0)
; #define PG8_WAIT_V(n) asm volatile("s_waitcnt vmcnt(" #n ")" ::: "memory")
; #define PG8_WAIT_L(n) asm volatile("s_waitcnt lgkmcnt(" #n ")" ::: "memory")
; #define PG8_BAR __builtin_amdgcn_s_barrier()
; template <class Epi, class Sched>
; __device__ __forceinline__ void gemm_phase(LAS unsigned char* lds, const int K, const int lda, const int ldb, const Sched& S, const Epi& E) {
;     ...
;             PG8_BAR; PG8_WAIT_L(0); PG8_MMA(1, 0, At, B0); PG8_BAR; PG8_SCHED;
;             PG8_STAGE(PG8_SB(0, 1), b2 + hstepB, voffB);
;             PG8_WAIT_V(6); PG8_BAR; PG8_MMA(1, 1, At, B1); PG8_BAR;
;             PG8_LDB(B0, 1, 0); PG8_SCHED; PG8_LDA(At, 1, 0); PG8_STAGE_A(PG8_SA(0, 1), a2, 1, vcur);
;             PG8_WAIT_L(8); PG8_BAR; PG8_WAIT_L(0); PG8_MMA(0, 0, At, B0); PG8_BAR; PG8_SCHED;
;             PG8_LDB(B1, 1, 1); PG8_STAGE(PG8_SB(1, 0), b3, voffB);
;             PG8_BAR; PG8_WAIT_L(0); PG8_MMA(0, 1, At, B1); PG8_BAR;
	s_add_u32 s70, s34, 0x40000
	s_addc_u32 s71, s35, 0
	s_add_i32 s2, s2, s49
	v_lshl_add_u64 v[146:147], s[70:71], 0, v[0:1]
	s_mov_b32 m0, s2
	s_nop 0
	global_load_lds_dwordx4 v[146:147], off
	v_lshl_add_u64 v[146:147], s[70:71], 0, v[134:135]
	s_add_i32 m0, s2, 0x2000
	s_nop 0
	global_load_lds_dwordx4 v[146:147], off
	s_waitcnt vmcnt(6)
	s_barrier
	s_setprio 1
	v_mfma_f32_16x16x32_bf16 v[50:53], v[216:219], v[162:165], v[50:53]
	v_mfma_f32_16x16x32_bf16 v[42:45], v[224:227], v[162:165], v[42:45]
	v_mfma_f32_16x16x32_bf16 v[34:37], v[216:219], v[170:173], v[34:37]
	v_mfma_f32_16x16x32_bf16 v[26:29], v[224:227], v[170:173], v[26:29]
	v_mfma_f32_16x16x32_bf16 v[18:21], v[216:219], v[178:181], v[18:21]
	v_mfma_f32_16x16x32_bf16 v[10:13], v[224:227], v[178:181], v[10:13]
	v_mfma_f32_16x16x32_bf16 v[6:9], v[216:219], v[186:189], v[6:9]
	v_mfma_f32_16x16x32_bf16 v[2:5], v[224:227], v[186:189], v[2:5]
	v_mfma_f32_16x16x32_bf16 v[50:53], v[220:223], v[166:169], v[50:53]
	v_mfma_f32_16x16x32_bf16 v[42:45], v[228:231], v[166:169], v[42:45]
	v_mfma_f32_16x16x32_bf16 v[34:37], v[220:223], v[174:177], v[34:37]
	v_mfma_f32_16x16x32_bf16 v[26:29], v[228:231], v[174:177], v[26:29]
	v_mfma_f32_16x16x32_bf16 v[18:21], v[220:223], v[182:185], v[18:21]
	v_mfma_f32_16x16x32_bf16 v[10:13], v[228:231], v[182:185], v[10:13]
	v_mfma_f32_16x16x32_bf16 v[6:9], v[220:223], v[190:193], v[6:9]
	v_mfma_f32_16x16x32_bf16 v[2:5], v[228:231], v[190:193], v[2:5]
	s_setprio 0
	s_add_i32 s2, 0, 0x18000
	v_add_u32_e32 v158, s2, v143
	s_barrier
	ds_read_b128 v[146:149], v158
	ds_read_b128 v[150:153], v158 offset:1024
	ds_read_b128 v[154:157], v158 offset:2048
	ds_read_b128 v[158:161], v158 offset:3072
	s_add_u32 s36, s36, 0x40000
	s_addc_u32 s37, s37, 0
	s_mov_b32 m0, s54
	v_lshl_add_u64 v[216:217], s[36:37], 0, v[130:131]
	ds_read_b128 v[162:165], v145 offset:32768
	ds_read_b128 v[166:169], v145 offset:33792
	ds_read_b128 v[170:173], v145 offset:34816
	ds_read_b128 v[174:177], v145 offset:35840
	ds_read_b128 v[178:181], v145 offset:36864
	ds_read_b128 v[182:185], v145 offset:37888
	ds_read_b128 v[186:189], v145 offset:38912
	ds_read_b128 v[190:193], v145 offset:39936
	global_load_lds_dwordx4 v[216:217], off
	v_lshl_add_u64 v[216:217], s[36:37], 0, v[132:133]
	s_mov_b32 m0, s55
	s_nop 0
	global_load_lds_dwordx4 v[216:217], off
	s_waitcnt lgkmcnt(8)
	s_barrier
	s_waitcnt lgkmcnt(0)
	s_setprio 1
	v_mfma_f32_16x16x32_bf16 v[126:129], v[146:149], v[162:165], v[126:129]
	v_mfma_f32_16x16x32_bf16 v[122:125], v[154:157], v[162:165], v[122:125]
	v_mfma_f32_16x16x32_bf16 v[118:121], v[146:149], v[170:173], v[118:121]
	v_mfma_f32_16x16x32_bf16 v[110:113], v[154:157], v[170:173], v[110:113]
	v_mfma_f32_16x16x32_bf16 v[102:105], v[146:149], v[178:181], v[102:105]
	v_mfma_f32_16x16x32_bf16 v[94:97], v[154:157], v[178:181], v[94:97]
	v_mfma_f32_16x16x32_bf16 v[86:89], v[146:149], v[186:189], v[86:89]
	v_mfma_f32_16x16x32_bf16 v[78:81], v[154:157], v[186:189], v[78:81]
	v_mfma_f32_16x16x32_bf16 v[126:129], v[150:153], v[166:169], v[126:129]
	v_mfma_f32_16x16x32_bf16 v[122:125], v[158:161], v[166:169], v[122:125]
	v_mfma_f32_16x16x32_bf16 v[118:121], v[150:153], v[174:177], v[118:121]
	v_mfma_f32_16x16x32_bf16 v[110:113], v[158:161], v[174:177], v[110:113]
	v_mfma_f32_16x16x32_bf16 v[102:105], v[150:153], v[182:185], v[102:105]
	v_mfma_f32_16x16x32_bf16 v[94:97], v[158:161], v[182:185], v[94:97]
	v_mfma_f32_16x16x32_bf16 v[86:89], v[150:153], v[190:193], v[86:89]
	v_mfma_f32_16x16x32_bf16 v[78:81], v[158:161], v[190:193], v[78:81]
	s_setprio 0
	s_barrier
	s_add_i32 s3, 0, 0x1c000
	s_add_i32 s2, s2, s49
	v_add_u32_e32 v228, s3, v143
	v_lshl_add_u64 v[140:141], v[140:141], 0, s[64:65]
	s_mov_b32 m0, s2
	ds_read_b128 v[216:219], v228
	ds_read_b128 v[220:223], v228 offset:1024
	ds_read_b128 v[224:227], v228 offset:2048
	ds_read_b128 v[228:231], v228 offset:3072
	global_load_lds_dwordx4 v[140:141], off
	v_lshl_add_u64 v[140:141], v[194:195], 0, s[64:65]
	s_add_i32 m0, s2, 0x2000
	s_nop 0
	global_load_lds_dwordx4 v[140:141], off
	s_barrier
; #define PG8_STAGE(bufoff, gbase, voff) do { _Pragma("unroll") for (int _i = 0; _i < 2; ++_i) \
;         __builtin_amdgcn_global_load_lds((const unsigned*)((const char*)(gbase) + (voff)[_i]), (LAS unsigned*)(lds + (bufoff) + ldsw + _i * 8192), 16, 0, 0); } while (0)
; #define PG8_STAGE_A(bufoff, gbase, h, vv) do { if constexpr (GATHER) { _Pragma("unroll") for (int _i = 0; _i < 2; ++_i) \
;         __builtin_amdgcn_global_load_lds((const unsigned*)((const char*)(gbase) + (vv)[h][_i]), (LAS unsigned*)(lds + (bufoff) + ldsw + _i * 8192), 16, 0, 0); } \
;         else { PG8_STAGE(bufoff, (gbase) + (h) * hstepA, voffA); } } while (0)
; #define PG8_LDA(dst, b, h) do { _Pragma("unroll") for (int m = 0; m < 4; ++m) _Pragma("unroll") for (int k = 0; k < 2; ++k) dst[m][k] = *(const LAS bf16x8*)(lds + PG8_SA(b, h) + aoff + m * 2048 + k * 1024); } while (0)
; #define PG8_MMA(ai, bj, At, Bt) do { __builtin_amdgcn_s_setprio(1); _Pragma("unroll") for (int m = 0; m < 4; ++m) _Pragma("unroll") for (int n = 0; n < 2; ++n) _Pragma("unroll") for (int k = 0; k < 2; ++k) \
;         acc[ai][bj][m][n] = __builtin_amdgcn_mfma_f32_16x16x32_bf16(Bt[n][k], At[m][k], acc[ai][bj][m][n], 0, 0, 0); __builtin_amdgcn_s_setprio(0); } while (0)
; template <class Epi, class Sched>
; __device__ __forceinline__ void gemm_phase(LAS unsigned char* lds, const int K, const int lda, const int ldb, const Sched& S, const Epi& E) {
;     ...
;             PG8_BAR; PG8_WAIT_L(0); PG8_MMA(0, 1, At, B1); PG8_BAR;
;             PG8_LDA(At, 1, 1); PG8_STAGE_A(PG8_SA(1, 0), a3, 0, vcur);
;             PG8_BAR; PG8_WAIT_L(0); PG8_MMA(1, 0, At, B0); PG8_BAR; PG8_SCHED;
;             PG8_STAGE(PG8_SB(1, 1), b3 + hstepB, voffB);
;             PG8_WAIT_V(6); PG8_BAR; PG8_MMA(1, 1, At, B1); PG8_BAR;
;         }
;         if constexpr (GATHER) { Unit n2; if (has_next && S.next(ui + 2, n2)) ld_ix(n2.pm, ix1); }
;         if constexpr (!Epi::AFTER_DRAIN) E(acc, cur, wr, wc, fr, fq);
;         if (!has_next) break;
; #pragma unroll
;         for (int a = 0; a < 2; ++a)
; #pragma unroll
;             for (int b = 0; b < 2; ++b)
; #pragma unroll
;                 for (int m = 0; m < 4; ++m)
; #pragma unroll
;                     for (int n = 0; n < 2; ++n) acc[a][b][m][n] = (f32x4){0.f, 0.f, 0.f, 0.f};
;         cur = nxt; cA = nA; cB = nB; ++ui;
;     }
;     PG8_WAIT_V(0);
;     if (wr == 0) PG8_BAR;
;     PG8_BAR;
	s_waitcnt lgkmcnt(0)
	s_setprio 1
	v_mfma_f32_16x16x32_bf16 v[114:117], v[216:219], v[162:165], v[114:117]
	v_mfma_f32_16x16x32_bf16 v[106:109], v[224:227], v[162:165], v[106:109]
	v_mfma_f32_16x16x32_bf16 v[98:101], v[216:219], v[170:173], v[98:101]
	v_mfma_f32_16x16x32_bf16 v[90:93], v[224:227], v[170:173], v[90:93]
	v_mfma_f32_16x16x32_bf16 v[82:85], v[216:219], v[178:181], v[82:85]
	v_mfma_f32_16x16x32_bf16 v[74:77], v[224:227], v[178:181], v[74:77]
	v_mfma_f32_16x16x32_bf16 v[70:73], v[216:219], v[186:189], v[70:73]
	v_mfma_f32_16x16x32_bf16 v[66:69], v[224:227], v[186:189], v[66:69]
	v_mfma_f32_16x16x32_bf16 v[114:117], v[220:223], v[166:169], v[114:117]
	v_mfma_f32_16x16x32_bf16 v[106:109], v[228:231], v[166:169], v[106:109]
	v_mfma_f32_16x16x32_bf16 v[98:101], v[220:223], v[174:177], v[98:101]
	v_mfma_f32_16x16x32_bf16 v[90:93], v[228:231], v[174:177], v[90:93]
	v_mfma_f32_16x16x32_bf16 v[82:85], v[220:223], v[182:185], v[82:85]
	v_mfma_f32_16x16x32_bf16 v[74:77], v[228:231], v[182:185], v[74:77]
	v_mfma_f32_16x16x32_bf16 v[70:73], v[220:223], v[190:193], v[70:73]
	v_mfma_f32_16x16x32_bf16 v[66:69], v[228:231], v[190:193], v[66:69]
	s_setprio 0
	s_mov_b32 m0, s63
	v_lshl_add_u64 v[140:141], v[214:215], 0, s[64:65]
	s_barrier
	ds_read_b128 v[162:165], v145 offset:49152
	ds_read_b128 v[166:169], v145 offset:50176
	ds_read_b128 v[170:173], v145 offset:51200
	ds_read_b128 v[174:177], v145 offset:52224
	ds_read_b128 v[178:181], v145 offset:53248
	ds_read_b128 v[182:185], v145 offset:54272
	ds_read_b128 v[186:189], v145 offset:55296
	ds_read_b128 v[190:193], v145 offset:56320
	global_load_lds_dwordx4 v[140:141], off
	v_lshl_add_u64 v[140:141], v[232:233], 0, s[64:65]
	s_mov_b32 m0, s66
	s_nop 0
	global_load_lds_dwordx4 v[140:141], off
	s_barrier
	s_waitcnt lgkmcnt(0)
	s_setprio 1
	v_mfma_f32_16x16x32_bf16 v[62:65], v[146:149], v[162:165], v[62:65]
	v_mfma_f32_16x16x32_bf16 v[58:61], v[154:157], v[162:165], v[58:61]
	v_mfma_f32_16x16x32_bf16 v[54:57], v[146:149], v[170:173], v[54:57]
	v_mfma_f32_16x16x32_bf16 v[46:49], v[154:157], v[170:173], v[46:49]
	v_mfma_f32_16x16x32_bf16 v[38:41], v[146:149], v[178:181], v[38:41]
	v_mfma_f32_16x16x32_bf16 v[30:33], v[154:157], v[178:181], v[30:33]
	v_mfma_f32_16x16x32_bf16 v[22:25], v[146:149], v[186:189], v[22:25]
	v_mfma_f32_16x16x32_bf16 v[14:17], v[154:157], v[186:189], v[14:17]
	v_mfma_f32_16x16x32_bf16 v[62:65], v[150:153], v[166:169], v[62:65]
	v_mfma_f32_16x16x32_bf16 v[58:61], v[158:161], v[166:169], v[58:61]
	v_mfma_f32_16x16x32_bf16 v[54:57], v[150:153], v[174:177], v[54:57]
	v_mfma_f32_16x16x32_bf16 v[46:49], v[158:161], v[174:177], v[46:49]
	v_mfma_f32_16x16x32_bf16 v[38:41], v[150:153], v[182:185], v[38:41]
	v_mfma_f32_16x16x32_bf16 v[30:33], v[158:161], v[182:185], v[30:33]
	v_mfma_f32_16x16x32_bf16 v[22:25], v[150:153], v[190:193], v[22:25]
	v_mfma_f32_16x16x32_bf16 v[14:17], v[158:161], v[190:193], v[14:17]
	s_setprio 0
	s_barrier
	s_add_u32 s34, s34, 0x40080
	s_addc_u32 s35, s35, 0
	s_add_i32 s2, s3, s49
	v_lshl_add_u64 v[140:141], s[34:35], 0, v[0:1]
	s_mov_b32 m0, s2
	s_nop 0
	global_load_lds_dwordx4 v[140:141], off
	v_lshl_add_u64 v[140:141], s[34:35], 0, v[134:135]
	s_add_i32 m0, s2, 0x2000
	s_nop 0
	global_load_lds_dwordx4 v[140:141], off
	s_waitcnt vmcnt(6)
	s_barrier
	s_setprio 1
	v_mfma_f32_16x16x32_bf16 v[50:53], v[216:219], v[162:165], v[50:53]
	v_mfma_f32_16x16x32_bf16 v[42:45], v[224:227], v[162:165], v[42:45]
	v_mfma_f32_16x16x32_bf16 v[34:37], v[216:219], v[170:173], v[34:37]
	v_mfma_f32_16x16x32_bf16 v[26:29], v[224:227], v[170:173], v[26:29]
	v_mfma_f32_16x16x32_bf16 v[18:21], v[216:219], v[178:181], v[18:21]
	v_mfma_f32_16x16x32_bf16 v[10:13], v[224:227], v[178:181], v[10:13]
	v_mfma_f32_16x16x32_bf16 v[6:9], v[216:219], v[186:189], v[6:9]
	v_mfma_f32_16x16x32_bf16 v[2:5], v[224:227], v[186:189], v[2:5]
	v_mfma_f32_16x16x32_bf16 v[50:53], v[220:223], v[166:169], v[50:53]
	v_mfma_f32_16x16x32_bf16 v[42:45], v[228:231], v[166:169], v[42:45]
	v_mfma_f32_16x16x32_bf16 v[34:37], v[220:223], v[174:177], v[34:37]
	v_mfma_f32_16x16x32_bf16 v[26:29], v[228:231], v[174:177], v[26:29]
	v_mfma_f32_16x16x32_bf16 v[18:21], v[220:223], v[182:185], v[18:21]
	v_mfma_f32_16x16x32_bf16 v[10:13], v[228:231], v[182:185], v[10:13]
	v_mfma_f32_16x16x32_bf16 v[6:9], v[220:223], v[190:193], v[6:9]
	v_mfma_f32_16x16x32_bf16 v[2:5], v[228:231], v[190:193], v[2:5]
	s_setprio 0
	s_add_i32 s68, s68, 2
	s_add_u32 s16, s16, 0x100
	s_addc_u32 s17, s17, 0
	s_add_u32 s7, s7, 0x100
	s_addc_u32 s11, s11, 0
	s_cmp_gt_u32 s68, 13
	s_barrier
	s_cbranch_scc0 .LBB0_761
	s_cmpk_gt_u32 s38, 0xff
	s_cbranch_scc1 .Lgx_e_pre
	s_barrier

; #define PG8_STAGE(bufoff, gbase, voff) do { _Pragma("unroll") for (int _i = 0; _i < 2; ++_i) \
;         __builtin_amdgcn_global_load_lds((const unsigned*)((const char*)(gbase) + (voff)[_i]), (LAS unsigned*)(lds + (bufoff) + ldsw + _i * 8192), 16, 0, 0); } while (0)
; #define PG8_STAGE_A(bufoff, gbase, h, vv) do { if constexpr (GATHER) { _Pragma("unroll") for (int _i = 0; _i < 2; ++_i) \
;         __builtin_amdgcn_global_load_lds((const unsigned*)((const char*)(gbase) + (vv)[h][_i]), (LAS unsigned*)(lds + (bufoff) + ldsw + _i * 8192), 16, 0, 0); } \
;         else { PG8_STAGE(bufoff, (gbase) + (h) * hstepA, voffA); } } while (0)
; #define PG8_LDA(dst, b, h) do { _Pragma("unroll") for (int m = 0; m < 4; ++m) _Pragma("unroll") for (int k = 0; k < 2; ++k) dst[m][k] = *(const LAS bf16x8*)(lds + PG8_SA(b, h) + aoff + m * 2048 + k * 1024); } while (0)
; #define PG8_LDB(dst, b, h) do { _Pragma("unroll") for (int n = 0; n < 2; ++n) _Pragma("unroll") for (int k = 0; k < 2; ++k) dst[n][k] = *(const LAS bf16x8*)(lds + PG8_SB(b, h) + boff + n * 2048 + k * 1024); } while (0)
; #define PG8_WAIT_L(n) asm volatile("s_waitcnt lgkmcnt(" #n ")" ::: "memory")
; template <class Epi, class Sched>
; __device__ __forceinline__ void gemm_phase(LAS unsigned char* lds, const int K, const int lda, const int ldb, const Sched& S, const Epi& E) {
;     ...
;         for (int t = 0; t < nt; t += 2) {
;             const bool last = (t == nt - 2);
;             const char* a1 = cA + (size_t)(t + 1) * kstep;
;             const char* a2 = last ? nA : cA + (size_t)(t + 2) * kstep; const char* b2 = last ? nB : cB + (size_t)(t + 2) * kstep;
;             const char* a3 = a2 + kstep; const char* b3 = b2 + kstep;
;             PG8_LDB(B0, 0, 0); PG8_SCHED; PG8_LDA(At, 0, 0); PG8_STAGE_A(PG8_SA(1, 1), a1, 1, vcur);
;             if constexpr (GATHER) { if (last) {
; #pragma unroll
;                 for (int h = 0; h < 2; ++h)
; #pragma unroll
;                     for (int i = 0; i < 2; ++i) vcur[h][i] = vnxt[h][i]; } }
;             PG8_WAIT_L(8); PG8_BAR; PG8_WAIT_L(0); PG8_MMA(0, 0, At, B0); PG8_BAR; PG8_SCHED;
;             PG8_LDB(B1, 0, 1); PG8_STAGE(PG8_SB(0, 0), b2, voffB);
;             PG8_BAR; PG8_WAIT_L(0); PG8_MMA(0, 1, At, B1); PG8_BAR;
;             PG8_LDA(At, 0, 1); PG8_STAGE_A(PG8_SA(0, 0), a2, 0, vcur);
;             PG8_BAR; PG8_WAIT_L(0); PG8_MMA(1, 0, At, B0); PG8_BAR; PG8_SCHED;
.LBB0_824:
	s_add_u32 s2, s0, s14
	s_addc_u32 s3, s1, s15
	s_add_u32 s2, s2, 0x100
	s_addc_u32 s3, s3, 0
	s_add_u32 s16, s63, s14
	s_addc_u32 s17, s66, s15
	s_add_i32 s20, 0, 0x10000
	v_add_u32_e32 v146, s20, v140
	ds_read_b128 v[142:145], v146
	ds_read_b128 v[150:153], v146 offset:1024
	ds_read_b128 v[154:157], v146 offset:2048
	ds_read_b128 v[158:161], v146 offset:3072
	s_cmpk_eq_i32 s14, 0x1b00
	s_cselect_b32 s35, s13, s3
	s_cselect_b32 s34, s12, s2
	s_cselect_b32 s17, s9, s17
	s_cselect_b32 s16, s8, s16
	v_lshl_add_u64 v[146:147], v[136:137], 0, s[14:15]
	s_add_i32 m0, s46, 0xc000
	ds_read_b128 v[162:165], v141
	ds_read_b128 v[166:169], v141 offset:1024
	ds_read_b128 v[170:173], v141 offset:2048
	ds_read_b128 v[174:177], v141 offset:3072
	ds_read_b128 v[178:181], v141 offset:4096
	ds_read_b128 v[186:189], v141 offset:5120
	ds_read_b128 v[190:193], v141 offset:6144
	ds_read_b128 v[216:219], v141 offset:7168
	global_load_lds_dwordx4 v[146:147], off
	v_lshl_add_u64 v[146:147], v[138:139], 0, s[14:15]
	s_add_i32 m0, s46, 0xe000
	s_nop 0
	global_load_lds_dwordx4 v[146:147], off
	s_waitcnt lgkmcnt(8)
	s_barrier
	s_waitcnt lgkmcnt(0)
	s_setprio 1
	v_mfma_f32_16x16x32_bf16 v[126:129], v[142:145], v[162:165], v[126:129]
	v_mfma_f32_16x16x32_bf16 v[102:105], v[154:157], v[162:165], v[102:105]
	v_mfma_f32_16x16x32_bf16 v[122:125], v[142:145], v[170:173], v[122:125]
	v_mfma_f32_16x16x32_bf16 v[98:101], v[154:157], v[170:173], v[98:101]
	v_mfma_f32_16x16x32_bf16 v[110:113], v[142:145], v[178:181], v[110:113]
	v_mfma_f32_16x16x32_bf16 v[78:81], v[154:157], v[178:181], v[78:81]
	v_mfma_f32_16x16x32_bf16 v[106:109], v[142:145], v[190:193], v[106:109]
	v_mfma_f32_16x16x32_bf16 v[74:77], v[154:157], v[190:193], v[74:77]
	v_mfma_f32_16x16x32_bf16 v[126:129], v[150:153], v[166:169], v[126:129]
	v_mfma_f32_16x16x32_bf16 v[102:105], v[158:161], v[166:169], v[102:105]
	v_mfma_f32_16x16x32_bf16 v[122:125], v[150:153], v[174:177], v[122:125]
	v_mfma_f32_16x16x32_bf16 v[98:101], v[158:161], v[174:177], v[98:101]
	v_mfma_f32_16x16x32_bf16 v[110:113], v[150:153], v[186:189], v[110:113]
	v_mfma_f32_16x16x32_bf16 v[78:81], v[158:161], v[186:189], v[78:81]
	v_mfma_f32_16x16x32_bf16 v[106:109], v[150:153], v[216:219], v[106:109]
	v_mfma_f32_16x16x32_bf16 v[74:77], v[158:161], v[216:219], v[74:77]
	s_setprio 0
	s_barrier
	s_add_i32 s2, 0, 0x14000
	v_add_u32_e32 v146, s2, v140
	s_add_i32 s3, s20, s45
	ds_read_b128 v[220:223], v146
	ds_read_b128 v[224:227], v146 offset:1024
	ds_read_b128 v[228:231], v146 offset:2048
	ds_read_b128 v[232:235], v146 offset:3072
	v_lshl_add_u64 v[146:147], s[16:17], 0, v[0:1]
	s_mov_b32 m0, s3
	v_lshl_add_u64 v[194:195], s[16:17], 0, v[130:131]
	global_load_lds_dwordx4 v[146:147], off
	s_add_i32 m0, s3, 0x2000
	s_nop 0
	global_load_lds_dwordx4 v[194:195], off
	s_barrier
	s_waitcnt lgkmcnt(0)
	s_setprio 1
	v_mfma_f32_16x16x32_bf16 v[62:65], v[220:223], v[162:165], v[62:65]
	v_mfma_f32_16x16x32_bf16 v[118:121], v[228:231], v[162:165], v[118:121]
	v_mfma_f32_16x16x32_bf16 v[54:57], v[220:223], v[170:173], v[54:57]
	v_mfma_f32_16x16x32_bf16 v[30:33], v[228:231], v[170:173], v[30:33]
	v_mfma_f32_16x16x32_bf16 v[46:49], v[220:223], v[178:181], v[46:49]
	v_mfma_f32_16x16x32_bf16 v[114:117], v[228:231], v[178:181], v[114:117]
	v_mfma_f32_16x16x32_bf16 v[42:45], v[220:223], v[190:193], v[42:45]
	v_mfma_f32_16x16x32_bf16 v[22:25], v[228:231], v[190:193], v[22:25]
	v_mfma_f32_16x16x32_bf16 v[62:65], v[224:227], v[166:169], v[62:65]
	v_mfma_f32_16x16x32_bf16 v[118:121], v[232:235], v[166:169], v[118:121]
	v_mfma_f32_16x16x32_bf16 v[54:57], v[224:227], v[174:177], v[54:57]
	v_mfma_f32_16x16x32_bf16 v[30:33], v[232:235], v[174:177], v[30:33]
	v_mfma_f32_16x16x32_bf16 v[46:49], v[224:227], v[186:189], v[46:49]
	v_mfma_f32_16x16x32_bf16 v[114:117], v[232:235], v[186:189], v[114:117]
	v_mfma_f32_16x16x32_bf16 v[42:45], v[224:227], v[216:219], v[42:45]
	v_mfma_f32_16x16x32_bf16 v[22:25], v[232:235], v[216:219], v[22:25]
	s_setprio 0
	s_mov_b32 m0, s46
	v_lshl_add_u64 v[214:215], s[34:35], 0, v[0:1]
	s_barrier
	ds_read_b128 v[162:165], v141 offset:16384
	ds_read_b128 v[166:169], v141 offset:17408
	ds_read_b128 v[170:173], v141 offset:18432
	ds_read_b128 v[174:177], v141 offset:19456
	ds_read_b128 v[178:181], v141 offset:20480
	ds_read_b128 v[186:189], v141 offset:21504
	ds_read_b128 v[190:193], v141 offset:22528
	ds_read_b128 v[216:219], v141 offset:23552
	global_load_lds_dwordx4 v[214:215], off
	v_lshl_add_u64 v[236:237], s[34:35], 0, v[130:131]
	s_mov_b32 m0, s47
	s_nop 0
	global_load_lds_dwordx4 v[236:237], off
	s_barrier
	s_waitcnt lgkmcnt(0)
	s_setprio 1
	v_mfma_f32_16x16x32_bf16 v[90:93], v[142:145], v[162:165], v[90:93]
	v_mfma_f32_16x16x32_bf16 v[70:73], v[154:157], v[162:165], v[70:73]
	v_mfma_f32_16x16x32_bf16 v[94:97], v[142:145], v[170:173], v[94:97]
	v_mfma_f32_16x16x32_bf16 v[66:69], v[154:157], v[170:173], v[66:69]
	v_mfma_f32_16x16x32_bf16 v[86:89], v[142:145], v[178:181], v[86:89]
	v_mfma_f32_16x16x32_bf16 v[58:61], v[154:157], v[178:181], v[58:61]
	v_mfma_f32_16x16x32_bf16 v[82:85], v[142:145], v[190:193], v[82:85]
	v_mfma_f32_16x16x32_bf16 v[50:53], v[154:157], v[190:193], v[50:53]
	v_mfma_f32_16x16x32_bf16 v[90:93], v[150:153], v[166:169], v[90:93]
	v_mfma_f32_16x16x32_bf16 v[70:73], v[158:161], v[166:169], v[70:73]
	v_mfma_f32_16x16x32_bf16 v[94:97], v[150:153], v[174:177], v[94:97]
	v_mfma_f32_16x16x32_bf16 v[66:69], v[158:161], v[174:177], v[66:69]
	v_mfma_f32_16x16x32_bf16 v[86:89], v[150:153], v[186:189], v[86:89]
	v_mfma_f32_16x16x32_bf16 v[58:61], v[158:161], v[186:189], v[58:61]
	v_mfma_f32_16x16x32_bf16 v[82:85], v[150:153], v[216:219], v[82:85]
	v_mfma_f32_16x16x32_bf16 v[50:53], v[158:161], v[216:219], v[50:53]
	s_setprio 0
	s_barrier
; #define PG8_STAGE(bufoff, gbase, voff) do { _Pragma("unroll") for (int _i = 0; _i < 2; ++_i) \
;         __builtin_amdgcn_global_load_lds((const unsigned*)((const char*)(gbase) + (voff)[_i]), (LAS unsigned*)(lds + (bufoff) + ldsw + _i * 8192), 16, 0, 0); } while (0)
; #define PG8_STAGE_A(bufoff, gbase, h, vv) do { if constexpr (GATHER) { _Pragma("unroll") for (int _i = 0; _i < 2; ++_i) \
;         __builtin_amdgcn_global_load_lds((const unsigned*)((const char*)(gbase) + (vv)[h][_i]), (LAS unsigned*)(lds + (bufoff) + ldsw + _i * 8192), 16, 0, 0); } \
;         else { PG8_STAGE(bufoff, (gbase) + (h) * hstepA, voffA); } } while (0)
; #define PG8_LDA(dst, b, h) do { _Pragma("unroll") for (int m = 0; m < 4; ++m) _Pragma("unroll") for (int k = 0; k < 2; ++k) dst[m][k] = *(const LAS bf16x8*)(lds + PG8_SA(b, h) + aoff + m * 2048 + k * 1024); } while (0)
; #define PG8_LDB(dst, b, h) do { _Pragma("unroll") for (int n = 0; n < 2; ++n) _Pragma("unroll") for (int k = 0; k < 2; ++k) dst[n][k] = *(const LAS bf16x8*)(lds + PG8_SB(b, h) + boff + n * 2048 + k * 1024); } while (0)
; #define PG8_MMA(ai, bj, At, Bt) do { __builtin_amdgcn_s_setprio(1); _Pragma("unroll") for (int m = 0; m < 4; ++m) _Pragma("unroll") for (int n = 0; n < 2; ++n) _Pragma("unroll") for (int k = 0; k < 2; ++k) \
;         acc[ai][bj][m][n] = __builtin_amdgcn_mfma_f32_16x16x32_bf16(Bt[n][k], At[m][k], acc[ai][bj][m][n], 0, 0, 0); __builtin_amdgcn_s_setprio(0); } while (0)
; #define PG8_WAIT_V(n) asm volatile("s_waitcnt vmcnt(" #n ")" ::: "memory")
; #define PG8_WAIT_L(n) asm volatile("s_waitcnt lgkmcnt(" #n ")" ::: "memory")
; #define PG8_BAR __builtin_amdgcn_s_barrier()
; template <class Epi, class Sched>
; __device__ __forceinline__ void gemm_phase(LAS unsigned char* lds, const int K, const int lda, const int ldb, const Sched& S, const Epi& E) {
;     ...
;             PG8_BAR; PG8_WAIT_L(0); PG8_MMA(1, 0, At, B0); PG8_BAR; PG8_SCHED;
;             PG8_STAGE(PG8_SB(0, 1), b2 + hstepB, voffB);
;             PG8_WAIT_V(6); PG8_BAR; PG8_MMA(1, 1, At, B1); PG8_BAR;
;             PG8_LDB(B0, 1, 0); PG8_SCHED; PG8_LDA(At, 1, 0); PG8_STAGE_A(PG8_SA(0, 1), a2, 1, vcur);
;             PG8_WAIT_L(8); PG8_BAR; PG8_WAIT_L(0); PG8_MMA(0, 0, At, B0); PG8_BAR; PG8_SCHED;
;             PG8_LDB(B1, 1, 1); PG8_STAGE(PG8_SB(1, 0), b3, voffB);
;             PG8_BAR; PG8_WAIT_L(0); PG8_MMA(0, 1, At, B1); PG8_BAR;
	s_add_u32 s68, s16, 0xe0000
	s_addc_u32 s69, s17, 0
	s_add_i32 s2, s2, s45
	v_lshl_add_u64 v[142:143], s[68:69], 0, v[0:1]
	s_mov_b32 m0, s2
	s_nop 0
	global_load_lds_dwordx4 v[142:143], off
	v_lshl_add_u64 v[142:143], s[68:69], 0, v[130:131]
	s_add_i32 m0, s2, 0x2000
	s_nop 0
	global_load_lds_dwordx4 v[142:143], off
	s_waitcnt vmcnt(6)
	s_barrier
	s_setprio 1
	v_mfma_f32_16x16x32_bf16 v[38:41], v[220:223], v[162:165], v[38:41]
	v_mfma_f32_16x16x32_bf16 v[10:13], v[228:231], v[162:165], v[10:13]
	v_mfma_f32_16x16x32_bf16 v[34:37], v[220:223], v[170:173], v[34:37]
	v_mfma_f32_16x16x32_bf16 v[14:17], v[228:231], v[170:173], v[14:17]
	v_mfma_f32_16x16x32_bf16 v[26:29], v[220:223], v[178:181], v[26:29]
	v_mfma_f32_16x16x32_bf16 v[6:9], v[228:231], v[178:181], v[6:9]
	v_mfma_f32_16x16x32_bf16 v[18:21], v[220:223], v[190:193], v[18:21]
	v_mfma_f32_16x16x32_bf16 v[2:5], v[228:231], v[190:193], v[2:5]
	v_mfma_f32_16x16x32_bf16 v[38:41], v[224:227], v[166:169], v[38:41]
	v_mfma_f32_16x16x32_bf16 v[10:13], v[232:235], v[166:169], v[10:13]
	v_mfma_f32_16x16x32_bf16 v[34:37], v[224:227], v[174:177], v[34:37]
	v_mfma_f32_16x16x32_bf16 v[14:17], v[232:235], v[174:177], v[14:17]
	v_mfma_f32_16x16x32_bf16 v[26:29], v[224:227], v[186:189], v[26:29]
	v_mfma_f32_16x16x32_bf16 v[6:9], v[232:235], v[186:189], v[6:9]
	v_mfma_f32_16x16x32_bf16 v[18:21], v[224:227], v[216:219], v[18:21]
	v_mfma_f32_16x16x32_bf16 v[2:5], v[232:235], v[216:219], v[2:5]
	s_setprio 0
	s_add_i32 s2, 0, 0x18000
	v_add_u32_e32 v148, s2, v140
	s_barrier
	ds_read_b128 v[142:145], v148
	ds_read_b128 v[150:153], v148 offset:1024
	ds_read_b128 v[154:157], v148 offset:2048
	ds_read_b128 v[158:161], v148 offset:3072
	s_add_u32 s34, s34, 0xe0000
	s_addc_u32 s35, s35, 0
	s_mov_b32 m0, s48
	v_lshl_add_u64 v[220:221], s[34:35], 0, v[0:1]
	ds_read_b128 v[162:165], v141 offset:32768
	ds_read_b128 v[166:169], v141 offset:33792
	ds_read_b128 v[170:173], v141 offset:34816
	ds_read_b128 v[174:177], v141 offset:35840
	ds_read_b128 v[178:181], v141 offset:36864
	ds_read_b128 v[186:189], v141 offset:37888
	ds_read_b128 v[190:193], v141 offset:38912
	ds_read_b128 v[216:219], v141 offset:39936
	global_load_lds_dwordx4 v[220:221], off
	v_lshl_add_u64 v[220:221], s[34:35], 0, v[130:131]
	s_mov_b32 m0, s49
	s_nop 0
	global_load_lds_dwordx4 v[220:221], off
	s_waitcnt lgkmcnt(8)
	s_barrier
	s_waitcnt lgkmcnt(0)
	s_setprio 1
	v_mfma_f32_16x16x32_bf16 v[126:129], v[142:145], v[162:165], v[126:129]
	v_mfma_f32_16x16x32_bf16 v[102:105], v[154:157], v[162:165], v[102:105]
	v_mfma_f32_16x16x32_bf16 v[122:125], v[142:145], v[170:173], v[122:125]
	v_mfma_f32_16x16x32_bf16 v[98:101], v[154:157], v[170:173], v[98:101]
	v_mfma_f32_16x16x32_bf16 v[110:113], v[142:145], v[178:181], v[110:113]
	v_mfma_f32_16x16x32_bf16 v[78:81], v[154:157], v[178:181], v[78:81]
	v_mfma_f32_16x16x32_bf16 v[106:109], v[142:145], v[190:193], v[106:109]
	v_mfma_f32_16x16x32_bf16 v[74:77], v[154:157], v[190:193], v[74:77]
	v_mfma_f32_16x16x32_bf16 v[126:129], v[150:153], v[166:169], v[126:129]
	v_mfma_f32_16x16x32_bf16 v[102:105], v[158:161], v[166:169], v[102:105]
	v_mfma_f32_16x16x32_bf16 v[122:125], v[150:153], v[174:177], v[122:125]
	v_mfma_f32_16x16x32_bf16 v[98:101], v[158:161], v[174:177], v[98:101]
	v_mfma_f32_16x16x32_bf16 v[110:113], v[150:153], v[186:189], v[110:113]
	v_mfma_f32_16x16x32_bf16 v[78:81], v[158:161], v[186:189], v[78:81]
	v_mfma_f32_16x16x32_bf16 v[106:109], v[150:153], v[216:219], v[106:109]
	v_mfma_f32_16x16x32_bf16 v[74:77], v[158:161], v[216:219], v[74:77]
	s_setprio 0
	s_barrier
	s_add_i32 s3, 0, 0x1c000
	s_add_i32 s2, s2, s45
	v_add_u32_e32 v148, s3, v140
	v_lshl_add_u64 v[146:147], v[146:147], 0, s[64:65]
	s_mov_b32 m0, s2
	ds_read_b128 v[220:223], v148
	ds_read_b128 v[224:227], v148 offset:1024
	ds_read_b128 v[228:231], v148 offset:2048
	ds_read_b128 v[232:235], v148 offset:3072
	global_load_lds_dwordx4 v[146:147], off
	v_lshl_add_u64 v[146:147], v[194:195], 0, s[64:65]
	s_add_i32 m0, s2, 0x2000
	s_nop 0
	global_load_lds_dwordx4 v[146:147], off
	s_barrier
	s_waitcnt lgkmcnt(0)
	s_setprio 1
	v_mfma_f32_16x16x32_bf16 v[62:65], v[220:223], v[162:165], v[62:65]
	v_mfma_f32_16x16x32_bf16 v[118:121], v[228:231], v[162:165], v[118:121]
	v_mfma_f32_16x16x32_bf16 v[54:57], v[220:223], v[170:173], v[54:57]
	v_mfma_f32_16x16x32_bf16 v[30:33], v[228:231], v[170:173], v[30:33]
	v_mfma_f32_16x16x32_bf16 v[46:49], v[220:223], v[178:181], v[46:49]
	v_mfma_f32_16x16x32_bf16 v[114:117], v[228:231], v[178:181], v[114:117]
	v_mfma_f32_16x16x32_bf16 v[42:45], v[220:223], v[190:193], v[42:45]
	v_mfma_f32_16x16x32_bf16 v[22:25], v[228:231], v[190:193], v[22:25]
	v_mfma_f32_16x16x32_bf16 v[62:65], v[224:227], v[166:169], v[62:65]
	v_mfma_f32_16x16x32_bf16 v[118:121], v[232:235], v[166:169], v[118:121]
	v_mfma_f32_16x16x32_bf16 v[54:57], v[224:227], v[174:177], v[54:57]
	v_mfma_f32_16x16x32_bf16 v[30:33], v[232:235], v[174:177], v[30:33]
	v_mfma_f32_16x16x32_bf16 v[46:49], v[224:227], v[186:189], v[46:49]
	v_mfma_f32_16x16x32_bf16 v[114:117], v[232:235], v[186:189], v[114:117]
	v_mfma_f32_16x16x32_bf16 v[42:45], v[224:227], v[216:219], v[42:45]
	v_mfma_f32_16x16x32_bf16 v[22:25], v[232:235], v[216:219], v[22:25]
	s_setprio 0
	s_mov_b32 m0, s52
	v_lshl_add_u64 v[146:147], v[214:215], 0, s[64:65]
	s_barrier
; #define PG8_STAGE(bufoff, gbase, voff) do { _Pragma("unroll") for (int _i = 0; _i < 2; ++_i) \
;         __builtin_amdgcn_global_load_lds((const unsigned*)((const char*)(gbase) + (voff)[_i]), (LAS unsigned*)(lds + (bufoff) + ldsw + _i * 8192), 16, 0, 0); } while (0)
; #define PG8_STAGE_A(bufoff, gbase, h, vv) do { if constexpr (GATHER) { _Pragma("unroll") for (int _i = 0; _i < 2; ++_i) \
;         __builtin_amdgcn_global_load_lds((const unsigned*)((const char*)(gbase) + (vv)[h][_i]), (LAS unsigned*)(lds + (bufoff) + ldsw + _i * 8192), 16, 0, 0); } \
;         else { PG8_STAGE(bufoff, (gbase) + (h) * hstepA, voffA); } } while (0)
; #define PG8_LDA(dst, b, h) do { _Pragma("unroll") for (int m = 0; m < 4; ++m) _Pragma("unroll") for (int k = 0; k < 2; ++k) dst[m][k] = *(const LAS bf16x8*)(lds + PG8_SA(b, h) + aoff + m * 2048 + k * 1024); } while (0)
; #define PG8_LDB(dst, b, h) do { _Pragma("unroll") for (int n = 0; n < 2; ++n) _Pragma("unroll") for (int k = 0; k < 2; ++k) dst[n][k] = *(const LAS bf16x8*)(lds + PG8_SB(b, h) + boff + n * 2048 + k * 1024); } while (0)
; #define PG8_BAR __builtin_amdgcn_s_barrier()
; template <class Epi, class Sched>
; __device__ __forceinline__ void gemm_phase(LAS unsigned char* lds, const int K, const int lda, const int ldb, const Sched& S, const Epi& E) {
;     ...
;             PG8_WAIT_L(8); PG8_BAR; PG8_WAIT_L(0); PG8_MMA(0, 0, At, B0); PG8_BAR; PG8_SCHED;
;             PG8_LDB(B1, 1, 1); PG8_STAGE(PG8_SB(1, 0), b3, voffB);
;             PG8_BAR; PG8_WAIT_L(0); PG8_MMA(0, 1, At, B1); PG8_BAR;
;             PG8_LDA(At, 1, 1); PG8_STAGE_A(PG8_SA(1, 0), a3, 0, vcur);
;             PG8_BAR; PG8_WAIT_L(0); PG8_MMA(1, 0, At, B0); PG8_BAR; PG8_SCHED;
;             PG8_STAGE(PG8_SB(1, 1), b3 + hstepB, voffB);
;             PG8_WAIT_V(6); PG8_BAR; PG8_MMA(1, 1, At, B1); PG8_BAR;
;         }
;         if constexpr (GATHER) { Unit n2; if (has_next && S.next(ui + 2, n2)) ld_ix(n2.pm, ix1); }
;         if constexpr (!Epi::AFTER_DRAIN) E(acc, cur, wr, wc, fr, fq);
;         if (!has_next) break;
; #pragma unroll
;         for (int a = 0; a < 2; ++a)
; #pragma unroll
;             for (int b = 0; b < 2; ++b)
; #pragma unroll
;                 for (int m = 0; m < 4; ++m)
; #pragma unroll
;                     for (int n = 0; n < 2; ++n) acc[a][b][m][n] = (f32x4){0.f, 0.f, 0.f, 0.f};
;         cur = nxt; cA = nA; cB = nB; ++ui;
	ds_read_b128 v[162:165], v141 offset:49152
	ds_read_b128 v[166:169], v141 offset:50176
	ds_read_b128 v[170:173], v141 offset:51200
	ds_read_b128 v[174:177], v141 offset:52224
	ds_read_b128 v[178:181], v141 offset:53248
	ds_read_b128 v[186:189], v141 offset:54272
	ds_read_b128 v[190:193], v141 offset:55296
	ds_read_b128 v[216:219], v141 offset:56320
	global_load_lds_dwordx4 v[146:147], off
	v_lshl_add_u64 v[146:147], v[236:237], 0, s[64:65]
	s_mov_b32 m0, s53
	s_nop 0
	global_load_lds_dwordx4 v[146:147], off
	s_barrier
	s_waitcnt lgkmcnt(0)
	s_setprio 1
	v_mfma_f32_16x16x32_bf16 v[90:93], v[142:145], v[162:165], v[90:93]
	v_mfma_f32_16x16x32_bf16 v[70:73], v[154:157], v[162:165], v[70:73]
	v_mfma_f32_16x16x32_bf16 v[94:97], v[142:145], v[170:173], v[94:97]
	v_mfma_f32_16x16x32_bf16 v[66:69], v[154:157], v[170:173], v[66:69]
	v_mfma_f32_16x16x32_bf16 v[86:89], v[142:145], v[178:181], v[86:89]
	v_mfma_f32_16x16x32_bf16 v[58:61], v[154:157], v[178:181], v[58:61]
	v_mfma_f32_16x16x32_bf16 v[82:85], v[142:145], v[190:193], v[82:85]
	v_mfma_f32_16x16x32_bf16 v[50:53], v[154:157], v[190:193], v[50:53]
	v_mfma_f32_16x16x32_bf16 v[90:93], v[150:153], v[166:169], v[90:93]
	v_mfma_f32_16x16x32_bf16 v[70:73], v[158:161], v[166:169], v[70:73]
	v_mfma_f32_16x16x32_bf16 v[94:97], v[150:153], v[174:177], v[94:97]
	v_mfma_f32_16x16x32_bf16 v[66:69], v[158:161], v[174:177], v[66:69]
	v_mfma_f32_16x16x32_bf16 v[86:89], v[150:153], v[186:189], v[86:89]
	v_mfma_f32_16x16x32_bf16 v[58:61], v[158:161], v[186:189], v[58:61]
	v_mfma_f32_16x16x32_bf16 v[82:85], v[150:153], v[216:219], v[82:85]
	v_mfma_f32_16x16x32_bf16 v[50:53], v[158:161], v[216:219], v[50:53]
	s_setprio 0
	s_barrier
	s_add_u32 s16, s16, 0xe0080
	s_addc_u32 s17, s17, 0
	s_add_i32 s2, s3, s45
	v_lshl_add_u64 v[142:143], s[16:17], 0, v[0:1]
	s_mov_b32 m0, s2
	s_nop 0
	global_load_lds_dwordx4 v[142:143], off
	v_lshl_add_u64 v[142:143], s[16:17], 0, v[130:131]
	s_add_i32 m0, s2, 0x2000
	s_nop 0
	global_load_lds_dwordx4 v[142:143], off
	s_waitcnt vmcnt(6)
	s_barrier
	s_setprio 1
	v_mfma_f32_16x16x32_bf16 v[38:41], v[220:223], v[162:165], v[38:41]
	v_mfma_f32_16x16x32_bf16 v[10:13], v[228:231], v[162:165], v[10:13]
	v_mfma_f32_16x16x32_bf16 v[34:37], v[220:223], v[170:173], v[34:37]
	v_mfma_f32_16x16x32_bf16 v[14:17], v[228:231], v[170:173], v[14:17]
	v_mfma_f32_16x16x32_bf16 v[26:29], v[220:223], v[178:181], v[26:29]
	v_mfma_f32_16x16x32_bf16 v[6:9], v[228:231], v[178:181], v[6:9]
	v_mfma_f32_16x16x32_bf16 v[18:21], v[220:223], v[190:193], v[18:21]
	v_mfma_f32_16x16x32_bf16 v[2:5], v[228:231], v[190:193], v[2:5]
	v_mfma_f32_16x16x32_bf16 v[38:41], v[224:227], v[166:169], v[38:41]
	v_mfma_f32_16x16x32_bf16 v[10:13], v[232:235], v[166:169], v[10:13]
	v_mfma_f32_16x16x32_bf16 v[34:37], v[224:227], v[174:177], v[34:37]
	v_mfma_f32_16x16x32_bf16 v[14:17], v[232:235], v[174:177], v[14:17]
	v_mfma_f32_16x16x32_bf16 v[26:29], v[224:227], v[186:189], v[26:29]
	v_mfma_f32_16x16x32_bf16 v[6:9], v[232:235], v[186:189], v[6:9]
	v_mfma_f32_16x16x32_bf16 v[18:21], v[224:227], v[216:219], v[18:21]
	v_mfma_f32_16x16x32_bf16 v[2:5], v[232:235], v[216:219], v[2:5]
	s_setprio 0
	s_add_i32 s67, s67, 2
	s_add_u32 s14, s14, 0x100
	s_addc_u32 s15, s15, 0
	s_cmp_gt_u32 s67, 53
	s_barrier
	s_cbranch_scc0 .LBB0_824
	s_add_u32 s14, s63, 0xffffff00
	s_addc_u32 s15, s66, -1
	s_andn2_b64 vcc, exec, s[10:11]
	s_cbranch_vccnz .LBB0_827
	v_mov_b32_e32 v2, 0
	s_mov_b32 s5, s55
	s_mov_b32 s4, s60
	s_mov_b64 s[0:1], s[12:13]
	s_mov_b32 s54, s62
	v_mov_b32_e32 v3, v2
	v_mov_b64_e32 v[4:5], 0
	v_mov_b64_e32 v[18:19], 0
	v_mov_b64_e32 v[20:21], 0
	v_mov_b64_e32 v[6:7], 0
	v_mov_b64_e32 v[8:9], 0
	v_mov_b64_e32 v[26:27], 0
	v_mov_b64_e32 v[28:29], 0
	v_mov_b64_e32 v[14:15], 0
	v_mov_b64_e32 v[16:17], 0
	v_mov_b64_e32 v[34:35], 0
	v_mov_b64_e32 v[36:37], 0
	v_mov_b64_e32 v[10:11], 0
	v_mov_b64_e32 v[12:13], 0
	v_mov_b64_e32 v[38:39], 0
	v_mov_b64_e32 v[40:41], 0
	v_mov_b64_e32 v[50:51], 0
	v_mov_b64_e32 v[52:53], 0
	v_mov_b64_e32 v[82:83], 0
	v_mov_b64_e32 v[84:85], 0
	v_mov_b64_e32 v[58:59], 0
	v_mov_b64_e32 v[60:61], 0
	v_mov_b64_e32 v[86:87], 0
	v_mov_b64_e32 v[88:89], 0
	v_mov_b64_e32 v[66:67], 0
	v_mov_b64_e32 v[68:69], 0
	v_mov_b64_e32 v[94:95], 0
	v_mov_b64_e32 v[96:97], 0
	v_mov_b64_e32 v[70:71], 0
	v_mov_b64_e32 v[72:73], 0
	v_mov_b64_e32 v[90:91], 0
	v_mov_b64_e32 v[92:93], 0
	v_mov_b64_e32 v[22:23], 0
	v_mov_b64_e32 v[24:25], 0
	v_mov_b64_e32 v[42:43], 0
	v_mov_b64_e32 v[44:45], 0
	v_mov_b64_e32 v[114:115], 0
	v_mov_b64_e32 v[116:117], 0
	v_mov_b64_e32 v[46:47], 0
	v_mov_b64_e32 v[48:49], 0
	v_mov_b64_e32 v[30:31], 0
	v_mov_b64_e32 v[32:33], 0
	v_mov_b64_e32 v[54:55], 0
	v_mov_b64_e32 v[56:57], 0
	v_mov_b64_e32 v[118:119], 0
	v_mov_b64_e32 v[120:121], 0
	v_mov_b64_e32 v[62:63], 0
	v_mov_b64_e32 v[64:65], 0
	v_mov_b64_e32 v[74:75], 0
	v_mov_b64_e32 v[76:77], 0
	v_mov_b64_e32 v[106:107], 0
	v_mov_b64_e32 v[108:109], 0
	v_mov_b64_e32 v[78:79], 0
	v_mov_b64_e32 v[80:81], 0
	v_mov_b64_e32 v[110:111], 0
	v_mov_b64_e32 v[112:113], 0
	v_mov_b64_e32 v[98:99], 0
	v_mov_b64_e32 v[100:101], 0
	v_mov_b64_e32 v[122:123], 0
	v_mov_b64_e32 v[124:125], 0
	v_mov_b64_e32 v[102:103], 0
	v_mov_b64_e32 v[104:105], 0
	v_mov_b64_e32 v[126:127], 0
	v_mov_b64_e32 v[128:129], 0
	s_branch .LBB0_828

; #define PG8_STAGE(bufoff, gbase, voff) do { _Pragma("unroll") for (int _i = 0; _i < 2; ++_i) \
;         __builtin_amdgcn_global_load_lds((const unsigned*)((const char*)(gbase) + (voff)[_i]), (LAS unsigned*)(lds + (bufoff) + ldsw + _i * 8192), 16, 0, 0); } while (0)
; #define PG8_STAGE_A(bufoff, gbase, h, vv) do { if constexpr (GATHER) { _Pragma("unroll") for (int _i = 0; _i < 2; ++_i) \
;         __builtin_amdgcn_global_load_lds((const unsigned*)((const char*)(gbase) + (vv)[h][_i]), (LAS unsigned*)(lds + (bufoff) + ldsw + _i * 8192), 16, 0, 0); } \
;         else { PG8_STAGE(bufoff, (gbase) + (h) * hstepA, voffA); } } while (0)
; #define PG8_LDA(dst, b, h) do { _Pragma("unroll") for (int m = 0; m < 4; ++m) _Pragma("unroll") for (int k = 0; k < 2; ++k) dst[m][k] = *(const LAS bf16x8*)(lds + PG8_SA(b, h) + aoff + m * 2048 + k * 1024); } while (0)
; #define PG8_LDB(dst, b, h) do { _Pragma("unroll") for (int n = 0; n < 2; ++n) _Pragma("unroll") for (int k = 0; k < 2; ++k) dst[n][k] = *(const LAS bf16x8*)(lds + PG8_SB(b, h) + boff + n * 2048 + k * 1024); } while (0)
; #define PG8_WAIT_L(n) asm volatile("s_waitcnt lgkmcnt(" #n ")" ::: "memory")
; template <class Epi, class Sched>
; __device__ __forceinline__ void gemm_phase(LAS unsigned char* lds, const int K, const int lda, const int ldb, const Sched& S, const Epi& E) {
;     ...
;         for (int t = 0; t < nt; t += 2) {
;             const bool last = (t == nt - 2);
;             const char* a1 = cA + (size_t)(t + 1) * kstep;
;             const char* a2 = last ? nA : cA + (size_t)(t + 2) * kstep; const char* b2 = last ? nB : cB + (size_t)(t + 2) * kstep;
;             const char* a3 = a2 + kstep; const char* b3 = b2 + kstep;
;             PG8_LDB(B0, 0, 0); PG8_SCHED; PG8_LDA(At, 0, 0); PG8_STAGE_A(PG8_SA(1, 1), a1, 1, vcur);
;             if constexpr (GATHER) { if (last) {
; #pragma unroll
;                 for (int h = 0; h < 2; ++h)
; #pragma unroll
;                     for (int i = 0; i < 2; ++i) vcur[h][i] = vnxt[h][i]; } }
;             PG8_WAIT_L(8); PG8_BAR; PG8_WAIT_L(0); PG8_MMA(0, 0, At, B0); PG8_BAR; PG8_SCHED;
;             PG8_LDB(B1, 0, 1); PG8_STAGE(PG8_SB(0, 0), b2, voffB);
;             PG8_BAR; PG8_WAIT_L(0); PG8_MMA(0, 1, At, B1); PG8_BAR;
;             PG8_LDA(At, 0, 1); PG8_STAGE_A(PG8_SA(0, 0), a2, 0, vcur);
;             PG8_BAR; PG8_WAIT_L(0); PG8_MMA(1, 0, At, B0); PG8_BAR; PG8_SCHED;
.LBB0_881:
	s_add_u32 s2, s14, 0xfffc0080
	s_addc_u32 s3, s15, -1
	s_add_i32 s20, 0, 0x10000
	v_add_u32_e32 v140, s20, v143
	ds_read_b128 v[146:149], v140
	ds_read_b128 v[150:153], v140 offset:1024
	ds_read_b128 v[154:157], v140 offset:2048
	ds_read_b128 v[158:161], v140 offset:3072
	s_cmp_eq_u32 s53, 12
	s_cselect_b32 s19, s9, s3
	s_cselect_b32 s18, s8, s2
	s_cselect_b32 s17, s11, s7
	s_cselect_b32 s16, s10, s5
	v_lshl_add_u64 v[140:141], s[14:15], 0, v[136:137]
	s_add_i32 m0, s13, 0xc000
	ds_read_b128 v[162:165], v145
	ds_read_b128 v[166:169], v145 offset:1024
	ds_read_b128 v[170:173], v145 offset:2048
	ds_read_b128 v[174:177], v145 offset:3072
	ds_read_b128 v[178:181], v145 offset:4096
	ds_read_b128 v[182:185], v145 offset:5120
	ds_read_b128 v[186:189], v145 offset:6144
	ds_read_b128 v[190:193], v145 offset:7168
	global_load_lds_dwordx4 v[140:141], off
	v_lshl_add_u64 v[140:141], s[14:15], 0, v[138:139]
	s_add_i32 m0, s13, 0xe000
	s_nop 0
	global_load_lds_dwordx4 v[140:141], off
	s_waitcnt lgkmcnt(8)
	s_barrier
	s_waitcnt lgkmcnt(0)
	s_setprio 1
	v_mfma_f32_16x16x32_bf16 v[126:129], v[146:149], v[162:165], v[126:129]
	v_mfma_f32_16x16x32_bf16 v[118:121], v[154:157], v[162:165], v[118:121]
	v_mfma_f32_16x16x32_bf16 v[110:113], v[146:149], v[170:173], v[110:113]
	v_mfma_f32_16x16x32_bf16 v[102:105], v[154:157], v[170:173], v[102:105]
	v_mfma_f32_16x16x32_bf16 v[94:97], v[146:149], v[178:181], v[94:97]
	v_mfma_f32_16x16x32_bf16 v[86:89], v[154:157], v[178:181], v[86:89]
	v_mfma_f32_16x16x32_bf16 v[78:81], v[146:149], v[186:189], v[78:81]
	v_mfma_f32_16x16x32_bf16 v[70:73], v[154:157], v[186:189], v[70:73]
	v_mfma_f32_16x16x32_bf16 v[126:129], v[150:153], v[166:169], v[126:129]
	v_mfma_f32_16x16x32_bf16 v[118:121], v[158:161], v[166:169], v[118:121]
	v_mfma_f32_16x16x32_bf16 v[110:113], v[150:153], v[174:177], v[110:113]
	v_mfma_f32_16x16x32_bf16 v[102:105], v[158:161], v[174:177], v[102:105]
	v_mfma_f32_16x16x32_bf16 v[94:97], v[150:153], v[182:185], v[94:97]
	v_mfma_f32_16x16x32_bf16 v[86:89], v[158:161], v[182:185], v[86:89]
	v_mfma_f32_16x16x32_bf16 v[78:81], v[150:153], v[190:193], v[78:81]
	v_mfma_f32_16x16x32_bf16 v[70:73], v[158:161], v[190:193], v[70:73]
	s_setprio 0
	s_barrier
	s_add_i32 s2, 0, 0x14000
	v_add_u32_e32 v140, s2, v143
	s_add_i32 s3, s20, s43
	ds_read_b128 v[216:219], v140
	ds_read_b128 v[220:223], v140 offset:1024
	ds_read_b128 v[224:227], v140 offset:2048
	ds_read_b128 v[228:231], v140 offset:3072
	v_lshl_add_u64 v[140:141], s[16:17], 0, v[0:1]
	s_mov_b32 m0, s3
	v_lshl_add_u64 v[194:195], s[16:17], 0, v[134:135]
	global_load_lds_dwordx4 v[140:141], off
	s_add_i32 m0, s3, 0x2000
	s_nop 0
	global_load_lds_dwordx4 v[194:195], off
	s_barrier
	s_waitcnt lgkmcnt(0)
	s_setprio 1
	v_mfma_f32_16x16x32_bf16 v[122:125], v[216:219], v[162:165], v[122:125]
	v_mfma_f32_16x16x32_bf16 v[114:117], v[224:227], v[162:165], v[114:117]
	v_mfma_f32_16x16x32_bf16 v[106:109], v[216:219], v[170:173], v[106:109]
	v_mfma_f32_16x16x32_bf16 v[98:101], v[224:227], v[170:173], v[98:101]
	v_mfma_f32_16x16x32_bf16 v[90:93], v[216:219], v[178:181], v[90:93]
	v_mfma_f32_16x16x32_bf16 v[82:85], v[224:227], v[178:181], v[82:85]
	v_mfma_f32_16x16x32_bf16 v[74:77], v[216:219], v[186:189], v[74:77]
	v_mfma_f32_16x16x32_bf16 v[66:69], v[224:227], v[186:189], v[66:69]
	v_mfma_f32_16x16x32_bf16 v[122:125], v[220:223], v[166:169], v[122:125]
	v_mfma_f32_16x16x32_bf16 v[114:117], v[228:231], v[166:169], v[114:117]
	v_mfma_f32_16x16x32_bf16 v[106:109], v[220:223], v[174:177], v[106:109]
	v_mfma_f32_16x16x32_bf16 v[98:101], v[228:231], v[174:177], v[98:101]
	v_mfma_f32_16x16x32_bf16 v[90:93], v[220:223], v[182:185], v[90:93]
	v_mfma_f32_16x16x32_bf16 v[82:85], v[228:231], v[182:185], v[82:85]
	v_mfma_f32_16x16x32_bf16 v[74:77], v[220:223], v[190:193], v[74:77]
	v_mfma_f32_16x16x32_bf16 v[66:69], v[228:231], v[190:193], v[66:69]
	s_setprio 0
	s_mov_b32 m0, s13
	v_lshl_add_u64 v[214:215], s[18:19], 0, v[130:131]
	s_barrier
	ds_read_b128 v[162:165], v145 offset:16384
	ds_read_b128 v[166:169], v145 offset:17408
	ds_read_b128 v[170:173], v145 offset:18432
	ds_read_b128 v[174:177], v145 offset:19456
	ds_read_b128 v[178:181], v145 offset:20480
	ds_read_b128 v[182:185], v145 offset:21504
	ds_read_b128 v[186:189], v145 offset:22528
	ds_read_b128 v[190:193], v145 offset:23552
	global_load_lds_dwordx4 v[214:215], off
	v_lshl_add_u64 v[232:233], s[18:19], 0, v[132:133]
	s_mov_b32 m0, s44
	s_nop 0
	global_load_lds_dwordx4 v[232:233], off
	s_barrier
	s_waitcnt lgkmcnt(0)
	s_setprio 1
	v_mfma_f32_16x16x32_bf16 v[62:65], v[146:149], v[162:165], v[62:65]
	v_mfma_f32_16x16x32_bf16 v[54:57], v[154:157], v[162:165], v[54:57]
	v_mfma_f32_16x16x32_bf16 v[46:49], v[146:149], v[170:173], v[46:49]
	v_mfma_f32_16x16x32_bf16 v[38:41], v[154:157], v[170:173], v[38:41]
	v_mfma_f32_16x16x32_bf16 v[30:33], v[146:149], v[178:181], v[30:33]
	v_mfma_f32_16x16x32_bf16 v[22:25], v[154:157], v[178:181], v[22:25]
	v_mfma_f32_16x16x32_bf16 v[14:17], v[146:149], v[186:189], v[14:17]
	v_mfma_f32_16x16x32_bf16 v[6:9], v[154:157], v[186:189], v[6:9]
	v_mfma_f32_16x16x32_bf16 v[62:65], v[150:153], v[166:169], v[62:65]
	v_mfma_f32_16x16x32_bf16 v[54:57], v[158:161], v[166:169], v[54:57]
	v_mfma_f32_16x16x32_bf16 v[46:49], v[150:153], v[174:177], v[46:49]
	v_mfma_f32_16x16x32_bf16 v[38:41], v[158:161], v[174:177], v[38:41]
	v_mfma_f32_16x16x32_bf16 v[30:33], v[150:153], v[182:185], v[30:33]
	v_mfma_f32_16x16x32_bf16 v[22:25], v[158:161], v[182:185], v[22:25]
	v_mfma_f32_16x16x32_bf16 v[14:17], v[150:153], v[190:193], v[14:17]
	v_mfma_f32_16x16x32_bf16 v[6:9], v[158:161], v[190:193], v[6:9]
	s_setprio 0
	s_barrier
; #define PG8_STAGE(bufoff, gbase, voff) do { _Pragma("unroll") for (int _i = 0; _i < 2; ++_i) \
;         __builtin_amdgcn_global_load_lds((const unsigned*)((const char*)(gbase) + (voff)[_i]), (LAS unsigned*)(lds + (bufoff) + ldsw + _i * 8192), 16, 0, 0); } while (0)
; #define PG8_STAGE_A(bufoff, gbase, h, vv) do { if constexpr (GATHER) { _Pragma("unroll") for (int _i = 0; _i < 2; ++_i) \
;         __builtin_amdgcn_global_load_lds((const unsigned*)((const char*)(gbase) + (vv)[h][_i]), (LAS unsigned*)(lds + (bufoff) + ldsw + _i * 8192), 16, 0, 0); } \
;         else { PG8_STAGE(bufoff, (gbase) + (h) * hstepA, voffA); } } while (0)
; #define PG8_LDA(dst, b, h) do { _Pragma("unroll") for (int m = 0; m < 4; ++m) _Pragma("unroll") for (int k = 0; k < 2; ++k) dst[m][k] = *(const LAS bf16x8*)(lds + PG8_SA(b, h) + aoff + m * 2048 + k * 1024); } while (0)
; #define PG8_LDB(dst, b, h) do { _Pragma("unroll") for (int n = 0; n < 2; ++n) _Pragma("unroll") for (int k = 0; k < 2; ++k) dst[n][k] = *(const LAS bf16x8*)(lds + PG8_SB(b, h) + boff + n * 2048 + k * 1024); } while (0)
; #define PG8_MMA(ai, bj, At, Bt) do { __builtin_amdgcn_s_setprio(1); _Pragma("unroll") for (int m = 0; m < 4; ++m) _Pragma("unroll") for (int n = 0; n < 2; ++n) _Pragma("unroll") for (int k = 0; k < 2; ++k) \
;         acc[ai][bj][m][n] = __builtin_amdgcn_mfma_f32_16x16x32_bf16(Bt[n][k], At[m][k], acc[ai][bj][m][n], 0, 0, 0); __builtin_amdgcn_s_setprio(0); } while (0)
; #define PG8_WAIT_V(n) asm volatile("s_waitcnt vmcnt(" #n ")" ::: "memory")
; #define PG8_WAIT_L(n) asm volatile("s_waitcnt lgkmcnt(" #n ")" ::: "memory")
; #define PG8_BAR __builtin_amdgcn_s_barrier()
; template <class Epi, class Sched>
; __device__ __forceinline__ void gemm_phase(LAS unsigned char* lds, const int K, const int lda, const int ldb, const Sched& S, const Epi& E) {
;     ...
;             PG8_BAR; PG8_WAIT_L(0); PG8_MMA(1, 0, At, B0); PG8_BAR; PG8_SCHED;
;             PG8_STAGE(PG8_SB(0, 1), b2 + hstepB, voffB);
;             PG8_WAIT_V(6); PG8_BAR; PG8_MMA(1, 1, At, B1); PG8_BAR;
;             PG8_LDB(B0, 1, 0); PG8_SCHED; PG8_LDA(At, 1, 0); PG8_STAGE_A(PG8_SA(0, 1), a2, 1, vcur);
;             PG8_WAIT_L(8); PG8_BAR; PG8_WAIT_L(0); PG8_MMA(0, 0, At, B0); PG8_BAR; PG8_SCHED;
;             PG8_LDB(B1, 1, 1); PG8_STAGE(PG8_SB(1, 0), b3, voffB);
;             PG8_BAR; PG8_WAIT_L(0); PG8_MMA(0, 1, At, B1); PG8_BAR;
	s_add_u32 s54, s16, 0x40000
	s_addc_u32 s55, s17, 0
	s_add_i32 s2, s2, s43
	v_lshl_add_u64 v[146:147], s[54:55], 0, v[0:1]
	s_mov_b32 m0, s2
	s_nop 0
	global_load_lds_dwordx4 v[146:147], off
	v_lshl_add_u64 v[146:147], s[54:55], 0, v[134:135]
	s_add_i32 m0, s2, 0x2000
	s_nop 0
	global_load_lds_dwordx4 v[146:147], off
	s_waitcnt vmcnt(6)
	s_barrier
	s_setprio 1
	v_mfma_f32_16x16x32_bf16 v[58:61], v[216:219], v[162:165], v[58:61]
	v_mfma_f32_16x16x32_bf16 v[50:53], v[224:227], v[162:165], v[50:53]
	v_mfma_f32_16x16x32_bf16 v[42:45], v[216:219], v[170:173], v[42:45]
	v_mfma_f32_16x16x32_bf16 v[34:37], v[224:227], v[170:173], v[34:37]
	v_mfma_f32_16x16x32_bf16 v[26:29], v[216:219], v[178:181], v[26:29]
	v_mfma_f32_16x16x32_bf16 v[18:21], v[224:227], v[178:181], v[18:21]
	v_mfma_f32_16x16x32_bf16 v[10:13], v[216:219], v[186:189], v[10:13]
	v_mfma_f32_16x16x32_bf16 v[2:5], v[224:227], v[186:189], v[2:5]
	v_mfma_f32_16x16x32_bf16 v[58:61], v[220:223], v[166:169], v[58:61]
	v_mfma_f32_16x16x32_bf16 v[50:53], v[228:231], v[166:169], v[50:53]
	v_mfma_f32_16x16x32_bf16 v[42:45], v[220:223], v[174:177], v[42:45]
	v_mfma_f32_16x16x32_bf16 v[34:37], v[228:231], v[174:177], v[34:37]
	v_mfma_f32_16x16x32_bf16 v[26:29], v[220:223], v[182:185], v[26:29]
	v_mfma_f32_16x16x32_bf16 v[18:21], v[228:231], v[182:185], v[18:21]
	v_mfma_f32_16x16x32_bf16 v[10:13], v[220:223], v[190:193], v[10:13]
	v_mfma_f32_16x16x32_bf16 v[2:5], v[228:231], v[190:193], v[2:5]
	s_setprio 0
	s_add_i32 s2, 0, 0x18000
	v_add_u32_e32 v158, s2, v143
	s_barrier
	ds_read_b128 v[146:149], v158
	ds_read_b128 v[150:153], v158 offset:1024
	ds_read_b128 v[154:157], v158 offset:2048
	ds_read_b128 v[158:161], v158 offset:3072
	s_add_u32 s18, s18, 0x40000
	s_addc_u32 s19, s19, 0
	s_mov_b32 m0, s45
	v_lshl_add_u64 v[216:217], s[18:19], 0, v[130:131]
	ds_read_b128 v[162:165], v145 offset:32768
	ds_read_b128 v[166:169], v145 offset:33792
	ds_read_b128 v[170:173], v145 offset:34816
	ds_read_b128 v[174:177], v145 offset:35840
	ds_read_b128 v[178:181], v145 offset:36864
	ds_read_b128 v[182:185], v145 offset:37888
	ds_read_b128 v[186:189], v145 offset:38912
	ds_read_b128 v[190:193], v145 offset:39936
	global_load_lds_dwordx4 v[216:217], off
	v_lshl_add_u64 v[216:217], s[18:19], 0, v[132:133]
	s_mov_b32 m0, s46
	s_nop 0
	global_load_lds_dwordx4 v[216:217], off
	s_waitcnt lgkmcnt(8)
	s_barrier
	s_waitcnt lgkmcnt(0)
	s_setprio 1
	v_mfma_f32_16x16x32_bf16 v[126:129], v[146:149], v[162:165], v[126:129]
	v_mfma_f32_16x16x32_bf16 v[118:121], v[154:157], v[162:165], v[118:121]
	v_mfma_f32_16x16x32_bf16 v[110:113], v[146:149], v[170:173], v[110:113]
	v_mfma_f32_16x16x32_bf16 v[102:105], v[154:157], v[170:173], v[102:105]
	v_mfma_f32_16x16x32_bf16 v[94:97], v[146:149], v[178:181], v[94:97]
	v_mfma_f32_16x16x32_bf16 v[86:89], v[154:157], v[178:181], v[86:89]
	v_mfma_f32_16x16x32_bf16 v[78:81], v[146:149], v[186:189], v[78:81]
	v_mfma_f32_16x16x32_bf16 v[70:73], v[154:157], v[186:189], v[70:73]
	v_mfma_f32_16x16x32_bf16 v[126:129], v[150:153], v[166:169], v[126:129]
	v_mfma_f32_16x16x32_bf16 v[118:121], v[158:161], v[166:169], v[118:121]
	v_mfma_f32_16x16x32_bf16 v[110:113], v[150:153], v[174:177], v[110:113]
	v_mfma_f32_16x16x32_bf16 v[102:105], v[158:161], v[174:177], v[102:105]
	v_mfma_f32_16x16x32_bf16 v[94:97], v[150:153], v[182:185], v[94:97]
	v_mfma_f32_16x16x32_bf16 v[86:89], v[158:161], v[182:185], v[86:89]
	v_mfma_f32_16x16x32_bf16 v[78:81], v[150:153], v[190:193], v[78:81]
	v_mfma_f32_16x16x32_bf16 v[70:73], v[158:161], v[190:193], v[70:73]
	s_setprio 0
	s_barrier
	s_add_i32 s3, 0, 0x1c000
	s_add_i32 s2, s2, s43
	v_add_u32_e32 v228, s3, v143
	v_lshl_add_u64 v[140:141], v[140:141], 0, s[64:65]
	s_mov_b32 m0, s2
	ds_read_b128 v[216:219], v228
	ds_read_b128 v[220:223], v228 offset:1024
	ds_read_b128 v[224:227], v228 offset:2048
	ds_read_b128 v[228:231], v228 offset:3072
	global_load_lds_dwordx4 v[140:141], off
	v_lshl_add_u64 v[140:141], v[194:195], 0, s[64:65]
	s_add_i32 m0, s2, 0x2000
	s_nop 0
	global_load_lds_dwordx4 v[140:141], off
	s_barrier
; #define PG8_STAGE(bufoff, gbase, voff) do { _Pragma("unroll") for (int _i = 0; _i < 2; ++_i) \
;         __builtin_amdgcn_global_load_lds((const unsigned*)((const char*)(gbase) + (voff)[_i]), (LAS unsigned*)(lds + (bufoff) + ldsw + _i * 8192), 16, 0, 0); } while (0)
; #define PG8_STAGE_A(bufoff, gbase, h, vv) do { if constexpr (GATHER) { _Pragma("unroll") for (int _i = 0; _i < 2; ++_i) \
;         __builtin_amdgcn_global_load_lds((const unsigned*)((const char*)(gbase) + (vv)[h][_i]), (LAS unsigned*)(lds + (bufoff) + ldsw + _i * 8192), 16, 0, 0); } \
;         else { PG8_STAGE(bufoff, (gbase) + (h) * hstepA, voffA); } } while (0)
; #define PG8_LDA(dst, b, h) do { _Pragma("unroll") for (int m = 0; m < 4; ++m) _Pragma("unroll") for (int k = 0; k < 2; ++k) dst[m][k] = *(const LAS bf16x8*)(lds + PG8_SA(b, h) + aoff + m * 2048 + k * 1024); } while (0)
; #define PG8_MMA(ai, bj, At, Bt) do { __builtin_amdgcn_s_setprio(1); _Pragma("unroll") for (int m = 0; m < 4; ++m) _Pragma("unroll") for (int n = 0; n < 2; ++n) _Pragma("unroll") for (int k = 0; k < 2; ++k) \
;         acc[ai][bj][m][n] = __builtin_amdgcn_mfma_f32_16x16x32_bf16(Bt[n][k], At[m][k], acc[ai][bj][m][n], 0, 0, 0); __builtin_amdgcn_s_setprio(0); } while (0)
; template <class Epi, class Sched>
; __device__ __forceinline__ void gemm_phase(LAS unsigned char* lds, const int K, const int lda, const int ldb, const Sched& S, const Epi& E) {
;     ...
;             PG8_BAR; PG8_WAIT_L(0); PG8_MMA(0, 1, At, B1); PG8_BAR;
;             PG8_LDA(At, 1, 1); PG8_STAGE_A(PG8_SA(1, 0), a3, 0, vcur);
;             PG8_BAR; PG8_WAIT_L(0); PG8_MMA(1, 0, At, B0); PG8_BAR; PG8_SCHED;
;             PG8_STAGE(PG8_SB(1, 1), b3 + hstepB, voffB);
;             PG8_WAIT_V(6); PG8_BAR; PG8_MMA(1, 1, At, B1); PG8_BAR;
;         }
;         if constexpr (GATHER) { Unit n2; if (has_next && S.next(ui + 2, n2)) ld_ix(n2.pm, ix1); }
;         if constexpr (!Epi::AFTER_DRAIN) E(acc, cur, wr, wc, fr, fq);
;         if (!has_next) break;
; #pragma unroll
;         for (int a = 0; a < 2; ++a)
; #pragma unroll
;             for (int b = 0; b < 2; ++b)
; #pragma unroll
;                 for (int m = 0; m < 4; ++m)
; #pragma unroll
;                     for (int n = 0; n < 2; ++n) acc[a][b][m][n] = (f32x4){0.f, 0.f, 0.f, 0.f};
;         cur = nxt; cA = nA; cB = nB; ++ui;
;     }
;     PG8_WAIT_V(0);
;     if (wr == 0) PG8_BAR;
;     PG8_BAR;
	s_waitcnt lgkmcnt(0)
	s_setprio 1
	v_mfma_f32_16x16x32_bf16 v[122:125], v[216:219], v[162:165], v[122:125]
	v_mfma_f32_16x16x32_bf16 v[114:117], v[224:227], v[162:165], v[114:117]
	v_mfma_f32_16x16x32_bf16 v[106:109], v[216:219], v[170:173], v[106:109]
	v_mfma_f32_16x16x32_bf16 v[98:101], v[224:227], v[170:173], v[98:101]
	v_mfma_f32_16x16x32_bf16 v[90:93], v[216:219], v[178:181], v[90:93]
	v_mfma_f32_16x16x32_bf16 v[82:85], v[224:227], v[178:181], v[82:85]
	v_mfma_f32_16x16x32_bf16 v[74:77], v[216:219], v[186:189], v[74:77]
	v_mfma_f32_16x16x32_bf16 v[66:69], v[224:227], v[186:189], v[66:69]
	v_mfma_f32_16x16x32_bf16 v[122:125], v[220:223], v[166:169], v[122:125]
	v_mfma_f32_16x16x32_bf16 v[114:117], v[228:231], v[166:169], v[114:117]
	v_mfma_f32_16x16x32_bf16 v[106:109], v[220:223], v[174:177], v[106:109]
	v_mfma_f32_16x16x32_bf16 v[98:101], v[228:231], v[174:177], v[98:101]
	v_mfma_f32_16x16x32_bf16 v[90:93], v[220:223], v[182:185], v[90:93]
	v_mfma_f32_16x16x32_bf16 v[82:85], v[228:231], v[182:185], v[82:85]
	v_mfma_f32_16x16x32_bf16 v[74:77], v[220:223], v[190:193], v[74:77]
	v_mfma_f32_16x16x32_bf16 v[66:69], v[228:231], v[190:193], v[66:69]
	s_setprio 0
	s_mov_b32 m0, s47
	v_lshl_add_u64 v[140:141], v[214:215], 0, s[64:65]
	s_barrier
	ds_read_b128 v[162:165], v145 offset:49152
	ds_read_b128 v[166:169], v145 offset:50176
	ds_read_b128 v[170:173], v145 offset:51200
	ds_read_b128 v[174:177], v145 offset:52224
	ds_read_b128 v[178:181], v145 offset:53248
	ds_read_b128 v[182:185], v145 offset:54272
	ds_read_b128 v[186:189], v145 offset:55296
	ds_read_b128 v[190:193], v145 offset:56320
	global_load_lds_dwordx4 v[140:141], off
	v_lshl_add_u64 v[140:141], v[232:233], 0, s[64:65]
	s_mov_b32 m0, s48
	s_nop 0
	global_load_lds_dwordx4 v[140:141], off
	s_barrier
	s_waitcnt lgkmcnt(0)
	s_setprio 1
	v_mfma_f32_16x16x32_bf16 v[62:65], v[146:149], v[162:165], v[62:65]
	v_mfma_f32_16x16x32_bf16 v[54:57], v[154:157], v[162:165], v[54:57]
	v_mfma_f32_16x16x32_bf16 v[46:49], v[146:149], v[170:173], v[46:49]
	v_mfma_f32_16x16x32_bf16 v[38:41], v[154:157], v[170:173], v[38:41]
	v_mfma_f32_16x16x32_bf16 v[30:33], v[146:149], v[178:181], v[30:33]
	v_mfma_f32_16x16x32_bf16 v[22:25], v[154:157], v[178:181], v[22:25]
	v_mfma_f32_16x16x32_bf16 v[14:17], v[146:149], v[186:189], v[14:17]
	v_mfma_f32_16x16x32_bf16 v[6:9], v[154:157], v[186:189], v[6:9]
	v_mfma_f32_16x16x32_bf16 v[62:65], v[150:153], v[166:169], v[62:65]
	v_mfma_f32_16x16x32_bf16 v[54:57], v[158:161], v[166:169], v[54:57]
	v_mfma_f32_16x16x32_bf16 v[46:49], v[150:153], v[174:177], v[46:49]
	v_mfma_f32_16x16x32_bf16 v[38:41], v[158:161], v[174:177], v[38:41]
	v_mfma_f32_16x16x32_bf16 v[30:33], v[150:153], v[182:185], v[30:33]
	v_mfma_f32_16x16x32_bf16 v[22:25], v[158:161], v[182:185], v[22:25]
	v_mfma_f32_16x16x32_bf16 v[14:17], v[150:153], v[190:193], v[14:17]
	v_mfma_f32_16x16x32_bf16 v[6:9], v[158:161], v[190:193], v[6:9]
	s_setprio 0
	s_barrier
	s_add_u32 s16, s16, 0x40080
	s_addc_u32 s17, s17, 0
	s_add_i32 s2, s3, s43
	v_lshl_add_u64 v[140:141], s[16:17], 0, v[0:1]
	s_mov_b32 m0, s2
	s_nop 0
	global_load_lds_dwordx4 v[140:141], off
	v_lshl_add_u64 v[140:141], s[16:17], 0, v[134:135]
	s_add_i32 m0, s2, 0x2000
	s_nop 0
	global_load_lds_dwordx4 v[140:141], off
	s_waitcnt vmcnt(6)
	s_barrier
	s_setprio 1
	v_mfma_f32_16x16x32_bf16 v[58:61], v[216:219], v[162:165], v[58:61]
	v_mfma_f32_16x16x32_bf16 v[50:53], v[224:227], v[162:165], v[50:53]
	v_mfma_f32_16x16x32_bf16 v[42:45], v[216:219], v[170:173], v[42:45]
	v_mfma_f32_16x16x32_bf16 v[34:37], v[224:227], v[170:173], v[34:37]
	v_mfma_f32_16x16x32_bf16 v[26:29], v[216:219], v[178:181], v[26:29]
	v_mfma_f32_16x16x32_bf16 v[18:21], v[224:227], v[178:181], v[18:21]
	v_mfma_f32_16x16x32_bf16 v[10:13], v[216:219], v[186:189], v[10:13]
	v_mfma_f32_16x16x32_bf16 v[2:5], v[224:227], v[186:189], v[2:5]
	v_mfma_f32_16x16x32_bf16 v[58:61], v[220:223], v[166:169], v[58:61]
	v_mfma_f32_16x16x32_bf16 v[50:53], v[228:231], v[166:169], v[50:53]
	v_mfma_f32_16x16x32_bf16 v[42:45], v[220:223], v[174:177], v[42:45]
	v_mfma_f32_16x16x32_bf16 v[34:37], v[228:231], v[174:177], v[34:37]
	v_mfma_f32_16x16x32_bf16 v[26:29], v[220:223], v[182:185], v[26:29]
	v_mfma_f32_16x16x32_bf16 v[18:21], v[228:231], v[182:185], v[18:21]
	v_mfma_f32_16x16x32_bf16 v[10:13], v[220:223], v[190:193], v[10:13]
	v_mfma_f32_16x16x32_bf16 v[2:5], v[228:231], v[190:193], v[2:5]
	s_setprio 0
	s_add_i32 s53, s53, 2
	s_add_u32 s14, s14, 0x100
	s_addc_u32 s15, s15, 0
	s_add_u32 s5, s5, 0x100
	s_addc_u32 s7, s7, 0
	s_cmp_gt_u32 s53, 13
	s_barrier
	s_cbranch_scc0 .LBB0_881
	s_cmpk_gt_u32 s36, 0xff
	s_cbranch_scc1 .Lgx_a_pre
	s_barrier

; #define PG8_STAGE(bufoff, gbase, voff) do { _Pragma("unroll") for (int _i = 0; _i < 2; ++_i) \
;         __builtin_amdgcn_global_load_lds((const unsigned*)((const char*)(gbase) + (voff)[_i]), (LAS unsigned*)(lds + (bufoff) + ldsw + _i * 8192), 16, 0, 0); } while (0)
; #define PG8_STAGE_A(bufoff, gbase, h, vv) do { if constexpr (GATHER) { _Pragma("unroll") for (int _i = 0; _i < 2; ++_i) \
;         __builtin_amdgcn_global_load_lds((const unsigned*)((const char*)(gbase) + (vv)[h][_i]), (LAS unsigned*)(lds + (bufoff) + ldsw + _i * 8192), 16, 0, 0); } \
;         else { PG8_STAGE(bufoff, (gbase) + (h) * hstepA, voffA); } } while (0)
; #define PG8_LDA(dst, b, h) do { _Pragma("unroll") for (int m = 0; m < 4; ++m) _Pragma("unroll") for (int k = 0; k < 2; ++k) dst[m][k] = *(const LAS bf16x8*)(lds + PG8_SA(b, h) + aoff + m * 2048 + k * 1024); } while (0)
; #define PG8_LDB(dst, b, h) do { _Pragma("unroll") for (int n = 0; n < 2; ++n) _Pragma("unroll") for (int k = 0; k < 2; ++k) dst[n][k] = *(const LAS bf16x8*)(lds + PG8_SB(b, h) + boff + n * 2048 + k * 1024); } while (0)
; #define PG8_WAIT_L(n) asm volatile("s_waitcnt lgkmcnt(" #n ")" ::: "memory")
; #define PG8_BAR __builtin_amdgcn_s_barrier()
; template <class Epi, class Sched>
; __device__ __forceinline__ void gemm_phase(LAS unsigned char* lds, const int K, const int lda, const int ldb, const Sched& S, const Epi& E) {
;     ...
;         for (int t = 0; t < nt; t += 2) {
;             const bool last = (t == nt - 2);
;             const char* a1 = cA + (size_t)(t + 1) * kstep;
;             const char* a2 = last ? nA : cA + (size_t)(t + 2) * kstep; const char* b2 = last ? nB : cB + (size_t)(t + 2) * kstep;
;             const char* a3 = a2 + kstep; const char* b3 = b2 + kstep;
;             PG8_LDB(B0, 0, 0); PG8_SCHED; PG8_LDA(At, 0, 0); PG8_STAGE_A(PG8_SA(1, 1), a1, 1, vcur);
;             if constexpr (GATHER) { if (last) {
; #pragma unroll
;                 for (int h = 0; h < 2; ++h)
; #pragma unroll
;                     for (int i = 0; i < 2; ++i) vcur[h][i] = vnxt[h][i]; } }
;             PG8_WAIT_L(8); PG8_BAR; PG8_WAIT_L(0); PG8_MMA(0, 0, At, B0); PG8_BAR; PG8_SCHED;
;             PG8_LDB(B1, 0, 1); PG8_STAGE(PG8_SB(0, 0), b2, voffB);
;             PG8_BAR; PG8_WAIT_L(0); PG8_MMA(0, 1, At, B1); PG8_BAR;
;             PG8_LDA(At, 0, 1); PG8_STAGE_A(PG8_SA(0, 0), a2, 0, vcur);
.LBB0_937:
	s_add_u32 s2, s8, s16
	s_addc_u32 s3, s9, s17
	s_add_u32 s20, s2, 0x100
	s_addc_u32 s21, s3, 0
	s_and_b64 s[18:19], s[14:15], exec
	s_cselect_b32 s19, s5, s21
	s_cselect_b32 s18, s4, s20
	s_add_u32 s16, s10, s16
	s_addc_u32 s17, s11, s17
	s_add_u32 s16, s16, 0x100
	s_addc_u32 s17, s17, 0
	s_add_i32 s20, 0, 0x10000
	s_and_b64 s[14:15], s[14:15], exec
	s_cselect_b32 s37, s7, s17
	s_cselect_b32 s36, s6, s16
	s_add_u32 s38, s2, 0x10080
	s_addc_u32 s39, s3, 0
	s_add_i32 s21, s20, s41
	s_add_i32 m0, s42, 0xc000
	s_add_i32 s2, s42, 0xe000
	s_add_i32 s3, 0, 0x14000
	s_add_i32 s50, s21, 0x2000
	s_add_u32 s34, s36, 0x10000
	v_add_u32_e32 v72, s20, v74
	s_addc_u32 s35, s37, 0
	s_add_i32 s51, s3, s41
	ds_read_b128 v[68:71], v72
	ds_read_b128 v[82:85], v72 offset:1024
	ds_read_b128 v[86:89], v72 offset:2048
	ds_read_b128 v[90:93], v72 offset:3072
	s_add_i32 s56, s51, 0x2000
	s_add_i32 s57, 0, 0x18000
	s_add_u32 s16, s18, 0x10000
	s_addc_u32 s17, s19, 0
	s_add_i32 s55, s57, s41
	s_add_i32 s54, 0, 0x1c000
	s_add_i32 s53, s55, 0x2000
	s_add_u32 s14, s36, 0x10080
	s_addc_u32 s15, s37, 0
	s_add_i32 s20, s54, s41
	s_add_i32 s60, s20, 0x2000
	v_lshl_add_u64 v[72:73], s[38:39], 0, v[0:1]
	ds_read_b128 v[94:97], v80
	ds_read_b128 v[98:101], v80 offset:1024
	ds_read_b128 v[102:105], v80 offset:2048
	ds_read_b128 v[106:109], v80 offset:3072
	ds_read_b128 v[110:113], v80 offset:4096
	ds_read_b128 v[114:117], v80 offset:5120
	ds_read_b128 v[118:121], v80 offset:6144
	ds_read_b128 v[122:125], v80 offset:7168
	global_load_lds_dwordx4 v[72:73], off
	v_lshl_add_u64 v[72:73], s[38:39], 0, v[66:67]
	s_mov_b32 m0, s2
	s_nop 0
	global_load_lds_dwordx4 v[72:73], off
	s_waitcnt lgkmcnt(8)
	s_barrier
	s_waitcnt lgkmcnt(0)
	s_setprio 1
	v_mfma_f32_16x16x32_bf16 v[62:65], v[68:71], v[94:97], v[62:65]
	v_mfma_f32_16x16x32_bf16 v[58:61], v[86:89], v[94:97], v[58:61]
	v_mfma_f32_16x16x32_bf16 v[46:49], v[68:71], v[102:105], v[46:49]
	v_mfma_f32_16x16x32_bf16 v[42:45], v[86:89], v[102:105], v[42:45]
	v_mfma_f32_16x16x32_bf16 v[30:33], v[68:71], v[110:113], v[30:33]
	v_mfma_f32_16x16x32_bf16 v[26:29], v[86:89], v[110:113], v[26:29]
	v_mfma_f32_16x16x32_bf16 v[14:17], v[68:71], v[118:121], v[14:17]
	v_mfma_f32_16x16x32_bf16 v[10:13], v[86:89], v[118:121], v[10:13]
	v_mfma_f32_16x16x32_bf16 v[62:65], v[82:85], v[98:101], v[62:65]
	v_mfma_f32_16x16x32_bf16 v[58:61], v[90:93], v[98:101], v[58:61]
	v_mfma_f32_16x16x32_bf16 v[46:49], v[82:85], v[106:109], v[46:49]
	v_mfma_f32_16x16x32_bf16 v[42:45], v[90:93], v[106:109], v[42:45]
	v_mfma_f32_16x16x32_bf16 v[30:33], v[82:85], v[114:117], v[30:33]
	v_mfma_f32_16x16x32_bf16 v[26:29], v[90:93], v[114:117], v[26:29]
	v_mfma_f32_16x16x32_bf16 v[14:17], v[82:85], v[122:125], v[14:17]
	v_mfma_f32_16x16x32_bf16 v[10:13], v[90:93], v[122:125], v[10:13]
	s_setprio 0
	s_barrier
	v_add_u32_e32 v72, s3, v74
	s_mov_b32 m0, s21
	ds_read_b128 v[68:71], v72
	ds_read_b128 v[82:85], v72 offset:1024
	ds_read_b128 v[86:89], v72 offset:2048
	ds_read_b128 v[90:93], v72 offset:3072
	v_lshl_add_u64 v[72:73], s[36:37], 0, v[0:1]
	global_load_lds_dwordx4 v[72:73], off
	v_lshl_add_u64 v[126:127], s[36:37], 0, v[66:67]
	s_mov_b32 m0, s50
	s_nop 0
	global_load_lds_dwordx4 v[126:127], off
	s_barrier
	s_waitcnt lgkmcnt(0)
	s_setprio 1
	v_mfma_f32_16x16x32_bf16 v[54:57], v[68:71], v[94:97], v[54:57]
	v_mfma_f32_16x16x32_bf16 v[50:53], v[86:89], v[94:97], v[50:53]
	v_mfma_f32_16x16x32_bf16 v[38:41], v[68:71], v[102:105], v[38:41]
	v_mfma_f32_16x16x32_bf16 v[34:37], v[86:89], v[102:105], v[34:37]
	v_mfma_f32_16x16x32_bf16 v[22:25], v[68:71], v[110:113], v[22:25]
	v_mfma_f32_16x16x32_bf16 v[18:21], v[86:89], v[110:113], v[18:21]
	v_mfma_f32_16x16x32_bf16 v[6:9], v[68:71], v[118:121], v[6:9]
	v_mfma_f32_16x16x32_bf16 v[2:5], v[86:89], v[118:121], v[2:5]
	v_mfma_f32_16x16x32_bf16 v[54:57], v[82:85], v[98:101], v[54:57]
	v_mfma_f32_16x16x32_bf16 v[50:53], v[90:93], v[98:101], v[50:53]
	v_mfma_f32_16x16x32_bf16 v[38:41], v[82:85], v[106:109], v[38:41]
	v_mfma_f32_16x16x32_bf16 v[34:37], v[90:93], v[106:109], v[34:37]
	v_mfma_f32_16x16x32_bf16 v[22:25], v[82:85], v[114:117], v[22:25]
	v_mfma_f32_16x16x32_bf16 v[18:21], v[90:93], v[114:117], v[18:21]
	v_mfma_f32_16x16x32_bf16 v[6:9], v[82:85], v[122:125], v[6:9]
	v_mfma_f32_16x16x32_bf16 v[2:5], v[90:93], v[122:125], v[2:5]
	s_setprio 0
	s_mov_b32 m0, s42
	v_lshl_add_u64 v[128:129], s[18:19], 0, v[0:1]
	s_barrier
	global_load_lds_dwordx4 v[128:129], off
	v_lshl_add_u64 v[130:131], s[18:19], 0, v[66:67]
	s_mov_b32 m0, s43
	s_nop 0
	global_load_lds_dwordx4 v[130:131], off
	s_barrier
; #define PG8_STAGE(bufoff, gbase, voff) do { _Pragma("unroll") for (int _i = 0; _i < 2; ++_i) \
;         __builtin_amdgcn_global_load_lds((const unsigned*)((const char*)(gbase) + (voff)[_i]), (LAS unsigned*)(lds + (bufoff) + ldsw + _i * 8192), 16, 0, 0); } while (0)
; #define PG8_STAGE_A(bufoff, gbase, h, vv) do { if constexpr (GATHER) { _Pragma("unroll") for (int _i = 0; _i < 2; ++_i) \
;         __builtin_amdgcn_global_load_lds((const unsigned*)((const char*)(gbase) + (vv)[h][_i]), (LAS unsigned*)(lds + (bufoff) + ldsw + _i * 8192), 16, 0, 0); } \
;         else { PG8_STAGE(bufoff, (gbase) + (h) * hstepA, voffA); } } while (0)
; #define PG8_LDA(dst, b, h) do { _Pragma("unroll") for (int m = 0; m < 4; ++m) _Pragma("unroll") for (int k = 0; k < 2; ++k) dst[m][k] = *(const LAS bf16x8*)(lds + PG8_SA(b, h) + aoff + m * 2048 + k * 1024); } while (0)
; #define PG8_LDB(dst, b, h) do { _Pragma("unroll") for (int n = 0; n < 2; ++n) _Pragma("unroll") for (int k = 0; k < 2; ++k) dst[n][k] = *(const LAS bf16x8*)(lds + PG8_SB(b, h) + boff + n * 2048 + k * 1024); } while (0)
; #define PG8_WAIT_V(n) asm volatile("s_waitcnt vmcnt(" #n ")" ::: "memory")
; #define PG8_WAIT_L(n) asm volatile("s_waitcnt lgkmcnt(" #n ")" ::: "memory")
; #define PG8_BAR __builtin_amdgcn_s_barrier()
; template <class Epi, class Sched>
; __device__ __forceinline__ void gemm_phase(LAS unsigned char* lds, const int K, const int lda, const int ldb, const Sched& S, const Epi& E) {
;     ...
;             PG8_LDA(At, 0, 1); PG8_STAGE_A(PG8_SA(0, 0), a2, 0, vcur);
;             PG8_BAR; PG8_WAIT_L(0); PG8_MMA(1, 0, At, B0); PG8_BAR; PG8_SCHED;
;             PG8_STAGE(PG8_SB(0, 1), b2 + hstepB, voffB);
;             PG8_WAIT_V(6); PG8_BAR; PG8_MMA(1, 1, At, B1); PG8_BAR;
;             PG8_LDB(B0, 1, 0); PG8_SCHED; PG8_LDA(At, 1, 0); PG8_STAGE_A(PG8_SA(0, 1), a2, 1, vcur);
;             PG8_WAIT_L(8); PG8_BAR; PG8_WAIT_L(0); PG8_MMA(0, 0, At, B0); PG8_BAR; PG8_SCHED;
;             PG8_LDB(B1, 1, 1); PG8_STAGE(PG8_SB(1, 0), b3, voffB);
;             PG8_BAR; PG8_WAIT_L(0); PG8_MMA(0, 1, At, B1); PG8_BAR;
;             PG8_LDA(At, 1, 1); PG8_STAGE_A(PG8_SA(1, 0), a3, 0, vcur);
;             PG8_BAR; PG8_WAIT_L(0); PG8_MMA(1, 0, At, B0); PG8_BAR; PG8_SCHED;
;             PG8_STAGE(PG8_SB(1, 1), b3 + hstepB, voffB);
;             PG8_WAIT_V(6); PG8_BAR; PG8_MMA(1, 1, At, B1); PG8_BAR;
;         }
	s_waitcnt lgkmcnt(0)
	s_setprio 1
	s_setprio 0
	s_barrier
	s_mov_b32 m0, s51
	v_lshl_add_u64 v[68:69], s[34:35], 0, v[0:1]
	global_load_lds_dwordx4 v[68:69], off
	v_lshl_add_u64 v[68:69], s[34:35], 0, v[66:67]
	s_mov_b32 m0, s56
	s_nop 0
	global_load_lds_dwordx4 v[68:69], off
	s_waitcnt vmcnt(6)
	s_barrier
	s_setprio 1
	s_setprio 0
	v_add_u32_e32 v81, s57, v74
	s_barrier
	ds_read_b128 v[68:71], v81
	ds_read_b128 v[82:85], v81 offset:1024
	ds_read_b128 v[86:89], v81 offset:2048
	ds_read_b128 v[90:93], v81 offset:3072
	s_mov_b32 m0, s44
	v_lshl_add_u64 v[132:133], s[16:17], 0, v[0:1]
	ds_read_b128 v[94:97], v80 offset:32768
	ds_read_b128 v[98:101], v80 offset:33792
	ds_read_b128 v[102:105], v80 offset:34816
	ds_read_b128 v[106:109], v80 offset:35840
	ds_read_b128 v[110:113], v80 offset:36864
	ds_read_b128 v[114:117], v80 offset:37888
	ds_read_b128 v[118:121], v80 offset:38912
	ds_read_b128 v[122:125], v80 offset:39936
	global_load_lds_dwordx4 v[132:133], off
	v_lshl_add_u64 v[132:133], s[16:17], 0, v[66:67]
	s_mov_b32 m0, s45
	s_nop 0
	global_load_lds_dwordx4 v[132:133], off
	s_waitcnt lgkmcnt(8)
	s_barrier
	s_waitcnt lgkmcnt(0)
	s_setprio 1
	v_mfma_f32_16x16x32_bf16 v[62:65], v[68:71], v[94:97], v[62:65]
	v_mfma_f32_16x16x32_bf16 v[58:61], v[86:89], v[94:97], v[58:61]
	v_mfma_f32_16x16x32_bf16 v[46:49], v[68:71], v[102:105], v[46:49]
	v_mfma_f32_16x16x32_bf16 v[42:45], v[86:89], v[102:105], v[42:45]
	v_mfma_f32_16x16x32_bf16 v[30:33], v[68:71], v[110:113], v[30:33]
	v_mfma_f32_16x16x32_bf16 v[26:29], v[86:89], v[110:113], v[26:29]
	v_mfma_f32_16x16x32_bf16 v[14:17], v[68:71], v[118:121], v[14:17]
	v_mfma_f32_16x16x32_bf16 v[10:13], v[86:89], v[118:121], v[10:13]
	v_mfma_f32_16x16x32_bf16 v[62:65], v[82:85], v[98:101], v[62:65]
	v_mfma_f32_16x16x32_bf16 v[58:61], v[90:93], v[98:101], v[58:61]
	v_mfma_f32_16x16x32_bf16 v[46:49], v[82:85], v[106:109], v[46:49]
	v_mfma_f32_16x16x32_bf16 v[42:45], v[90:93], v[106:109], v[42:45]
	v_mfma_f32_16x16x32_bf16 v[30:33], v[82:85], v[114:117], v[30:33]
	v_mfma_f32_16x16x32_bf16 v[26:29], v[90:93], v[114:117], v[26:29]
	v_mfma_f32_16x16x32_bf16 v[14:17], v[82:85], v[122:125], v[14:17]
	v_mfma_f32_16x16x32_bf16 v[10:13], v[90:93], v[122:125], v[10:13]
	s_setprio 0
	s_barrier
	s_mov_b32 m0, s55
	v_add_u32_e32 v81, s54, v74
	v_lshl_add_u64 v[72:73], v[72:73], 0, s[64:65]
	ds_read_b128 v[68:71], v81
	ds_read_b128 v[82:85], v81 offset:1024
	ds_read_b128 v[86:89], v81 offset:2048
	ds_read_b128 v[90:93], v81 offset:3072
	global_load_lds_dwordx4 v[72:73], off
	v_lshl_add_u64 v[72:73], v[126:127], 0, s[64:65]
	s_mov_b32 m0, s53
	s_nop 0
	global_load_lds_dwordx4 v[72:73], off
	s_barrier
	s_waitcnt lgkmcnt(0)
	s_setprio 1
	v_mfma_f32_16x16x32_bf16 v[54:57], v[68:71], v[94:97], v[54:57]
	v_mfma_f32_16x16x32_bf16 v[50:53], v[86:89], v[94:97], v[50:53]
	v_mfma_f32_16x16x32_bf16 v[38:41], v[68:71], v[102:105], v[38:41]
	v_mfma_f32_16x16x32_bf16 v[34:37], v[86:89], v[102:105], v[34:37]
	v_mfma_f32_16x16x32_bf16 v[22:25], v[68:71], v[110:113], v[22:25]
	v_mfma_f32_16x16x32_bf16 v[18:21], v[86:89], v[110:113], v[18:21]
	v_mfma_f32_16x16x32_bf16 v[6:9], v[68:71], v[118:121], v[6:9]
	v_mfma_f32_16x16x32_bf16 v[2:5], v[86:89], v[118:121], v[2:5]
	v_mfma_f32_16x16x32_bf16 v[54:57], v[82:85], v[98:101], v[54:57]
	v_mfma_f32_16x16x32_bf16 v[50:53], v[90:93], v[98:101], v[50:53]
	v_mfma_f32_16x16x32_bf16 v[38:41], v[82:85], v[106:109], v[38:41]
	v_mfma_f32_16x16x32_bf16 v[34:37], v[90:93], v[106:109], v[34:37]
	v_mfma_f32_16x16x32_bf16 v[22:25], v[82:85], v[114:117], v[22:25]
	v_mfma_f32_16x16x32_bf16 v[18:21], v[90:93], v[114:117], v[18:21]
	v_mfma_f32_16x16x32_bf16 v[6:9], v[82:85], v[122:125], v[6:9]
	v_mfma_f32_16x16x32_bf16 v[2:5], v[90:93], v[122:125], v[2:5]
	s_setprio 0
	s_mov_b32 m0, s46
	v_lshl_add_u64 v[68:69], v[128:129], 0, s[64:65]
	s_barrier
	global_load_lds_dwordx4 v[68:69], off
	v_lshl_add_u64 v[68:69], v[130:131], 0, s[64:65]
	s_mov_b32 m0, s47
	s_nop 0
	global_load_lds_dwordx4 v[68:69], off
	s_barrier
	s_waitcnt lgkmcnt(0)
	s_setprio 1
	s_setprio 0
	s_barrier
	s_mov_b32 m0, s20
	v_lshl_add_u64 v[68:69], s[14:15], 0, v[0:1]
	global_load_lds_dwordx4 v[68:69], off
	v_lshl_add_u64 v[68:69], s[14:15], 0, v[66:67]
	s_mov_b32 m0, s60
	s_nop 0
	global_load_lds_dwordx4 v[68:69], off
	s_waitcnt vmcnt(6)
	s_barrier
	s_setprio 1
	s_setprio 0
	s_andn2_b64 vcc, exec, s[12:13]
	s_mov_b64 s[14:15], -1
	s_mov_b64 s[12:13], 0
	s_mov_b64 s[16:17], 0x100
	s_barrier
	s_cbranch_vccz .LBB0_937
	s_cmpk_gt_u32 s40, 0xff
	s_cbranch_scc1 .Lgx_c_pre
	s_barrier

; #define PG8_STAGE(bufoff, gbase, voff) do { _Pragma("unroll") for (int _i = 0; _i < 2; ++_i) \
;         __builtin_amdgcn_global_load_lds((const unsigned*)((const char*)(gbase) + (voff)[_i]), (LAS unsigned*)(lds + (bufoff) + ldsw + _i * 8192), 16, 0, 0); } while (0)
; #define PG8_STAGE_A(bufoff, gbase, h, vv) do { if constexpr (GATHER) { _Pragma("unroll") for (int _i = 0; _i < 2; ++_i) \
;         __builtin_amdgcn_global_load_lds((const unsigned*)((const char*)(gbase) + (vv)[h][_i]), (LAS unsigned*)(lds + (bufoff) + ldsw + _i * 8192), 16, 0, 0); } \
;         else { PG8_STAGE(bufoff, (gbase) + (h) * hstepA, voffA); } } while (0)
; #define PG8_LDA(dst, b, h) do { _Pragma("unroll") for (int m = 0; m < 4; ++m) _Pragma("unroll") for (int k = 0; k < 2; ++k) dst[m][k] = *(const LAS bf16x8*)(lds + PG8_SA(b, h) + aoff + m * 2048 + k * 1024); } while (0)
; #define PG8_LDB(dst, b, h) do { _Pragma("unroll") for (int n = 0; n < 2; ++n) _Pragma("unroll") for (int k = 0; k < 2; ++k) dst[n][k] = *(const LAS bf16x8*)(lds + PG8_SB(b, h) + boff + n * 2048 + k * 1024); } while (0)
; #define PG8_WAIT_L(n) asm volatile("s_waitcnt lgkmcnt(" #n ")" ::: "memory")
; template <class Epi, class Sched>
; __device__ __forceinline__ void gemm_phase(LAS unsigned char* lds, const int K, const int lda, const int ldb, const Sched& S, const Epi& E) {
;     ...
;         for (int t = 0; t < nt; t += 2) {
;             const bool last = (t == nt - 2);
;             const char* a1 = cA + (size_t)(t + 1) * kstep;
;             const char* a2 = last ? nA : cA + (size_t)(t + 2) * kstep; const char* b2 = last ? nB : cB + (size_t)(t + 2) * kstep;
;             const char* a3 = a2 + kstep; const char* b3 = b2 + kstep;
;             PG8_LDB(B0, 0, 0); PG8_SCHED; PG8_LDA(At, 0, 0); PG8_STAGE_A(PG8_SA(1, 1), a1, 1, vcur);
;             if constexpr (GATHER) { if (last) {
; #pragma unroll
;                 for (int h = 0; h < 2; ++h)
; #pragma unroll
;                     for (int i = 0; i < 2; ++i) vcur[h][i] = vnxt[h][i]; } }
;             PG8_WAIT_L(8); PG8_BAR; PG8_WAIT_L(0); PG8_MMA(0, 0, At, B0); PG8_BAR; PG8_SCHED;
;             PG8_LDB(B1, 0, 1); PG8_STAGE(PG8_SB(0, 0), b2, voffB);
;             PG8_BAR; PG8_WAIT_L(0); PG8_MMA(0, 1, At, B1); PG8_BAR;
;             PG8_LDA(At, 0, 1); PG8_STAGE_A(PG8_SA(0, 0), a2, 0, vcur);
;             PG8_BAR; PG8_WAIT_L(0); PG8_MMA(1, 0, At, B0); PG8_BAR; PG8_SCHED;
.LBB0_951:
	s_add_u32 s2, s8, s16
	s_addc_u32 s3, s9, s17
	s_add_u32 s20, s2, 0x100
	s_addc_u32 s21, s3, 0
	s_and_b64 s[18:19], s[14:15], exec
	s_cselect_b32 s21, s5, s21
	s_cselect_b32 s20, s4, s20
	s_add_u32 s16, s10, s16
	s_addc_u32 s17, s11, s17
	s_add_u32 s16, s16, 0x100
	s_addc_u32 s17, s17, 0
	s_add_i32 s50, 0, 0x10000
	s_and_b64 s[14:15], s[14:15], exec
	s_cselect_b32 s35, s7, s17
	s_cselect_b32 s34, s6, s16
	s_add_u32 s36, s2, 0x10080
	s_addc_u32 s37, s3, 0
	s_add_i32 s68, s50, s40
	s_add_i32 m0, s41, 0xc000
	s_add_i32 s2, s41, 0xe000
	s_add_i32 s67, 0, 0x14000
	s_add_i32 s66, s68, 0x2000
	s_add_u32 s18, s34, 0x10000
	v_add_u32_e32 v166, s50, v170
	s_addc_u32 s19, s35, 0
	s_add_i32 s55, s67, s40
	ds_read_b128 v[154:157], v166
	ds_read_b128 v[158:161], v166 offset:1024
	ds_read_b128 v[162:165], v166 offset:2048
	ds_read_b128 v[166:169], v166 offset:3072
	s_add_i32 s54, s55, 0x2000
	s_add_i32 s53, 0, 0x18000
	s_add_u32 s16, s20, 0x10000
	s_addc_u32 s17, s21, 0
	s_add_i32 s52, s53, s40
	s_add_i32 s45, 0, 0x1c000
	s_add_i32 s44, s52, 0x2000
	s_add_u32 s14, s34, 0x10080
	s_addc_u32 s15, s35, 0
	s_add_i32 s63, s45, s40
	s_add_i32 s62, s63, 0x2000
	v_lshl_add_u64 v[228:229], s[36:37], 0, v[134:135]
	ds_read_b128 v[176:179], v175
	ds_read_b128 v[180:183], v175 offset:1024
	ds_read_b128 v[184:187], v175 offset:2048
	ds_read_b128 v[188:191], v175 offset:3072
	ds_read_b128 v[192:195], v175 offset:4096
	ds_read_b128 v[216:219], v175 offset:5120
	ds_read_b128 v[220:223], v175 offset:6144
	ds_read_b128 v[224:227], v175 offset:7168
	global_load_lds_dwordx4 v[228:229], off
	v_lshl_add_u64 v[228:229], s[36:37], 0, v[132:133]
	s_mov_b32 m0, s2
	s_nop 0
	global_load_lds_dwordx4 v[228:229], off
	s_waitcnt lgkmcnt(8)
	s_barrier
	s_waitcnt lgkmcnt(0)
	s_setprio 1
	v_mfma_f32_16x16x32_bf16 v[126:129], v[154:157], v[176:179], v[126:129]
	v_mfma_f32_16x16x32_bf16 v[118:121], v[162:165], v[176:179], v[118:121]
	v_mfma_f32_16x16x32_bf16 v[94:97], v[154:157], v[184:187], v[94:97]
	v_mfma_f32_16x16x32_bf16 v[86:89], v[162:165], v[184:187], v[86:89]
	v_mfma_f32_16x16x32_bf16 v[62:65], v[154:157], v[192:195], v[62:65]
	v_mfma_f32_16x16x32_bf16 v[54:57], v[162:165], v[192:195], v[54:57]
	v_mfma_f32_16x16x32_bf16 v[30:33], v[154:157], v[220:223], v[30:33]
	v_mfma_f32_16x16x32_bf16 v[22:25], v[162:165], v[220:223], v[22:25]
	v_mfma_f32_16x16x32_bf16 v[126:129], v[158:161], v[180:183], v[126:129]
	v_mfma_f32_16x16x32_bf16 v[118:121], v[166:169], v[180:183], v[118:121]
	v_mfma_f32_16x16x32_bf16 v[94:97], v[158:161], v[188:191], v[94:97]
	v_mfma_f32_16x16x32_bf16 v[86:89], v[166:169], v[188:191], v[86:89]
	v_mfma_f32_16x16x32_bf16 v[62:65], v[158:161], v[216:219], v[62:65]
	v_mfma_f32_16x16x32_bf16 v[54:57], v[166:169], v[216:219], v[54:57]
	v_mfma_f32_16x16x32_bf16 v[30:33], v[158:161], v[224:227], v[30:33]
	v_mfma_f32_16x16x32_bf16 v[22:25], v[166:169], v[224:227], v[22:25]
	s_setprio 0
	s_barrier
	s_mov_b32 m0, s68
	v_add_u32_e32 v214, s67, v170
	v_lshl_add_u64 v[244:245], s[34:35], 0, v[0:1]
	ds_read_b128 v[228:231], v214
	ds_read_b128 v[232:235], v214 offset:1024
	ds_read_b128 v[236:239], v214 offset:2048
	ds_read_b128 v[240:243], v214 offset:3072
	global_load_lds_dwordx4 v[244:245], off
	v_lshl_add_u64 v[246:247], s[34:35], 0, v[130:131]
	s_mov_b32 m0, s66
	s_nop 0
	global_load_lds_dwordx4 v[246:247], off
	s_barrier
	s_waitcnt lgkmcnt(0)
	s_setprio 1
	v_mfma_f32_16x16x32_bf16 v[110:113], v[228:231], v[176:179], v[110:113]
	v_mfma_f32_16x16x32_bf16 v[106:109], v[236:239], v[176:179], v[106:109]
	v_mfma_f32_16x16x32_bf16 v[78:81], v[228:231], v[184:187], v[78:81]
	v_mfma_f32_16x16x32_bf16 v[74:77], v[236:239], v[184:187], v[74:77]
	v_mfma_f32_16x16x32_bf16 v[46:49], v[228:231], v[192:195], v[46:49]
	v_mfma_f32_16x16x32_bf16 v[42:45], v[236:239], v[192:195], v[42:45]
	v_mfma_f32_16x16x32_bf16 v[14:17], v[228:231], v[220:223], v[14:17]
	v_mfma_f32_16x16x32_bf16 v[10:13], v[236:239], v[220:223], v[10:13]
	v_mfma_f32_16x16x32_bf16 v[110:113], v[232:235], v[180:183], v[110:113]
	v_mfma_f32_16x16x32_bf16 v[106:109], v[240:243], v[180:183], v[106:109]
	v_mfma_f32_16x16x32_bf16 v[78:81], v[232:235], v[188:191], v[78:81]
	v_mfma_f32_16x16x32_bf16 v[74:77], v[240:243], v[188:191], v[74:77]
	v_mfma_f32_16x16x32_bf16 v[46:49], v[232:235], v[216:219], v[46:49]
	v_mfma_f32_16x16x32_bf16 v[42:45], v[240:243], v[216:219], v[42:45]
	v_mfma_f32_16x16x32_bf16 v[14:17], v[232:235], v[224:227], v[14:17]
	v_mfma_f32_16x16x32_bf16 v[10:13], v[240:243], v[224:227], v[10:13]
	s_setprio 0
	s_mov_b32 m0, s41
	v_lshl_add_u64 v[248:249], s[20:21], 0, v[134:135]
	s_barrier
	ds_read_b128 v[176:179], v175 offset:16384
	ds_read_b128 v[180:183], v175 offset:17408
	ds_read_b128 v[184:187], v175 offset:18432
	ds_read_b128 v[188:191], v175 offset:19456
	ds_read_b128 v[192:195], v175 offset:20480
	ds_read_b128 v[216:219], v175 offset:21504
	ds_read_b128 v[220:223], v175 offset:22528
	ds_read_b128 v[224:227], v175 offset:23552
	global_load_lds_dwordx4 v[248:249], off
	v_lshl_add_u64 v[214:215], s[20:21], 0, v[132:133]
	s_mov_b32 m0, s42
	s_nop 0
	global_load_lds_dwordx4 v[214:215], off
	s_barrier
; #define PG8_STAGE(bufoff, gbase, voff) do { _Pragma("unroll") for (int _i = 0; _i < 2; ++_i) \
;         __builtin_amdgcn_global_load_lds((const unsigned*)((const char*)(gbase) + (voff)[_i]), (LAS unsigned*)(lds + (bufoff) + ldsw + _i * 8192), 16, 0, 0); } while (0)
; #define PG8_STAGE_A(bufoff, gbase, h, vv) do { if constexpr (GATHER) { _Pragma("unroll") for (int _i = 0; _i < 2; ++_i) \
;         __builtin_amdgcn_global_load_lds((const unsigned*)((const char*)(gbase) + (vv)[h][_i]), (LAS unsigned*)(lds + (bufoff) + ldsw + _i * 8192), 16, 0, 0); } \
;         else { PG8_STAGE(bufoff, (gbase) + (h) * hstepA, voffA); } } while (0)
; #define PG8_LDA(dst, b, h) do { _Pragma("unroll") for (int m = 0; m < 4; ++m) _Pragma("unroll") for (int k = 0; k < 2; ++k) dst[m][k] = *(const LAS bf16x8*)(lds + PG8_SA(b, h) + aoff + m * 2048 + k * 1024); } while (0)
; #define PG8_LDB(dst, b, h) do { _Pragma("unroll") for (int n = 0; n < 2; ++n) _Pragma("unroll") for (int k = 0; k < 2; ++k) dst[n][k] = *(const LAS bf16x8*)(lds + PG8_SB(b, h) + boff + n * 2048 + k * 1024); } while (0)
; #define PG8_MMA(ai, bj, At, Bt) do { __builtin_amdgcn_s_setprio(1); _Pragma("unroll") for (int m = 0; m < 4; ++m) _Pragma("unroll") for (int n = 0; n < 2; ++n) _Pragma("unroll") for (int k = 0; k < 2; ++k) \
;         acc[ai][bj][m][n] = __builtin_amdgcn_mfma_f32_16x16x32_bf16(Bt[n][k], At[m][k], acc[ai][bj][m][n], 0, 0, 0); __builtin_amdgcn_s_setprio(0); } while (0)
; #define PG8_WAIT_V(n) asm volatile("s_waitcnt vmcnt(" #n ")" ::: "memory")
; #define PG8_WAIT_L(n) asm volatile("s_waitcnt lgkmcnt(" #n ")" ::: "memory")
; #define PG8_BAR __builtin_amdgcn_s_barrier()
; #define PG8_SCHED __builtin_amdgcn_sched_barrier(0)
; template <class Epi, class Sched>
; __device__ __forceinline__ void gemm_phase(LAS unsigned char* lds, const int K, const int lda, const int ldb, const Sched& S, const Epi& E) {
;     ...
;             PG8_BAR; PG8_WAIT_L(0); PG8_MMA(1, 0, At, B0); PG8_BAR; PG8_SCHED;
;             PG8_STAGE(PG8_SB(0, 1), b2 + hstepB, voffB);
;             PG8_WAIT_V(6); PG8_BAR; PG8_MMA(1, 1, At, B1); PG8_BAR;
;             PG8_LDB(B0, 1, 0); PG8_SCHED; PG8_LDA(At, 1, 0); PG8_STAGE_A(PG8_SA(0, 1), a2, 1, vcur);
;             PG8_WAIT_L(8); PG8_BAR; PG8_WAIT_L(0); PG8_MMA(0, 0, At, B0); PG8_BAR; PG8_SCHED;
	s_waitcnt lgkmcnt(0)
	s_setprio 1
	v_mfma_f32_16x16x32_bf16 v[122:125], v[154:157], v[176:179], v[122:125]
	v_mfma_f32_16x16x32_bf16 v[114:117], v[162:165], v[176:179], v[114:117]
	v_mfma_f32_16x16x32_bf16 v[90:93], v[154:157], v[184:187], v[90:93]
	v_mfma_f32_16x16x32_bf16 v[82:85], v[162:165], v[184:187], v[82:85]
	v_mfma_f32_16x16x32_bf16 v[58:61], v[154:157], v[192:195], v[58:61]
	v_mfma_f32_16x16x32_bf16 v[50:53], v[162:165], v[192:195], v[50:53]
	v_mfma_f32_16x16x32_bf16 v[26:29], v[154:157], v[220:223], v[26:29]
	v_mfma_f32_16x16x32_bf16 v[18:21], v[162:165], v[220:223], v[18:21]
	v_mfma_f32_16x16x32_bf16 v[122:125], v[158:161], v[180:183], v[122:125]
	v_mfma_f32_16x16x32_bf16 v[114:117], v[166:169], v[180:183], v[114:117]
	v_mfma_f32_16x16x32_bf16 v[90:93], v[158:161], v[188:191], v[90:93]
	v_mfma_f32_16x16x32_bf16 v[82:85], v[166:169], v[188:191], v[82:85]
	v_mfma_f32_16x16x32_bf16 v[58:61], v[158:161], v[216:219], v[58:61]
	v_mfma_f32_16x16x32_bf16 v[50:53], v[166:169], v[216:219], v[50:53]
	v_mfma_f32_16x16x32_bf16 v[26:29], v[158:161], v[224:227], v[26:29]
	v_mfma_f32_16x16x32_bf16 v[18:21], v[166:169], v[224:227], v[18:21]
	s_setprio 0
	s_barrier
	s_mov_b32 m0, s55
	v_lshl_add_u64 v[154:155], s[18:19], 0, v[0:1]
	global_load_lds_dwordx4 v[154:155], off
	v_lshl_add_u64 v[154:155], s[18:19], 0, v[130:131]
	s_mov_b32 m0, s54
	s_nop 0
	global_load_lds_dwordx4 v[154:155], off
	s_waitcnt vmcnt(6)
	s_barrier
	s_setprio 1
	v_mfma_f32_16x16x32_bf16 v[102:105], v[228:231], v[176:179], v[102:105]
	v_mfma_f32_16x16x32_bf16 v[98:101], v[236:239], v[176:179], v[98:101]
	v_mfma_f32_16x16x32_bf16 v[70:73], v[228:231], v[184:187], v[70:73]
	v_mfma_f32_16x16x32_bf16 v[66:69], v[236:239], v[184:187], v[66:69]
	v_mfma_f32_16x16x32_bf16 v[38:41], v[228:231], v[192:195], v[38:41]
	v_mfma_f32_16x16x32_bf16 v[34:37], v[236:239], v[192:195], v[34:37]
	v_mfma_f32_16x16x32_bf16 v[6:9], v[228:231], v[220:223], v[6:9]
	v_mfma_f32_16x16x32_bf16 v[2:5], v[236:239], v[220:223], v[2:5]
	v_mfma_f32_16x16x32_bf16 v[102:105], v[232:235], v[180:183], v[102:105]
	v_mfma_f32_16x16x32_bf16 v[98:101], v[240:243], v[180:183], v[98:101]
	v_mfma_f32_16x16x32_bf16 v[70:73], v[232:235], v[188:191], v[70:73]
	v_mfma_f32_16x16x32_bf16 v[66:69], v[240:243], v[188:191], v[66:69]
	v_mfma_f32_16x16x32_bf16 v[38:41], v[232:235], v[216:219], v[38:41]
	v_mfma_f32_16x16x32_bf16 v[34:37], v[240:243], v[216:219], v[34:37]
	v_mfma_f32_16x16x32_bf16 v[6:9], v[232:235], v[224:227], v[6:9]
	v_mfma_f32_16x16x32_bf16 v[2:5], v[240:243], v[224:227], v[2:5]
	s_setprio 0
	v_add_u32_e32 v166, s53, v170
	s_barrier
	ds_read_b128 v[154:157], v166
	ds_read_b128 v[158:161], v166 offset:1024
	ds_read_b128 v[162:165], v166 offset:2048
	ds_read_b128 v[166:169], v166 offset:3072
	s_mov_b32 m0, s43
	v_lshl_add_u64 v[228:229], s[16:17], 0, v[134:135]
	ds_read_b128 v[176:179], v175 offset:32768
	ds_read_b128 v[180:183], v175 offset:33792
	ds_read_b128 v[184:187], v175 offset:34816
	ds_read_b128 v[188:191], v175 offset:35840
	ds_read_b128 v[192:195], v175 offset:36864
	ds_read_b128 v[216:219], v175 offset:37888
	ds_read_b128 v[220:223], v175 offset:38912
	ds_read_b128 v[224:227], v175 offset:39936
	global_load_lds_dwordx4 v[228:229], off
	v_lshl_add_u64 v[228:229], s[16:17], 0, v[132:133]
	s_mov_b32 m0, s46
	s_nop 0
	global_load_lds_dwordx4 v[228:229], off
	s_waitcnt lgkmcnt(8)
	s_barrier
	s_waitcnt lgkmcnt(0)
	s_setprio 1
	v_mfma_f32_16x16x32_bf16 v[126:129], v[154:157], v[176:179], v[126:129]
	v_mfma_f32_16x16x32_bf16 v[118:121], v[162:165], v[176:179], v[118:121]
	v_mfma_f32_16x16x32_bf16 v[94:97], v[154:157], v[184:187], v[94:97]
	v_mfma_f32_16x16x32_bf16 v[86:89], v[162:165], v[184:187], v[86:89]
	v_mfma_f32_16x16x32_bf16 v[62:65], v[154:157], v[192:195], v[62:65]
	v_mfma_f32_16x16x32_bf16 v[54:57], v[162:165], v[192:195], v[54:57]
	v_mfma_f32_16x16x32_bf16 v[30:33], v[154:157], v[220:223], v[30:33]
	v_mfma_f32_16x16x32_bf16 v[22:25], v[162:165], v[220:223], v[22:25]
	v_mfma_f32_16x16x32_bf16 v[126:129], v[158:161], v[180:183], v[126:129]
	v_mfma_f32_16x16x32_bf16 v[118:121], v[166:169], v[180:183], v[118:121]
	v_mfma_f32_16x16x32_bf16 v[94:97], v[158:161], v[188:191], v[94:97]
	v_mfma_f32_16x16x32_bf16 v[86:89], v[166:169], v[188:191], v[86:89]
	v_mfma_f32_16x16x32_bf16 v[62:65], v[158:161], v[216:219], v[62:65]
	v_mfma_f32_16x16x32_bf16 v[54:57], v[166:169], v[216:219], v[54:57]
	v_mfma_f32_16x16x32_bf16 v[30:33], v[158:161], v[224:227], v[30:33]
	v_mfma_f32_16x16x32_bf16 v[22:25], v[166:169], v[224:227], v[22:25]
	s_setprio 0
	s_barrier
; #define PG8_STAGE(bufoff, gbase, voff) do { _Pragma("unroll") for (int _i = 0; _i < 2; ++_i) \
;         __builtin_amdgcn_global_load_lds((const unsigned*)((const char*)(gbase) + (voff)[_i]), (LAS unsigned*)(lds + (bufoff) + ldsw + _i * 8192), 16, 0, 0); } while (0)
; #define PG8_STAGE_A(bufoff, gbase, h, vv) do { if constexpr (GATHER) { _Pragma("unroll") for (int _i = 0; _i < 2; ++_i) \
;         __builtin_amdgcn_global_load_lds((const unsigned*)((const char*)(gbase) + (vv)[h][_i]), (LAS unsigned*)(lds + (bufoff) + ldsw + _i * 8192), 16, 0, 0); } \
;         else { PG8_STAGE(bufoff, (gbase) + (h) * hstepA, voffA); } } while (0)
; #define PG8_LDA(dst, b, h) do { _Pragma("unroll") for (int m = 0; m < 4; ++m) _Pragma("unroll") for (int k = 0; k < 2; ++k) dst[m][k] = *(const LAS bf16x8*)(lds + PG8_SA(b, h) + aoff + m * 2048 + k * 1024); } while (0)
; #define PG8_LDB(dst, b, h) do { _Pragma("unroll") for (int n = 0; n < 2; ++n) _Pragma("unroll") for (int k = 0; k < 2; ++k) dst[n][k] = *(const LAS bf16x8*)(lds + PG8_SB(b, h) + boff + n * 2048 + k * 1024); } while (0)
; #define PG8_MMA(ai, bj, At, Bt) do { __builtin_amdgcn_s_setprio(1); _Pragma("unroll") for (int m = 0; m < 4; ++m) _Pragma("unroll") for (int n = 0; n < 2; ++n) _Pragma("unroll") for (int k = 0; k < 2; ++k) \
;         acc[ai][bj][m][n] = __builtin_amdgcn_mfma_f32_16x16x32_bf16(Bt[n][k], At[m][k], acc[ai][bj][m][n], 0, 0, 0); __builtin_amdgcn_s_setprio(0); } while (0)
; #define PG8_WAIT_V(n) asm volatile("s_waitcnt vmcnt(" #n ")" ::: "memory")
; #define PG8_WAIT_L(n) asm volatile("s_waitcnt lgkmcnt(" #n ")" ::: "memory")
; #define PG8_BAR __builtin_amdgcn_s_barrier()
; template <class Epi, class Sched>
; __device__ __forceinline__ void gemm_phase(LAS unsigned char* lds, const int K, const int lda, const int ldb, const Sched& S, const Epi& E) {
;     ...
;             PG8_WAIT_L(8); PG8_BAR; PG8_WAIT_L(0); PG8_MMA(0, 0, At, B0); PG8_BAR; PG8_SCHED;
;             PG8_LDB(B1, 1, 1); PG8_STAGE(PG8_SB(1, 0), b3, voffB);
;             PG8_BAR; PG8_WAIT_L(0); PG8_MMA(0, 1, At, B1); PG8_BAR;
;             PG8_LDA(At, 1, 1); PG8_STAGE_A(PG8_SA(1, 0), a3, 0, vcur);
;             PG8_BAR; PG8_WAIT_L(0); PG8_MMA(1, 0, At, B0); PG8_BAR; PG8_SCHED;
;             PG8_STAGE(PG8_SB(1, 1), b3 + hstepB, voffB);
;             PG8_WAIT_V(6); PG8_BAR; PG8_MMA(1, 1, At, B1); PG8_BAR;
;         }
	s_mov_b32 m0, s52
	v_add_u32_e32 v240, s45, v170
	v_lshl_add_u64 v[244:245], v[244:245], 0, s[64:65]
	ds_read_b128 v[228:231], v240
	ds_read_b128 v[232:235], v240 offset:1024
	ds_read_b128 v[236:239], v240 offset:2048
	ds_read_b128 v[240:243], v240 offset:3072
	global_load_lds_dwordx4 v[244:245], off
	v_lshl_add_u64 v[244:245], v[246:247], 0, s[64:65]
	s_mov_b32 m0, s44
	s_nop 0
	global_load_lds_dwordx4 v[244:245], off
	s_barrier
	s_waitcnt lgkmcnt(0)
	s_setprio 1
	v_mfma_f32_16x16x32_bf16 v[110:113], v[228:231], v[176:179], v[110:113]
	v_mfma_f32_16x16x32_bf16 v[106:109], v[236:239], v[176:179], v[106:109]
	v_mfma_f32_16x16x32_bf16 v[78:81], v[228:231], v[184:187], v[78:81]
	v_mfma_f32_16x16x32_bf16 v[74:77], v[236:239], v[184:187], v[74:77]
	v_mfma_f32_16x16x32_bf16 v[46:49], v[228:231], v[192:195], v[46:49]
	v_mfma_f32_16x16x32_bf16 v[42:45], v[236:239], v[192:195], v[42:45]
	v_mfma_f32_16x16x32_bf16 v[14:17], v[228:231], v[220:223], v[14:17]
	v_mfma_f32_16x16x32_bf16 v[10:13], v[236:239], v[220:223], v[10:13]
	v_mfma_f32_16x16x32_bf16 v[110:113], v[232:235], v[180:183], v[110:113]
	v_mfma_f32_16x16x32_bf16 v[106:109], v[240:243], v[180:183], v[106:109]
	v_mfma_f32_16x16x32_bf16 v[78:81], v[232:235], v[188:191], v[78:81]
	v_mfma_f32_16x16x32_bf16 v[74:77], v[240:243], v[188:191], v[74:77]
	v_mfma_f32_16x16x32_bf16 v[46:49], v[232:235], v[216:219], v[46:49]
	v_mfma_f32_16x16x32_bf16 v[42:45], v[240:243], v[216:219], v[42:45]
	v_mfma_f32_16x16x32_bf16 v[14:17], v[232:235], v[224:227], v[14:17]
	v_mfma_f32_16x16x32_bf16 v[10:13], v[240:243], v[224:227], v[10:13]
	s_setprio 0
	s_mov_b32 m0, s47
	v_lshl_add_u64 v[244:245], v[248:249], 0, s[64:65]
	s_barrier
	ds_read_b128 v[176:179], v175 offset:49152
	ds_read_b128 v[180:183], v175 offset:50176
	ds_read_b128 v[184:187], v175 offset:51200
	ds_read_b128 v[188:191], v175 offset:52224
	ds_read_b128 v[192:195], v175 offset:53248
	ds_read_b128 v[216:219], v175 offset:54272
	ds_read_b128 v[220:223], v175 offset:55296
	ds_read_b128 v[224:227], v175 offset:56320
	global_load_lds_dwordx4 v[244:245], off
	v_lshl_add_u64 v[214:215], v[214:215], 0, s[64:65]
	s_mov_b32 m0, s48
	s_nop 0
	global_load_lds_dwordx4 v[214:215], off
	s_barrier
	s_waitcnt lgkmcnt(0)
	s_setprio 1
	v_mfma_f32_16x16x32_bf16 v[122:125], v[154:157], v[176:179], v[122:125]
	v_mfma_f32_16x16x32_bf16 v[114:117], v[162:165], v[176:179], v[114:117]
	v_mfma_f32_16x16x32_bf16 v[90:93], v[154:157], v[184:187], v[90:93]
	v_mfma_f32_16x16x32_bf16 v[82:85], v[162:165], v[184:187], v[82:85]
	v_mfma_f32_16x16x32_bf16 v[58:61], v[154:157], v[192:195], v[58:61]
	v_mfma_f32_16x16x32_bf16 v[50:53], v[162:165], v[192:195], v[50:53]
	v_mfma_f32_16x16x32_bf16 v[26:29], v[154:157], v[220:223], v[26:29]
	v_mfma_f32_16x16x32_bf16 v[18:21], v[162:165], v[220:223], v[18:21]
	v_mfma_f32_16x16x32_bf16 v[122:125], v[158:161], v[180:183], v[122:125]
	v_mfma_f32_16x16x32_bf16 v[114:117], v[166:169], v[180:183], v[114:117]
	v_mfma_f32_16x16x32_bf16 v[90:93], v[158:161], v[188:191], v[90:93]
	v_mfma_f32_16x16x32_bf16 v[82:85], v[166:169], v[188:191], v[82:85]
	v_mfma_f32_16x16x32_bf16 v[58:61], v[158:161], v[216:219], v[58:61]
	v_mfma_f32_16x16x32_bf16 v[50:53], v[166:169], v[216:219], v[50:53]
	v_mfma_f32_16x16x32_bf16 v[26:29], v[158:161], v[224:227], v[26:29]
	v_mfma_f32_16x16x32_bf16 v[18:21], v[166:169], v[224:227], v[18:21]
	s_setprio 0
	s_barrier
	s_mov_b32 m0, s63
	v_lshl_add_u64 v[154:155], s[14:15], 0, v[0:1]
	global_load_lds_dwordx4 v[154:155], off
	v_lshl_add_u64 v[154:155], s[14:15], 0, v[130:131]
	s_mov_b32 m0, s62
	s_nop 0
	global_load_lds_dwordx4 v[154:155], off
	s_waitcnt vmcnt(6)
	s_barrier
	s_setprio 1
	v_mfma_f32_16x16x32_bf16 v[102:105], v[228:231], v[176:179], v[102:105]
	v_mfma_f32_16x16x32_bf16 v[98:101], v[236:239], v[176:179], v[98:101]
	v_mfma_f32_16x16x32_bf16 v[70:73], v[228:231], v[184:187], v[70:73]
	v_mfma_f32_16x16x32_bf16 v[66:69], v[236:239], v[184:187], v[66:69]
	v_mfma_f32_16x16x32_bf16 v[38:41], v[228:231], v[192:195], v[38:41]
	v_mfma_f32_16x16x32_bf16 v[34:37], v[236:239], v[192:195], v[34:37]
	v_mfma_f32_16x16x32_bf16 v[6:9], v[228:231], v[220:223], v[6:9]
	v_mfma_f32_16x16x32_bf16 v[2:5], v[236:239], v[220:223], v[2:5]
	v_mfma_f32_16x16x32_bf16 v[102:105], v[232:235], v[180:183], v[102:105]
	v_mfma_f32_16x16x32_bf16 v[98:101], v[240:243], v[180:183], v[98:101]
	v_mfma_f32_16x16x32_bf16 v[70:73], v[232:235], v[188:191], v[70:73]
	v_mfma_f32_16x16x32_bf16 v[66:69], v[240:243], v[188:191], v[66:69]
	v_mfma_f32_16x16x32_bf16 v[38:41], v[232:235], v[216:219], v[38:41]
	v_mfma_f32_16x16x32_bf16 v[34:37], v[240:243], v[216:219], v[34:37]
	v_mfma_f32_16x16x32_bf16 v[6:9], v[232:235], v[224:227], v[6:9]
	v_mfma_f32_16x16x32_bf16 v[2:5], v[240:243], v[224:227], v[2:5]
	s_setprio 0
	s_andn2_b64 vcc, exec, s[12:13]
	s_mov_b64 s[14:15], -1
	s_mov_b64 s[12:13], 0
	s_mov_b64 s[16:17], 0x100
	s_barrier
	s_cbranch_vccz .LBB0_951
	s_cmpk_gt_u32 s39, 0xff
	s_cbranch_scc1 .Lgx_d_pre
	s_barrier

; #define PG8_STAGE(bufoff, gbase, voff) do { _Pragma("unroll") for (int _i = 0; _i < 2; ++_i) \
;         __builtin_amdgcn_global_load_lds((const unsigned*)((const char*)(gbase) + (voff)[_i]), (LAS unsigned*)(lds + (bufoff) + ldsw + _i * 8192), 16, 0, 0); } while (0)
; #define PG8_STAGE_A(bufoff, gbase, h, vv) do { if constexpr (GATHER) { _Pragma("unroll") for (int _i = 0; _i < 2; ++_i) \
;         __builtin_amdgcn_global_load_lds((const unsigned*)((const char*)(gbase) + (vv)[h][_i]), (LAS unsigned*)(lds + (bufoff) + ldsw + _i * 8192), 16, 0, 0); } \
;         else { PG8_STAGE(bufoff, (gbase) + (h) * hstepA, voffA); } } while (0)
; #define PG8_LDA(dst, b, h) do { _Pragma("unroll") for (int m = 0; m < 4; ++m) _Pragma("unroll") for (int k = 0; k < 2; ++k) dst[m][k] = *(const LAS bf16x8*)(lds + PG8_SA(b, h) + aoff + m * 2048 + k * 1024); } while (0)
; #define PG8_LDB(dst, b, h) do { _Pragma("unroll") for (int n = 0; n < 2; ++n) _Pragma("unroll") for (int k = 0; k < 2; ++k) dst[n][k] = *(const LAS bf16x8*)(lds + PG8_SB(b, h) + boff + n * 2048 + k * 1024); } while (0)
; #define PG8_WAIT_L(n) asm volatile("s_waitcnt lgkmcnt(" #n ")" ::: "memory")
; template <class Epi, class Sched>
; __device__ __forceinline__ void gemm_phase(LAS unsigned char* lds, const int K, const int lda, const int ldb, const Sched& S, const Epi& E) {
;     ...
;         for (int t = 0; t < nt; t += 2) {
;             const bool last = (t == nt - 2);
;             const char* a1 = cA + (size_t)(t + 1) * kstep;
;             const char* a2 = last ? nA : cA + (size_t)(t + 2) * kstep; const char* b2 = last ? nB : cB + (size_t)(t + 2) * kstep;
;             const char* a3 = a2 + kstep; const char* b3 = b2 + kstep;
;             PG8_LDB(B0, 0, 0); PG8_SCHED; PG8_LDA(At, 0, 0); PG8_STAGE_A(PG8_SA(1, 1), a1, 1, vcur);
;             if constexpr (GATHER) { if (last) {
; #pragma unroll
;                 for (int h = 0; h < 2; ++h)
; #pragma unroll
;                     for (int i = 0; i < 2; ++i) vcur[h][i] = vnxt[h][i]; } }
;             PG8_WAIT_L(8); PG8_BAR; PG8_WAIT_L(0); PG8_MMA(0, 0, At, B0); PG8_BAR; PG8_SCHED;
;             PG8_LDB(B1, 0, 1); PG8_STAGE(PG8_SB(0, 0), b2, voffB);
;             PG8_BAR; PG8_WAIT_L(0); PG8_MMA(0, 1, At, B1); PG8_BAR;
;             PG8_LDA(At, 0, 1); PG8_STAGE_A(PG8_SA(0, 0), a2, 0, vcur);
;             PG8_BAR; PG8_WAIT_L(0); PG8_MMA(1, 0, At, B0); PG8_BAR; PG8_SCHED;
.LBB0_969:
	s_add_u32 s2, s14, 0xfffc0080
	s_addc_u32 s3, s15, -1
	s_add_i32 s48, 0, 0x10000
	v_add_u32_e32 v0, s48, v146
	ds_read_b128 v[148:151], v0
	ds_read_b128 v[152:155], v0 offset:1024
	ds_read_b128 v[156:159], v0 offset:2048
	ds_read_b128 v[160:163], v0 offset:3072
	s_cmp_eq_u32 s9, 12
	s_cselect_b32 s19, s11, s3
	s_cselect_b32 s18, s10, s2
	s_cselect_b32 s17, s13, s7
	s_cselect_b32 s16, s12, s1
	v_lshl_add_u64 v[144:145], s[14:15], 0, v[140:141]
	s_add_i32 m0, s39, 0xc000
	ds_read_b128 v[164:167], v147
	ds_read_b128 v[168:171], v147 offset:1024
	ds_read_b128 v[172:175], v147 offset:2048
	ds_read_b128 v[176:179], v147 offset:3072
	ds_read_b128 v[180:183], v147 offset:4096
	ds_read_b128 v[184:187], v147 offset:5120
	ds_read_b128 v[188:191], v147 offset:6144
	ds_read_b128 v[192:195], v147 offset:7168
	global_load_lds_dwordx4 v[144:145], off
	v_lshl_add_u64 v[144:145], s[14:15], 0, v[142:143]
	s_add_i32 m0, s39, 0xe000
	s_nop 0
	global_load_lds_dwordx4 v[144:145], off
	s_waitcnt lgkmcnt(8)
	s_barrier
	s_waitcnt lgkmcnt(0)
	s_setprio 1
	v_mfma_f32_16x16x32_bf16 v[126:129], v[148:151], v[164:167], v[126:129]
	v_mfma_f32_16x16x32_bf16 v[122:125], v[156:159], v[164:167], v[122:125]
	v_mfma_f32_16x16x32_bf16 v[110:113], v[148:151], v[172:175], v[110:113]
	v_mfma_f32_16x16x32_bf16 v[106:109], v[156:159], v[172:175], v[106:109]
	v_mfma_f32_16x16x32_bf16 v[94:97], v[148:151], v[180:183], v[94:97]
	v_mfma_f32_16x16x32_bf16 v[90:93], v[156:159], v[180:183], v[90:93]
	v_mfma_f32_16x16x32_bf16 v[78:81], v[148:151], v[188:191], v[78:81]
	v_mfma_f32_16x16x32_bf16 v[74:77], v[156:159], v[188:191], v[74:77]
	v_mfma_f32_16x16x32_bf16 v[126:129], v[152:155], v[168:171], v[126:129]
	v_mfma_f32_16x16x32_bf16 v[122:125], v[160:163], v[168:171], v[122:125]
	v_mfma_f32_16x16x32_bf16 v[110:113], v[152:155], v[176:179], v[110:113]
	v_mfma_f32_16x16x32_bf16 v[106:109], v[160:163], v[176:179], v[106:109]
	v_mfma_f32_16x16x32_bf16 v[94:97], v[152:155], v[184:187], v[94:97]
	v_mfma_f32_16x16x32_bf16 v[90:93], v[160:163], v[184:187], v[90:93]
	v_mfma_f32_16x16x32_bf16 v[78:81], v[152:155], v[192:195], v[78:81]
	v_mfma_f32_16x16x32_bf16 v[74:77], v[160:163], v[192:195], v[74:77]
	s_setprio 0
	s_barrier
	s_add_i32 s2, 0, 0x14000
	s_add_i32 s3, s48, s38
	v_add_u32_e32 v0, s2, v146
	v_lshl_add_u64 v[144:145], s[16:17], 0, v[132:133]
	s_mov_b32 m0, s3
	ds_read_b128 v[216:219], v0
	ds_read_b128 v[220:223], v0 offset:1024
	ds_read_b128 v[224:227], v0 offset:2048
	ds_read_b128 v[228:231], v0 offset:3072
	global_load_lds_dwordx4 v[144:145], off
	v_lshl_add_u64 v[232:233], s[16:17], 0, v[136:137]
	s_add_i32 m0, s3, 0x2000
	s_nop 0
	global_load_lds_dwordx4 v[232:233], off
	s_barrier
	s_waitcnt lgkmcnt(0)
	s_setprio 1
	v_mfma_f32_16x16x32_bf16 v[118:121], v[216:219], v[164:167], v[118:121]
	v_mfma_f32_16x16x32_bf16 v[114:117], v[224:227], v[164:167], v[114:117]
	v_mfma_f32_16x16x32_bf16 v[102:105], v[216:219], v[172:175], v[102:105]
	v_mfma_f32_16x16x32_bf16 v[98:101], v[224:227], v[172:175], v[98:101]
	v_mfma_f32_16x16x32_bf16 v[86:89], v[216:219], v[180:183], v[86:89]
	v_mfma_f32_16x16x32_bf16 v[82:85], v[224:227], v[180:183], v[82:85]
	v_mfma_f32_16x16x32_bf16 v[70:73], v[216:219], v[188:191], v[70:73]
	v_mfma_f32_16x16x32_bf16 v[66:69], v[224:227], v[188:191], v[66:69]
	v_mfma_f32_16x16x32_bf16 v[118:121], v[220:223], v[168:171], v[118:121]
	v_mfma_f32_16x16x32_bf16 v[114:117], v[228:231], v[168:171], v[114:117]
	v_mfma_f32_16x16x32_bf16 v[102:105], v[220:223], v[176:179], v[102:105]
	v_mfma_f32_16x16x32_bf16 v[98:101], v[228:231], v[176:179], v[98:101]
	v_mfma_f32_16x16x32_bf16 v[86:89], v[220:223], v[184:187], v[86:89]
	v_mfma_f32_16x16x32_bf16 v[82:85], v[228:231], v[184:187], v[82:85]
	v_mfma_f32_16x16x32_bf16 v[70:73], v[220:223], v[192:195], v[70:73]
	v_mfma_f32_16x16x32_bf16 v[66:69], v[228:231], v[192:195], v[66:69]
	s_setprio 0
	s_mov_b32 m0, s39
	v_lshl_add_u64 v[234:235], s[18:19], 0, v[130:131]
	s_barrier
	ds_read_b128 v[164:167], v147 offset:16384
	ds_read_b128 v[168:171], v147 offset:17408
	ds_read_b128 v[172:175], v147 offset:18432
	ds_read_b128 v[176:179], v147 offset:19456
	ds_read_b128 v[180:183], v147 offset:20480
	ds_read_b128 v[184:187], v147 offset:21504
	ds_read_b128 v[188:191], v147 offset:22528
	ds_read_b128 v[192:195], v147 offset:23552
	global_load_lds_dwordx4 v[234:235], off
	v_lshl_add_u64 v[236:237], s[18:19], 0, v[134:135]
	s_mov_b32 m0, s40
	s_nop 0
	global_load_lds_dwordx4 v[236:237], off
	s_barrier
	s_waitcnt lgkmcnt(0)
	s_setprio 1
	v_mfma_f32_16x16x32_bf16 v[62:65], v[148:151], v[164:167], v[62:65]
	v_mfma_f32_16x16x32_bf16 v[58:61], v[156:159], v[164:167], v[58:61]
	v_mfma_f32_16x16x32_bf16 v[46:49], v[148:151], v[172:175], v[46:49]
	v_mfma_f32_16x16x32_bf16 v[42:45], v[156:159], v[172:175], v[42:45]
	v_mfma_f32_16x16x32_bf16 v[30:33], v[148:151], v[180:183], v[30:33]
	v_mfma_f32_16x16x32_bf16 v[26:29], v[156:159], v[180:183], v[26:29]
	v_mfma_f32_16x16x32_bf16 v[14:17], v[148:151], v[188:191], v[14:17]
	v_mfma_f32_16x16x32_bf16 v[10:13], v[156:159], v[188:191], v[10:13]
	v_mfma_f32_16x16x32_bf16 v[62:65], v[152:155], v[168:171], v[62:65]
	v_mfma_f32_16x16x32_bf16 v[58:61], v[160:163], v[168:171], v[58:61]
	v_mfma_f32_16x16x32_bf16 v[46:49], v[152:155], v[176:179], v[46:49]
	v_mfma_f32_16x16x32_bf16 v[42:45], v[160:163], v[176:179], v[42:45]
	v_mfma_f32_16x16x32_bf16 v[30:33], v[152:155], v[184:187], v[30:33]
	v_mfma_f32_16x16x32_bf16 v[26:29], v[160:163], v[184:187], v[26:29]
	v_mfma_f32_16x16x32_bf16 v[14:17], v[152:155], v[192:195], v[14:17]
	v_mfma_f32_16x16x32_bf16 v[10:13], v[160:163], v[192:195], v[10:13]
	s_setprio 0
	s_barrier
; #define PG8_STAGE(bufoff, gbase, voff) do { _Pragma("unroll") for (int _i = 0; _i < 2; ++_i) \
;         __builtin_amdgcn_global_load_lds((const unsigned*)((const char*)(gbase) + (voff)[_i]), (LAS unsigned*)(lds + (bufoff) + ldsw + _i * 8192), 16, 0, 0); } while (0)
; #define PG8_STAGE_A(bufoff, gbase, h, vv) do { if constexpr (GATHER) { _Pragma("unroll") for (int _i = 0; _i < 2; ++_i) \
;         __builtin_amdgcn_global_load_lds((const unsigned*)((const char*)(gbase) + (vv)[h][_i]), (LAS unsigned*)(lds + (bufoff) + ldsw + _i * 8192), 16, 0, 0); } \
;         else { PG8_STAGE(bufoff, (gbase) + (h) * hstepA, voffA); } } while (0)
; #define PG8_LDA(dst, b, h) do { _Pragma("unroll") for (int m = 0; m < 4; ++m) _Pragma("unroll") for (int k = 0; k < 2; ++k) dst[m][k] = *(const LAS bf16x8*)(lds + PG8_SA(b, h) + aoff + m * 2048 + k * 1024); } while (0)
; #define PG8_LDB(dst, b, h) do { _Pragma("unroll") for (int n = 0; n < 2; ++n) _Pragma("unroll") for (int k = 0; k < 2; ++k) dst[n][k] = *(const LAS bf16x8*)(lds + PG8_SB(b, h) + boff + n * 2048 + k * 1024); } while (0)
; #define PG8_MMA(ai, bj, At, Bt) do { __builtin_amdgcn_s_setprio(1); _Pragma("unroll") for (int m = 0; m < 4; ++m) _Pragma("unroll") for (int n = 0; n < 2; ++n) _Pragma("unroll") for (int k = 0; k < 2; ++k) \
;         acc[ai][bj][m][n] = __builtin_amdgcn_mfma_f32_16x16x32_bf16(Bt[n][k], At[m][k], acc[ai][bj][m][n], 0, 0, 0); __builtin_amdgcn_s_setprio(0); } while (0)
; #define PG8_WAIT_V(n) asm volatile("s_waitcnt vmcnt(" #n ")" ::: "memory")
; #define PG8_WAIT_L(n) asm volatile("s_waitcnt lgkmcnt(" #n ")" ::: "memory")
; #define PG8_BAR __builtin_amdgcn_s_barrier()
; template <class Epi, class Sched>
; __device__ __forceinline__ void gemm_phase(LAS unsigned char* lds, const int K, const int lda, const int ldb, const Sched& S, const Epi& E) {
;     ...
;             PG8_BAR; PG8_WAIT_L(0); PG8_MMA(1, 0, At, B0); PG8_BAR; PG8_SCHED;
;             PG8_STAGE(PG8_SB(0, 1), b2 + hstepB, voffB);
;             PG8_WAIT_V(6); PG8_BAR; PG8_MMA(1, 1, At, B1); PG8_BAR;
;             PG8_LDB(B0, 1, 0); PG8_SCHED; PG8_LDA(At, 1, 0); PG8_STAGE_A(PG8_SA(0, 1), a2, 1, vcur);
;             PG8_WAIT_L(8); PG8_BAR; PG8_WAIT_L(0); PG8_MMA(0, 0, At, B0); PG8_BAR; PG8_SCHED;
;             PG8_LDB(B1, 1, 1); PG8_STAGE(PG8_SB(1, 0), b3, voffB);
;             PG8_BAR; PG8_WAIT_L(0); PG8_MMA(0, 1, At, B1); PG8_BAR;
	s_add_u32 s48, s16, 0x40000
	s_addc_u32 s49, s17, 0
	s_add_i32 s2, s2, s38
	v_lshl_add_u64 v[148:149], s[48:49], 0, v[132:133]
	s_mov_b32 m0, s2
	s_nop 0
	global_load_lds_dwordx4 v[148:149], off
	v_lshl_add_u64 v[148:149], s[48:49], 0, v[136:137]
	s_add_i32 m0, s2, 0x2000
	s_nop 0
	global_load_lds_dwordx4 v[148:149], off
	s_waitcnt vmcnt(6)
	s_barrier
	s_setprio 1
	v_mfma_f32_16x16x32_bf16 v[54:57], v[216:219], v[164:167], v[54:57]
	v_mfma_f32_16x16x32_bf16 v[50:53], v[224:227], v[164:167], v[50:53]
	v_mfma_f32_16x16x32_bf16 v[38:41], v[216:219], v[172:175], v[38:41]
	v_mfma_f32_16x16x32_bf16 v[34:37], v[224:227], v[172:175], v[34:37]
	v_mfma_f32_16x16x32_bf16 v[22:25], v[216:219], v[180:183], v[22:25]
	v_mfma_f32_16x16x32_bf16 v[18:21], v[224:227], v[180:183], v[18:21]
	v_mfma_f32_16x16x32_bf16 v[6:9], v[216:219], v[188:191], v[6:9]
	v_mfma_f32_16x16x32_bf16 v[2:5], v[224:227], v[188:191], v[2:5]
	v_mfma_f32_16x16x32_bf16 v[54:57], v[220:223], v[168:171], v[54:57]
	v_mfma_f32_16x16x32_bf16 v[50:53], v[228:231], v[168:171], v[50:53]
	v_mfma_f32_16x16x32_bf16 v[38:41], v[220:223], v[176:179], v[38:41]
	v_mfma_f32_16x16x32_bf16 v[34:37], v[228:231], v[176:179], v[34:37]
	v_mfma_f32_16x16x32_bf16 v[22:25], v[220:223], v[184:187], v[22:25]
	v_mfma_f32_16x16x32_bf16 v[18:21], v[228:231], v[184:187], v[18:21]
	v_mfma_f32_16x16x32_bf16 v[6:9], v[220:223], v[192:195], v[6:9]
	v_mfma_f32_16x16x32_bf16 v[2:5], v[228:231], v[192:195], v[2:5]
	s_setprio 0
	s_add_i32 s2, 0, 0x18000
	v_add_u32_e32 v0, s2, v146
	s_barrier
	ds_read_b128 v[148:151], v0
	ds_read_b128 v[152:155], v0 offset:1024
	ds_read_b128 v[156:159], v0 offset:2048
	ds_read_b128 v[160:163], v0 offset:3072
	s_add_u32 s18, s18, 0x40000
	s_addc_u32 s19, s19, 0
	s_mov_b32 m0, s41
	v_lshl_add_u64 v[216:217], s[18:19], 0, v[130:131]
	ds_read_b128 v[164:167], v147 offset:32768
	ds_read_b128 v[168:171], v147 offset:33792
	ds_read_b128 v[172:175], v147 offset:34816
	ds_read_b128 v[176:179], v147 offset:35840
	ds_read_b128 v[180:183], v147 offset:36864
	ds_read_b128 v[184:187], v147 offset:37888
	ds_read_b128 v[188:191], v147 offset:38912
	ds_read_b128 v[192:195], v147 offset:39936
	global_load_lds_dwordx4 v[216:217], off
	v_lshl_add_u64 v[216:217], s[18:19], 0, v[134:135]
	s_mov_b32 m0, s42
	s_nop 0
	global_load_lds_dwordx4 v[216:217], off
	s_waitcnt lgkmcnt(8)
	s_barrier
	s_waitcnt lgkmcnt(0)
	s_setprio 1
	v_mfma_f32_16x16x32_bf16 v[126:129], v[148:151], v[164:167], v[126:129]
	v_mfma_f32_16x16x32_bf16 v[122:125], v[156:159], v[164:167], v[122:125]
	v_mfma_f32_16x16x32_bf16 v[110:113], v[148:151], v[172:175], v[110:113]
	v_mfma_f32_16x16x32_bf16 v[106:109], v[156:159], v[172:175], v[106:109]
	v_mfma_f32_16x16x32_bf16 v[94:97], v[148:151], v[180:183], v[94:97]
	v_mfma_f32_16x16x32_bf16 v[90:93], v[156:159], v[180:183], v[90:93]
	v_mfma_f32_16x16x32_bf16 v[78:81], v[148:151], v[188:191], v[78:81]
	v_mfma_f32_16x16x32_bf16 v[74:77], v[156:159], v[188:191], v[74:77]
	v_mfma_f32_16x16x32_bf16 v[126:129], v[152:155], v[168:171], v[126:129]
	v_mfma_f32_16x16x32_bf16 v[122:125], v[160:163], v[168:171], v[122:125]
	v_mfma_f32_16x16x32_bf16 v[110:113], v[152:155], v[176:179], v[110:113]
	v_mfma_f32_16x16x32_bf16 v[106:109], v[160:163], v[176:179], v[106:109]
	v_mfma_f32_16x16x32_bf16 v[94:97], v[152:155], v[184:187], v[94:97]
	v_mfma_f32_16x16x32_bf16 v[90:93], v[160:163], v[184:187], v[90:93]
	v_mfma_f32_16x16x32_bf16 v[78:81], v[152:155], v[192:195], v[78:81]
	v_mfma_f32_16x16x32_bf16 v[74:77], v[160:163], v[192:195], v[74:77]
	s_setprio 0
	s_barrier
	s_add_i32 s3, 0, 0x1c000
	s_add_i32 s2, s2, s38
	v_add_u32_e32 v0, s3, v146
	v_lshl_add_u64 v[144:145], v[144:145], 0, s[64:65]
	s_mov_b32 m0, s2
	ds_read_b128 v[216:219], v0
	ds_read_b128 v[220:223], v0 offset:1024
	ds_read_b128 v[224:227], v0 offset:2048
	ds_read_b128 v[228:231], v0 offset:3072
	global_load_lds_dwordx4 v[144:145], off
	v_lshl_add_u64 v[144:145], v[232:233], 0, s[64:65]
	s_add_i32 m0, s2, 0x2000
	s_nop 0
	global_load_lds_dwordx4 v[144:145], off
	s_barrier
; #define PG8_STAGE(bufoff, gbase, voff) do { _Pragma("unroll") for (int _i = 0; _i < 2; ++_i) \
;         __builtin_amdgcn_global_load_lds((const unsigned*)((const char*)(gbase) + (voff)[_i]), (LAS unsigned*)(lds + (bufoff) + ldsw + _i * 8192), 16, 0, 0); } while (0)
; #define PG8_STAGE_A(bufoff, gbase, h, vv) do { if constexpr (GATHER) { _Pragma("unroll") for (int _i = 0; _i < 2; ++_i) \
;         __builtin_amdgcn_global_load_lds((const unsigned*)((const char*)(gbase) + (vv)[h][_i]), (LAS unsigned*)(lds + (bufoff) + ldsw + _i * 8192), 16, 0, 0); } \
;         else { PG8_STAGE(bufoff, (gbase) + (h) * hstepA, voffA); } } while (0)
; #define PG8_LDA(dst, b, h) do { _Pragma("unroll") for (int m = 0; m < 4; ++m) _Pragma("unroll") for (int k = 0; k < 2; ++k) dst[m][k] = *(const LAS bf16x8*)(lds + PG8_SA(b, h) + aoff + m * 2048 + k * 1024); } while (0)
; #define PG8_MMA(ai, bj, At, Bt) do { __builtin_amdgcn_s_setprio(1); _Pragma("unroll") for (int m = 0; m < 4; ++m) _Pragma("unroll") for (int n = 0; n < 2; ++n) _Pragma("unroll") for (int k = 0; k < 2; ++k) \
;         acc[ai][bj][m][n] = __builtin_amdgcn_mfma_f32_16x16x32_bf16(Bt[n][k], At[m][k], acc[ai][bj][m][n], 0, 0, 0); __builtin_amdgcn_s_setprio(0); } while (0)
; #define PG8_WAIT_V(n) asm volatile("s_waitcnt vmcnt(" #n ")" ::: "memory")
; #define PG8_WAIT_L(n) asm volatile("s_waitcnt lgkmcnt(" #n ")" ::: "memory")
; #define PG8_BAR __builtin_amdgcn_s_barrier()
; #define PG8_SCHED __builtin_amdgcn_sched_barrier(0)
; template <class Epi, class Sched>
; __device__ __forceinline__ void gemm_phase(LAS unsigned char* lds, const int K, const int lda, const int ldb, const Sched& S, const Epi& E) {
;     ...
;             PG8_BAR; PG8_WAIT_L(0); PG8_MMA(0, 1, At, B1); PG8_BAR;
;             PG8_LDA(At, 1, 1); PG8_STAGE_A(PG8_SA(1, 0), a3, 0, vcur);
;             PG8_BAR; PG8_WAIT_L(0); PG8_MMA(1, 0, At, B0); PG8_BAR; PG8_SCHED;
;             PG8_STAGE(PG8_SB(1, 1), b3 + hstepB, voffB);
;             PG8_WAIT_V(6); PG8_BAR; PG8_MMA(1, 1, At, B1); PG8_BAR;
;         }
;     ...
;     PG8_WAIT_V(0);
;     if (wr == 0) PG8_BAR;
;     PG8_BAR;
	s_waitcnt lgkmcnt(0)
	s_setprio 1
	v_mfma_f32_16x16x32_bf16 v[118:121], v[216:219], v[164:167], v[118:121]
	v_mfma_f32_16x16x32_bf16 v[114:117], v[224:227], v[164:167], v[114:117]
	v_mfma_f32_16x16x32_bf16 v[102:105], v[216:219], v[172:175], v[102:105]
	v_mfma_f32_16x16x32_bf16 v[98:101], v[224:227], v[172:175], v[98:101]
	v_mfma_f32_16x16x32_bf16 v[86:89], v[216:219], v[180:183], v[86:89]
	v_mfma_f32_16x16x32_bf16 v[82:85], v[224:227], v[180:183], v[82:85]
	v_mfma_f32_16x16x32_bf16 v[70:73], v[216:219], v[188:191], v[70:73]
	v_mfma_f32_16x16x32_bf16 v[66:69], v[224:227], v[188:191], v[66:69]
	v_mfma_f32_16x16x32_bf16 v[118:121], v[220:223], v[168:171], v[118:121]
	v_mfma_f32_16x16x32_bf16 v[114:117], v[228:231], v[168:171], v[114:117]
	v_mfma_f32_16x16x32_bf16 v[102:105], v[220:223], v[176:179], v[102:105]
	v_mfma_f32_16x16x32_bf16 v[98:101], v[228:231], v[176:179], v[98:101]
	v_mfma_f32_16x16x32_bf16 v[86:89], v[220:223], v[184:187], v[86:89]
	v_mfma_f32_16x16x32_bf16 v[82:85], v[228:231], v[184:187], v[82:85]
	v_mfma_f32_16x16x32_bf16 v[70:73], v[220:223], v[192:195], v[70:73]
	v_mfma_f32_16x16x32_bf16 v[66:69], v[228:231], v[192:195], v[66:69]
	s_setprio 0
	s_mov_b32 m0, s44
	v_lshl_add_u64 v[144:145], v[234:235], 0, s[64:65]
	s_barrier
	ds_read_b128 v[164:167], v147 offset:49152
	ds_read_b128 v[168:171], v147 offset:50176
	ds_read_b128 v[172:175], v147 offset:51200
	ds_read_b128 v[176:179], v147 offset:52224
	ds_read_b128 v[180:183], v147 offset:53248
	ds_read_b128 v[184:187], v147 offset:54272
	ds_read_b128 v[188:191], v147 offset:55296
	ds_read_b128 v[192:195], v147 offset:56320
	global_load_lds_dwordx4 v[144:145], off
	v_lshl_add_u64 v[144:145], v[236:237], 0, s[64:65]
	s_mov_b32 m0, s45
	s_nop 0
	global_load_lds_dwordx4 v[144:145], off
	s_barrier
	s_waitcnt lgkmcnt(0)
	s_setprio 1
	v_mfma_f32_16x16x32_bf16 v[62:65], v[148:151], v[164:167], v[62:65]
	v_mfma_f32_16x16x32_bf16 v[58:61], v[156:159], v[164:167], v[58:61]
	v_mfma_f32_16x16x32_bf16 v[46:49], v[148:151], v[172:175], v[46:49]
	v_mfma_f32_16x16x32_bf16 v[42:45], v[156:159], v[172:175], v[42:45]
	v_mfma_f32_16x16x32_bf16 v[30:33], v[148:151], v[180:183], v[30:33]
	v_mfma_f32_16x16x32_bf16 v[26:29], v[156:159], v[180:183], v[26:29]
	v_mfma_f32_16x16x32_bf16 v[14:17], v[148:151], v[188:191], v[14:17]
	v_mfma_f32_16x16x32_bf16 v[10:13], v[156:159], v[188:191], v[10:13]
	v_mfma_f32_16x16x32_bf16 v[62:65], v[152:155], v[168:171], v[62:65]
	v_mfma_f32_16x16x32_bf16 v[58:61], v[160:163], v[168:171], v[58:61]
	v_mfma_f32_16x16x32_bf16 v[46:49], v[152:155], v[176:179], v[46:49]
	v_mfma_f32_16x16x32_bf16 v[42:45], v[160:163], v[176:179], v[42:45]
	v_mfma_f32_16x16x32_bf16 v[30:33], v[152:155], v[184:187], v[30:33]
	v_mfma_f32_16x16x32_bf16 v[26:29], v[160:163], v[184:187], v[26:29]
	v_mfma_f32_16x16x32_bf16 v[14:17], v[152:155], v[192:195], v[14:17]
	v_mfma_f32_16x16x32_bf16 v[10:13], v[160:163], v[192:195], v[10:13]
	s_setprio 0
	s_barrier
	s_add_u32 s16, s16, 0x40080
	s_addc_u32 s17, s17, 0
	s_add_i32 s2, s3, s38
	v_lshl_add_u64 v[144:145], s[16:17], 0, v[132:133]
	s_mov_b32 m0, s2
	s_nop 0
	global_load_lds_dwordx4 v[144:145], off
	v_lshl_add_u64 v[144:145], s[16:17], 0, v[136:137]
	s_add_i32 m0, s2, 0x2000
	s_nop 0
	global_load_lds_dwordx4 v[144:145], off
	s_waitcnt vmcnt(6)
	s_barrier
	s_setprio 1
	v_mfma_f32_16x16x32_bf16 v[54:57], v[216:219], v[164:167], v[54:57]
	v_mfma_f32_16x16x32_bf16 v[50:53], v[224:227], v[164:167], v[50:53]
	v_mfma_f32_16x16x32_bf16 v[38:41], v[216:219], v[172:175], v[38:41]
	v_mfma_f32_16x16x32_bf16 v[34:37], v[224:227], v[172:175], v[34:37]
	v_mfma_f32_16x16x32_bf16 v[22:25], v[216:219], v[180:183], v[22:25]
	v_mfma_f32_16x16x32_bf16 v[18:21], v[224:227], v[180:183], v[18:21]
	v_mfma_f32_16x16x32_bf16 v[6:9], v[216:219], v[188:191], v[6:9]
	v_mfma_f32_16x16x32_bf16 v[2:5], v[224:227], v[188:191], v[2:5]
	v_mfma_f32_16x16x32_bf16 v[54:57], v[220:223], v[168:171], v[54:57]
	v_mfma_f32_16x16x32_bf16 v[50:53], v[228:231], v[168:171], v[50:53]
	v_mfma_f32_16x16x32_bf16 v[38:41], v[220:223], v[176:179], v[38:41]
	v_mfma_f32_16x16x32_bf16 v[34:37], v[228:231], v[176:179], v[34:37]
	v_mfma_f32_16x16x32_bf16 v[22:25], v[220:223], v[184:187], v[22:25]
	v_mfma_f32_16x16x32_bf16 v[18:21], v[228:231], v[184:187], v[18:21]
	v_mfma_f32_16x16x32_bf16 v[6:9], v[220:223], v[192:195], v[6:9]
	v_mfma_f32_16x16x32_bf16 v[2:5], v[228:231], v[192:195], v[2:5]
	s_setprio 0
	s_add_i32 s9, s9, 2
	s_add_u32 s14, s14, 0x100
	s_addc_u32 s15, s15, 0
	s_add_u32 s1, s1, 0x100
	s_addc_u32 s7, s7, 0
	s_cmp_gt_u32 s9, 13
	s_barrier
	s_cbranch_scc0 .LBB0_969
	s_cmpk_gt_u32 s36, 0xff
	s_cbranch_scc1 .Lgx_f_pre
	s_barrier
